# select: hand-written threshold search (batched candidate loads, v_cmp+s_bcnt1 counting); indexer MFMA/VALU fine interleave; attention PV V-fragment ds_read2_b64 split into two ds_read_b64
# speedup vs baseline: 1.0285x; 1.0217x over previous
.LBB0_455:
	s_andn2_b64 vcc, exec, s[20:21]
	s_waitcnt vmcnt(6)
	ds_write_b128 v176, v[124:127] offset:17408
	ds_write_b128 v176, v[120:123] offset:17424
	s_cbranch_vccnz .LBB0_457
	ds_read_b64 v[80:81], v181
	ds_read_b64 v[82:83], v181 offset:16
	ds_read_b64 v[84:85], v181 offset:32
	ds_read_b64 v[86:87], v181 offset:48
	ds_read_b64 v[88:89], v181 offset:64
	ds_read_b64 v[90:91], v181 offset:80
	ds_read_b64 v[92:93], v181 offset:96
	ds_read_b64 v[94:95], v181 offset:112
	s_waitcnt lgkmcnt(6)
	v_mfma_f32_32x32x16_bf16 v[64:79], v[80:83], v[132:135], v[64:79]
	s_waitcnt lgkmcnt(4)
	v_mfma_f32_32x32x16_bf16 v[64:79], v[84:87], v[140:143], v[64:79]
	v_add_u32_e32 v0, 0x1000, v181
	ds_read_b64 v[80:81], v0 offset:256
	ds_read_b64 v[82:83], v0 offset:272
	ds_read_b64 v[84:85], v0 offset:288
	ds_read_b64 v[86:87], v0 offset:304
	s_waitcnt lgkmcnt(6)
	v_mfma_f32_32x32x16_bf16 v[64:79], v[88:91], v[136:139], v[64:79]
	s_waitcnt lgkmcnt(4)
	v_mfma_f32_32x32x16_bf16 v[64:79], v[92:95], v[144:147], v[64:79]
	ds_read_b64 v[88:89], v0 offset:320
	ds_read_b64 v[90:91], v0 offset:336
	ds_read_b64 v[92:93], v0 offset:352
	ds_read_b64 v[94:95], v0 offset:368
	s_waitcnt lgkmcnt(6)
	v_mfma_f32_32x32x16_bf16 v[48:63], v[80:83], v[132:135], v[48:63]
	s_waitcnt lgkmcnt(4)
	v_mfma_f32_32x32x16_bf16 v[48:63], v[84:87], v[140:143], v[48:63]
	v_add_u32_e32 v0, 0x2000, v181
	ds_read_b64 v[80:81], v0 offset:512
	ds_read_b64 v[82:83], v0 offset:528
	ds_read_b64 v[84:85], v0 offset:544
	ds_read_b64 v[86:87], v0 offset:560
	s_waitcnt lgkmcnt(6)
	v_mfma_f32_32x32x16_bf16 v[48:63], v[88:91], v[136:139], v[48:63]
	s_waitcnt lgkmcnt(4)
	v_mfma_f32_32x32x16_bf16 v[48:63], v[92:95], v[144:147], v[48:63]
	ds_read_b64 v[88:89], v0 offset:576
	ds_read_b64 v[90:91], v0 offset:592
	ds_read_b64 v[92:93], v0 offset:608
	ds_read_b64 v[94:95], v0 offset:624
	s_waitcnt lgkmcnt(6)
	v_mfma_f32_32x32x16_bf16 v[32:47], v[80:83], v[132:135], v[32:47]
	s_waitcnt lgkmcnt(4)
	v_mfma_f32_32x32x16_bf16 v[32:47], v[84:87], v[140:143], v[32:47]
	v_add_u32_e32 v0, 0x3000, v181
	ds_read_b64 v[80:81], v0 offset:768
	ds_read_b64 v[82:83], v0 offset:784
	ds_read_b64 v[84:85], v0 offset:800
	ds_read_b64 v[86:87], v0 offset:816
	s_waitcnt lgkmcnt(6)
	v_mfma_f32_32x32x16_bf16 v[32:47], v[88:91], v[136:139], v[32:47]
	s_waitcnt lgkmcnt(4)
	v_mfma_f32_32x32x16_bf16 v[32:47], v[92:95], v[144:147], v[32:47]
	ds_read_b64 v[88:89], v0 offset:832
	ds_read_b64 v[90:91], v0 offset:848
	ds_read_b64 v[92:93], v0 offset:864
	ds_read_b64 v[94:95], v0 offset:880
	s_waitcnt lgkmcnt(6)
	v_mfma_f32_32x32x16_bf16 v[16:31], v[80:83], v[132:135], v[16:31]
	s_waitcnt lgkmcnt(4)
	v_mfma_f32_32x32x16_bf16 v[16:31], v[84:87], v[140:143], v[16:31]
	s_waitcnt lgkmcnt(2)
	v_mfma_f32_32x32x16_bf16 v[16:31], v[88:91], v[136:139], v[16:31]
	s_waitcnt lgkmcnt(0)
	v_mfma_f32_32x32x16_bf16 v[16:31], v[92:95], v[144:147], v[16:31]

.LBB0_462:
	s_andn2_b64 vcc, exec, s[20:21]
	s_waitcnt vmcnt(6)
	ds_write_b128 v176, v[128:131]
	ds_write_b128 v176, v[10:13] offset:16
	s_cbranch_vccnz .LBB0_464
	v_add_u32_e32 v0, 0x4000, v181
	ds_read_b64 v[10:11], v0 offset:1024
	ds_read_b64 v[12:13], v0 offset:1040
	ds_read_b64 v[80:81], v0 offset:1056
	ds_read_b64 v[82:83], v0 offset:1072
	ds_read_b64 v[84:85], v0 offset:1088
	ds_read_b64 v[86:87], v0 offset:1104
	ds_read_b64 v[88:89], v0 offset:1120
	ds_read_b64 v[90:91], v0 offset:1136
	s_waitcnt lgkmcnt(6)
	v_mfma_f32_32x32x16_bf16 v[64:79], v[10:13], v[148:151], v[64:79]
	s_waitcnt lgkmcnt(4)
	v_mfma_f32_32x32x16_bf16 v[64:79], v[80:83], v[156:159], v[64:79]
	v_add_u32_e32 v0, 0x5000, v181
	ds_read_b64 v[10:11], v0 offset:1280
	ds_read_b64 v[12:13], v0 offset:1296
	ds_read_b64 v[80:81], v0 offset:1312
	ds_read_b64 v[82:83], v0 offset:1328
	s_waitcnt lgkmcnt(6)
	v_mfma_f32_32x32x16_bf16 v[64:79], v[84:87], v[152:155], v[64:79]
	s_waitcnt lgkmcnt(4)
	v_mfma_f32_32x32x16_bf16 v[64:79], v[88:91], v[160:163], v[64:79]
	ds_read_b64 v[84:85], v0 offset:1344
	ds_read_b64 v[86:87], v0 offset:1360
	ds_read_b64 v[88:89], v0 offset:1376
	ds_read_b64 v[90:91], v0 offset:1392
	s_waitcnt lgkmcnt(6)
	v_mfma_f32_32x32x16_bf16 v[48:63], v[10:13], v[148:151], v[48:63]
	s_waitcnt lgkmcnt(4)
	v_mfma_f32_32x32x16_bf16 v[48:63], v[80:83], v[156:159], v[48:63]
	v_add_u32_e32 v0, 0x6000, v181
	ds_read_b64 v[10:11], v0 offset:1536
	ds_read_b64 v[12:13], v0 offset:1552
	ds_read_b64 v[80:81], v0 offset:1568
	ds_read_b64 v[82:83], v0 offset:1584
	s_waitcnt lgkmcnt(6)
	v_mfma_f32_32x32x16_bf16 v[48:63], v[84:87], v[152:155], v[48:63]
	s_waitcnt lgkmcnt(4)
	v_mfma_f32_32x32x16_bf16 v[48:63], v[88:91], v[160:163], v[48:63]
	ds_read_b64 v[84:85], v0 offset:1600
	ds_read_b64 v[86:87], v0 offset:1616
	ds_read_b64 v[88:89], v0 offset:1632
	ds_read_b64 v[90:91], v0 offset:1648
	s_waitcnt lgkmcnt(6)
	v_mfma_f32_32x32x16_bf16 v[32:47], v[10:13], v[148:151], v[32:47]
	s_waitcnt lgkmcnt(4)
	v_mfma_f32_32x32x16_bf16 v[32:47], v[80:83], v[156:159], v[32:47]
	v_add_u32_e32 v0, 0x7000, v181
	ds_read_b64 v[10:11], v0 offset:1792
	ds_read_b64 v[12:13], v0 offset:1808
	ds_read_b64 v[80:81], v0 offset:1824
	ds_read_b64 v[82:83], v0 offset:1840
	s_waitcnt lgkmcnt(6)
	v_mfma_f32_32x32x16_bf16 v[32:47], v[84:87], v[152:155], v[32:47]
	s_waitcnt lgkmcnt(4)
	v_mfma_f32_32x32x16_bf16 v[32:47], v[88:91], v[160:163], v[32:47]
	ds_read_b64 v[84:85], v0 offset:1856
	ds_read_b64 v[86:87], v0 offset:1872
	ds_read_b64 v[88:89], v0 offset:1888
	ds_read_b64 v[90:91], v0 offset:1904
	s_waitcnt lgkmcnt(6)
	v_mfma_f32_32x32x16_bf16 v[16:31], v[10:13], v[148:151], v[16:31]
	s_waitcnt lgkmcnt(4)
	v_mfma_f32_32x32x16_bf16 v[16:31], v[80:83], v[156:159], v[16:31]
	s_waitcnt lgkmcnt(2)
	v_mfma_f32_32x32x16_bf16 v[16:31], v[84:87], v[152:155], v[16:31]
	s_waitcnt lgkmcnt(0)
	v_mfma_f32_32x32x16_bf16 v[16:31], v[88:91], v[160:163], v[16:31]

.LBB0_487:
	ds_read_b64 v[2:3], v226
	ds_read_b64 v[4:5], v226 offset:16
	ds_read_b64 v[6:7], v226 offset:32
	ds_read_b64 v[8:9], v226 offset:48
	ds_read_b64 v[10:11], v226 offset:64
	ds_read_b64 v[12:13], v226 offset:80
	ds_read_b64 v[14:15], v226 offset:96
	ds_read_b64 v[16:17], v226 offset:112
	s_waitcnt lgkmcnt(6)
	v_mfma_f32_32x32x16_bf16 v[66:81], v[2:5], v[178:181], v[66:81]
	s_waitcnt lgkmcnt(4)
	v_mfma_f32_32x32x16_bf16 v[66:81], v[6:9], v[186:189], v[66:81]
	v_add_u32_e32 v0, 0x1000, v226
	ds_read_b64 v[2:3], v0 offset:256
	ds_read_b64 v[4:5], v0 offset:272
	ds_read_b64 v[6:7], v0 offset:288
	ds_read_b64 v[8:9], v0 offset:304
	s_waitcnt lgkmcnt(6)
	v_mfma_f32_32x32x16_bf16 v[66:81], v[10:13], v[182:185], v[66:81]
	s_waitcnt lgkmcnt(4)
	v_mfma_f32_32x32x16_bf16 v[66:81], v[14:17], v[190:193], v[66:81]
	ds_read_b64 v[10:11], v0 offset:320
	ds_read_b64 v[12:13], v0 offset:336
	ds_read_b64 v[14:15], v0 offset:352
	ds_read_b64 v[16:17], v0 offset:368
	s_waitcnt lgkmcnt(6)
	v_mfma_f32_32x32x16_bf16 v[82:97], v[2:5], v[178:181], v[82:97]
	s_waitcnt lgkmcnt(4)
	v_mfma_f32_32x32x16_bf16 v[82:97], v[6:9], v[186:189], v[82:97]
	v_add_u32_e32 v0, 0x2000, v226
	ds_read_b64 v[2:3], v0 offset:512
	ds_read_b64 v[4:5], v0 offset:528
	ds_read_b64 v[6:7], v0 offset:544
	ds_read_b64 v[8:9], v0 offset:560
	s_waitcnt lgkmcnt(6)
	v_mfma_f32_32x32x16_bf16 v[82:97], v[10:13], v[182:185], v[82:97]
	s_waitcnt lgkmcnt(4)
	v_mfma_f32_32x32x16_bf16 v[82:97], v[14:17], v[190:193], v[82:97]
	ds_read_b64 v[10:11], v0 offset:576
	ds_read_b64 v[12:13], v0 offset:592
	ds_read_b64 v[14:15], v0 offset:608
	ds_read_b64 v[16:17], v0 offset:624
	s_waitcnt lgkmcnt(6)
	v_mfma_f32_32x32x16_bf16 v[98:113], v[2:5], v[178:181], v[98:113]
	s_waitcnt lgkmcnt(4)
	v_mfma_f32_32x32x16_bf16 v[98:113], v[6:9], v[186:189], v[98:113]
	v_add_u32_e32 v0, 0x3000, v226
	ds_read_b64 v[2:3], v0 offset:768
	ds_read_b64 v[4:5], v0 offset:784
	ds_read_b64 v[6:7], v0 offset:800
	ds_read_b64 v[8:9], v0 offset:816
	s_waitcnt lgkmcnt(6)
	v_mfma_f32_32x32x16_bf16 v[98:113], v[10:13], v[182:185], v[98:113]
	s_waitcnt lgkmcnt(4)
	v_mfma_f32_32x32x16_bf16 v[98:113], v[14:17], v[190:193], v[98:113]
	ds_read_b64 v[10:11], v0 offset:832
	ds_read_b64 v[12:13], v0 offset:848
	ds_read_b64 v[14:15], v0 offset:864
	ds_read_b64 v[16:17], v0 offset:880
	s_waitcnt lgkmcnt(6)
	v_mfma_f32_32x32x16_bf16 v[114:129], v[2:5], v[178:181], v[114:129]
	s_waitcnt lgkmcnt(4)
	v_mfma_f32_32x32x16_bf16 v[114:129], v[6:9], v[186:189], v[114:129]
	s_waitcnt lgkmcnt(2)
	v_mfma_f32_32x32x16_bf16 v[114:129], v[10:13], v[182:185], v[114:129]
	s_waitcnt lgkmcnt(0)
	v_mfma_f32_32x32x16_bf16 v[114:129], v[14:17], v[190:193], v[114:129]

.LBB0_499:
	v_mov_b64_e32 v[128:129], v[16:17]
	v_mov_b64_e32 v[112:113], v[32:33]
	v_mov_b64_e32 v[96:97], v[48:49]
	v_mov_b64_e32 v[80:81], v[64:65]
	s_and_b64 vcc, exec, s[4:5]
	v_mov_b64_e32 v[126:127], v[14:15]
	v_mov_b64_e32 v[124:125], v[12:13]
	v_mov_b64_e32 v[122:123], v[10:11]
	v_mov_b64_e32 v[120:121], v[8:9]
	v_mov_b64_e32 v[118:119], v[6:7]
	v_mov_b64_e32 v[116:117], v[4:5]
	v_mov_b64_e32 v[114:115], v[2:3]
	v_mov_b64_e32 v[110:111], v[30:31]
	v_mov_b64_e32 v[108:109], v[28:29]
	v_mov_b64_e32 v[106:107], v[26:27]
	v_mov_b64_e32 v[104:105], v[24:25]
	v_mov_b64_e32 v[102:103], v[22:23]
	v_mov_b64_e32 v[100:101], v[20:21]
	v_mov_b64_e32 v[98:99], v[18:19]
	v_mov_b64_e32 v[94:95], v[46:47]
	v_mov_b64_e32 v[92:93], v[44:45]
	v_mov_b64_e32 v[90:91], v[42:43]
	v_mov_b64_e32 v[88:89], v[40:41]
	v_mov_b64_e32 v[86:87], v[38:39]
	v_mov_b64_e32 v[84:85], v[36:37]
	v_mov_b64_e32 v[82:83], v[34:35]
	v_mov_b64_e32 v[78:79], v[62:63]
	v_mov_b64_e32 v[76:77], v[60:61]
	v_mov_b64_e32 v[74:75], v[58:59]
	v_mov_b64_e32 v[72:73], v[56:57]
	v_mov_b64_e32 v[70:71], v[54:55]
	v_mov_b64_e32 v[68:69], v[52:53]
	v_mov_b64_e32 v[66:67], v[50:51]
	s_waitcnt vmcnt(6)
	ds_write_b128 v219, v[158:161]
	ds_write_b128 v219, v[154:157] offset:16
	s_cbranch_vccnz .LBB0_483
	v_add_u32_e32 v0, 0x4000, v226
	ds_read_b64 v[82:83], v0 offset:1024
	ds_read_b64 v[84:85], v0 offset:1040
	ds_read_b64 v[86:87], v0 offset:1056
	ds_read_b64 v[88:89], v0 offset:1072
	ds_read_b64 v[90:91], v0 offset:1088
	ds_read_b64 v[92:93], v0 offset:1104
	ds_read_b64 v[94:95], v0 offset:1120
	ds_read_b64 v[96:97], v0 offset:1136
	v_mov_b64_e32 v[80:81], v[64:65]
	v_mov_b64_e32 v[78:79], v[62:63]
	v_mov_b64_e32 v[76:77], v[60:61]
	v_mov_b64_e32 v[74:75], v[58:59]
	v_mov_b64_e32 v[72:73], v[56:57]
	v_mov_b64_e32 v[70:71], v[54:55]
	v_mov_b64_e32 v[68:69], v[52:53]
	v_mov_b64_e32 v[66:67], v[50:51]
	s_waitcnt lgkmcnt(6)
	s_nop 0
	v_mfma_f32_32x32x16_bf16 v[66:81], v[82:85], v[162:165], v[66:81]
	s_waitcnt lgkmcnt(4)
	v_mfma_f32_32x32x16_bf16 v[66:81], v[86:89], v[170:173], v[66:81]
	v_add_u32_e32 v0, 0x5000, v226
	ds_read_b64 v[98:99], v0 offset:1280
	ds_read_b64 v[100:101], v0 offset:1296
	ds_read_b64 v[102:103], v0 offset:1312
	ds_read_b64 v[104:105], v0 offset:1328
	s_waitcnt lgkmcnt(6)
	v_mfma_f32_32x32x16_bf16 v[66:81], v[90:93], v[166:169], v[66:81]
	s_waitcnt lgkmcnt(4)
	v_mfma_f32_32x32x16_bf16 v[66:81], v[94:97], v[174:177], v[66:81]
	ds_read_b64 v[106:107], v0 offset:1344
	ds_read_b64 v[108:109], v0 offset:1360
	ds_read_b64 v[110:111], v0 offset:1376
	ds_read_b64 v[112:113], v0 offset:1392
	v_mov_b64_e32 v[96:97], v[48:49]
	v_mov_b64_e32 v[94:95], v[46:47]
	v_mov_b64_e32 v[92:93], v[44:45]
	v_mov_b64_e32 v[90:91], v[42:43]
	v_mov_b64_e32 v[88:89], v[40:41]
	v_mov_b64_e32 v[86:87], v[38:39]
	v_mov_b64_e32 v[84:85], v[36:37]
	v_mov_b64_e32 v[82:83], v[34:35]
	s_waitcnt lgkmcnt(6)
	s_nop 0
	v_mfma_f32_32x32x16_bf16 v[82:97], v[98:101], v[162:165], v[82:97]
	s_waitcnt lgkmcnt(4)
	v_mfma_f32_32x32x16_bf16 v[82:97], v[102:105], v[170:173], v[82:97]
	v_add_u32_e32 v0, 0x6000, v226
	ds_read_b64 v[114:115], v0 offset:1536
	ds_read_b64 v[116:117], v0 offset:1552
	ds_read_b64 v[118:119], v0 offset:1568
	ds_read_b64 v[120:121], v0 offset:1584
	s_waitcnt lgkmcnt(6)
	v_mfma_f32_32x32x16_bf16 v[82:97], v[106:109], v[166:169], v[82:97]
	s_waitcnt lgkmcnt(4)
	v_mfma_f32_32x32x16_bf16 v[82:97], v[110:113], v[174:177], v[82:97]
	ds_read_b64 v[122:123], v0 offset:1600
	ds_read_b64 v[124:125], v0 offset:1616
	ds_read_b64 v[126:127], v0 offset:1632
	ds_read_b64 v[128:129], v0 offset:1648
	v_mov_b64_e32 v[112:113], v[32:33]
	v_mov_b64_e32 v[110:111], v[30:31]
	v_mov_b64_e32 v[108:109], v[28:29]
	v_mov_b64_e32 v[106:107], v[26:27]
	v_mov_b64_e32 v[104:105], v[24:25]
	v_mov_b64_e32 v[102:103], v[22:23]
	v_mov_b64_e32 v[100:101], v[20:21]
	v_mov_b64_e32 v[98:99], v[18:19]
	s_waitcnt lgkmcnt(6)
	s_nop 0
	v_mfma_f32_32x32x16_bf16 v[98:113], v[114:117], v[162:165], v[98:113]
	s_waitcnt lgkmcnt(4)
	v_mfma_f32_32x32x16_bf16 v[98:113], v[118:121], v[170:173], v[98:113]
	v_add_u32_e32 v0, 0x7000, v226
	ds_read_b64 v[154:155], v0 offset:1792
	ds_read_b64 v[156:157], v0 offset:1808
	ds_read_b64 v[158:159], v0 offset:1824
	ds_read_b64 v[160:161], v0 offset:1840
	s_waitcnt lgkmcnt(6)
	v_mfma_f32_32x32x16_bf16 v[98:113], v[122:125], v[166:169], v[98:113]
	s_waitcnt lgkmcnt(4)
	v_mfma_f32_32x32x16_bf16 v[98:113], v[126:129], v[174:177], v[98:113]
	ds_read_b64 v[200:201], v0 offset:1856
	ds_read_b64 v[202:203], v0 offset:1872
	ds_read_b64 v[230:231], v0 offset:1888
	ds_read_b64 v[232:233], v0 offset:1904
	v_mov_b64_e32 v[128:129], v[16:17]
	v_mov_b64_e32 v[126:127], v[14:15]
	v_mov_b64_e32 v[124:125], v[12:13]
	v_mov_b64_e32 v[122:123], v[10:11]
	v_mov_b64_e32 v[120:121], v[8:9]
	v_mov_b64_e32 v[118:119], v[6:7]
	v_mov_b64_e32 v[116:117], v[4:5]
	v_mov_b64_e32 v[114:115], v[2:3]
	s_waitcnt lgkmcnt(6)
	s_nop 0
	v_mfma_f32_32x32x16_bf16 v[114:129], v[154:157], v[162:165], v[114:129]
	s_waitcnt lgkmcnt(4)
	v_mfma_f32_32x32x16_bf16 v[114:129], v[158:161], v[170:173], v[114:129]
	s_waitcnt lgkmcnt(2)
	v_mfma_f32_32x32x16_bf16 v[114:129], v[200:203], v[166:169], v[114:129]
	s_waitcnt lgkmcnt(0)
	v_mfma_f32_32x32x16_bf16 v[114:129], v[230:233], v[174:177], v[114:129]
	s_branch .LBB0_483

.LBB0_532:
	v_mov_b32_e32 v129, v194
	v_readfirstlane_b32 s83, v194
	v_and_b32_e32 v180, 31, v194
	v_bfe_u32 v131, v194, 5, 1
	v_and_b32_e32 v243, 63, v194
	s_ashr_i32 s84, s83, 6
	s_lshl_b32 s0, s84, 5
	v_or_b32_e32 v130, s0, v180
	v_lshlrev_b32_e32 v243, 2, v243
	s_lshl_b32 s0, s2, 17
	s_lshl_b32 s1, s84, 8
	s_add_u32 s0, s0, s1
	s_add_u32 s8, s28, s0
	s_addc_u32 s9, s29, 0
	s_lshl_b32 s21, s84, 12
	s_cmp_lg_u32 s82, 0
	s_cbranch_scc1 .Lix_reload
	v_bfe_u32 v0, v194, 2, 1
	v_lshrrev_b32_e32 v1, 1, v194
	v_and_b32_e32 v1, 12, v1
	v_and_b32_e32 v228, 3, v194
	v_or_b32_e32 v1, v1, v228
	v_add_u32_e32 v0, s34, v0
	v_lshlrev_b32_e32 v0, 11, v0
	v_lshl_add_u32 v0, v1, 7, v0
	v_lshl_add_u32 v0, v131, 4, v0
	v_add_u32_e32 v1, 0x1000, v0
	global_load_dwordx4 v[70:73], v0, s[36:37]
	global_load_dwordx4 v[74:77], v0, s[36:37] offset:32
	global_load_dwordx4 v[78:81], v0, s[36:37] offset:64
	global_load_dwordx4 v[82:85], v0, s[36:37] offset:96
	global_load_dwordx4 v[86:89], v1, s[36:37]
	global_load_dwordx4 v[90:93], v1, s[36:37] offset:32
	global_load_dwordx4 v[94:97], v1, s[36:37] offset:64
	global_load_dwordx4 v[98:101], v1, s[36:37] offset:96
	v_add_u32_e32 v228, s34, v131
	v_lshlrev_b32_e32 v228, 6, v228
	global_load_dwordx4 v[22:25], v228, s[38:39]
	global_load_dwordx4 v[26:29], v228, s[38:39] offset:16
	global_load_dwordx4 v[30:33], v228, s[38:39] offset:32
	global_load_dwordx4 v[34:37], v228, s[38:39] offset:48
	global_load_dwordx2 v[244:245], v228, s[38:39] offset:128
	global_load_dwordx2 v[246:247], v228, s[38:39] offset:136
	global_load_dwordx2 v[248:249], v228, s[38:39] offset:144
	global_load_dwordx2 v[250:251], v228, s[38:39] offset:152
	global_load_dwordx2 v[252:253], v228, s[38:39] offset:160
	global_load_dwordx2 v[254:255], v228, s[38:39] offset:168
	global_load_dwordx2 v[200:201], v228, s[38:39] offset:176
	global_load_dwordx2 v[202:203], v228, s[38:39] offset:184
	v_lshrrev_b32_e32 v0, 2, v243
	v_lshrrev_b32_e32 v1, 3, v0
	v_lshrrev_b32_e32 v228, 4, v0
	v_and_b32_e32 v229, 7, v0
	v_xor_b32_e32 v228, v229, v228
	v_xor_b32_e32 v229, 4, v228
	s_lshl_b32 s0, s84, 12
	v_lshl_add_u32 v1, v1, 7, s0
	v_lshl_add_u32 v102, v228, 4, v1
	v_lshl_add_u32 v110, v229, 4, v1
	v_add_u32_e32 v110, 0x400, v110
	v_add_u32_e32 v112, 0x800, v102
	v_add_u32_e32 v193, 0x800, v110
	v_lshlrev_b32_e32 v0, 7, v130
	v_bfe_u32 v1, v180, 1, 3
	v_or_b32_e32 v228, 0, v131
	v_xor_b32_e32 v228, v228, v1
	v_lshl_add_u32 v5, v228, 4, v0
	v_or_b32_e32 v228, 2, v131
	v_xor_b32_e32 v228, v228, v1
	v_lshl_add_u32 v52, v228, 4, v0
	v_or_b32_e32 v228, 4, v131
	v_xor_b32_e32 v228, v228, v1
	v_lshl_add_u32 v55, v228, 4, v0
	v_or_b32_e32 v228, 6, v131
	v_xor_b32_e32 v228, v228, v1
	v_lshl_add_u32 v56, v228, 4, v0
	s_mov_b32 s6, s14
	s_mov_b32 s7, s15
	s_add_i32 s10, s0, 10496
	s_sub_i32 s11, s35, s84
	s_add_i32 m0, s10, 0
	s_nop 0
	global_load_lds_dwordx4 v102, s[6:7]
	s_add_i32 m0, s10, 1024
	s_nop 0
	global_load_lds_dwordx4 v110, s[6:7]
	s_add_i32 m0, s10, 2048
	s_nop 0
	global_load_lds_dwordx4 v112, s[6:7]
	s_add_i32 m0, s10, 3072
	s_nop 0
	global_load_lds_dwordx4 v193, s[6:7]
	s_add_u32 s6, s6, 0x8000
	s_addc_u32 s7, s7, 0
	s_add_i32 m0, s10, 32768
	s_nop 0
	global_load_lds_dwordx4 v102, s[6:7]
	s_add_i32 m0, s10, 33792
	s_nop 0
	global_load_lds_dwordx4 v110, s[6:7]
	s_add_i32 m0, s10, 34816
	s_nop 0
	global_load_lds_dwordx4 v112, s[6:7]
	s_add_i32 m0, s10, 35840
	s_nop 0
	global_load_lds_dwordx4 v193, s[6:7]
	s_add_u32 s6, s6, 0x8000
	s_addc_u32 s7, s7, 0
	s_add_i32 m0, s10, 65536
	s_nop 0
	global_load_lds_dwordx4 v102, s[6:7]
	s_add_i32 m0, s10, 66560
	s_nop 0
	global_load_lds_dwordx4 v110, s[6:7]
	s_add_i32 m0, s10, 67584
	s_nop 0
	global_load_lds_dwordx4 v112, s[6:7]
	s_add_i32 m0, s10, 68608
	s_nop 0
	global_load_lds_dwordx4 v193, s[6:7]
	s_add_u32 s6, s6, 0x8000
	s_addc_u32 s7, s7, 0
	s_waitcnt vmcnt(8)
	ds_read_b128 v[38:41], v5 offset:10496
	ds_read_b128 v[42:45], v52 offset:10496
	ds_read_b128 v[46:49], v55 offset:10496
	ds_read_b128 v[196:199], v56 offset:10496
	s_waitcnt lgkmcnt(3)
	v_mfma_f32_32x32x16_bf16 v[212:227], v[70:73], v[38:41], 0
	s_add_i32 m0, s10, 98304
	s_nop 0
	global_load_lds_dwordx4 v102, s[6:7]
	s_waitcnt lgkmcnt(2)
	v_mfma_f32_32x32x16_bf16 v[212:227], v[74:77], v[42:45], v[212:227]
	s_add_i32 m0, s10, 99328
	s_nop 0
	global_load_lds_dwordx4 v110, s[6:7]
	s_waitcnt lgkmcnt(1)
	v_mfma_f32_32x32x16_bf16 v[212:227], v[78:81], v[46:49], v[212:227]
	s_add_i32 m0, s10, 100352
	s_nop 0
	global_load_lds_dwordx4 v112, s[6:7]
	s_waitcnt lgkmcnt(0)
	v_mfma_f32_32x32x16_bf16 v[212:227], v[82:85], v[196:199], v[212:227]
	s_add_i32 m0, s10, 101376
	s_nop 0
	global_load_lds_dwordx4 v193, s[6:7]
	s_add_u32 s6, s6, 0x8000
	s_addc_u32 s7, s7, 0
	v_mfma_f32_32x32x16_bf16 v[6:21], v[86:89], v[38:41], 0
	s_nop 7
	s_nop 2
	v_max_f32_e32 v108, 0, v212
	v_max_f32_e32 v109, 0, v213
	v_pk_mul_f32 v[0:1], v[22:23], v[108:109]
	v_max_f32_e32 v210, 0, v214
	v_max_f32_e32 v211, 0, v215
	v_pk_fma_f32 v[0:1], v[24:25], v[210:211], v[0:1]
	v_max_f32_e32 v108, 0, v216
	v_max_f32_e32 v109, 0, v217
	v_pk_fma_f32 v[0:1], v[26:27], v[108:109], v[0:1]
	v_mfma_f32_32x32x16_bf16 v[6:21], v[90:93], v[42:45], v[6:21]
	v_max_f32_e32 v210, 0, v218
	v_max_f32_e32 v211, 0, v219
	v_pk_fma_f32 v[0:1], v[28:29], v[210:211], v[0:1]
	v_max_f32_e32 v108, 0, v220
	v_max_f32_e32 v109, 0, v221
	v_pk_fma_f32 v[0:1], v[30:31], v[108:109], v[0:1]
	v_max_f32_e32 v210, 0, v222
	v_max_f32_e32 v211, 0, v223
	v_pk_fma_f32 v[0:1], v[32:33], v[210:211], v[0:1]
	v_mfma_f32_32x32x16_bf16 v[6:21], v[94:97], v[46:49], v[6:21]
	v_max_f32_e32 v108, 0, v224
	v_max_f32_e32 v109, 0, v225
	v_pk_fma_f32 v[0:1], v[34:35], v[108:109], v[0:1]
	v_max_f32_e32 v210, 0, v226
	v_max_f32_e32 v211, 0, v227
	v_pk_fma_f32 v[0:1], v[36:37], v[210:211], v[0:1]
	v_add_f32_e32 v0, v0, v1
	v_ashrrev_i32_e32 v1, 31, v0
	v_mfma_f32_32x32x16_bf16 v[6:21], v[98:101], v[196:199], v[6:21]
	s_waitcnt vmcnt(8)
	ds_read_b128 v[38:41], v5 offset:43264
	ds_read_b128 v[42:45], v52 offset:43264
	ds_read_b128 v[46:49], v55 offset:43264
	ds_read_b128 v[196:199], v56 offset:43264
	v_or_b32_e32 v1, 0x80000000, v1
	s_cmpk_gt_i32 s11, 0
	s_cselect_b64 vcc, -1, 0
	v_xor_b32_e32 v0, v1, v0
	v_cndmask_b32_e32 v133, v123, v0, vcc
	s_nop 1
	s_waitcnt lgkmcnt(3)
	v_mfma_f32_32x32x16_bf16 v[212:227], v[70:73], v[38:41], 0
	v_max_f32_e32 v108, 0, v6
	v_max_f32_e32 v109, 0, v7
	v_pk_mul_f32 v[50:51], v[244:245], v[108:109]
	v_max_f32_e32 v210, 0, v8
	v_max_f32_e32 v211, 0, v9
	v_pk_fma_f32 v[50:51], v[246:247], v[210:211], v[50:51]
	v_max_f32_e32 v108, 0, v10
	v_max_f32_e32 v109, 0, v11
	v_pk_fma_f32 v[50:51], v[248:249], v[108:109], v[50:51]
	s_waitcnt lgkmcnt(2)
	v_mfma_f32_32x32x16_bf16 v[212:227], v[74:77], v[42:45], v[212:227]
	v_max_f32_e32 v210, 0, v12
	v_max_f32_e32 v211, 0, v13
	v_pk_fma_f32 v[50:51], v[250:251], v[210:211], v[50:51]
	v_max_f32_e32 v108, 0, v14
	v_max_f32_e32 v109, 0, v15
	v_pk_fma_f32 v[50:51], v[252:253], v[108:109], v[50:51]
	v_max_f32_e32 v210, 0, v16
	v_max_f32_e32 v211, 0, v17
	v_pk_fma_f32 v[50:51], v[254:255], v[210:211], v[50:51]
	s_waitcnt lgkmcnt(1)
	v_mfma_f32_32x32x16_bf16 v[212:227], v[78:81], v[46:49], v[212:227]
	v_max_f32_e32 v108, 0, v18
	v_max_f32_e32 v109, 0, v19
	v_pk_fma_f32 v[50:51], v[200:201], v[108:109], v[50:51]
	v_max_f32_e32 v210, 0, v20
	v_max_f32_e32 v211, 0, v21
	v_pk_fma_f32 v[50:51], v[202:203], v[210:211], v[50:51]
	v_add_f32_e32 v50, v50, v51
	v_ashrrev_i32_e32 v51, 31, v50
	s_waitcnt lgkmcnt(0)
	v_mfma_f32_32x32x16_bf16 v[212:227], v[82:85], v[196:199], v[212:227]
	v_or_b32_e32 v51, 0x80000000, v51
	s_cmpk_gt_i32 s11, 0
	s_cselect_b64 vcc, -1, 0
	v_xor_b32_e32 v50, v51, v50
	v_cndmask_b32_e32 v50, v123, v50, vcc
	global_store_dword v243, v50, s[8:9]
	v_mfma_f32_32x32x16_bf16 v[6:21], v[86:89], v[38:41], 0
	s_add_i32 m0, s10, 0
	s_nop 0
	global_load_lds_dwordx4 v102, s[6:7]
	s_add_i32 m0, s10, 1024
	s_nop 0
	global_load_lds_dwordx4 v110, s[6:7]
	s_add_i32 m0, s10, 2048
	s_nop 0
	global_load_lds_dwordx4 v112, s[6:7]
	s_add_i32 m0, s10, 3072
	s_nop 0
	global_load_lds_dwordx4 v193, s[6:7]
	s_add_u32 s6, s6, 0x8000
	s_addc_u32 s7, s7, 0
	v_max_f32_e32 v108, 0, v212
	v_max_f32_e32 v109, 0, v213
	v_pk_mul_f32 v[0:1], v[22:23], v[108:109]
	v_max_f32_e32 v210, 0, v214
	v_max_f32_e32 v211, 0, v215
	v_pk_fma_f32 v[0:1], v[24:25], v[210:211], v[0:1]
	v_max_f32_e32 v108, 0, v216
	v_max_f32_e32 v109, 0, v217
	v_pk_fma_f32 v[0:1], v[26:27], v[108:109], v[0:1]
	v_mfma_f32_32x32x16_bf16 v[6:21], v[90:93], v[42:45], v[6:21]
	v_max_f32_e32 v210, 0, v218
	v_max_f32_e32 v211, 0, v219
	v_pk_fma_f32 v[0:1], v[28:29], v[210:211], v[0:1]
	v_max_f32_e32 v108, 0, v220
	v_max_f32_e32 v109, 0, v221
	v_pk_fma_f32 v[0:1], v[30:31], v[108:109], v[0:1]
	v_max_f32_e32 v210, 0, v222
	v_max_f32_e32 v211, 0, v223
	v_pk_fma_f32 v[0:1], v[32:33], v[210:211], v[0:1]
	v_mfma_f32_32x32x16_bf16 v[6:21], v[94:97], v[46:49], v[6:21]
	v_max_f32_e32 v108, 0, v224
	v_max_f32_e32 v109, 0, v225
	v_pk_fma_f32 v[0:1], v[34:35], v[108:109], v[0:1]
	v_max_f32_e32 v210, 0, v226
	v_max_f32_e32 v211, 0, v227
	v_pk_fma_f32 v[0:1], v[36:37], v[210:211], v[0:1]
	v_add_f32_e32 v0, v0, v1
	v_ashrrev_i32_e32 v1, 31, v0
	v_mfma_f32_32x32x16_bf16 v[6:21], v[98:101], v[196:199], v[6:21]
	s_waitcnt vmcnt(9)
	v_add_u32_e32 v228, 0x10000, v5
	ds_read_b128 v[38:41], v228 offset:10496
	v_add_u32_e32 v228, 0x10000, v52
	ds_read_b128 v[42:45], v228 offset:10496
	v_add_u32_e32 v228, 0x10000, v55
	ds_read_b128 v[46:49], v228 offset:10496
	v_add_u32_e32 v228, 0x10000, v56
	ds_read_b128 v[196:199], v228 offset:10496
	v_or_b32_e32 v1, 0x80000000, v1
	s_cmpk_gt_i32 s11, 8
	s_cselect_b64 vcc, -1, 0
	v_xor_b32_e32 v0, v1, v0
	v_cndmask_b32_e32 v132, v123, v0, vcc
	s_nop 1
	s_waitcnt lgkmcnt(3)
	v_mfma_f32_32x32x16_bf16 v[212:227], v[70:73], v[38:41], 0
	v_max_f32_e32 v108, 0, v6
	v_max_f32_e32 v109, 0, v7
	v_pk_mul_f32 v[50:51], v[244:245], v[108:109]
	v_max_f32_e32 v210, 0, v8
	v_max_f32_e32 v211, 0, v9
	v_pk_fma_f32 v[50:51], v[246:247], v[210:211], v[50:51]
	v_max_f32_e32 v108, 0, v10
	v_max_f32_e32 v109, 0, v11
	v_pk_fma_f32 v[50:51], v[248:249], v[108:109], v[50:51]
	s_waitcnt lgkmcnt(2)
	v_mfma_f32_32x32x16_bf16 v[212:227], v[74:77], v[42:45], v[212:227]
	v_max_f32_e32 v210, 0, v12
	v_max_f32_e32 v211, 0, v13
	v_pk_fma_f32 v[50:51], v[250:251], v[210:211], v[50:51]
	v_max_f32_e32 v108, 0, v14
	v_max_f32_e32 v109, 0, v15
	v_pk_fma_f32 v[50:51], v[252:253], v[108:109], v[50:51]
	v_max_f32_e32 v210, 0, v16
	v_max_f32_e32 v211, 0, v17
	v_pk_fma_f32 v[50:51], v[254:255], v[210:211], v[50:51]
	s_waitcnt lgkmcnt(1)
	v_mfma_f32_32x32x16_bf16 v[212:227], v[78:81], v[46:49], v[212:227]
	v_max_f32_e32 v108, 0, v18
	v_max_f32_e32 v109, 0, v19
	v_pk_fma_f32 v[50:51], v[200:201], v[108:109], v[50:51]
	v_max_f32_e32 v210, 0, v20
	v_max_f32_e32 v211, 0, v21
	v_pk_fma_f32 v[50:51], v[202:203], v[210:211], v[50:51]
	v_add_f32_e32 v50, v50, v51
	v_ashrrev_i32_e32 v51, 31, v50
	s_waitcnt lgkmcnt(0)
	v_mfma_f32_32x32x16_bf16 v[212:227], v[82:85], v[196:199], v[212:227]
	v_or_b32_e32 v51, 0x80000000, v51
	s_cmpk_gt_i32 s11, 8
	s_cselect_b64 vcc, -1, 0
	v_xor_b32_e32 v50, v51, v50
	v_cndmask_b32_e32 v50, v123, v50, vcc
	global_store_dword v243, v50, s[8:9] offset:2048
	s_add_u32 s8, s8, 0x1000
	s_addc_u32 s9, s9, 0
	v_mfma_f32_32x32x16_bf16 v[6:21], v[86:89], v[38:41], 0
	s_add_i32 m0, s10, 32768
	s_nop 0
	global_load_lds_dwordx4 v102, s[6:7]
	s_add_i32 m0, s10, 33792
	s_nop 0
	global_load_lds_dwordx4 v110, s[6:7]
	s_add_i32 m0, s10, 34816
	s_nop 0
	global_load_lds_dwordx4 v112, s[6:7]
	s_add_i32 m0, s10, 35840
	s_nop 0
	global_load_lds_dwordx4 v193, s[6:7]
	s_add_u32 s6, s6, 0x8000
	s_addc_u32 s7, s7, 0
	v_max_f32_e32 v108, 0, v212
	v_max_f32_e32 v109, 0, v213
	v_pk_mul_f32 v[0:1], v[22:23], v[108:109]
	v_max_f32_e32 v210, 0, v214
	v_max_f32_e32 v211, 0, v215
	v_pk_fma_f32 v[0:1], v[24:25], v[210:211], v[0:1]
	v_max_f32_e32 v108, 0, v216
	v_max_f32_e32 v109, 0, v217
	v_pk_fma_f32 v[0:1], v[26:27], v[108:109], v[0:1]
	v_mfma_f32_32x32x16_bf16 v[6:21], v[90:93], v[42:45], v[6:21]
	v_max_f32_e32 v210, 0, v218
	v_max_f32_e32 v211, 0, v219
	v_pk_fma_f32 v[0:1], v[28:29], v[210:211], v[0:1]
	v_max_f32_e32 v108, 0, v220
	v_max_f32_e32 v109, 0, v221
	v_pk_fma_f32 v[0:1], v[30:31], v[108:109], v[0:1]
	v_max_f32_e32 v210, 0, v222
	v_max_f32_e32 v211, 0, v223
	v_pk_fma_f32 v[0:1], v[32:33], v[210:211], v[0:1]
	v_mfma_f32_32x32x16_bf16 v[6:21], v[94:97], v[46:49], v[6:21]
	v_max_f32_e32 v108, 0, v224
	v_max_f32_e32 v109, 0, v225
	v_pk_fma_f32 v[0:1], v[34:35], v[108:109], v[0:1]
	v_max_f32_e32 v210, 0, v226
	v_max_f32_e32 v211, 0, v227
	v_pk_fma_f32 v[0:1], v[36:37], v[210:211], v[0:1]
	v_add_f32_e32 v0, v0, v1
	v_ashrrev_i32_e32 v1, 31, v0
	v_mfma_f32_32x32x16_bf16 v[6:21], v[98:101], v[196:199], v[6:21]
	s_waitcnt vmcnt(10)
	v_add_u32_e32 v228, 0x10000, v5
	ds_read_b128 v[38:41], v228 offset:43264
	v_add_u32_e32 v228, 0x10000, v52
	ds_read_b128 v[42:45], v228 offset:43264
	v_add_u32_e32 v228, 0x10000, v55
	ds_read_b128 v[46:49], v228 offset:43264
	v_add_u32_e32 v228, 0x10000, v56
	ds_read_b128 v[196:199], v228 offset:43264
	v_or_b32_e32 v1, 0x80000000, v1
	s_cmpk_gt_i32 s11, 16
	s_cselect_b64 vcc, -1, 0
	v_xor_b32_e32 v0, v1, v0
	v_cndmask_b32_e32 v135, v123, v0, vcc
	s_nop 1
	s_waitcnt lgkmcnt(3)
	v_mfma_f32_32x32x16_bf16 v[212:227], v[70:73], v[38:41], 0
	v_max_f32_e32 v108, 0, v6
	v_max_f32_e32 v109, 0, v7
	v_pk_mul_f32 v[50:51], v[244:245], v[108:109]
	v_max_f32_e32 v210, 0, v8
	v_max_f32_e32 v211, 0, v9
	v_pk_fma_f32 v[50:51], v[246:247], v[210:211], v[50:51]
	v_max_f32_e32 v108, 0, v10
	v_max_f32_e32 v109, 0, v11
	v_pk_fma_f32 v[50:51], v[248:249], v[108:109], v[50:51]
	s_waitcnt lgkmcnt(2)
	v_mfma_f32_32x32x16_bf16 v[212:227], v[74:77], v[42:45], v[212:227]
	v_max_f32_e32 v210, 0, v12
	v_max_f32_e32 v211, 0, v13
	v_pk_fma_f32 v[50:51], v[250:251], v[210:211], v[50:51]
	v_max_f32_e32 v108, 0, v14
	v_max_f32_e32 v109, 0, v15
	v_pk_fma_f32 v[50:51], v[252:253], v[108:109], v[50:51]
	v_max_f32_e32 v210, 0, v16
	v_max_f32_e32 v211, 0, v17
	v_pk_fma_f32 v[50:51], v[254:255], v[210:211], v[50:51]
	s_waitcnt lgkmcnt(1)
	v_mfma_f32_32x32x16_bf16 v[212:227], v[78:81], v[46:49], v[212:227]
	v_max_f32_e32 v108, 0, v18
	v_max_f32_e32 v109, 0, v19
	v_pk_fma_f32 v[50:51], v[200:201], v[108:109], v[50:51]
	v_max_f32_e32 v210, 0, v20
	v_max_f32_e32 v211, 0, v21
	v_pk_fma_f32 v[50:51], v[202:203], v[210:211], v[50:51]
	v_add_f32_e32 v50, v50, v51
	v_ashrrev_i32_e32 v51, 31, v50
	s_waitcnt lgkmcnt(0)
	v_mfma_f32_32x32x16_bf16 v[212:227], v[82:85], v[196:199], v[212:227]
	v_or_b32_e32 v51, 0x80000000, v51
	s_cmpk_gt_i32 s11, 16
	s_cselect_b64 vcc, -1, 0
	v_xor_b32_e32 v50, v51, v50
	v_cndmask_b32_e32 v50, v123, v50, vcc
	global_store_dword v243, v50, s[8:9]
	v_mfma_f32_32x32x16_bf16 v[6:21], v[86:89], v[38:41], 0
	s_add_i32 m0, s10, 65536
	s_nop 0
	global_load_lds_dwordx4 v102, s[6:7]
	s_add_i32 m0, s10, 66560
	s_nop 0
	global_load_lds_dwordx4 v110, s[6:7]
	s_add_i32 m0, s10, 67584
	s_nop 0
	global_load_lds_dwordx4 v112, s[6:7]
	s_add_i32 m0, s10, 68608
	s_nop 0
	global_load_lds_dwordx4 v193, s[6:7]
	s_add_u32 s6, s6, 0x8000
	s_addc_u32 s7, s7, 0
	v_max_f32_e32 v108, 0, v212
	v_max_f32_e32 v109, 0, v213
	v_pk_mul_f32 v[0:1], v[22:23], v[108:109]
	v_max_f32_e32 v210, 0, v214
	v_max_f32_e32 v211, 0, v215
	v_pk_fma_f32 v[0:1], v[24:25], v[210:211], v[0:1]
	v_max_f32_e32 v108, 0, v216
	v_max_f32_e32 v109, 0, v217
	v_pk_fma_f32 v[0:1], v[26:27], v[108:109], v[0:1]
	v_mfma_f32_32x32x16_bf16 v[6:21], v[90:93], v[42:45], v[6:21]
	v_max_f32_e32 v210, 0, v218
	v_max_f32_e32 v211, 0, v219
	v_pk_fma_f32 v[0:1], v[28:29], v[210:211], v[0:1]
	v_max_f32_e32 v108, 0, v220
	v_max_f32_e32 v109, 0, v221
	v_pk_fma_f32 v[0:1], v[30:31], v[108:109], v[0:1]
	v_max_f32_e32 v210, 0, v222
	v_max_f32_e32 v211, 0, v223
	v_pk_fma_f32 v[0:1], v[32:33], v[210:211], v[0:1]
	v_mfma_f32_32x32x16_bf16 v[6:21], v[94:97], v[46:49], v[6:21]
	v_max_f32_e32 v108, 0, v224
	v_max_f32_e32 v109, 0, v225
	v_pk_fma_f32 v[0:1], v[34:35], v[108:109], v[0:1]
	v_max_f32_e32 v210, 0, v226
	v_max_f32_e32 v211, 0, v227
	v_pk_fma_f32 v[0:1], v[36:37], v[210:211], v[0:1]
	v_add_f32_e32 v0, v0, v1
	v_ashrrev_i32_e32 v1, 31, v0
	v_mfma_f32_32x32x16_bf16 v[6:21], v[98:101], v[196:199], v[6:21]
	s_waitcnt vmcnt(10)
	ds_read_b128 v[38:41], v5 offset:10496
	ds_read_b128 v[42:45], v52 offset:10496
	ds_read_b128 v[46:49], v55 offset:10496
	ds_read_b128 v[196:199], v56 offset:10496
	v_or_b32_e32 v1, 0x80000000, v1
	s_cmpk_gt_i32 s11, 24
	s_cselect_b64 vcc, -1, 0
	v_xor_b32_e32 v0, v1, v0
	v_cndmask_b32_e32 v134, v123, v0, vcc
	s_nop 1
	s_waitcnt lgkmcnt(3)
	v_mfma_f32_32x32x16_bf16 v[212:227], v[70:73], v[38:41], 0
	v_max_f32_e32 v108, 0, v6
	v_max_f32_e32 v109, 0, v7
	v_pk_mul_f32 v[50:51], v[244:245], v[108:109]
	v_max_f32_e32 v210, 0, v8
	v_max_f32_e32 v211, 0, v9
	v_pk_fma_f32 v[50:51], v[246:247], v[210:211], v[50:51]
	v_max_f32_e32 v108, 0, v10
	v_max_f32_e32 v109, 0, v11
	v_pk_fma_f32 v[50:51], v[248:249], v[108:109], v[50:51]
	s_waitcnt lgkmcnt(2)
	v_mfma_f32_32x32x16_bf16 v[212:227], v[74:77], v[42:45], v[212:227]
	v_max_f32_e32 v210, 0, v12
	v_max_f32_e32 v211, 0, v13
	v_pk_fma_f32 v[50:51], v[250:251], v[210:211], v[50:51]
	v_max_f32_e32 v108, 0, v14
	v_max_f32_e32 v109, 0, v15
	v_pk_fma_f32 v[50:51], v[252:253], v[108:109], v[50:51]
	v_max_f32_e32 v210, 0, v16
	v_max_f32_e32 v211, 0, v17
	v_pk_fma_f32 v[50:51], v[254:255], v[210:211], v[50:51]
	s_waitcnt lgkmcnt(1)
	v_mfma_f32_32x32x16_bf16 v[212:227], v[78:81], v[46:49], v[212:227]
	v_max_f32_e32 v108, 0, v18
	v_max_f32_e32 v109, 0, v19
	v_pk_fma_f32 v[50:51], v[200:201], v[108:109], v[50:51]
	v_max_f32_e32 v210, 0, v20
	v_max_f32_e32 v211, 0, v21
	v_pk_fma_f32 v[50:51], v[202:203], v[210:211], v[50:51]
	v_add_f32_e32 v50, v50, v51
	v_ashrrev_i32_e32 v51, 31, v50
	s_waitcnt lgkmcnt(0)
	v_mfma_f32_32x32x16_bf16 v[212:227], v[82:85], v[196:199], v[212:227]
	v_or_b32_e32 v51, 0x80000000, v51
	s_cmpk_gt_i32 s11, 24
	s_cselect_b64 vcc, -1, 0
	v_xor_b32_e32 v50, v51, v50
	v_cndmask_b32_e32 v50, v123, v50, vcc
	global_store_dword v243, v50, s[8:9] offset:2048
	s_add_u32 s8, s8, 0x1000
	s_addc_u32 s9, s9, 0
	v_mfma_f32_32x32x16_bf16 v[6:21], v[86:89], v[38:41], 0
	s_add_i32 m0, s10, 98304
	s_nop 0
	global_load_lds_dwordx4 v102, s[6:7]
	s_add_i32 m0, s10, 99328
	s_nop 0
	global_load_lds_dwordx4 v110, s[6:7]
	s_add_i32 m0, s10, 100352
	s_nop 0
	global_load_lds_dwordx4 v112, s[6:7]
	s_add_i32 m0, s10, 101376
	s_nop 0
	global_load_lds_dwordx4 v193, s[6:7]
	s_add_u32 s6, s6, 0x8000
	s_addc_u32 s7, s7, 0
	v_max_f32_e32 v108, 0, v212
	v_max_f32_e32 v109, 0, v213
	v_pk_mul_f32 v[0:1], v[22:23], v[108:109]
	v_max_f32_e32 v210, 0, v214
	v_max_f32_e32 v211, 0, v215
	v_pk_fma_f32 v[0:1], v[24:25], v[210:211], v[0:1]
	v_max_f32_e32 v108, 0, v216
	v_max_f32_e32 v109, 0, v217
	v_pk_fma_f32 v[0:1], v[26:27], v[108:109], v[0:1]
	v_mfma_f32_32x32x16_bf16 v[6:21], v[90:93], v[42:45], v[6:21]
	v_max_f32_e32 v210, 0, v218
	v_max_f32_e32 v211, 0, v219
	v_pk_fma_f32 v[0:1], v[28:29], v[210:211], v[0:1]
	v_max_f32_e32 v108, 0, v220
	v_max_f32_e32 v109, 0, v221
	v_pk_fma_f32 v[0:1], v[30:31], v[108:109], v[0:1]
	v_max_f32_e32 v210, 0, v222
	v_max_f32_e32 v211, 0, v223
	v_pk_fma_f32 v[0:1], v[32:33], v[210:211], v[0:1]
	v_mfma_f32_32x32x16_bf16 v[6:21], v[94:97], v[46:49], v[6:21]
	v_max_f32_e32 v108, 0, v224
	v_max_f32_e32 v109, 0, v225
	v_pk_fma_f32 v[0:1], v[34:35], v[108:109], v[0:1]
	v_max_f32_e32 v210, 0, v226
	v_max_f32_e32 v211, 0, v227
	v_pk_fma_f32 v[0:1], v[36:37], v[210:211], v[0:1]
	v_add_f32_e32 v0, v0, v1
	v_ashrrev_i32_e32 v1, 31, v0
	v_mfma_f32_32x32x16_bf16 v[6:21], v[98:101], v[196:199], v[6:21]
	s_waitcnt vmcnt(10)
	ds_read_b128 v[38:41], v5 offset:43264
	ds_read_b128 v[42:45], v52 offset:43264
	ds_read_b128 v[46:49], v55 offset:43264
	ds_read_b128 v[196:199], v56 offset:43264
	v_or_b32_e32 v1, 0x80000000, v1
	s_cmpk_gt_i32 s11, 32
	s_cselect_b64 vcc, -1, 0
	v_xor_b32_e32 v0, v1, v0
	v_cndmask_b32_e32 v138, v123, v0, vcc
	s_nop 1
	s_waitcnt lgkmcnt(3)
	v_mfma_f32_32x32x16_bf16 v[212:227], v[70:73], v[38:41], 0
	v_max_f32_e32 v108, 0, v6
	v_max_f32_e32 v109, 0, v7
	v_pk_mul_f32 v[50:51], v[244:245], v[108:109]
	v_max_f32_e32 v210, 0, v8
	v_max_f32_e32 v211, 0, v9
	v_pk_fma_f32 v[50:51], v[246:247], v[210:211], v[50:51]
	v_max_f32_e32 v108, 0, v10
	v_max_f32_e32 v109, 0, v11
	v_pk_fma_f32 v[50:51], v[248:249], v[108:109], v[50:51]
	s_waitcnt lgkmcnt(2)
	v_mfma_f32_32x32x16_bf16 v[212:227], v[74:77], v[42:45], v[212:227]
	v_max_f32_e32 v210, 0, v12
	v_max_f32_e32 v211, 0, v13
	v_pk_fma_f32 v[50:51], v[250:251], v[210:211], v[50:51]
	v_max_f32_e32 v108, 0, v14
	v_max_f32_e32 v109, 0, v15
	v_pk_fma_f32 v[50:51], v[252:253], v[108:109], v[50:51]
	v_max_f32_e32 v210, 0, v16
	v_max_f32_e32 v211, 0, v17
	v_pk_fma_f32 v[50:51], v[254:255], v[210:211], v[50:51]
	s_waitcnt lgkmcnt(1)
	v_mfma_f32_32x32x16_bf16 v[212:227], v[78:81], v[46:49], v[212:227]
	v_max_f32_e32 v108, 0, v18
	v_max_f32_e32 v109, 0, v19
	v_pk_fma_f32 v[50:51], v[200:201], v[108:109], v[50:51]
	v_max_f32_e32 v210, 0, v20
	v_max_f32_e32 v211, 0, v21
	v_pk_fma_f32 v[50:51], v[202:203], v[210:211], v[50:51]
	v_add_f32_e32 v50, v50, v51
	v_ashrrev_i32_e32 v51, 31, v50
	s_waitcnt lgkmcnt(0)
	v_mfma_f32_32x32x16_bf16 v[212:227], v[82:85], v[196:199], v[212:227]
	v_or_b32_e32 v51, 0x80000000, v51
	s_cmpk_gt_i32 s11, 32
	s_cselect_b64 vcc, -1, 0
	v_xor_b32_e32 v50, v51, v50
	v_cndmask_b32_e32 v50, v123, v50, vcc
	global_store_dword v243, v50, s[8:9]
	v_mfma_f32_32x32x16_bf16 v[6:21], v[86:89], v[38:41], 0
	s_add_i32 m0, s10, 0
	s_nop 0
	global_load_lds_dwordx4 v102, s[6:7]
	s_add_i32 m0, s10, 1024
	s_nop 0
	global_load_lds_dwordx4 v110, s[6:7]
	s_add_i32 m0, s10, 2048
	s_nop 0
	global_load_lds_dwordx4 v112, s[6:7]
	s_add_i32 m0, s10, 3072
	s_nop 0
	global_load_lds_dwordx4 v193, s[6:7]
	s_add_u32 s6, s6, 0x8000
	s_addc_u32 s7, s7, 0
	v_max_f32_e32 v108, 0, v212
	v_max_f32_e32 v109, 0, v213
	v_pk_mul_f32 v[0:1], v[22:23], v[108:109]
	v_max_f32_e32 v210, 0, v214
	v_max_f32_e32 v211, 0, v215
	v_pk_fma_f32 v[0:1], v[24:25], v[210:211], v[0:1]
	v_max_f32_e32 v108, 0, v216
	v_max_f32_e32 v109, 0, v217
	v_pk_fma_f32 v[0:1], v[26:27], v[108:109], v[0:1]
	v_mfma_f32_32x32x16_bf16 v[6:21], v[90:93], v[42:45], v[6:21]
	v_max_f32_e32 v210, 0, v218
	v_max_f32_e32 v211, 0, v219
	v_pk_fma_f32 v[0:1], v[28:29], v[210:211], v[0:1]
	v_max_f32_e32 v108, 0, v220
	v_max_f32_e32 v109, 0, v221
	v_pk_fma_f32 v[0:1], v[30:31], v[108:109], v[0:1]
	v_max_f32_e32 v210, 0, v222
	v_max_f32_e32 v211, 0, v223
	v_pk_fma_f32 v[0:1], v[32:33], v[210:211], v[0:1]
	v_mfma_f32_32x32x16_bf16 v[6:21], v[94:97], v[46:49], v[6:21]
	v_max_f32_e32 v108, 0, v224
	v_max_f32_e32 v109, 0, v225
	v_pk_fma_f32 v[0:1], v[34:35], v[108:109], v[0:1]
	v_max_f32_e32 v210, 0, v226
	v_max_f32_e32 v211, 0, v227
	v_pk_fma_f32 v[0:1], v[36:37], v[210:211], v[0:1]
	v_add_f32_e32 v0, v0, v1
	v_ashrrev_i32_e32 v1, 31, v0
	v_mfma_f32_32x32x16_bf16 v[6:21], v[98:101], v[196:199], v[6:21]
	s_waitcnt vmcnt(10)
	v_add_u32_e32 v228, 0x10000, v5
	ds_read_b128 v[38:41], v228 offset:10496
	v_add_u32_e32 v228, 0x10000, v52
	ds_read_b128 v[42:45], v228 offset:10496
	v_add_u32_e32 v228, 0x10000, v55
	ds_read_b128 v[46:49], v228 offset:10496
	v_add_u32_e32 v228, 0x10000, v56
	ds_read_b128 v[196:199], v228 offset:10496
	v_or_b32_e32 v1, 0x80000000, v1
	s_cmpk_gt_i32 s11, 40
	s_cselect_b64 vcc, -1, 0
	v_xor_b32_e32 v0, v1, v0
	v_cndmask_b32_e32 v137, v123, v0, vcc
	s_nop 1
	s_waitcnt lgkmcnt(3)
	v_mfma_f32_32x32x16_bf16 v[212:227], v[70:73], v[38:41], 0
	v_max_f32_e32 v108, 0, v6
	v_max_f32_e32 v109, 0, v7
	v_pk_mul_f32 v[50:51], v[244:245], v[108:109]
	v_max_f32_e32 v210, 0, v8
	v_max_f32_e32 v211, 0, v9
	v_pk_fma_f32 v[50:51], v[246:247], v[210:211], v[50:51]
	v_max_f32_e32 v108, 0, v10
	v_max_f32_e32 v109, 0, v11
	v_pk_fma_f32 v[50:51], v[248:249], v[108:109], v[50:51]
	s_waitcnt lgkmcnt(2)
	v_mfma_f32_32x32x16_bf16 v[212:227], v[74:77], v[42:45], v[212:227]
	v_max_f32_e32 v210, 0, v12
	v_max_f32_e32 v211, 0, v13
	v_pk_fma_f32 v[50:51], v[250:251], v[210:211], v[50:51]
	v_max_f32_e32 v108, 0, v14
	v_max_f32_e32 v109, 0, v15
	v_pk_fma_f32 v[50:51], v[252:253], v[108:109], v[50:51]
	v_max_f32_e32 v210, 0, v16
	v_max_f32_e32 v211, 0, v17
	v_pk_fma_f32 v[50:51], v[254:255], v[210:211], v[50:51]
	s_waitcnt lgkmcnt(1)
	v_mfma_f32_32x32x16_bf16 v[212:227], v[78:81], v[46:49], v[212:227]
	v_max_f32_e32 v108, 0, v18
	v_max_f32_e32 v109, 0, v19
	v_pk_fma_f32 v[50:51], v[200:201], v[108:109], v[50:51]
	v_max_f32_e32 v210, 0, v20
	v_max_f32_e32 v211, 0, v21
	v_pk_fma_f32 v[50:51], v[202:203], v[210:211], v[50:51]
	v_add_f32_e32 v50, v50, v51
	v_ashrrev_i32_e32 v51, 31, v50
	s_waitcnt lgkmcnt(0)
	v_mfma_f32_32x32x16_bf16 v[212:227], v[82:85], v[196:199], v[212:227]
	v_or_b32_e32 v51, 0x80000000, v51
	s_cmpk_gt_i32 s11, 40
	s_cselect_b64 vcc, -1, 0
	v_xor_b32_e32 v50, v51, v50
	v_cndmask_b32_e32 v50, v123, v50, vcc
	global_store_dword v243, v50, s[8:9] offset:2048
	s_add_u32 s8, s8, 0x1000
	s_addc_u32 s9, s9, 0
	v_mfma_f32_32x32x16_bf16 v[6:21], v[86:89], v[38:41], 0
	s_add_i32 m0, s10, 32768
	s_nop 0
	global_load_lds_dwordx4 v102, s[6:7]
	s_add_i32 m0, s10, 33792
	s_nop 0
	global_load_lds_dwordx4 v110, s[6:7]
	s_add_i32 m0, s10, 34816
	s_nop 0
	global_load_lds_dwordx4 v112, s[6:7]
	s_add_i32 m0, s10, 35840
	s_nop 0
	global_load_lds_dwordx4 v193, s[6:7]
	s_add_u32 s6, s6, 0x8000
	s_addc_u32 s7, s7, 0
	v_max_f32_e32 v108, 0, v212
	v_max_f32_e32 v109, 0, v213
	v_pk_mul_f32 v[0:1], v[22:23], v[108:109]
	v_max_f32_e32 v210, 0, v214
	v_max_f32_e32 v211, 0, v215
	v_pk_fma_f32 v[0:1], v[24:25], v[210:211], v[0:1]
	v_max_f32_e32 v108, 0, v216
	v_max_f32_e32 v109, 0, v217
	v_pk_fma_f32 v[0:1], v[26:27], v[108:109], v[0:1]
	v_mfma_f32_32x32x16_bf16 v[6:21], v[90:93], v[42:45], v[6:21]
	v_max_f32_e32 v210, 0, v218
	v_max_f32_e32 v211, 0, v219
	v_pk_fma_f32 v[0:1], v[28:29], v[210:211], v[0:1]
	v_max_f32_e32 v108, 0, v220
	v_max_f32_e32 v109, 0, v221
	v_pk_fma_f32 v[0:1], v[30:31], v[108:109], v[0:1]
	v_max_f32_e32 v210, 0, v222
	v_max_f32_e32 v211, 0, v223
	v_pk_fma_f32 v[0:1], v[32:33], v[210:211], v[0:1]
	v_mfma_f32_32x32x16_bf16 v[6:21], v[94:97], v[46:49], v[6:21]
	v_max_f32_e32 v108, 0, v224
	v_max_f32_e32 v109, 0, v225
	v_pk_fma_f32 v[0:1], v[34:35], v[108:109], v[0:1]
	v_max_f32_e32 v210, 0, v226
	v_max_f32_e32 v211, 0, v227
	v_pk_fma_f32 v[0:1], v[36:37], v[210:211], v[0:1]
	v_add_f32_e32 v0, v0, v1
	v_ashrrev_i32_e32 v1, 31, v0
	v_mfma_f32_32x32x16_bf16 v[6:21], v[98:101], v[196:199], v[6:21]
	s_waitcnt vmcnt(10)
	v_add_u32_e32 v228, 0x10000, v5
	ds_read_b128 v[38:41], v228 offset:43264
	v_add_u32_e32 v228, 0x10000, v52
	ds_read_b128 v[42:45], v228 offset:43264
	v_add_u32_e32 v228, 0x10000, v55
	ds_read_b128 v[46:49], v228 offset:43264
	v_add_u32_e32 v228, 0x10000, v56
	ds_read_b128 v[196:199], v228 offset:43264
	v_or_b32_e32 v1, 0x80000000, v1
	s_cmpk_gt_i32 s11, 48
	s_cselect_b64 vcc, -1, 0
	v_xor_b32_e32 v0, v1, v0
	v_cndmask_b32_e32 v140, v123, v0, vcc
	s_nop 1
	s_waitcnt lgkmcnt(3)
	v_mfma_f32_32x32x16_bf16 v[212:227], v[70:73], v[38:41], 0
	v_max_f32_e32 v108, 0, v6
	v_max_f32_e32 v109, 0, v7
	v_pk_mul_f32 v[50:51], v[244:245], v[108:109]
	v_max_f32_e32 v210, 0, v8
	v_max_f32_e32 v211, 0, v9
	v_pk_fma_f32 v[50:51], v[246:247], v[210:211], v[50:51]
	v_max_f32_e32 v108, 0, v10
	v_max_f32_e32 v109, 0, v11
	v_pk_fma_f32 v[50:51], v[248:249], v[108:109], v[50:51]
	s_waitcnt lgkmcnt(2)
	v_mfma_f32_32x32x16_bf16 v[212:227], v[74:77], v[42:45], v[212:227]
	v_max_f32_e32 v210, 0, v12
	v_max_f32_e32 v211, 0, v13
	v_pk_fma_f32 v[50:51], v[250:251], v[210:211], v[50:51]
	v_max_f32_e32 v108, 0, v14
	v_max_f32_e32 v109, 0, v15
	v_pk_fma_f32 v[50:51], v[252:253], v[108:109], v[50:51]
	v_max_f32_e32 v210, 0, v16
	v_max_f32_e32 v211, 0, v17
	v_pk_fma_f32 v[50:51], v[254:255], v[210:211], v[50:51]
	s_waitcnt lgkmcnt(1)
	v_mfma_f32_32x32x16_bf16 v[212:227], v[78:81], v[46:49], v[212:227]
	v_max_f32_e32 v108, 0, v18
	v_max_f32_e32 v109, 0, v19
	v_pk_fma_f32 v[50:51], v[200:201], v[108:109], v[50:51]
	v_max_f32_e32 v210, 0, v20
	v_max_f32_e32 v211, 0, v21
	v_pk_fma_f32 v[50:51], v[202:203], v[210:211], v[50:51]
	v_add_f32_e32 v50, v50, v51
	v_ashrrev_i32_e32 v51, 31, v50
	s_waitcnt lgkmcnt(0)
	v_mfma_f32_32x32x16_bf16 v[212:227], v[82:85], v[196:199], v[212:227]
	v_or_b32_e32 v51, 0x80000000, v51
	s_cmpk_gt_i32 s11, 48
	s_cselect_b64 vcc, -1, 0
	v_xor_b32_e32 v50, v51, v50
	v_cndmask_b32_e32 v50, v123, v50, vcc
	global_store_dword v243, v50, s[8:9]
	v_mfma_f32_32x32x16_bf16 v[6:21], v[86:89], v[38:41], 0
	s_add_i32 m0, s10, 65536
	s_nop 0
	global_load_lds_dwordx4 v102, s[6:7]
	s_add_i32 m0, s10, 66560
	s_nop 0
	global_load_lds_dwordx4 v110, s[6:7]
	s_add_i32 m0, s10, 67584
	s_nop 0
	global_load_lds_dwordx4 v112, s[6:7]
	s_add_i32 m0, s10, 68608
	s_nop 0
	global_load_lds_dwordx4 v193, s[6:7]
	s_add_u32 s6, s6, 0x8000
	s_addc_u32 s7, s7, 0
	v_max_f32_e32 v108, 0, v212
	v_max_f32_e32 v109, 0, v213
	v_pk_mul_f32 v[0:1], v[22:23], v[108:109]
	v_max_f32_e32 v210, 0, v214
	v_max_f32_e32 v211, 0, v215
	v_pk_fma_f32 v[0:1], v[24:25], v[210:211], v[0:1]
	v_max_f32_e32 v108, 0, v216
	v_max_f32_e32 v109, 0, v217
	v_pk_fma_f32 v[0:1], v[26:27], v[108:109], v[0:1]
	v_mfma_f32_32x32x16_bf16 v[6:21], v[90:93], v[42:45], v[6:21]
	v_max_f32_e32 v210, 0, v218
	v_max_f32_e32 v211, 0, v219
	v_pk_fma_f32 v[0:1], v[28:29], v[210:211], v[0:1]
	v_max_f32_e32 v108, 0, v220
	v_max_f32_e32 v109, 0, v221
	v_pk_fma_f32 v[0:1], v[30:31], v[108:109], v[0:1]
	v_max_f32_e32 v210, 0, v222
	v_max_f32_e32 v211, 0, v223
	v_pk_fma_f32 v[0:1], v[32:33], v[210:211], v[0:1]
	v_mfma_f32_32x32x16_bf16 v[6:21], v[94:97], v[46:49], v[6:21]
	v_max_f32_e32 v108, 0, v224
	v_max_f32_e32 v109, 0, v225
	v_pk_fma_f32 v[0:1], v[34:35], v[108:109], v[0:1]
	v_max_f32_e32 v210, 0, v226
	v_max_f32_e32 v211, 0, v227
	v_pk_fma_f32 v[0:1], v[36:37], v[210:211], v[0:1]
	v_add_f32_e32 v0, v0, v1
	v_ashrrev_i32_e32 v1, 31, v0
	v_mfma_f32_32x32x16_bf16 v[6:21], v[98:101], v[196:199], v[6:21]
	s_waitcnt vmcnt(10)
	ds_read_b128 v[38:41], v5 offset:10496
	ds_read_b128 v[42:45], v52 offset:10496
	ds_read_b128 v[46:49], v55 offset:10496
	ds_read_b128 v[196:199], v56 offset:10496
	v_or_b32_e32 v1, 0x80000000, v1
	s_cmpk_gt_i32 s11, 56
	s_cselect_b64 vcc, -1, 0
	v_xor_b32_e32 v0, v1, v0
	v_cndmask_b32_e32 v139, v123, v0, vcc
	s_nop 1
	v_max_f32_e32 v108, 0, v6
	v_max_f32_e32 v109, 0, v7
	v_pk_mul_f32 v[50:51], v[244:245], v[108:109]
	v_max_f32_e32 v210, 0, v8
	v_max_f32_e32 v211, 0, v9
	v_pk_fma_f32 v[50:51], v[246:247], v[210:211], v[50:51]
	v_max_f32_e32 v108, 0, v10
	v_max_f32_e32 v109, 0, v11
	v_pk_fma_f32 v[50:51], v[248:249], v[108:109], v[50:51]
	v_max_f32_e32 v210, 0, v12
	v_max_f32_e32 v211, 0, v13
	v_pk_fma_f32 v[50:51], v[250:251], v[210:211], v[50:51]
	v_max_f32_e32 v108, 0, v14
	v_max_f32_e32 v109, 0, v15
	v_pk_fma_f32 v[50:51], v[252:253], v[108:109], v[50:51]
	v_max_f32_e32 v210, 0, v16
	v_max_f32_e32 v211, 0, v17
	v_pk_fma_f32 v[50:51], v[254:255], v[210:211], v[50:51]
	v_max_f32_e32 v108, 0, v18
	v_max_f32_e32 v109, 0, v19
	v_pk_fma_f32 v[50:51], v[200:201], v[108:109], v[50:51]
	v_max_f32_e32 v210, 0, v20
	v_max_f32_e32 v211, 0, v21
	v_pk_fma_f32 v[50:51], v[202:203], v[210:211], v[50:51]
	v_add_f32_e32 v50, v50, v51
	v_ashrrev_i32_e32 v51, 31, v50
	v_or_b32_e32 v51, 0x80000000, v51
	s_cmpk_gt_i32 s11, 56
	s_cselect_b64 vcc, -1, 0
	v_xor_b32_e32 v50, v51, v50
	v_cndmask_b32_e32 v50, v123, v50, vcc
	global_store_dword v243, v50, s[8:9] offset:2048
	s_add_u32 s8, s8, 0x1000
	s_addc_u32 s9, s9, 0
	s_cmpk_gt_i32 s81, 8
	s_cbranch_scc0 .Lix_fill_1
	s_waitcnt lgkmcnt(3)
	v_mfma_f32_32x32x16_bf16 v[212:227], v[70:73], v[38:41], 0
	s_add_i32 m0, s10, 98304
	s_nop 0
	global_load_lds_dwordx4 v102, s[6:7]
	s_waitcnt lgkmcnt(2)
	v_mfma_f32_32x32x16_bf16 v[212:227], v[74:77], v[42:45], v[212:227]
	s_add_i32 m0, s10, 99328
	s_nop 0
	global_load_lds_dwordx4 v110, s[6:7]
	s_waitcnt lgkmcnt(1)
	v_mfma_f32_32x32x16_bf16 v[212:227], v[78:81], v[46:49], v[212:227]
	s_add_i32 m0, s10, 100352
	s_nop 0
	global_load_lds_dwordx4 v112, s[6:7]
	s_waitcnt lgkmcnt(0)
	v_mfma_f32_32x32x16_bf16 v[212:227], v[82:85], v[196:199], v[212:227]
	s_add_i32 m0, s10, 101376
	s_nop 0
	global_load_lds_dwordx4 v193, s[6:7]
	s_add_u32 s6, s6, 0x8000
	s_addc_u32 s7, s7, 0
	v_mfma_f32_32x32x16_bf16 v[6:21], v[86:89], v[38:41], 0
	s_nop 7
	s_nop 2
	v_max_f32_e32 v108, 0, v212
	v_max_f32_e32 v109, 0, v213
	v_pk_mul_f32 v[0:1], v[22:23], v[108:109]
	v_max_f32_e32 v210, 0, v214
	v_max_f32_e32 v211, 0, v215
	v_pk_fma_f32 v[0:1], v[24:25], v[210:211], v[0:1]
	v_max_f32_e32 v108, 0, v216
	v_max_f32_e32 v109, 0, v217
	v_pk_fma_f32 v[0:1], v[26:27], v[108:109], v[0:1]
	v_mfma_f32_32x32x16_bf16 v[6:21], v[90:93], v[42:45], v[6:21]
	v_max_f32_e32 v210, 0, v218
	v_max_f32_e32 v211, 0, v219
	v_pk_fma_f32 v[0:1], v[28:29], v[210:211], v[0:1]
	v_max_f32_e32 v108, 0, v220
	v_max_f32_e32 v109, 0, v221
	v_pk_fma_f32 v[0:1], v[30:31], v[108:109], v[0:1]
	v_max_f32_e32 v210, 0, v222
	v_max_f32_e32 v211, 0, v223
	v_pk_fma_f32 v[0:1], v[32:33], v[210:211], v[0:1]
	v_mfma_f32_32x32x16_bf16 v[6:21], v[94:97], v[46:49], v[6:21]
	v_max_f32_e32 v108, 0, v224
	v_max_f32_e32 v109, 0, v225
	v_pk_fma_f32 v[0:1], v[34:35], v[108:109], v[0:1]
	v_max_f32_e32 v210, 0, v226
	v_max_f32_e32 v211, 0, v227
	v_pk_fma_f32 v[0:1], v[36:37], v[210:211], v[0:1]
	v_add_f32_e32 v0, v0, v1
	v_ashrrev_i32_e32 v1, 31, v0
	v_mfma_f32_32x32x16_bf16 v[6:21], v[98:101], v[196:199], v[6:21]
	s_waitcnt vmcnt(10)
	ds_read_b128 v[38:41], v5 offset:43264
	ds_read_b128 v[42:45], v52 offset:43264
	ds_read_b128 v[46:49], v55 offset:43264
	ds_read_b128 v[196:199], v56 offset:43264
	v_or_b32_e32 v1, 0x80000000, v1
	s_cmpk_gt_i32 s11, 64
	s_cselect_b64 vcc, -1, 0
	v_xor_b32_e32 v0, v1, v0
	v_cndmask_b32_e32 v142, v123, v0, vcc
	s_nop 1
	s_waitcnt lgkmcnt(3)
	v_mfma_f32_32x32x16_bf16 v[212:227], v[70:73], v[38:41], 0
	v_max_f32_e32 v108, 0, v6
	v_max_f32_e32 v109, 0, v7
	v_pk_mul_f32 v[50:51], v[244:245], v[108:109]
	v_max_f32_e32 v210, 0, v8
	v_max_f32_e32 v211, 0, v9
	v_pk_fma_f32 v[50:51], v[246:247], v[210:211], v[50:51]
	v_max_f32_e32 v108, 0, v10
	v_max_f32_e32 v109, 0, v11
	v_pk_fma_f32 v[50:51], v[248:249], v[108:109], v[50:51]
	s_waitcnt lgkmcnt(2)
	v_mfma_f32_32x32x16_bf16 v[212:227], v[74:77], v[42:45], v[212:227]
	v_max_f32_e32 v210, 0, v12
	v_max_f32_e32 v211, 0, v13
	v_pk_fma_f32 v[50:51], v[250:251], v[210:211], v[50:51]
	v_max_f32_e32 v108, 0, v14
	v_max_f32_e32 v109, 0, v15
	v_pk_fma_f32 v[50:51], v[252:253], v[108:109], v[50:51]
	v_max_f32_e32 v210, 0, v16
	v_max_f32_e32 v211, 0, v17
	v_pk_fma_f32 v[50:51], v[254:255], v[210:211], v[50:51]
	s_waitcnt lgkmcnt(1)
	v_mfma_f32_32x32x16_bf16 v[212:227], v[78:81], v[46:49], v[212:227]
	v_max_f32_e32 v108, 0, v18
	v_max_f32_e32 v109, 0, v19
	v_pk_fma_f32 v[50:51], v[200:201], v[108:109], v[50:51]
	v_max_f32_e32 v210, 0, v20
	v_max_f32_e32 v211, 0, v21
	v_pk_fma_f32 v[50:51], v[202:203], v[210:211], v[50:51]
	v_add_f32_e32 v50, v50, v51
	v_ashrrev_i32_e32 v51, 31, v50
	s_waitcnt lgkmcnt(0)
	v_mfma_f32_32x32x16_bf16 v[212:227], v[82:85], v[196:199], v[212:227]
	v_or_b32_e32 v51, 0x80000000, v51
	s_cmpk_gt_i32 s11, 64
	s_cselect_b64 vcc, -1, 0
	v_xor_b32_e32 v50, v51, v50
	v_cndmask_b32_e32 v50, v123, v50, vcc
	global_store_dword v243, v50, s[8:9]
	v_mfma_f32_32x32x16_bf16 v[6:21], v[86:89], v[38:41], 0
	s_add_i32 m0, s10, 0
	s_nop 0
	global_load_lds_dwordx4 v102, s[6:7]
	s_add_i32 m0, s10, 1024
	s_nop 0
	global_load_lds_dwordx4 v110, s[6:7]
	s_add_i32 m0, s10, 2048
	s_nop 0
	global_load_lds_dwordx4 v112, s[6:7]
	s_add_i32 m0, s10, 3072
	s_nop 0
	global_load_lds_dwordx4 v193, s[6:7]
	s_add_u32 s6, s6, 0x8000
	s_addc_u32 s7, s7, 0
	v_max_f32_e32 v108, 0, v212
	v_max_f32_e32 v109, 0, v213
	v_pk_mul_f32 v[0:1], v[22:23], v[108:109]
	v_max_f32_e32 v210, 0, v214
	v_max_f32_e32 v211, 0, v215
	v_pk_fma_f32 v[0:1], v[24:25], v[210:211], v[0:1]
	v_max_f32_e32 v108, 0, v216
	v_max_f32_e32 v109, 0, v217
	v_pk_fma_f32 v[0:1], v[26:27], v[108:109], v[0:1]
	v_mfma_f32_32x32x16_bf16 v[6:21], v[90:93], v[42:45], v[6:21]
	v_max_f32_e32 v210, 0, v218
	v_max_f32_e32 v211, 0, v219
	v_pk_fma_f32 v[0:1], v[28:29], v[210:211], v[0:1]
	v_max_f32_e32 v108, 0, v220
	v_max_f32_e32 v109, 0, v221
	v_pk_fma_f32 v[0:1], v[30:31], v[108:109], v[0:1]
	v_max_f32_e32 v210, 0, v222
	v_max_f32_e32 v211, 0, v223
	v_pk_fma_f32 v[0:1], v[32:33], v[210:211], v[0:1]
	v_mfma_f32_32x32x16_bf16 v[6:21], v[94:97], v[46:49], v[6:21]
	v_max_f32_e32 v108, 0, v224
	v_max_f32_e32 v109, 0, v225
	v_pk_fma_f32 v[0:1], v[34:35], v[108:109], v[0:1]
	v_max_f32_e32 v210, 0, v226
	v_max_f32_e32 v211, 0, v227
	v_pk_fma_f32 v[0:1], v[36:37], v[210:211], v[0:1]
	v_add_f32_e32 v0, v0, v1
	v_ashrrev_i32_e32 v1, 31, v0
	v_mfma_f32_32x32x16_bf16 v[6:21], v[98:101], v[196:199], v[6:21]
	s_waitcnt vmcnt(10)
	v_add_u32_e32 v228, 0x10000, v5
	ds_read_b128 v[38:41], v228 offset:10496
	v_add_u32_e32 v228, 0x10000, v52
	ds_read_b128 v[42:45], v228 offset:10496
	v_add_u32_e32 v228, 0x10000, v55
	ds_read_b128 v[46:49], v228 offset:10496
	v_add_u32_e32 v228, 0x10000, v56
	ds_read_b128 v[196:199], v228 offset:10496
	v_or_b32_e32 v1, 0x80000000, v1
	s_cmpk_gt_i32 s11, 72
	s_cselect_b64 vcc, -1, 0
	v_xor_b32_e32 v0, v1, v0
	v_cndmask_b32_e32 v141, v123, v0, vcc
	s_nop 1
	s_waitcnt lgkmcnt(3)
	v_mfma_f32_32x32x16_bf16 v[212:227], v[70:73], v[38:41], 0
	v_max_f32_e32 v108, 0, v6
	v_max_f32_e32 v109, 0, v7
	v_pk_mul_f32 v[50:51], v[244:245], v[108:109]
	v_max_f32_e32 v210, 0, v8
	v_max_f32_e32 v211, 0, v9
	v_pk_fma_f32 v[50:51], v[246:247], v[210:211], v[50:51]
	v_max_f32_e32 v108, 0, v10
	v_max_f32_e32 v109, 0, v11
	v_pk_fma_f32 v[50:51], v[248:249], v[108:109], v[50:51]
	s_waitcnt lgkmcnt(2)
	v_mfma_f32_32x32x16_bf16 v[212:227], v[74:77], v[42:45], v[212:227]
	v_max_f32_e32 v210, 0, v12
	v_max_f32_e32 v211, 0, v13
	v_pk_fma_f32 v[50:51], v[250:251], v[210:211], v[50:51]
	v_max_f32_e32 v108, 0, v14
	v_max_f32_e32 v109, 0, v15
	v_pk_fma_f32 v[50:51], v[252:253], v[108:109], v[50:51]
	v_max_f32_e32 v210, 0, v16
	v_max_f32_e32 v211, 0, v17
	v_pk_fma_f32 v[50:51], v[254:255], v[210:211], v[50:51]
	s_waitcnt lgkmcnt(1)
	v_mfma_f32_32x32x16_bf16 v[212:227], v[78:81], v[46:49], v[212:227]
	v_max_f32_e32 v108, 0, v18
	v_max_f32_e32 v109, 0, v19
	v_pk_fma_f32 v[50:51], v[200:201], v[108:109], v[50:51]
	v_max_f32_e32 v210, 0, v20
	v_max_f32_e32 v211, 0, v21
	v_pk_fma_f32 v[50:51], v[202:203], v[210:211], v[50:51]
	v_add_f32_e32 v50, v50, v51
	v_ashrrev_i32_e32 v51, 31, v50
	s_waitcnt lgkmcnt(0)
	v_mfma_f32_32x32x16_bf16 v[212:227], v[82:85], v[196:199], v[212:227]
	v_or_b32_e32 v51, 0x80000000, v51
	s_cmpk_gt_i32 s11, 72
	s_cselect_b64 vcc, -1, 0
	v_xor_b32_e32 v50, v51, v50
	v_cndmask_b32_e32 v50, v123, v50, vcc
	global_store_dword v243, v50, s[8:9] offset:2048
	s_add_u32 s8, s8, 0x1000
	s_addc_u32 s9, s9, 0
	v_mfma_f32_32x32x16_bf16 v[6:21], v[86:89], v[38:41], 0
	s_add_i32 m0, s10, 32768
	s_nop 0
	global_load_lds_dwordx4 v102, s[6:7]
	s_add_i32 m0, s10, 33792
	s_nop 0
	global_load_lds_dwordx4 v110, s[6:7]
	s_add_i32 m0, s10, 34816
	s_nop 0
	global_load_lds_dwordx4 v112, s[6:7]
	s_add_i32 m0, s10, 35840
	s_nop 0
	global_load_lds_dwordx4 v193, s[6:7]
	s_add_u32 s6, s6, 0x8000
	s_addc_u32 s7, s7, 0
	v_max_f32_e32 v108, 0, v212
	v_max_f32_e32 v109, 0, v213
	v_pk_mul_f32 v[0:1], v[22:23], v[108:109]
	v_max_f32_e32 v210, 0, v214
	v_max_f32_e32 v211, 0, v215
	v_pk_fma_f32 v[0:1], v[24:25], v[210:211], v[0:1]
	v_max_f32_e32 v108, 0, v216
	v_max_f32_e32 v109, 0, v217
	v_pk_fma_f32 v[0:1], v[26:27], v[108:109], v[0:1]
	v_mfma_f32_32x32x16_bf16 v[6:21], v[90:93], v[42:45], v[6:21]
	v_max_f32_e32 v210, 0, v218
	v_max_f32_e32 v211, 0, v219
	v_pk_fma_f32 v[0:1], v[28:29], v[210:211], v[0:1]
	v_max_f32_e32 v108, 0, v220
	v_max_f32_e32 v109, 0, v221
	v_pk_fma_f32 v[0:1], v[30:31], v[108:109], v[0:1]
	v_max_f32_e32 v210, 0, v222
	v_max_f32_e32 v211, 0, v223
	v_pk_fma_f32 v[0:1], v[32:33], v[210:211], v[0:1]
	v_mfma_f32_32x32x16_bf16 v[6:21], v[94:97], v[46:49], v[6:21]
	v_max_f32_e32 v108, 0, v224
	v_max_f32_e32 v109, 0, v225
	v_pk_fma_f32 v[0:1], v[34:35], v[108:109], v[0:1]
	v_max_f32_e32 v210, 0, v226
	v_max_f32_e32 v211, 0, v227
	v_pk_fma_f32 v[0:1], v[36:37], v[210:211], v[0:1]
	v_add_f32_e32 v0, v0, v1
	v_ashrrev_i32_e32 v1, 31, v0
	v_mfma_f32_32x32x16_bf16 v[6:21], v[98:101], v[196:199], v[6:21]
	s_waitcnt vmcnt(10)
	v_add_u32_e32 v228, 0x10000, v5
	ds_read_b128 v[38:41], v228 offset:43264
	v_add_u32_e32 v228, 0x10000, v52
	ds_read_b128 v[42:45], v228 offset:43264
	v_add_u32_e32 v228, 0x10000, v55
	ds_read_b128 v[46:49], v228 offset:43264
	v_add_u32_e32 v228, 0x10000, v56
	ds_read_b128 v[196:199], v228 offset:43264
	v_or_b32_e32 v1, 0x80000000, v1
	s_cmpk_gt_i32 s11, 80
	s_cselect_b64 vcc, -1, 0
	v_xor_b32_e32 v0, v1, v0
	v_cndmask_b32_e32 v144, v123, v0, vcc
	s_nop 1
	s_waitcnt lgkmcnt(3)
	v_mfma_f32_32x32x16_bf16 v[212:227], v[70:73], v[38:41], 0
	v_max_f32_e32 v108, 0, v6
	v_max_f32_e32 v109, 0, v7
	v_pk_mul_f32 v[50:51], v[244:245], v[108:109]
	v_max_f32_e32 v210, 0, v8
	v_max_f32_e32 v211, 0, v9
	v_pk_fma_f32 v[50:51], v[246:247], v[210:211], v[50:51]
	v_max_f32_e32 v108, 0, v10
	v_max_f32_e32 v109, 0, v11
	v_pk_fma_f32 v[50:51], v[248:249], v[108:109], v[50:51]
	s_waitcnt lgkmcnt(2)
	v_mfma_f32_32x32x16_bf16 v[212:227], v[74:77], v[42:45], v[212:227]
	v_max_f32_e32 v210, 0, v12
	v_max_f32_e32 v211, 0, v13
	v_pk_fma_f32 v[50:51], v[250:251], v[210:211], v[50:51]
	v_max_f32_e32 v108, 0, v14
	v_max_f32_e32 v109, 0, v15
	v_pk_fma_f32 v[50:51], v[252:253], v[108:109], v[50:51]
	v_max_f32_e32 v210, 0, v16
	v_max_f32_e32 v211, 0, v17
	v_pk_fma_f32 v[50:51], v[254:255], v[210:211], v[50:51]
	s_waitcnt lgkmcnt(1)
	v_mfma_f32_32x32x16_bf16 v[212:227], v[78:81], v[46:49], v[212:227]
	v_max_f32_e32 v108, 0, v18
	v_max_f32_e32 v109, 0, v19
	v_pk_fma_f32 v[50:51], v[200:201], v[108:109], v[50:51]
	v_max_f32_e32 v210, 0, v20
	v_max_f32_e32 v211, 0, v21
	v_pk_fma_f32 v[50:51], v[202:203], v[210:211], v[50:51]
	v_add_f32_e32 v50, v50, v51
	v_ashrrev_i32_e32 v51, 31, v50
	s_waitcnt lgkmcnt(0)
	v_mfma_f32_32x32x16_bf16 v[212:227], v[82:85], v[196:199], v[212:227]
	v_or_b32_e32 v51, 0x80000000, v51
	s_cmpk_gt_i32 s11, 80
	s_cselect_b64 vcc, -1, 0
	v_xor_b32_e32 v50, v51, v50
	v_cndmask_b32_e32 v50, v123, v50, vcc
	global_store_dword v243, v50, s[8:9]
	v_mfma_f32_32x32x16_bf16 v[6:21], v[86:89], v[38:41], 0
	s_add_i32 m0, s10, 65536
	s_nop 0
	global_load_lds_dwordx4 v102, s[6:7]
	s_add_i32 m0, s10, 66560
	s_nop 0
	global_load_lds_dwordx4 v110, s[6:7]
	s_add_i32 m0, s10, 67584
	s_nop 0
	global_load_lds_dwordx4 v112, s[6:7]
	s_add_i32 m0, s10, 68608
	s_nop 0
	global_load_lds_dwordx4 v193, s[6:7]
	s_add_u32 s6, s6, 0x8000
	s_addc_u32 s7, s7, 0
	v_max_f32_e32 v108, 0, v212
	v_max_f32_e32 v109, 0, v213
	v_pk_mul_f32 v[0:1], v[22:23], v[108:109]
	v_max_f32_e32 v210, 0, v214
	v_max_f32_e32 v211, 0, v215
	v_pk_fma_f32 v[0:1], v[24:25], v[210:211], v[0:1]
	v_max_f32_e32 v108, 0, v216
	v_max_f32_e32 v109, 0, v217
	v_pk_fma_f32 v[0:1], v[26:27], v[108:109], v[0:1]
	v_mfma_f32_32x32x16_bf16 v[6:21], v[90:93], v[42:45], v[6:21]
	v_max_f32_e32 v210, 0, v218
	v_max_f32_e32 v211, 0, v219
	v_pk_fma_f32 v[0:1], v[28:29], v[210:211], v[0:1]
	v_max_f32_e32 v108, 0, v220
	v_max_f32_e32 v109, 0, v221
	v_pk_fma_f32 v[0:1], v[30:31], v[108:109], v[0:1]
	v_max_f32_e32 v210, 0, v222
	v_max_f32_e32 v211, 0, v223
	v_pk_fma_f32 v[0:1], v[32:33], v[210:211], v[0:1]
	v_mfma_f32_32x32x16_bf16 v[6:21], v[94:97], v[46:49], v[6:21]
	v_max_f32_e32 v108, 0, v224
	v_max_f32_e32 v109, 0, v225
	v_pk_fma_f32 v[0:1], v[34:35], v[108:109], v[0:1]
	v_max_f32_e32 v210, 0, v226
	v_max_f32_e32 v211, 0, v227
	v_pk_fma_f32 v[0:1], v[36:37], v[210:211], v[0:1]
	v_add_f32_e32 v0, v0, v1
	v_ashrrev_i32_e32 v1, 31, v0
	v_mfma_f32_32x32x16_bf16 v[6:21], v[98:101], v[196:199], v[6:21]
	s_waitcnt vmcnt(10)
	ds_read_b128 v[38:41], v5 offset:10496
	ds_read_b128 v[42:45], v52 offset:10496
	ds_read_b128 v[46:49], v55 offset:10496
	ds_read_b128 v[196:199], v56 offset:10496
	v_or_b32_e32 v1, 0x80000000, v1
	s_cmpk_gt_i32 s11, 88
	s_cselect_b64 vcc, -1, 0
	v_xor_b32_e32 v0, v1, v0
	v_cndmask_b32_e32 v143, v123, v0, vcc
	s_nop 1
	s_waitcnt lgkmcnt(3)
	v_mfma_f32_32x32x16_bf16 v[212:227], v[70:73], v[38:41], 0
	v_max_f32_e32 v108, 0, v6
	v_max_f32_e32 v109, 0, v7
	v_pk_mul_f32 v[50:51], v[244:245], v[108:109]
	v_max_f32_e32 v210, 0, v8
	v_max_f32_e32 v211, 0, v9
	v_pk_fma_f32 v[50:51], v[246:247], v[210:211], v[50:51]
	v_max_f32_e32 v108, 0, v10
	v_max_f32_e32 v109, 0, v11
	v_pk_fma_f32 v[50:51], v[248:249], v[108:109], v[50:51]
	s_waitcnt lgkmcnt(2)
	v_mfma_f32_32x32x16_bf16 v[212:227], v[74:77], v[42:45], v[212:227]
	v_max_f32_e32 v210, 0, v12
	v_max_f32_e32 v211, 0, v13
	v_pk_fma_f32 v[50:51], v[250:251], v[210:211], v[50:51]
	v_max_f32_e32 v108, 0, v14
	v_max_f32_e32 v109, 0, v15
	v_pk_fma_f32 v[50:51], v[252:253], v[108:109], v[50:51]
	v_max_f32_e32 v210, 0, v16
	v_max_f32_e32 v211, 0, v17
	v_pk_fma_f32 v[50:51], v[254:255], v[210:211], v[50:51]
	s_waitcnt lgkmcnt(1)
	v_mfma_f32_32x32x16_bf16 v[212:227], v[78:81], v[46:49], v[212:227]
	v_max_f32_e32 v108, 0, v18
	v_max_f32_e32 v109, 0, v19
	v_pk_fma_f32 v[50:51], v[200:201], v[108:109], v[50:51]
	v_max_f32_e32 v210, 0, v20
	v_max_f32_e32 v211, 0, v21
	v_pk_fma_f32 v[50:51], v[202:203], v[210:211], v[50:51]
	v_add_f32_e32 v50, v50, v51
	v_ashrrev_i32_e32 v51, 31, v50
	s_waitcnt lgkmcnt(0)
	v_mfma_f32_32x32x16_bf16 v[212:227], v[82:85], v[196:199], v[212:227]
	v_or_b32_e32 v51, 0x80000000, v51
	s_cmpk_gt_i32 s11, 88
	s_cselect_b64 vcc, -1, 0
	v_xor_b32_e32 v50, v51, v50
	v_cndmask_b32_e32 v50, v123, v50, vcc
	global_store_dword v243, v50, s[8:9] offset:2048
	s_add_u32 s8, s8, 0x1000
	s_addc_u32 s9, s9, 0
	v_mfma_f32_32x32x16_bf16 v[6:21], v[86:89], v[38:41], 0
	s_add_i32 m0, s10, 98304
	s_nop 0
	global_load_lds_dwordx4 v102, s[6:7]
	s_add_i32 m0, s10, 99328
	s_nop 0
	global_load_lds_dwordx4 v110, s[6:7]
	s_add_i32 m0, s10, 100352
	s_nop 0
	global_load_lds_dwordx4 v112, s[6:7]
	s_add_i32 m0, s10, 101376
	s_nop 0
	global_load_lds_dwordx4 v193, s[6:7]
	s_add_u32 s6, s6, 0x8000
	s_addc_u32 s7, s7, 0
	v_max_f32_e32 v108, 0, v212
	v_max_f32_e32 v109, 0, v213
	v_pk_mul_f32 v[0:1], v[22:23], v[108:109]
	v_max_f32_e32 v210, 0, v214
	v_max_f32_e32 v211, 0, v215
	v_pk_fma_f32 v[0:1], v[24:25], v[210:211], v[0:1]
	v_max_f32_e32 v108, 0, v216
	v_max_f32_e32 v109, 0, v217
	v_pk_fma_f32 v[0:1], v[26:27], v[108:109], v[0:1]
	v_mfma_f32_32x32x16_bf16 v[6:21], v[90:93], v[42:45], v[6:21]
	v_max_f32_e32 v210, 0, v218
	v_max_f32_e32 v211, 0, v219
	v_pk_fma_f32 v[0:1], v[28:29], v[210:211], v[0:1]
	v_max_f32_e32 v108, 0, v220
	v_max_f32_e32 v109, 0, v221
	v_pk_fma_f32 v[0:1], v[30:31], v[108:109], v[0:1]
	v_max_f32_e32 v210, 0, v222
	v_max_f32_e32 v211, 0, v223
	v_pk_fma_f32 v[0:1], v[32:33], v[210:211], v[0:1]
	v_mfma_f32_32x32x16_bf16 v[6:21], v[94:97], v[46:49], v[6:21]
	v_max_f32_e32 v108, 0, v224
	v_max_f32_e32 v109, 0, v225
	v_pk_fma_f32 v[0:1], v[34:35], v[108:109], v[0:1]
	v_max_f32_e32 v210, 0, v226
	v_max_f32_e32 v211, 0, v227
	v_pk_fma_f32 v[0:1], v[36:37], v[210:211], v[0:1]
	v_add_f32_e32 v0, v0, v1
	v_ashrrev_i32_e32 v1, 31, v0
	v_mfma_f32_32x32x16_bf16 v[6:21], v[98:101], v[196:199], v[6:21]
	s_waitcnt vmcnt(10)
	ds_read_b128 v[38:41], v5 offset:43264
	ds_read_b128 v[42:45], v52 offset:43264
	ds_read_b128 v[46:49], v55 offset:43264
	ds_read_b128 v[196:199], v56 offset:43264
	v_or_b32_e32 v1, 0x80000000, v1
	s_cmpk_gt_i32 s11, 96
	s_cselect_b64 vcc, -1, 0
	v_xor_b32_e32 v0, v1, v0
	v_cndmask_b32_e32 v146, v123, v0, vcc
	s_nop 1
	s_waitcnt lgkmcnt(3)
	v_mfma_f32_32x32x16_bf16 v[212:227], v[70:73], v[38:41], 0
	v_max_f32_e32 v108, 0, v6
	v_max_f32_e32 v109, 0, v7
	v_pk_mul_f32 v[50:51], v[244:245], v[108:109]
	v_max_f32_e32 v210, 0, v8
	v_max_f32_e32 v211, 0, v9
	v_pk_fma_f32 v[50:51], v[246:247], v[210:211], v[50:51]
	v_max_f32_e32 v108, 0, v10
	v_max_f32_e32 v109, 0, v11
	v_pk_fma_f32 v[50:51], v[248:249], v[108:109], v[50:51]
	s_waitcnt lgkmcnt(2)
	v_mfma_f32_32x32x16_bf16 v[212:227], v[74:77], v[42:45], v[212:227]
	v_max_f32_e32 v210, 0, v12
	v_max_f32_e32 v211, 0, v13
	v_pk_fma_f32 v[50:51], v[250:251], v[210:211], v[50:51]
	v_max_f32_e32 v108, 0, v14
	v_max_f32_e32 v109, 0, v15
	v_pk_fma_f32 v[50:51], v[252:253], v[108:109], v[50:51]
	v_max_f32_e32 v210, 0, v16
	v_max_f32_e32 v211, 0, v17
	v_pk_fma_f32 v[50:51], v[254:255], v[210:211], v[50:51]
	s_waitcnt lgkmcnt(1)
	v_mfma_f32_32x32x16_bf16 v[212:227], v[78:81], v[46:49], v[212:227]
	v_max_f32_e32 v108, 0, v18
	v_max_f32_e32 v109, 0, v19
	v_pk_fma_f32 v[50:51], v[200:201], v[108:109], v[50:51]
	v_max_f32_e32 v210, 0, v20
	v_max_f32_e32 v211, 0, v21
	v_pk_fma_f32 v[50:51], v[202:203], v[210:211], v[50:51]
	v_add_f32_e32 v50, v50, v51
	v_ashrrev_i32_e32 v51, 31, v50
	s_waitcnt lgkmcnt(0)
	v_mfma_f32_32x32x16_bf16 v[212:227], v[82:85], v[196:199], v[212:227]
	v_or_b32_e32 v51, 0x80000000, v51
	s_cmpk_gt_i32 s11, 96
	s_cselect_b64 vcc, -1, 0
	v_xor_b32_e32 v50, v51, v50
	v_cndmask_b32_e32 v50, v123, v50, vcc
	global_store_dword v243, v50, s[8:9]
	v_mfma_f32_32x32x16_bf16 v[6:21], v[86:89], v[38:41], 0
	s_add_i32 m0, s10, 0
	s_nop 0
	global_load_lds_dwordx4 v102, s[6:7]
	s_add_i32 m0, s10, 1024
	s_nop 0
	global_load_lds_dwordx4 v110, s[6:7]
	s_add_i32 m0, s10, 2048
	s_nop 0
	global_load_lds_dwordx4 v112, s[6:7]
	s_add_i32 m0, s10, 3072
	s_nop 0
	global_load_lds_dwordx4 v193, s[6:7]
	s_add_u32 s6, s6, 0x8000
	s_addc_u32 s7, s7, 0
	v_max_f32_e32 v108, 0, v212
	v_max_f32_e32 v109, 0, v213
	v_pk_mul_f32 v[0:1], v[22:23], v[108:109]
	v_max_f32_e32 v210, 0, v214
	v_max_f32_e32 v211, 0, v215
	v_pk_fma_f32 v[0:1], v[24:25], v[210:211], v[0:1]
	v_max_f32_e32 v108, 0, v216
	v_max_f32_e32 v109, 0, v217
	v_pk_fma_f32 v[0:1], v[26:27], v[108:109], v[0:1]
	v_mfma_f32_32x32x16_bf16 v[6:21], v[90:93], v[42:45], v[6:21]
	v_max_f32_e32 v210, 0, v218
	v_max_f32_e32 v211, 0, v219
	v_pk_fma_f32 v[0:1], v[28:29], v[210:211], v[0:1]
	v_max_f32_e32 v108, 0, v220
	v_max_f32_e32 v109, 0, v221
	v_pk_fma_f32 v[0:1], v[30:31], v[108:109], v[0:1]
	v_max_f32_e32 v210, 0, v222
	v_max_f32_e32 v211, 0, v223
	v_pk_fma_f32 v[0:1], v[32:33], v[210:211], v[0:1]
	v_mfma_f32_32x32x16_bf16 v[6:21], v[94:97], v[46:49], v[6:21]
	v_max_f32_e32 v108, 0, v224
	v_max_f32_e32 v109, 0, v225
	v_pk_fma_f32 v[0:1], v[34:35], v[108:109], v[0:1]
	v_max_f32_e32 v210, 0, v226
	v_max_f32_e32 v211, 0, v227
	v_pk_fma_f32 v[0:1], v[36:37], v[210:211], v[0:1]
	v_add_f32_e32 v0, v0, v1
	v_ashrrev_i32_e32 v1, 31, v0
	v_mfma_f32_32x32x16_bf16 v[6:21], v[98:101], v[196:199], v[6:21]
	s_waitcnt vmcnt(10)
	v_add_u32_e32 v228, 0x10000, v5
	ds_read_b128 v[38:41], v228 offset:10496
	v_add_u32_e32 v228, 0x10000, v52
	ds_read_b128 v[42:45], v228 offset:10496
	v_add_u32_e32 v228, 0x10000, v55
	ds_read_b128 v[46:49], v228 offset:10496
	v_add_u32_e32 v228, 0x10000, v56
	ds_read_b128 v[196:199], v228 offset:10496
	v_or_b32_e32 v1, 0x80000000, v1
	s_cmpk_gt_i32 s11, 104
	s_cselect_b64 vcc, -1, 0
	v_xor_b32_e32 v0, v1, v0
	v_cndmask_b32_e32 v145, v123, v0, vcc
	s_nop 1
	s_waitcnt lgkmcnt(3)
	v_mfma_f32_32x32x16_bf16 v[212:227], v[70:73], v[38:41], 0
	v_max_f32_e32 v108, 0, v6
	v_max_f32_e32 v109, 0, v7
	v_pk_mul_f32 v[50:51], v[244:245], v[108:109]
	v_max_f32_e32 v210, 0, v8
	v_max_f32_e32 v211, 0, v9
	v_pk_fma_f32 v[50:51], v[246:247], v[210:211], v[50:51]
	v_max_f32_e32 v108, 0, v10
	v_max_f32_e32 v109, 0, v11
	v_pk_fma_f32 v[50:51], v[248:249], v[108:109], v[50:51]
	s_waitcnt lgkmcnt(2)
	v_mfma_f32_32x32x16_bf16 v[212:227], v[74:77], v[42:45], v[212:227]
	v_max_f32_e32 v210, 0, v12
	v_max_f32_e32 v211, 0, v13
	v_pk_fma_f32 v[50:51], v[250:251], v[210:211], v[50:51]
	v_max_f32_e32 v108, 0, v14
	v_max_f32_e32 v109, 0, v15
	v_pk_fma_f32 v[50:51], v[252:253], v[108:109], v[50:51]
	v_max_f32_e32 v210, 0, v16
	v_max_f32_e32 v211, 0, v17
	v_pk_fma_f32 v[50:51], v[254:255], v[210:211], v[50:51]
	s_waitcnt lgkmcnt(1)
	v_mfma_f32_32x32x16_bf16 v[212:227], v[78:81], v[46:49], v[212:227]
	v_max_f32_e32 v108, 0, v18
	v_max_f32_e32 v109, 0, v19
	v_pk_fma_f32 v[50:51], v[200:201], v[108:109], v[50:51]
	v_max_f32_e32 v210, 0, v20
	v_max_f32_e32 v211, 0, v21
	v_pk_fma_f32 v[50:51], v[202:203], v[210:211], v[50:51]
	v_add_f32_e32 v50, v50, v51
	v_ashrrev_i32_e32 v51, 31, v50
	s_waitcnt lgkmcnt(0)
	v_mfma_f32_32x32x16_bf16 v[212:227], v[82:85], v[196:199], v[212:227]
	v_or_b32_e32 v51, 0x80000000, v51
	s_cmpk_gt_i32 s11, 104
	s_cselect_b64 vcc, -1, 0
	v_xor_b32_e32 v50, v51, v50
	v_cndmask_b32_e32 v50, v123, v50, vcc
	global_store_dword v243, v50, s[8:9] offset:2048
	s_add_u32 s8, s8, 0x1000
	s_addc_u32 s9, s9, 0
	v_mfma_f32_32x32x16_bf16 v[6:21], v[86:89], v[38:41], 0
	s_add_i32 m0, s10, 32768
	s_nop 0
	global_load_lds_dwordx4 v102, s[6:7]
	s_add_i32 m0, s10, 33792
	s_nop 0
	global_load_lds_dwordx4 v110, s[6:7]
	s_add_i32 m0, s10, 34816
	s_nop 0
	global_load_lds_dwordx4 v112, s[6:7]
	s_add_i32 m0, s10, 35840
	s_nop 0
	global_load_lds_dwordx4 v193, s[6:7]
	s_add_u32 s6, s6, 0x8000
	s_addc_u32 s7, s7, 0
	v_max_f32_e32 v108, 0, v212
	v_max_f32_e32 v109, 0, v213
	v_pk_mul_f32 v[0:1], v[22:23], v[108:109]
	v_max_f32_e32 v210, 0, v214
	v_max_f32_e32 v211, 0, v215
	v_pk_fma_f32 v[0:1], v[24:25], v[210:211], v[0:1]
	v_max_f32_e32 v108, 0, v216
	v_max_f32_e32 v109, 0, v217
	v_pk_fma_f32 v[0:1], v[26:27], v[108:109], v[0:1]
	v_mfma_f32_32x32x16_bf16 v[6:21], v[90:93], v[42:45], v[6:21]
	v_max_f32_e32 v210, 0, v218
	v_max_f32_e32 v211, 0, v219
	v_pk_fma_f32 v[0:1], v[28:29], v[210:211], v[0:1]
	v_max_f32_e32 v108, 0, v220
	v_max_f32_e32 v109, 0, v221
	v_pk_fma_f32 v[0:1], v[30:31], v[108:109], v[0:1]
	v_max_f32_e32 v210, 0, v222
	v_max_f32_e32 v211, 0, v223
	v_pk_fma_f32 v[0:1], v[32:33], v[210:211], v[0:1]
	v_mfma_f32_32x32x16_bf16 v[6:21], v[94:97], v[46:49], v[6:21]
	v_max_f32_e32 v108, 0, v224
	v_max_f32_e32 v109, 0, v225
	v_pk_fma_f32 v[0:1], v[34:35], v[108:109], v[0:1]
	v_max_f32_e32 v210, 0, v226
	v_max_f32_e32 v211, 0, v227
	v_pk_fma_f32 v[0:1], v[36:37], v[210:211], v[0:1]
	v_add_f32_e32 v0, v0, v1
	v_ashrrev_i32_e32 v1, 31, v0
	v_mfma_f32_32x32x16_bf16 v[6:21], v[98:101], v[196:199], v[6:21]
	s_waitcnt vmcnt(10)
	v_add_u32_e32 v228, 0x10000, v5
	ds_read_b128 v[38:41], v228 offset:43264
	v_add_u32_e32 v228, 0x10000, v52
	ds_read_b128 v[42:45], v228 offset:43264
	v_add_u32_e32 v228, 0x10000, v55
	ds_read_b128 v[46:49], v228 offset:43264
	v_add_u32_e32 v228, 0x10000, v56
	ds_read_b128 v[196:199], v228 offset:43264
	v_or_b32_e32 v1, 0x80000000, v1
	s_cmpk_gt_i32 s11, 112
	s_cselect_b64 vcc, -1, 0
	v_xor_b32_e32 v0, v1, v0
	v_cndmask_b32_e32 v147, v123, v0, vcc
	s_nop 1
	s_waitcnt lgkmcnt(3)
	v_mfma_f32_32x32x16_bf16 v[212:227], v[70:73], v[38:41], 0
	v_max_f32_e32 v108, 0, v6
	v_max_f32_e32 v109, 0, v7
	v_pk_mul_f32 v[50:51], v[244:245], v[108:109]
	v_max_f32_e32 v210, 0, v8
	v_max_f32_e32 v211, 0, v9
	v_pk_fma_f32 v[50:51], v[246:247], v[210:211], v[50:51]
	v_max_f32_e32 v108, 0, v10
	v_max_f32_e32 v109, 0, v11
	v_pk_fma_f32 v[50:51], v[248:249], v[108:109], v[50:51]
	s_waitcnt lgkmcnt(2)
	v_mfma_f32_32x32x16_bf16 v[212:227], v[74:77], v[42:45], v[212:227]
	v_max_f32_e32 v210, 0, v12
	v_max_f32_e32 v211, 0, v13
	v_pk_fma_f32 v[50:51], v[250:251], v[210:211], v[50:51]
	v_max_f32_e32 v108, 0, v14
	v_max_f32_e32 v109, 0, v15
	v_pk_fma_f32 v[50:51], v[252:253], v[108:109], v[50:51]
	v_max_f32_e32 v210, 0, v16
	v_max_f32_e32 v211, 0, v17
	v_pk_fma_f32 v[50:51], v[254:255], v[210:211], v[50:51]
	s_waitcnt lgkmcnt(1)
	v_mfma_f32_32x32x16_bf16 v[212:227], v[78:81], v[46:49], v[212:227]
	v_max_f32_e32 v108, 0, v18
	v_max_f32_e32 v109, 0, v19
	v_pk_fma_f32 v[50:51], v[200:201], v[108:109], v[50:51]
	v_max_f32_e32 v210, 0, v20
	v_max_f32_e32 v211, 0, v21
	v_pk_fma_f32 v[50:51], v[202:203], v[210:211], v[50:51]
	v_add_f32_e32 v50, v50, v51
	v_ashrrev_i32_e32 v51, 31, v50
	s_waitcnt lgkmcnt(0)
	v_mfma_f32_32x32x16_bf16 v[212:227], v[82:85], v[196:199], v[212:227]
	v_or_b32_e32 v51, 0x80000000, v51
	s_cmpk_gt_i32 s11, 112
	s_cselect_b64 vcc, -1, 0
	v_xor_b32_e32 v50, v51, v50
	v_cndmask_b32_e32 v50, v123, v50, vcc
	global_store_dword v243, v50, s[8:9]
	v_mfma_f32_32x32x16_bf16 v[6:21], v[86:89], v[38:41], 0
	s_add_i32 m0, s10, 65536
	s_nop 0
	global_load_lds_dwordx4 v102, s[6:7]
	s_add_i32 m0, s10, 66560
	s_nop 0
	global_load_lds_dwordx4 v110, s[6:7]
	s_add_i32 m0, s10, 67584
	s_nop 0
	global_load_lds_dwordx4 v112, s[6:7]
	s_add_i32 m0, s10, 68608
	s_nop 0
	global_load_lds_dwordx4 v193, s[6:7]
	s_add_u32 s6, s6, 0x8000
	s_addc_u32 s7, s7, 0
	v_max_f32_e32 v108, 0, v212
	v_max_f32_e32 v109, 0, v213
	v_pk_mul_f32 v[0:1], v[22:23], v[108:109]
	v_max_f32_e32 v210, 0, v214
	v_max_f32_e32 v211, 0, v215
	v_pk_fma_f32 v[0:1], v[24:25], v[210:211], v[0:1]
	v_max_f32_e32 v108, 0, v216
	v_max_f32_e32 v109, 0, v217
	v_pk_fma_f32 v[0:1], v[26:27], v[108:109], v[0:1]
	v_mfma_f32_32x32x16_bf16 v[6:21], v[90:93], v[42:45], v[6:21]
	v_max_f32_e32 v210, 0, v218
	v_max_f32_e32 v211, 0, v219
	v_pk_fma_f32 v[0:1], v[28:29], v[210:211], v[0:1]
	v_max_f32_e32 v108, 0, v220
	v_max_f32_e32 v109, 0, v221
	v_pk_fma_f32 v[0:1], v[30:31], v[108:109], v[0:1]
	v_max_f32_e32 v210, 0, v222
	v_max_f32_e32 v211, 0, v223
	v_pk_fma_f32 v[0:1], v[32:33], v[210:211], v[0:1]
	v_mfma_f32_32x32x16_bf16 v[6:21], v[94:97], v[46:49], v[6:21]
	v_max_f32_e32 v108, 0, v224
	v_max_f32_e32 v109, 0, v225
	v_pk_fma_f32 v[0:1], v[34:35], v[108:109], v[0:1]
	v_max_f32_e32 v210, 0, v226
	v_max_f32_e32 v211, 0, v227
	v_pk_fma_f32 v[0:1], v[36:37], v[210:211], v[0:1]
	v_add_f32_e32 v0, v0, v1
	v_ashrrev_i32_e32 v1, 31, v0
	v_mfma_f32_32x32x16_bf16 v[6:21], v[98:101], v[196:199], v[6:21]
	s_waitcnt vmcnt(10)
	ds_read_b128 v[38:41], v5 offset:10496
	ds_read_b128 v[42:45], v52 offset:10496
	ds_read_b128 v[46:49], v55 offset:10496
	ds_read_b128 v[196:199], v56 offset:10496
	v_or_b32_e32 v1, 0x80000000, v1
	s_cmpk_gt_i32 s11, 120
	s_cselect_b64 vcc, -1, 0
	v_xor_b32_e32 v0, v1, v0
	v_cndmask_b32_e32 v136, v123, v0, vcc
	s_nop 1
	v_max_f32_e32 v108, 0, v6
	v_max_f32_e32 v109, 0, v7
	v_pk_mul_f32 v[50:51], v[244:245], v[108:109]
	v_max_f32_e32 v210, 0, v8
	v_max_f32_e32 v211, 0, v9
	v_pk_fma_f32 v[50:51], v[246:247], v[210:211], v[50:51]
	v_max_f32_e32 v108, 0, v10
	v_max_f32_e32 v109, 0, v11
	v_pk_fma_f32 v[50:51], v[248:249], v[108:109], v[50:51]
	v_max_f32_e32 v210, 0, v12
	v_max_f32_e32 v211, 0, v13
	v_pk_fma_f32 v[50:51], v[250:251], v[210:211], v[50:51]
	v_max_f32_e32 v108, 0, v14
	v_max_f32_e32 v109, 0, v15
	v_pk_fma_f32 v[50:51], v[252:253], v[108:109], v[50:51]
	v_max_f32_e32 v210, 0, v16
	v_max_f32_e32 v211, 0, v17
	v_pk_fma_f32 v[50:51], v[254:255], v[210:211], v[50:51]
	v_max_f32_e32 v108, 0, v18
	v_max_f32_e32 v109, 0, v19
	v_pk_fma_f32 v[50:51], v[200:201], v[108:109], v[50:51]
	v_max_f32_e32 v210, 0, v20
	v_max_f32_e32 v211, 0, v21
	v_pk_fma_f32 v[50:51], v[202:203], v[210:211], v[50:51]
	v_add_f32_e32 v50, v50, v51
	v_ashrrev_i32_e32 v51, 31, v50
	v_or_b32_e32 v51, 0x80000000, v51
	s_cmpk_gt_i32 s11, 120
	s_cselect_b64 vcc, -1, 0
	v_xor_b32_e32 v50, v51, v50
	v_cndmask_b32_e32 v50, v123, v50, vcc
	global_store_dword v243, v50, s[8:9] offset:2048
	s_add_u32 s8, s8, 0x1000
	s_addc_u32 s9, s9, 0
	s_cmpk_gt_i32 s81, 16
	s_cbranch_scc0 .Lix_fill_2
	s_waitcnt lgkmcnt(3)
	v_mfma_f32_32x32x16_bf16 v[212:227], v[70:73], v[38:41], 0
	s_add_i32 m0, s10, 98304
	s_nop 0
	global_load_lds_dwordx4 v102, s[6:7]
	s_waitcnt lgkmcnt(2)
	v_mfma_f32_32x32x16_bf16 v[212:227], v[74:77], v[42:45], v[212:227]
	s_add_i32 m0, s10, 99328
	s_nop 0
	global_load_lds_dwordx4 v110, s[6:7]
	s_waitcnt lgkmcnt(1)
	v_mfma_f32_32x32x16_bf16 v[212:227], v[78:81], v[46:49], v[212:227]
	s_add_i32 m0, s10, 100352
	s_nop 0
	global_load_lds_dwordx4 v112, s[6:7]
	s_waitcnt lgkmcnt(0)
	v_mfma_f32_32x32x16_bf16 v[212:227], v[82:85], v[196:199], v[212:227]
	s_add_i32 m0, s10, 101376
	s_nop 0
	global_load_lds_dwordx4 v193, s[6:7]
	s_add_u32 s6, s6, 0x8000
	s_addc_u32 s7, s7, 0
	v_mfma_f32_32x32x16_bf16 v[6:21], v[86:89], v[38:41], 0
	s_nop 7
	s_nop 2
	v_max_f32_e32 v108, 0, v212
	v_max_f32_e32 v109, 0, v213
	v_pk_mul_f32 v[0:1], v[22:23], v[108:109]
	v_max_f32_e32 v210, 0, v214
	v_max_f32_e32 v211, 0, v215
	v_pk_fma_f32 v[0:1], v[24:25], v[210:211], v[0:1]
	v_max_f32_e32 v108, 0, v216
	v_max_f32_e32 v109, 0, v217
	v_pk_fma_f32 v[0:1], v[26:27], v[108:109], v[0:1]
	v_mfma_f32_32x32x16_bf16 v[6:21], v[90:93], v[42:45], v[6:21]
	v_max_f32_e32 v210, 0, v218
	v_max_f32_e32 v211, 0, v219
	v_pk_fma_f32 v[0:1], v[28:29], v[210:211], v[0:1]
	v_max_f32_e32 v108, 0, v220
	v_max_f32_e32 v109, 0, v221
	v_pk_fma_f32 v[0:1], v[30:31], v[108:109], v[0:1]
	v_max_f32_e32 v210, 0, v222
	v_max_f32_e32 v211, 0, v223
	v_pk_fma_f32 v[0:1], v[32:33], v[210:211], v[0:1]
	v_mfma_f32_32x32x16_bf16 v[6:21], v[94:97], v[46:49], v[6:21]
	v_max_f32_e32 v108, 0, v224
	v_max_f32_e32 v109, 0, v225
	v_pk_fma_f32 v[0:1], v[34:35], v[108:109], v[0:1]
	v_max_f32_e32 v210, 0, v226
	v_max_f32_e32 v211, 0, v227
	v_pk_fma_f32 v[0:1], v[36:37], v[210:211], v[0:1]
	v_add_f32_e32 v0, v0, v1
	v_ashrrev_i32_e32 v1, 31, v0
	v_mfma_f32_32x32x16_bf16 v[6:21], v[98:101], v[196:199], v[6:21]
	s_waitcnt vmcnt(10)
	ds_read_b128 v[38:41], v5 offset:43264
	ds_read_b128 v[42:45], v52 offset:43264
	ds_read_b128 v[46:49], v55 offset:43264
	ds_read_b128 v[196:199], v56 offset:43264
	v_or_b32_e32 v1, 0x80000000, v1
	s_cmpk_gt_i32 s11, 128
	s_cselect_b64 vcc, -1, 0
	v_xor_b32_e32 v0, v1, v0
	v_cndmask_b32_e32 v149, v123, v0, vcc
	s_nop 1
	s_waitcnt lgkmcnt(3)
	v_mfma_f32_32x32x16_bf16 v[212:227], v[70:73], v[38:41], 0
	v_max_f32_e32 v108, 0, v6
	v_max_f32_e32 v109, 0, v7
	v_pk_mul_f32 v[50:51], v[244:245], v[108:109]
	v_max_f32_e32 v210, 0, v8
	v_max_f32_e32 v211, 0, v9
	v_pk_fma_f32 v[50:51], v[246:247], v[210:211], v[50:51]
	v_max_f32_e32 v108, 0, v10
	v_max_f32_e32 v109, 0, v11
	v_pk_fma_f32 v[50:51], v[248:249], v[108:109], v[50:51]
	s_waitcnt lgkmcnt(2)
	v_mfma_f32_32x32x16_bf16 v[212:227], v[74:77], v[42:45], v[212:227]
	v_max_f32_e32 v210, 0, v12
	v_max_f32_e32 v211, 0, v13
	v_pk_fma_f32 v[50:51], v[250:251], v[210:211], v[50:51]
	v_max_f32_e32 v108, 0, v14
	v_max_f32_e32 v109, 0, v15
	v_pk_fma_f32 v[50:51], v[252:253], v[108:109], v[50:51]
	v_max_f32_e32 v210, 0, v16
	v_max_f32_e32 v211, 0, v17
	v_pk_fma_f32 v[50:51], v[254:255], v[210:211], v[50:51]
	s_waitcnt lgkmcnt(1)
	v_mfma_f32_32x32x16_bf16 v[212:227], v[78:81], v[46:49], v[212:227]
	v_max_f32_e32 v108, 0, v18
	v_max_f32_e32 v109, 0, v19
	v_pk_fma_f32 v[50:51], v[200:201], v[108:109], v[50:51]
	v_max_f32_e32 v210, 0, v20
	v_max_f32_e32 v211, 0, v21
	v_pk_fma_f32 v[50:51], v[202:203], v[210:211], v[50:51]
	v_add_f32_e32 v50, v50, v51
	v_ashrrev_i32_e32 v51, 31, v50
	s_waitcnt lgkmcnt(0)
	v_mfma_f32_32x32x16_bf16 v[212:227], v[82:85], v[196:199], v[212:227]
	v_or_b32_e32 v51, 0x80000000, v51
	s_cmpk_gt_i32 s11, 128
	s_cselect_b64 vcc, -1, 0
	v_xor_b32_e32 v50, v51, v50
	v_cndmask_b32_e32 v50, v123, v50, vcc
	global_store_dword v243, v50, s[8:9]
	v_mfma_f32_32x32x16_bf16 v[6:21], v[86:89], v[38:41], 0
	s_add_i32 m0, s10, 0
	s_nop 0
	global_load_lds_dwordx4 v102, s[6:7]
	s_add_i32 m0, s10, 1024
	s_nop 0
	global_load_lds_dwordx4 v110, s[6:7]
	s_add_i32 m0, s10, 2048
	s_nop 0
	global_load_lds_dwordx4 v112, s[6:7]
	s_add_i32 m0, s10, 3072
	s_nop 0
	global_load_lds_dwordx4 v193, s[6:7]
	s_add_u32 s6, s6, 0x8000
	s_addc_u32 s7, s7, 0
	v_max_f32_e32 v108, 0, v212
	v_max_f32_e32 v109, 0, v213
	v_pk_mul_f32 v[0:1], v[22:23], v[108:109]
	v_max_f32_e32 v210, 0, v214
	v_max_f32_e32 v211, 0, v215
	v_pk_fma_f32 v[0:1], v[24:25], v[210:211], v[0:1]
	v_max_f32_e32 v108, 0, v216
	v_max_f32_e32 v109, 0, v217
	v_pk_fma_f32 v[0:1], v[26:27], v[108:109], v[0:1]
	v_mfma_f32_32x32x16_bf16 v[6:21], v[90:93], v[42:45], v[6:21]
	v_max_f32_e32 v210, 0, v218
	v_max_f32_e32 v211, 0, v219
	v_pk_fma_f32 v[0:1], v[28:29], v[210:211], v[0:1]
	v_max_f32_e32 v108, 0, v220
	v_max_f32_e32 v109, 0, v221
	v_pk_fma_f32 v[0:1], v[30:31], v[108:109], v[0:1]
	v_max_f32_e32 v210, 0, v222
	v_max_f32_e32 v211, 0, v223
	v_pk_fma_f32 v[0:1], v[32:33], v[210:211], v[0:1]
	v_mfma_f32_32x32x16_bf16 v[6:21], v[94:97], v[46:49], v[6:21]
	v_max_f32_e32 v108, 0, v224
	v_max_f32_e32 v109, 0, v225
	v_pk_fma_f32 v[0:1], v[34:35], v[108:109], v[0:1]
	v_max_f32_e32 v210, 0, v226
	v_max_f32_e32 v211, 0, v227
	v_pk_fma_f32 v[0:1], v[36:37], v[210:211], v[0:1]
	v_add_f32_e32 v0, v0, v1
	v_ashrrev_i32_e32 v1, 31, v0
	v_mfma_f32_32x32x16_bf16 v[6:21], v[98:101], v[196:199], v[6:21]
	s_waitcnt vmcnt(10)
	v_add_u32_e32 v228, 0x10000, v5
	ds_read_b128 v[38:41], v228 offset:10496
	v_add_u32_e32 v228, 0x10000, v52
	ds_read_b128 v[42:45], v228 offset:10496
	v_add_u32_e32 v228, 0x10000, v55
	ds_read_b128 v[46:49], v228 offset:10496
	v_add_u32_e32 v228, 0x10000, v56
	ds_read_b128 v[196:199], v228 offset:10496
	v_or_b32_e32 v1, 0x80000000, v1
	s_cmpk_gt_i32 s11, 136
	s_cselect_b64 vcc, -1, 0
	v_xor_b32_e32 v0, v1, v0
	v_cndmask_b32_e32 v148, v123, v0, vcc
	s_nop 1
	s_waitcnt lgkmcnt(3)
	v_mfma_f32_32x32x16_bf16 v[212:227], v[70:73], v[38:41], 0
	v_max_f32_e32 v108, 0, v6
	v_max_f32_e32 v109, 0, v7
	v_pk_mul_f32 v[50:51], v[244:245], v[108:109]
	v_max_f32_e32 v210, 0, v8
	v_max_f32_e32 v211, 0, v9
	v_pk_fma_f32 v[50:51], v[246:247], v[210:211], v[50:51]
	v_max_f32_e32 v108, 0, v10
	v_max_f32_e32 v109, 0, v11
	v_pk_fma_f32 v[50:51], v[248:249], v[108:109], v[50:51]
	s_waitcnt lgkmcnt(2)
	v_mfma_f32_32x32x16_bf16 v[212:227], v[74:77], v[42:45], v[212:227]
	v_max_f32_e32 v210, 0, v12
	v_max_f32_e32 v211, 0, v13
	v_pk_fma_f32 v[50:51], v[250:251], v[210:211], v[50:51]
	v_max_f32_e32 v108, 0, v14
	v_max_f32_e32 v109, 0, v15
	v_pk_fma_f32 v[50:51], v[252:253], v[108:109], v[50:51]
	v_max_f32_e32 v210, 0, v16
	v_max_f32_e32 v211, 0, v17
	v_pk_fma_f32 v[50:51], v[254:255], v[210:211], v[50:51]
	s_waitcnt lgkmcnt(1)
	v_mfma_f32_32x32x16_bf16 v[212:227], v[78:81], v[46:49], v[212:227]
	v_max_f32_e32 v108, 0, v18
	v_max_f32_e32 v109, 0, v19
	v_pk_fma_f32 v[50:51], v[200:201], v[108:109], v[50:51]
	v_max_f32_e32 v210, 0, v20
	v_max_f32_e32 v211, 0, v21
	v_pk_fma_f32 v[50:51], v[202:203], v[210:211], v[50:51]
	v_add_f32_e32 v50, v50, v51
	v_ashrrev_i32_e32 v51, 31, v50
	s_waitcnt lgkmcnt(0)
	v_mfma_f32_32x32x16_bf16 v[212:227], v[82:85], v[196:199], v[212:227]
	v_or_b32_e32 v51, 0x80000000, v51
	s_cmpk_gt_i32 s11, 136
	s_cselect_b64 vcc, -1, 0
	v_xor_b32_e32 v50, v51, v50
	v_cndmask_b32_e32 v50, v123, v50, vcc
	global_store_dword v243, v50, s[8:9] offset:2048
	s_add_u32 s8, s8, 0x1000
	s_addc_u32 s9, s9, 0
	v_mfma_f32_32x32x16_bf16 v[6:21], v[86:89], v[38:41], 0
	s_add_i32 m0, s10, 32768
	s_nop 0
	global_load_lds_dwordx4 v102, s[6:7]
	s_add_i32 m0, s10, 33792
	s_nop 0
	global_load_lds_dwordx4 v110, s[6:7]
	s_add_i32 m0, s10, 34816
	s_nop 0
	global_load_lds_dwordx4 v112, s[6:7]
	s_add_i32 m0, s10, 35840
	s_nop 0
	global_load_lds_dwordx4 v193, s[6:7]
	s_add_u32 s6, s6, 0x8000
	s_addc_u32 s7, s7, 0
	v_max_f32_e32 v108, 0, v212
	v_max_f32_e32 v109, 0, v213
	v_pk_mul_f32 v[0:1], v[22:23], v[108:109]
	v_max_f32_e32 v210, 0, v214
	v_max_f32_e32 v211, 0, v215
	v_pk_fma_f32 v[0:1], v[24:25], v[210:211], v[0:1]
	v_max_f32_e32 v108, 0, v216
	v_max_f32_e32 v109, 0, v217
	v_pk_fma_f32 v[0:1], v[26:27], v[108:109], v[0:1]
	v_mfma_f32_32x32x16_bf16 v[6:21], v[90:93], v[42:45], v[6:21]
	v_max_f32_e32 v210, 0, v218
	v_max_f32_e32 v211, 0, v219
	v_pk_fma_f32 v[0:1], v[28:29], v[210:211], v[0:1]
	v_max_f32_e32 v108, 0, v220
	v_max_f32_e32 v109, 0, v221
	v_pk_fma_f32 v[0:1], v[30:31], v[108:109], v[0:1]
	v_max_f32_e32 v210, 0, v222
	v_max_f32_e32 v211, 0, v223
	v_pk_fma_f32 v[0:1], v[32:33], v[210:211], v[0:1]
	v_mfma_f32_32x32x16_bf16 v[6:21], v[94:97], v[46:49], v[6:21]
	v_max_f32_e32 v108, 0, v224
	v_max_f32_e32 v109, 0, v225
	v_pk_fma_f32 v[0:1], v[34:35], v[108:109], v[0:1]
	v_max_f32_e32 v210, 0, v226
	v_max_f32_e32 v211, 0, v227
	v_pk_fma_f32 v[0:1], v[36:37], v[210:211], v[0:1]
	v_add_f32_e32 v0, v0, v1
	v_ashrrev_i32_e32 v1, 31, v0
	v_mfma_f32_32x32x16_bf16 v[6:21], v[98:101], v[196:199], v[6:21]
	s_waitcnt vmcnt(10)
	v_add_u32_e32 v228, 0x10000, v5
	ds_read_b128 v[38:41], v228 offset:43264
	v_add_u32_e32 v228, 0x10000, v52
	ds_read_b128 v[42:45], v228 offset:43264
	v_add_u32_e32 v228, 0x10000, v55
	ds_read_b128 v[46:49], v228 offset:43264
	v_add_u32_e32 v228, 0x10000, v56
	ds_read_b128 v[196:199], v228 offset:43264
	v_or_b32_e32 v1, 0x80000000, v1
	s_cmpk_gt_i32 s11, 144
	s_cselect_b64 vcc, -1, 0
	v_xor_b32_e32 v0, v1, v0
	v_cndmask_b32_e32 v151, v123, v0, vcc
	s_nop 1
	s_waitcnt lgkmcnt(3)
	v_mfma_f32_32x32x16_bf16 v[212:227], v[70:73], v[38:41], 0
	v_max_f32_e32 v108, 0, v6
	v_max_f32_e32 v109, 0, v7
	v_pk_mul_f32 v[50:51], v[244:245], v[108:109]
	v_max_f32_e32 v210, 0, v8
	v_max_f32_e32 v211, 0, v9
	v_pk_fma_f32 v[50:51], v[246:247], v[210:211], v[50:51]
	v_max_f32_e32 v108, 0, v10
	v_max_f32_e32 v109, 0, v11
	v_pk_fma_f32 v[50:51], v[248:249], v[108:109], v[50:51]
	s_waitcnt lgkmcnt(2)
	v_mfma_f32_32x32x16_bf16 v[212:227], v[74:77], v[42:45], v[212:227]
	v_max_f32_e32 v210, 0, v12
	v_max_f32_e32 v211, 0, v13
	v_pk_fma_f32 v[50:51], v[250:251], v[210:211], v[50:51]
	v_max_f32_e32 v108, 0, v14
	v_max_f32_e32 v109, 0, v15
	v_pk_fma_f32 v[50:51], v[252:253], v[108:109], v[50:51]
	v_max_f32_e32 v210, 0, v16
	v_max_f32_e32 v211, 0, v17
	v_pk_fma_f32 v[50:51], v[254:255], v[210:211], v[50:51]
	s_waitcnt lgkmcnt(1)
	v_mfma_f32_32x32x16_bf16 v[212:227], v[78:81], v[46:49], v[212:227]
	v_max_f32_e32 v108, 0, v18
	v_max_f32_e32 v109, 0, v19
	v_pk_fma_f32 v[50:51], v[200:201], v[108:109], v[50:51]
	v_max_f32_e32 v210, 0, v20
	v_max_f32_e32 v211, 0, v21
	v_pk_fma_f32 v[50:51], v[202:203], v[210:211], v[50:51]
	v_add_f32_e32 v50, v50, v51
	v_ashrrev_i32_e32 v51, 31, v50
	s_waitcnt lgkmcnt(0)
	v_mfma_f32_32x32x16_bf16 v[212:227], v[82:85], v[196:199], v[212:227]
	v_or_b32_e32 v51, 0x80000000, v51
	s_cmpk_gt_i32 s11, 144
	s_cselect_b64 vcc, -1, 0
	v_xor_b32_e32 v50, v51, v50
	v_cndmask_b32_e32 v50, v123, v50, vcc
	global_store_dword v243, v50, s[8:9]
	v_mfma_f32_32x32x16_bf16 v[6:21], v[86:89], v[38:41], 0
	s_add_i32 m0, s10, 65536
	s_nop 0
	global_load_lds_dwordx4 v102, s[6:7]
	s_add_i32 m0, s10, 66560
	s_nop 0
	global_load_lds_dwordx4 v110, s[6:7]
	s_add_i32 m0, s10, 67584
	s_nop 0
	global_load_lds_dwordx4 v112, s[6:7]
	s_add_i32 m0, s10, 68608
	s_nop 0
	global_load_lds_dwordx4 v193, s[6:7]
	s_add_u32 s6, s6, 0x8000
	s_addc_u32 s7, s7, 0
	v_max_f32_e32 v108, 0, v212
	v_max_f32_e32 v109, 0, v213
	v_pk_mul_f32 v[0:1], v[22:23], v[108:109]
	v_max_f32_e32 v210, 0, v214
	v_max_f32_e32 v211, 0, v215
	v_pk_fma_f32 v[0:1], v[24:25], v[210:211], v[0:1]
	v_max_f32_e32 v108, 0, v216
	v_max_f32_e32 v109, 0, v217
	v_pk_fma_f32 v[0:1], v[26:27], v[108:109], v[0:1]
	v_mfma_f32_32x32x16_bf16 v[6:21], v[90:93], v[42:45], v[6:21]
	v_max_f32_e32 v210, 0, v218
	v_max_f32_e32 v211, 0, v219
	v_pk_fma_f32 v[0:1], v[28:29], v[210:211], v[0:1]
	v_max_f32_e32 v108, 0, v220
	v_max_f32_e32 v109, 0, v221
	v_pk_fma_f32 v[0:1], v[30:31], v[108:109], v[0:1]
	v_max_f32_e32 v210, 0, v222
	v_max_f32_e32 v211, 0, v223
	v_pk_fma_f32 v[0:1], v[32:33], v[210:211], v[0:1]
	v_mfma_f32_32x32x16_bf16 v[6:21], v[94:97], v[46:49], v[6:21]
	v_max_f32_e32 v108, 0, v224
	v_max_f32_e32 v109, 0, v225
	v_pk_fma_f32 v[0:1], v[34:35], v[108:109], v[0:1]
	v_max_f32_e32 v210, 0, v226
	v_max_f32_e32 v211, 0, v227
	v_pk_fma_f32 v[0:1], v[36:37], v[210:211], v[0:1]
	v_add_f32_e32 v0, v0, v1
	v_ashrrev_i32_e32 v1, 31, v0
	v_mfma_f32_32x32x16_bf16 v[6:21], v[98:101], v[196:199], v[6:21]
	s_waitcnt vmcnt(10)
	ds_read_b128 v[38:41], v5 offset:10496
	ds_read_b128 v[42:45], v52 offset:10496
	ds_read_b128 v[46:49], v55 offset:10496
	ds_read_b128 v[196:199], v56 offset:10496
	v_or_b32_e32 v1, 0x80000000, v1
	s_cmpk_gt_i32 s11, 152
	s_cselect_b64 vcc, -1, 0
	v_xor_b32_e32 v0, v1, v0
	v_cndmask_b32_e32 v150, v123, v0, vcc
	s_nop 1
	s_waitcnt lgkmcnt(3)
	v_mfma_f32_32x32x16_bf16 v[212:227], v[70:73], v[38:41], 0
	v_max_f32_e32 v108, 0, v6
	v_max_f32_e32 v109, 0, v7
	v_pk_mul_f32 v[50:51], v[244:245], v[108:109]
	v_max_f32_e32 v210, 0, v8
	v_max_f32_e32 v211, 0, v9
	v_pk_fma_f32 v[50:51], v[246:247], v[210:211], v[50:51]
	v_max_f32_e32 v108, 0, v10
	v_max_f32_e32 v109, 0, v11
	v_pk_fma_f32 v[50:51], v[248:249], v[108:109], v[50:51]
	s_waitcnt lgkmcnt(2)
	v_mfma_f32_32x32x16_bf16 v[212:227], v[74:77], v[42:45], v[212:227]
	v_max_f32_e32 v210, 0, v12
	v_max_f32_e32 v211, 0, v13
	v_pk_fma_f32 v[50:51], v[250:251], v[210:211], v[50:51]
	v_max_f32_e32 v108, 0, v14
	v_max_f32_e32 v109, 0, v15
	v_pk_fma_f32 v[50:51], v[252:253], v[108:109], v[50:51]
	v_max_f32_e32 v210, 0, v16
	v_max_f32_e32 v211, 0, v17
	v_pk_fma_f32 v[50:51], v[254:255], v[210:211], v[50:51]
	s_waitcnt lgkmcnt(1)
	v_mfma_f32_32x32x16_bf16 v[212:227], v[78:81], v[46:49], v[212:227]
	v_max_f32_e32 v108, 0, v18
	v_max_f32_e32 v109, 0, v19
	v_pk_fma_f32 v[50:51], v[200:201], v[108:109], v[50:51]
	v_max_f32_e32 v210, 0, v20
	v_max_f32_e32 v211, 0, v21
	v_pk_fma_f32 v[50:51], v[202:203], v[210:211], v[50:51]
	v_add_f32_e32 v50, v50, v51
	v_ashrrev_i32_e32 v51, 31, v50
	s_waitcnt lgkmcnt(0)
	v_mfma_f32_32x32x16_bf16 v[212:227], v[82:85], v[196:199], v[212:227]
	v_or_b32_e32 v51, 0x80000000, v51
	s_cmpk_gt_i32 s11, 152
	s_cselect_b64 vcc, -1, 0
	v_xor_b32_e32 v50, v51, v50
	v_cndmask_b32_e32 v50, v123, v50, vcc
	global_store_dword v243, v50, s[8:9] offset:2048
	s_add_u32 s8, s8, 0x1000
	s_addc_u32 s9, s9, 0
	v_mfma_f32_32x32x16_bf16 v[6:21], v[86:89], v[38:41], 0
	s_add_i32 m0, s10, 98304
	s_nop 0
	global_load_lds_dwordx4 v102, s[6:7]
	s_add_i32 m0, s10, 99328
	s_nop 0
	global_load_lds_dwordx4 v110, s[6:7]
	s_add_i32 m0, s10, 100352
	s_nop 0
	global_load_lds_dwordx4 v112, s[6:7]
	s_add_i32 m0, s10, 101376
	s_nop 0
	global_load_lds_dwordx4 v193, s[6:7]
	s_add_u32 s6, s6, 0x8000
	s_addc_u32 s7, s7, 0
	v_max_f32_e32 v108, 0, v212
	v_max_f32_e32 v109, 0, v213
	v_pk_mul_f32 v[0:1], v[22:23], v[108:109]
	v_max_f32_e32 v210, 0, v214
	v_max_f32_e32 v211, 0, v215
	v_pk_fma_f32 v[0:1], v[24:25], v[210:211], v[0:1]
	v_max_f32_e32 v108, 0, v216
	v_max_f32_e32 v109, 0, v217
	v_pk_fma_f32 v[0:1], v[26:27], v[108:109], v[0:1]
	v_mfma_f32_32x32x16_bf16 v[6:21], v[90:93], v[42:45], v[6:21]
	v_max_f32_e32 v210, 0, v218
	v_max_f32_e32 v211, 0, v219
	v_pk_fma_f32 v[0:1], v[28:29], v[210:211], v[0:1]
	v_max_f32_e32 v108, 0, v220
	v_max_f32_e32 v109, 0, v221
	v_pk_fma_f32 v[0:1], v[30:31], v[108:109], v[0:1]
	v_max_f32_e32 v210, 0, v222
	v_max_f32_e32 v211, 0, v223
	v_pk_fma_f32 v[0:1], v[32:33], v[210:211], v[0:1]
	v_mfma_f32_32x32x16_bf16 v[6:21], v[94:97], v[46:49], v[6:21]
	v_max_f32_e32 v108, 0, v224
	v_max_f32_e32 v109, 0, v225
	v_pk_fma_f32 v[0:1], v[34:35], v[108:109], v[0:1]
	v_max_f32_e32 v210, 0, v226
	v_max_f32_e32 v211, 0, v227
	v_pk_fma_f32 v[0:1], v[36:37], v[210:211], v[0:1]
	v_add_f32_e32 v0, v0, v1
	v_ashrrev_i32_e32 v1, 31, v0
	v_mfma_f32_32x32x16_bf16 v[6:21], v[98:101], v[196:199], v[6:21]
	s_waitcnt vmcnt(10)
	ds_read_b128 v[38:41], v5 offset:43264
	ds_read_b128 v[42:45], v52 offset:43264
	ds_read_b128 v[46:49], v55 offset:43264
	ds_read_b128 v[196:199], v56 offset:43264
	v_or_b32_e32 v1, 0x80000000, v1
	s_cmpk_gt_i32 s11, 160
	s_cselect_b64 vcc, -1, 0
	v_xor_b32_e32 v0, v1, v0
	v_cndmask_b32_e32 v154, v123, v0, vcc
	s_nop 1
	s_waitcnt lgkmcnt(3)
	v_mfma_f32_32x32x16_bf16 v[212:227], v[70:73], v[38:41], 0
	v_max_f32_e32 v108, 0, v6
	v_max_f32_e32 v109, 0, v7
	v_pk_mul_f32 v[50:51], v[244:245], v[108:109]
	v_max_f32_e32 v210, 0, v8
	v_max_f32_e32 v211, 0, v9
	v_pk_fma_f32 v[50:51], v[246:247], v[210:211], v[50:51]
	v_max_f32_e32 v108, 0, v10
	v_max_f32_e32 v109, 0, v11
	v_pk_fma_f32 v[50:51], v[248:249], v[108:109], v[50:51]
	s_waitcnt lgkmcnt(2)
	v_mfma_f32_32x32x16_bf16 v[212:227], v[74:77], v[42:45], v[212:227]
	v_max_f32_e32 v210, 0, v12
	v_max_f32_e32 v211, 0, v13
	v_pk_fma_f32 v[50:51], v[250:251], v[210:211], v[50:51]
	v_max_f32_e32 v108, 0, v14
	v_max_f32_e32 v109, 0, v15
	v_pk_fma_f32 v[50:51], v[252:253], v[108:109], v[50:51]
	v_max_f32_e32 v210, 0, v16
	v_max_f32_e32 v211, 0, v17
	v_pk_fma_f32 v[50:51], v[254:255], v[210:211], v[50:51]
	s_waitcnt lgkmcnt(1)
	v_mfma_f32_32x32x16_bf16 v[212:227], v[78:81], v[46:49], v[212:227]
	v_max_f32_e32 v108, 0, v18
	v_max_f32_e32 v109, 0, v19
	v_pk_fma_f32 v[50:51], v[200:201], v[108:109], v[50:51]
	v_max_f32_e32 v210, 0, v20
	v_max_f32_e32 v211, 0, v21
	v_pk_fma_f32 v[50:51], v[202:203], v[210:211], v[50:51]
	v_add_f32_e32 v50, v50, v51
	v_ashrrev_i32_e32 v51, 31, v50
	s_waitcnt lgkmcnt(0)
	v_mfma_f32_32x32x16_bf16 v[212:227], v[82:85], v[196:199], v[212:227]
	v_or_b32_e32 v51, 0x80000000, v51
	s_cmpk_gt_i32 s11, 160
	s_cselect_b64 vcc, -1, 0
	v_xor_b32_e32 v50, v51, v50
	v_cndmask_b32_e32 v50, v123, v50, vcc
	global_store_dword v243, v50, s[8:9]
	v_mfma_f32_32x32x16_bf16 v[6:21], v[86:89], v[38:41], 0
	s_add_i32 m0, s10, 0
	s_nop 0
	global_load_lds_dwordx4 v102, s[6:7]
	s_add_i32 m0, s10, 1024
	s_nop 0
	global_load_lds_dwordx4 v110, s[6:7]
	s_add_i32 m0, s10, 2048
	s_nop 0
	global_load_lds_dwordx4 v112, s[6:7]
	s_add_i32 m0, s10, 3072
	s_nop 0
	global_load_lds_dwordx4 v193, s[6:7]
	s_add_u32 s6, s6, 0x8000
	s_addc_u32 s7, s7, 0
	v_max_f32_e32 v108, 0, v212
	v_max_f32_e32 v109, 0, v213
	v_pk_mul_f32 v[0:1], v[22:23], v[108:109]
	v_max_f32_e32 v210, 0, v214
	v_max_f32_e32 v211, 0, v215
	v_pk_fma_f32 v[0:1], v[24:25], v[210:211], v[0:1]
	v_max_f32_e32 v108, 0, v216
	v_max_f32_e32 v109, 0, v217
	v_pk_fma_f32 v[0:1], v[26:27], v[108:109], v[0:1]
	v_mfma_f32_32x32x16_bf16 v[6:21], v[90:93], v[42:45], v[6:21]
	v_max_f32_e32 v210, 0, v218
	v_max_f32_e32 v211, 0, v219
	v_pk_fma_f32 v[0:1], v[28:29], v[210:211], v[0:1]
	v_max_f32_e32 v108, 0, v220
	v_max_f32_e32 v109, 0, v221
	v_pk_fma_f32 v[0:1], v[30:31], v[108:109], v[0:1]
	v_max_f32_e32 v210, 0, v222
	v_max_f32_e32 v211, 0, v223
	v_pk_fma_f32 v[0:1], v[32:33], v[210:211], v[0:1]
	v_mfma_f32_32x32x16_bf16 v[6:21], v[94:97], v[46:49], v[6:21]
	v_max_f32_e32 v108, 0, v224
	v_max_f32_e32 v109, 0, v225
	v_pk_fma_f32 v[0:1], v[34:35], v[108:109], v[0:1]
	v_max_f32_e32 v210, 0, v226
	v_max_f32_e32 v211, 0, v227
	v_pk_fma_f32 v[0:1], v[36:37], v[210:211], v[0:1]
	v_add_f32_e32 v0, v0, v1
	v_ashrrev_i32_e32 v1, 31, v0
	v_mfma_f32_32x32x16_bf16 v[6:21], v[98:101], v[196:199], v[6:21]
	s_waitcnt vmcnt(10)
	v_add_u32_e32 v228, 0x10000, v5
	ds_read_b128 v[38:41], v228 offset:10496
	v_add_u32_e32 v228, 0x10000, v52
	ds_read_b128 v[42:45], v228 offset:10496
	v_add_u32_e32 v228, 0x10000, v55
	ds_read_b128 v[46:49], v228 offset:10496
	v_add_u32_e32 v228, 0x10000, v56
	ds_read_b128 v[196:199], v228 offset:10496
	v_or_b32_e32 v1, 0x80000000, v1
	s_cmpk_gt_i32 s11, 168
	s_cselect_b64 vcc, -1, 0
	v_xor_b32_e32 v0, v1, v0
	v_cndmask_b32_e32 v153, v123, v0, vcc
	s_nop 1
	s_waitcnt lgkmcnt(3)
	v_mfma_f32_32x32x16_bf16 v[212:227], v[70:73], v[38:41], 0
	v_max_f32_e32 v108, 0, v6
	v_max_f32_e32 v109, 0, v7
	v_pk_mul_f32 v[50:51], v[244:245], v[108:109]
	v_max_f32_e32 v210, 0, v8
	v_max_f32_e32 v211, 0, v9
	v_pk_fma_f32 v[50:51], v[246:247], v[210:211], v[50:51]
	v_max_f32_e32 v108, 0, v10
	v_max_f32_e32 v109, 0, v11
	v_pk_fma_f32 v[50:51], v[248:249], v[108:109], v[50:51]
	s_waitcnt lgkmcnt(2)
	v_mfma_f32_32x32x16_bf16 v[212:227], v[74:77], v[42:45], v[212:227]
	v_max_f32_e32 v210, 0, v12
	v_max_f32_e32 v211, 0, v13
	v_pk_fma_f32 v[50:51], v[250:251], v[210:211], v[50:51]
	v_max_f32_e32 v108, 0, v14
	v_max_f32_e32 v109, 0, v15
	v_pk_fma_f32 v[50:51], v[252:253], v[108:109], v[50:51]
	v_max_f32_e32 v210, 0, v16
	v_max_f32_e32 v211, 0, v17
	v_pk_fma_f32 v[50:51], v[254:255], v[210:211], v[50:51]
	s_waitcnt lgkmcnt(1)
	v_mfma_f32_32x32x16_bf16 v[212:227], v[78:81], v[46:49], v[212:227]
	v_max_f32_e32 v108, 0, v18
	v_max_f32_e32 v109, 0, v19
	v_pk_fma_f32 v[50:51], v[200:201], v[108:109], v[50:51]
	v_max_f32_e32 v210, 0, v20
	v_max_f32_e32 v211, 0, v21
	v_pk_fma_f32 v[50:51], v[202:203], v[210:211], v[50:51]
	v_add_f32_e32 v50, v50, v51
	v_ashrrev_i32_e32 v51, 31, v50
	s_waitcnt lgkmcnt(0)
	v_mfma_f32_32x32x16_bf16 v[212:227], v[82:85], v[196:199], v[212:227]
	v_or_b32_e32 v51, 0x80000000, v51
	s_cmpk_gt_i32 s11, 168
	s_cselect_b64 vcc, -1, 0
	v_xor_b32_e32 v50, v51, v50
	v_cndmask_b32_e32 v50, v123, v50, vcc
	global_store_dword v243, v50, s[8:9] offset:2048
	s_add_u32 s8, s8, 0x1000
	s_addc_u32 s9, s9, 0
	v_mfma_f32_32x32x16_bf16 v[6:21], v[86:89], v[38:41], 0
	s_add_i32 m0, s10, 32768
	s_nop 0
	global_load_lds_dwordx4 v102, s[6:7]
	s_add_i32 m0, s10, 33792
	s_nop 0
	global_load_lds_dwordx4 v110, s[6:7]
	s_add_i32 m0, s10, 34816
	s_nop 0
	global_load_lds_dwordx4 v112, s[6:7]
	s_add_i32 m0, s10, 35840
	s_nop 0
	global_load_lds_dwordx4 v193, s[6:7]
	s_add_u32 s6, s6, 0x8000
	s_addc_u32 s7, s7, 0
	v_max_f32_e32 v108, 0, v212
	v_max_f32_e32 v109, 0, v213
	v_pk_mul_f32 v[0:1], v[22:23], v[108:109]
	v_max_f32_e32 v210, 0, v214
	v_max_f32_e32 v211, 0, v215
	v_pk_fma_f32 v[0:1], v[24:25], v[210:211], v[0:1]
	v_max_f32_e32 v108, 0, v216
	v_max_f32_e32 v109, 0, v217
	v_pk_fma_f32 v[0:1], v[26:27], v[108:109], v[0:1]
	v_mfma_f32_32x32x16_bf16 v[6:21], v[90:93], v[42:45], v[6:21]
	v_max_f32_e32 v210, 0, v218
	v_max_f32_e32 v211, 0, v219
	v_pk_fma_f32 v[0:1], v[28:29], v[210:211], v[0:1]
	v_max_f32_e32 v108, 0, v220
	v_max_f32_e32 v109, 0, v221
	v_pk_fma_f32 v[0:1], v[30:31], v[108:109], v[0:1]
	v_max_f32_e32 v210, 0, v222
	v_max_f32_e32 v211, 0, v223
	v_pk_fma_f32 v[0:1], v[32:33], v[210:211], v[0:1]
	v_mfma_f32_32x32x16_bf16 v[6:21], v[94:97], v[46:49], v[6:21]
	v_max_f32_e32 v108, 0, v224
	v_max_f32_e32 v109, 0, v225
	v_pk_fma_f32 v[0:1], v[34:35], v[108:109], v[0:1]
	v_max_f32_e32 v210, 0, v226
	v_max_f32_e32 v211, 0, v227
	v_pk_fma_f32 v[0:1], v[36:37], v[210:211], v[0:1]
	v_add_f32_e32 v0, v0, v1
	v_ashrrev_i32_e32 v1, 31, v0
	v_mfma_f32_32x32x16_bf16 v[6:21], v[98:101], v[196:199], v[6:21]
	s_waitcnt vmcnt(10)
	v_add_u32_e32 v228, 0x10000, v5
	ds_read_b128 v[38:41], v228 offset:43264
	v_add_u32_e32 v228, 0x10000, v52
	ds_read_b128 v[42:45], v228 offset:43264
	v_add_u32_e32 v228, 0x10000, v55
	ds_read_b128 v[46:49], v228 offset:43264
	v_add_u32_e32 v228, 0x10000, v56
	ds_read_b128 v[196:199], v228 offset:43264
	v_or_b32_e32 v1, 0x80000000, v1
	s_cmpk_gt_i32 s11, 176
	s_cselect_b64 vcc, -1, 0
	v_xor_b32_e32 v0, v1, v0
	v_cndmask_b32_e32 v156, v123, v0, vcc
	s_nop 1
	s_waitcnt lgkmcnt(3)
	v_mfma_f32_32x32x16_bf16 v[212:227], v[70:73], v[38:41], 0
	v_max_f32_e32 v108, 0, v6
	v_max_f32_e32 v109, 0, v7
	v_pk_mul_f32 v[50:51], v[244:245], v[108:109]
	v_max_f32_e32 v210, 0, v8
	v_max_f32_e32 v211, 0, v9
	v_pk_fma_f32 v[50:51], v[246:247], v[210:211], v[50:51]
	v_max_f32_e32 v108, 0, v10
	v_max_f32_e32 v109, 0, v11
	v_pk_fma_f32 v[50:51], v[248:249], v[108:109], v[50:51]
	s_waitcnt lgkmcnt(2)
	v_mfma_f32_32x32x16_bf16 v[212:227], v[74:77], v[42:45], v[212:227]
	v_max_f32_e32 v210, 0, v12
	v_max_f32_e32 v211, 0, v13
	v_pk_fma_f32 v[50:51], v[250:251], v[210:211], v[50:51]
	v_max_f32_e32 v108, 0, v14
	v_max_f32_e32 v109, 0, v15
	v_pk_fma_f32 v[50:51], v[252:253], v[108:109], v[50:51]
	v_max_f32_e32 v210, 0, v16
	v_max_f32_e32 v211, 0, v17
	v_pk_fma_f32 v[50:51], v[254:255], v[210:211], v[50:51]
	s_waitcnt lgkmcnt(1)
	v_mfma_f32_32x32x16_bf16 v[212:227], v[78:81], v[46:49], v[212:227]
	v_max_f32_e32 v108, 0, v18
	v_max_f32_e32 v109, 0, v19
	v_pk_fma_f32 v[50:51], v[200:201], v[108:109], v[50:51]
	v_max_f32_e32 v210, 0, v20
	v_max_f32_e32 v211, 0, v21
	v_pk_fma_f32 v[50:51], v[202:203], v[210:211], v[50:51]
	v_add_f32_e32 v50, v50, v51
	v_ashrrev_i32_e32 v51, 31, v50
	s_waitcnt lgkmcnt(0)
	v_mfma_f32_32x32x16_bf16 v[212:227], v[82:85], v[196:199], v[212:227]
	v_or_b32_e32 v51, 0x80000000, v51
	s_cmpk_gt_i32 s11, 176
	s_cselect_b64 vcc, -1, 0
	v_xor_b32_e32 v50, v51, v50
	v_cndmask_b32_e32 v50, v123, v50, vcc
	global_store_dword v243, v50, s[8:9]
	v_mfma_f32_32x32x16_bf16 v[6:21], v[86:89], v[38:41], 0
	s_add_i32 m0, s10, 65536
	s_nop 0
	global_load_lds_dwordx4 v102, s[6:7]
	s_add_i32 m0, s10, 66560
	s_nop 0
	global_load_lds_dwordx4 v110, s[6:7]
	s_add_i32 m0, s10, 67584
	s_nop 0
	global_load_lds_dwordx4 v112, s[6:7]
	s_add_i32 m0, s10, 68608
	s_nop 0
	global_load_lds_dwordx4 v193, s[6:7]
	s_add_u32 s6, s6, 0x8000
	s_addc_u32 s7, s7, 0
	v_max_f32_e32 v108, 0, v212
	v_max_f32_e32 v109, 0, v213
	v_pk_mul_f32 v[0:1], v[22:23], v[108:109]
	v_max_f32_e32 v210, 0, v214
	v_max_f32_e32 v211, 0, v215
	v_pk_fma_f32 v[0:1], v[24:25], v[210:211], v[0:1]
	v_max_f32_e32 v108, 0, v216
	v_max_f32_e32 v109, 0, v217
	v_pk_fma_f32 v[0:1], v[26:27], v[108:109], v[0:1]
	v_mfma_f32_32x32x16_bf16 v[6:21], v[90:93], v[42:45], v[6:21]
	v_max_f32_e32 v210, 0, v218
	v_max_f32_e32 v211, 0, v219
	v_pk_fma_f32 v[0:1], v[28:29], v[210:211], v[0:1]
	v_max_f32_e32 v108, 0, v220
	v_max_f32_e32 v109, 0, v221
	v_pk_fma_f32 v[0:1], v[30:31], v[108:109], v[0:1]
	v_max_f32_e32 v210, 0, v222
	v_max_f32_e32 v211, 0, v223
	v_pk_fma_f32 v[0:1], v[32:33], v[210:211], v[0:1]
	v_mfma_f32_32x32x16_bf16 v[6:21], v[94:97], v[46:49], v[6:21]
	v_max_f32_e32 v108, 0, v224
	v_max_f32_e32 v109, 0, v225
	v_pk_fma_f32 v[0:1], v[34:35], v[108:109], v[0:1]
	v_max_f32_e32 v210, 0, v226
	v_max_f32_e32 v211, 0, v227
	v_pk_fma_f32 v[0:1], v[36:37], v[210:211], v[0:1]
	v_add_f32_e32 v0, v0, v1
	v_ashrrev_i32_e32 v1, 31, v0
	v_mfma_f32_32x32x16_bf16 v[6:21], v[98:101], v[196:199], v[6:21]
	s_waitcnt vmcnt(10)
	ds_read_b128 v[38:41], v5 offset:10496
	ds_read_b128 v[42:45], v52 offset:10496
	ds_read_b128 v[46:49], v55 offset:10496
	ds_read_b128 v[196:199], v56 offset:10496
	v_or_b32_e32 v1, 0x80000000, v1
	s_cmpk_gt_i32 s11, 184
	s_cselect_b64 vcc, -1, 0
	v_xor_b32_e32 v0, v1, v0
	v_cndmask_b32_e32 v155, v123, v0, vcc
	s_nop 1
	v_max_f32_e32 v108, 0, v6
	v_max_f32_e32 v109, 0, v7
	v_pk_mul_f32 v[50:51], v[244:245], v[108:109]
	v_max_f32_e32 v210, 0, v8
	v_max_f32_e32 v211, 0, v9
	v_pk_fma_f32 v[50:51], v[246:247], v[210:211], v[50:51]
	v_max_f32_e32 v108, 0, v10
	v_max_f32_e32 v109, 0, v11
	v_pk_fma_f32 v[50:51], v[248:249], v[108:109], v[50:51]
	v_max_f32_e32 v210, 0, v12
	v_max_f32_e32 v211, 0, v13
	v_pk_fma_f32 v[50:51], v[250:251], v[210:211], v[50:51]
	v_max_f32_e32 v108, 0, v14
	v_max_f32_e32 v109, 0, v15
	v_pk_fma_f32 v[50:51], v[252:253], v[108:109], v[50:51]
	v_max_f32_e32 v210, 0, v16
	v_max_f32_e32 v211, 0, v17
	v_pk_fma_f32 v[50:51], v[254:255], v[210:211], v[50:51]
	v_max_f32_e32 v108, 0, v18
	v_max_f32_e32 v109, 0, v19
	v_pk_fma_f32 v[50:51], v[200:201], v[108:109], v[50:51]
	v_max_f32_e32 v210, 0, v20
	v_max_f32_e32 v211, 0, v21
	v_pk_fma_f32 v[50:51], v[202:203], v[210:211], v[50:51]
	v_add_f32_e32 v50, v50, v51
	v_ashrrev_i32_e32 v51, 31, v50
	v_or_b32_e32 v51, 0x80000000, v51
	s_cmpk_gt_i32 s11, 184
	s_cselect_b64 vcc, -1, 0
	v_xor_b32_e32 v50, v51, v50
	v_cndmask_b32_e32 v50, v123, v50, vcc
	global_store_dword v243, v50, s[8:9] offset:2048
	s_add_u32 s8, s8, 0x1000
	s_addc_u32 s9, s9, 0
	s_cmpk_gt_i32 s81, 24
	s_cbranch_scc0 .Lix_fill_3
	s_waitcnt lgkmcnt(3)
	v_mfma_f32_32x32x16_bf16 v[212:227], v[70:73], v[38:41], 0
	s_add_i32 m0, s10, 98304
	s_nop 0
	global_load_lds_dwordx4 v102, s[6:7]
	s_waitcnt lgkmcnt(2)
	v_mfma_f32_32x32x16_bf16 v[212:227], v[74:77], v[42:45], v[212:227]
	s_add_i32 m0, s10, 99328
	s_nop 0
	global_load_lds_dwordx4 v110, s[6:7]
	s_waitcnt lgkmcnt(1)
	v_mfma_f32_32x32x16_bf16 v[212:227], v[78:81], v[46:49], v[212:227]
	s_add_i32 m0, s10, 100352
	s_nop 0
	global_load_lds_dwordx4 v112, s[6:7]
	s_waitcnt lgkmcnt(0)
	v_mfma_f32_32x32x16_bf16 v[212:227], v[82:85], v[196:199], v[212:227]
	s_add_i32 m0, s10, 101376
	s_nop 0
	global_load_lds_dwordx4 v193, s[6:7]
	s_add_u32 s6, s6, 0x8000
	s_addc_u32 s7, s7, 0
	v_mfma_f32_32x32x16_bf16 v[6:21], v[86:89], v[38:41], 0
	s_nop 7
	s_nop 2
	v_max_f32_e32 v108, 0, v212
	v_max_f32_e32 v109, 0, v213
	v_pk_mul_f32 v[0:1], v[22:23], v[108:109]
	v_max_f32_e32 v210, 0, v214
	v_max_f32_e32 v211, 0, v215
	v_pk_fma_f32 v[0:1], v[24:25], v[210:211], v[0:1]
	v_max_f32_e32 v108, 0, v216
	v_max_f32_e32 v109, 0, v217
	v_pk_fma_f32 v[0:1], v[26:27], v[108:109], v[0:1]
	v_mfma_f32_32x32x16_bf16 v[6:21], v[90:93], v[42:45], v[6:21]
	v_max_f32_e32 v210, 0, v218
	v_max_f32_e32 v211, 0, v219
	v_pk_fma_f32 v[0:1], v[28:29], v[210:211], v[0:1]
	v_max_f32_e32 v108, 0, v220
	v_max_f32_e32 v109, 0, v221
	v_pk_fma_f32 v[0:1], v[30:31], v[108:109], v[0:1]
	v_max_f32_e32 v210, 0, v222
	v_max_f32_e32 v211, 0, v223
	v_pk_fma_f32 v[0:1], v[32:33], v[210:211], v[0:1]
	v_mfma_f32_32x32x16_bf16 v[6:21], v[94:97], v[46:49], v[6:21]
	v_max_f32_e32 v108, 0, v224
	v_max_f32_e32 v109, 0, v225
	v_pk_fma_f32 v[0:1], v[34:35], v[108:109], v[0:1]
	v_max_f32_e32 v210, 0, v226
	v_max_f32_e32 v211, 0, v227
	v_pk_fma_f32 v[0:1], v[36:37], v[210:211], v[0:1]
	v_add_f32_e32 v0, v0, v1
	v_ashrrev_i32_e32 v1, 31, v0
	v_mfma_f32_32x32x16_bf16 v[6:21], v[98:101], v[196:199], v[6:21]
	s_waitcnt vmcnt(10)
	ds_read_b128 v[38:41], v5 offset:43264
	ds_read_b128 v[42:45], v52 offset:43264
	ds_read_b128 v[46:49], v55 offset:43264
	ds_read_b128 v[196:199], v56 offset:43264
	v_or_b32_e32 v1, 0x80000000, v1
	s_cmpk_gt_i32 s11, 192
	s_cselect_b64 vcc, -1, 0
	v_xor_b32_e32 v0, v1, v0
	v_cndmask_b32_e32 v158, v123, v0, vcc
	s_nop 1
	s_waitcnt lgkmcnt(3)
	v_mfma_f32_32x32x16_bf16 v[212:227], v[70:73], v[38:41], 0
	v_max_f32_e32 v108, 0, v6
	v_max_f32_e32 v109, 0, v7
	v_pk_mul_f32 v[50:51], v[244:245], v[108:109]
	v_max_f32_e32 v210, 0, v8
	v_max_f32_e32 v211, 0, v9
	v_pk_fma_f32 v[50:51], v[246:247], v[210:211], v[50:51]
	v_max_f32_e32 v108, 0, v10
	v_max_f32_e32 v109, 0, v11
	v_pk_fma_f32 v[50:51], v[248:249], v[108:109], v[50:51]
	s_waitcnt lgkmcnt(2)
	v_mfma_f32_32x32x16_bf16 v[212:227], v[74:77], v[42:45], v[212:227]
	v_max_f32_e32 v210, 0, v12
	v_max_f32_e32 v211, 0, v13
	v_pk_fma_f32 v[50:51], v[250:251], v[210:211], v[50:51]
	v_max_f32_e32 v108, 0, v14
	v_max_f32_e32 v109, 0, v15
	v_pk_fma_f32 v[50:51], v[252:253], v[108:109], v[50:51]
	v_max_f32_e32 v210, 0, v16
	v_max_f32_e32 v211, 0, v17
	v_pk_fma_f32 v[50:51], v[254:255], v[210:211], v[50:51]
	s_waitcnt lgkmcnt(1)
	v_mfma_f32_32x32x16_bf16 v[212:227], v[78:81], v[46:49], v[212:227]
	v_max_f32_e32 v108, 0, v18
	v_max_f32_e32 v109, 0, v19
	v_pk_fma_f32 v[50:51], v[200:201], v[108:109], v[50:51]
	v_max_f32_e32 v210, 0, v20
	v_max_f32_e32 v211, 0, v21
	v_pk_fma_f32 v[50:51], v[202:203], v[210:211], v[50:51]
	v_add_f32_e32 v50, v50, v51
	v_ashrrev_i32_e32 v51, 31, v50
	s_waitcnt lgkmcnt(0)
	v_mfma_f32_32x32x16_bf16 v[212:227], v[82:85], v[196:199], v[212:227]
	v_or_b32_e32 v51, 0x80000000, v51
	s_cmpk_gt_i32 s11, 192
	s_cselect_b64 vcc, -1, 0
	v_xor_b32_e32 v50, v51, v50
	v_cndmask_b32_e32 v50, v123, v50, vcc
	global_store_dword v243, v50, s[8:9]
	v_mfma_f32_32x32x16_bf16 v[6:21], v[86:89], v[38:41], 0
	s_add_i32 m0, s10, 0
	s_nop 0
	global_load_lds_dwordx4 v102, s[6:7]
	s_add_i32 m0, s10, 1024
	s_nop 0
	global_load_lds_dwordx4 v110, s[6:7]
	s_add_i32 m0, s10, 2048
	s_nop 0
	global_load_lds_dwordx4 v112, s[6:7]
	s_add_i32 m0, s10, 3072
	s_nop 0
	global_load_lds_dwordx4 v193, s[6:7]
	s_add_u32 s6, s6, 0x8000
	s_addc_u32 s7, s7, 0
	v_max_f32_e32 v108, 0, v212
	v_max_f32_e32 v109, 0, v213
	v_pk_mul_f32 v[0:1], v[22:23], v[108:109]
	v_max_f32_e32 v210, 0, v214
	v_max_f32_e32 v211, 0, v215
	v_pk_fma_f32 v[0:1], v[24:25], v[210:211], v[0:1]
	v_max_f32_e32 v108, 0, v216
	v_max_f32_e32 v109, 0, v217
	v_pk_fma_f32 v[0:1], v[26:27], v[108:109], v[0:1]
	v_mfma_f32_32x32x16_bf16 v[6:21], v[90:93], v[42:45], v[6:21]
	v_max_f32_e32 v210, 0, v218
	v_max_f32_e32 v211, 0, v219
	v_pk_fma_f32 v[0:1], v[28:29], v[210:211], v[0:1]
	v_max_f32_e32 v108, 0, v220
	v_max_f32_e32 v109, 0, v221
	v_pk_fma_f32 v[0:1], v[30:31], v[108:109], v[0:1]
	v_max_f32_e32 v210, 0, v222
	v_max_f32_e32 v211, 0, v223
	v_pk_fma_f32 v[0:1], v[32:33], v[210:211], v[0:1]
	v_mfma_f32_32x32x16_bf16 v[6:21], v[94:97], v[46:49], v[6:21]
	v_max_f32_e32 v108, 0, v224
	v_max_f32_e32 v109, 0, v225
	v_pk_fma_f32 v[0:1], v[34:35], v[108:109], v[0:1]
	v_max_f32_e32 v210, 0, v226
	v_max_f32_e32 v211, 0, v227
	v_pk_fma_f32 v[0:1], v[36:37], v[210:211], v[0:1]
	v_add_f32_e32 v0, v0, v1
	v_ashrrev_i32_e32 v1, 31, v0
	v_mfma_f32_32x32x16_bf16 v[6:21], v[98:101], v[196:199], v[6:21]
	s_waitcnt vmcnt(10)
	v_add_u32_e32 v228, 0x10000, v5
	ds_read_b128 v[38:41], v228 offset:10496
	v_add_u32_e32 v228, 0x10000, v52
	ds_read_b128 v[42:45], v228 offset:10496
	v_add_u32_e32 v228, 0x10000, v55
	ds_read_b128 v[46:49], v228 offset:10496
	v_add_u32_e32 v228, 0x10000, v56
	ds_read_b128 v[196:199], v228 offset:10496
	v_or_b32_e32 v1, 0x80000000, v1
	s_cmpk_gt_i32 s11, 200
	s_cselect_b64 vcc, -1, 0
	v_xor_b32_e32 v0, v1, v0
	v_cndmask_b32_e32 v157, v123, v0, vcc
	s_nop 1
	s_waitcnt lgkmcnt(3)
	v_mfma_f32_32x32x16_bf16 v[212:227], v[70:73], v[38:41], 0
	v_max_f32_e32 v108, 0, v6
	v_max_f32_e32 v109, 0, v7
	v_pk_mul_f32 v[50:51], v[244:245], v[108:109]
	v_max_f32_e32 v210, 0, v8
	v_max_f32_e32 v211, 0, v9
	v_pk_fma_f32 v[50:51], v[246:247], v[210:211], v[50:51]
	v_max_f32_e32 v108, 0, v10
	v_max_f32_e32 v109, 0, v11
	v_pk_fma_f32 v[50:51], v[248:249], v[108:109], v[50:51]
	s_waitcnt lgkmcnt(2)
	v_mfma_f32_32x32x16_bf16 v[212:227], v[74:77], v[42:45], v[212:227]
	v_max_f32_e32 v210, 0, v12
	v_max_f32_e32 v211, 0, v13
	v_pk_fma_f32 v[50:51], v[250:251], v[210:211], v[50:51]
	v_max_f32_e32 v108, 0, v14
	v_max_f32_e32 v109, 0, v15
	v_pk_fma_f32 v[50:51], v[252:253], v[108:109], v[50:51]
	v_max_f32_e32 v210, 0, v16
	v_max_f32_e32 v211, 0, v17
	v_pk_fma_f32 v[50:51], v[254:255], v[210:211], v[50:51]
	s_waitcnt lgkmcnt(1)
	v_mfma_f32_32x32x16_bf16 v[212:227], v[78:81], v[46:49], v[212:227]
	v_max_f32_e32 v108, 0, v18
	v_max_f32_e32 v109, 0, v19
	v_pk_fma_f32 v[50:51], v[200:201], v[108:109], v[50:51]
	v_max_f32_e32 v210, 0, v20
	v_max_f32_e32 v211, 0, v21
	v_pk_fma_f32 v[50:51], v[202:203], v[210:211], v[50:51]
	v_add_f32_e32 v50, v50, v51
	v_ashrrev_i32_e32 v51, 31, v50
	s_waitcnt lgkmcnt(0)
	v_mfma_f32_32x32x16_bf16 v[212:227], v[82:85], v[196:199], v[212:227]
	v_or_b32_e32 v51, 0x80000000, v51
	s_cmpk_gt_i32 s11, 200
	s_cselect_b64 vcc, -1, 0
	v_xor_b32_e32 v50, v51, v50
	v_cndmask_b32_e32 v50, v123, v50, vcc
	global_store_dword v243, v50, s[8:9] offset:2048
	s_add_u32 s8, s8, 0x1000
	s_addc_u32 s9, s9, 0
	v_mfma_f32_32x32x16_bf16 v[6:21], v[86:89], v[38:41], 0
	s_add_i32 m0, s10, 32768
	s_nop 0
	global_load_lds_dwordx4 v102, s[6:7]
	s_add_i32 m0, s10, 33792
	s_nop 0
	global_load_lds_dwordx4 v110, s[6:7]
	s_add_i32 m0, s10, 34816
	s_nop 0
	global_load_lds_dwordx4 v112, s[6:7]
	s_add_i32 m0, s10, 35840
	s_nop 0
	global_load_lds_dwordx4 v193, s[6:7]
	s_add_u32 s6, s6, 0x8000
	s_addc_u32 s7, s7, 0
	v_max_f32_e32 v108, 0, v212
	v_max_f32_e32 v109, 0, v213
	v_pk_mul_f32 v[0:1], v[22:23], v[108:109]
	v_max_f32_e32 v210, 0, v214
	v_max_f32_e32 v211, 0, v215
	v_pk_fma_f32 v[0:1], v[24:25], v[210:211], v[0:1]
	v_max_f32_e32 v108, 0, v216
	v_max_f32_e32 v109, 0, v217
	v_pk_fma_f32 v[0:1], v[26:27], v[108:109], v[0:1]
	v_mfma_f32_32x32x16_bf16 v[6:21], v[90:93], v[42:45], v[6:21]
	v_max_f32_e32 v210, 0, v218
	v_max_f32_e32 v211, 0, v219
	v_pk_fma_f32 v[0:1], v[28:29], v[210:211], v[0:1]
	v_max_f32_e32 v108, 0, v220
	v_max_f32_e32 v109, 0, v221
	v_pk_fma_f32 v[0:1], v[30:31], v[108:109], v[0:1]
	v_max_f32_e32 v210, 0, v222
	v_max_f32_e32 v211, 0, v223
	v_pk_fma_f32 v[0:1], v[32:33], v[210:211], v[0:1]
	v_mfma_f32_32x32x16_bf16 v[6:21], v[94:97], v[46:49], v[6:21]
	v_max_f32_e32 v108, 0, v224
	v_max_f32_e32 v109, 0, v225
	v_pk_fma_f32 v[0:1], v[34:35], v[108:109], v[0:1]
	v_max_f32_e32 v210, 0, v226
	v_max_f32_e32 v211, 0, v227
	v_pk_fma_f32 v[0:1], v[36:37], v[210:211], v[0:1]
	v_add_f32_e32 v0, v0, v1
	v_ashrrev_i32_e32 v1, 31, v0
	v_mfma_f32_32x32x16_bf16 v[6:21], v[98:101], v[196:199], v[6:21]
	s_waitcnt vmcnt(10)
	v_add_u32_e32 v228, 0x10000, v5
	ds_read_b128 v[38:41], v228 offset:43264
	v_add_u32_e32 v228, 0x10000, v52
	ds_read_b128 v[42:45], v228 offset:43264
	v_add_u32_e32 v228, 0x10000, v55
	ds_read_b128 v[46:49], v228 offset:43264
	v_add_u32_e32 v228, 0x10000, v56
	ds_read_b128 v[196:199], v228 offset:43264
	v_or_b32_e32 v1, 0x80000000, v1
	s_cmpk_gt_i32 s11, 208
	s_cselect_b64 vcc, -1, 0
	v_xor_b32_e32 v0, v1, v0
	v_cndmask_b32_e32 v160, v123, v0, vcc
	s_nop 1
	s_waitcnt lgkmcnt(3)
	v_mfma_f32_32x32x16_bf16 v[212:227], v[70:73], v[38:41], 0
	v_max_f32_e32 v108, 0, v6
	v_max_f32_e32 v109, 0, v7
	v_pk_mul_f32 v[50:51], v[244:245], v[108:109]
	v_max_f32_e32 v210, 0, v8
	v_max_f32_e32 v211, 0, v9
	v_pk_fma_f32 v[50:51], v[246:247], v[210:211], v[50:51]
	v_max_f32_e32 v108, 0, v10
	v_max_f32_e32 v109, 0, v11
	v_pk_fma_f32 v[50:51], v[248:249], v[108:109], v[50:51]
	s_waitcnt lgkmcnt(2)
	v_mfma_f32_32x32x16_bf16 v[212:227], v[74:77], v[42:45], v[212:227]
	v_max_f32_e32 v210, 0, v12
	v_max_f32_e32 v211, 0, v13
	v_pk_fma_f32 v[50:51], v[250:251], v[210:211], v[50:51]
	v_max_f32_e32 v108, 0, v14
	v_max_f32_e32 v109, 0, v15
	v_pk_fma_f32 v[50:51], v[252:253], v[108:109], v[50:51]
	v_max_f32_e32 v210, 0, v16
	v_max_f32_e32 v211, 0, v17
	v_pk_fma_f32 v[50:51], v[254:255], v[210:211], v[50:51]
	s_waitcnt lgkmcnt(1)
	v_mfma_f32_32x32x16_bf16 v[212:227], v[78:81], v[46:49], v[212:227]
	v_max_f32_e32 v108, 0, v18
	v_max_f32_e32 v109, 0, v19
	v_pk_fma_f32 v[50:51], v[200:201], v[108:109], v[50:51]
	v_max_f32_e32 v210, 0, v20
	v_max_f32_e32 v211, 0, v21
	v_pk_fma_f32 v[50:51], v[202:203], v[210:211], v[50:51]
	v_add_f32_e32 v50, v50, v51
	v_ashrrev_i32_e32 v51, 31, v50
	s_waitcnt lgkmcnt(0)
	v_mfma_f32_32x32x16_bf16 v[212:227], v[82:85], v[196:199], v[212:227]
	v_or_b32_e32 v51, 0x80000000, v51
	s_cmpk_gt_i32 s11, 208
	s_cselect_b64 vcc, -1, 0
	v_xor_b32_e32 v50, v51, v50
	v_cndmask_b32_e32 v50, v123, v50, vcc
	global_store_dword v243, v50, s[8:9]
	v_mfma_f32_32x32x16_bf16 v[6:21], v[86:89], v[38:41], 0
	s_add_i32 m0, s10, 65536
	s_nop 0
	global_load_lds_dwordx4 v102, s[6:7]
	s_add_i32 m0, s10, 66560
	s_nop 0
	global_load_lds_dwordx4 v110, s[6:7]
	s_add_i32 m0, s10, 67584
	s_nop 0
	global_load_lds_dwordx4 v112, s[6:7]
	s_add_i32 m0, s10, 68608
	s_nop 0
	global_load_lds_dwordx4 v193, s[6:7]
	s_add_u32 s6, s6, 0x8000
	s_addc_u32 s7, s7, 0
	v_max_f32_e32 v108, 0, v212
	v_max_f32_e32 v109, 0, v213
	v_pk_mul_f32 v[0:1], v[22:23], v[108:109]
	v_max_f32_e32 v210, 0, v214
	v_max_f32_e32 v211, 0, v215
	v_pk_fma_f32 v[0:1], v[24:25], v[210:211], v[0:1]
	v_max_f32_e32 v108, 0, v216
	v_max_f32_e32 v109, 0, v217
	v_pk_fma_f32 v[0:1], v[26:27], v[108:109], v[0:1]
	v_mfma_f32_32x32x16_bf16 v[6:21], v[90:93], v[42:45], v[6:21]
	v_max_f32_e32 v210, 0, v218
	v_max_f32_e32 v211, 0, v219
	v_pk_fma_f32 v[0:1], v[28:29], v[210:211], v[0:1]
	v_max_f32_e32 v108, 0, v220
	v_max_f32_e32 v109, 0, v221
	v_pk_fma_f32 v[0:1], v[30:31], v[108:109], v[0:1]
	v_max_f32_e32 v210, 0, v222
	v_max_f32_e32 v211, 0, v223
	v_pk_fma_f32 v[0:1], v[32:33], v[210:211], v[0:1]
	v_mfma_f32_32x32x16_bf16 v[6:21], v[94:97], v[46:49], v[6:21]
	v_max_f32_e32 v108, 0, v224
	v_max_f32_e32 v109, 0, v225
	v_pk_fma_f32 v[0:1], v[34:35], v[108:109], v[0:1]
	v_max_f32_e32 v210, 0, v226
	v_max_f32_e32 v211, 0, v227
	v_pk_fma_f32 v[0:1], v[36:37], v[210:211], v[0:1]
	v_add_f32_e32 v0, v0, v1
	v_ashrrev_i32_e32 v1, 31, v0
	v_mfma_f32_32x32x16_bf16 v[6:21], v[98:101], v[196:199], v[6:21]
	s_waitcnt vmcnt(10)
	ds_read_b128 v[38:41], v5 offset:10496
	ds_read_b128 v[42:45], v52 offset:10496
	ds_read_b128 v[46:49], v55 offset:10496
	ds_read_b128 v[196:199], v56 offset:10496
	v_or_b32_e32 v1, 0x80000000, v1
	s_cmpk_gt_i32 s11, 216
	s_cselect_b64 vcc, -1, 0
	v_xor_b32_e32 v0, v1, v0
	v_cndmask_b32_e32 v159, v123, v0, vcc
	s_nop 1
	s_waitcnt lgkmcnt(3)
	v_mfma_f32_32x32x16_bf16 v[212:227], v[70:73], v[38:41], 0
	v_max_f32_e32 v108, 0, v6
	v_max_f32_e32 v109, 0, v7
	v_pk_mul_f32 v[50:51], v[244:245], v[108:109]
	v_max_f32_e32 v210, 0, v8
	v_max_f32_e32 v211, 0, v9
	v_pk_fma_f32 v[50:51], v[246:247], v[210:211], v[50:51]
	v_max_f32_e32 v108, 0, v10
	v_max_f32_e32 v109, 0, v11
	v_pk_fma_f32 v[50:51], v[248:249], v[108:109], v[50:51]
	s_waitcnt lgkmcnt(2)
	v_mfma_f32_32x32x16_bf16 v[212:227], v[74:77], v[42:45], v[212:227]
	v_max_f32_e32 v210, 0, v12
	v_max_f32_e32 v211, 0, v13
	v_pk_fma_f32 v[50:51], v[250:251], v[210:211], v[50:51]
	v_max_f32_e32 v108, 0, v14
	v_max_f32_e32 v109, 0, v15
	v_pk_fma_f32 v[50:51], v[252:253], v[108:109], v[50:51]
	v_max_f32_e32 v210, 0, v16
	v_max_f32_e32 v211, 0, v17
	v_pk_fma_f32 v[50:51], v[254:255], v[210:211], v[50:51]
	s_waitcnt lgkmcnt(1)
	v_mfma_f32_32x32x16_bf16 v[212:227], v[78:81], v[46:49], v[212:227]
	v_max_f32_e32 v108, 0, v18
	v_max_f32_e32 v109, 0, v19
	v_pk_fma_f32 v[50:51], v[200:201], v[108:109], v[50:51]
	v_max_f32_e32 v210, 0, v20
	v_max_f32_e32 v211, 0, v21
	v_pk_fma_f32 v[50:51], v[202:203], v[210:211], v[50:51]
	v_add_f32_e32 v50, v50, v51
	v_ashrrev_i32_e32 v51, 31, v50
	s_waitcnt lgkmcnt(0)
	v_mfma_f32_32x32x16_bf16 v[212:227], v[82:85], v[196:199], v[212:227]
	v_or_b32_e32 v51, 0x80000000, v51
	s_cmpk_gt_i32 s11, 216
	s_cselect_b64 vcc, -1, 0
	v_xor_b32_e32 v50, v51, v50
	v_cndmask_b32_e32 v50, v123, v50, vcc
	global_store_dword v243, v50, s[8:9] offset:2048
	s_add_u32 s8, s8, 0x1000
	s_addc_u32 s9, s9, 0
	v_mfma_f32_32x32x16_bf16 v[6:21], v[86:89], v[38:41], 0
	s_add_i32 m0, s10, 98304
	s_nop 0
	global_load_lds_dwordx4 v102, s[6:7]
	s_add_i32 m0, s10, 99328
	s_nop 0
	global_load_lds_dwordx4 v110, s[6:7]
	s_add_i32 m0, s10, 100352
	s_nop 0
	global_load_lds_dwordx4 v112, s[6:7]
	s_add_i32 m0, s10, 101376
	s_nop 0
	global_load_lds_dwordx4 v193, s[6:7]
	s_add_u32 s6, s6, 0x8000
	s_addc_u32 s7, s7, 0
	v_max_f32_e32 v108, 0, v212
	v_max_f32_e32 v109, 0, v213
	v_pk_mul_f32 v[0:1], v[22:23], v[108:109]
	v_max_f32_e32 v210, 0, v214
	v_max_f32_e32 v211, 0, v215
	v_pk_fma_f32 v[0:1], v[24:25], v[210:211], v[0:1]
	v_max_f32_e32 v108, 0, v216
	v_max_f32_e32 v109, 0, v217
	v_pk_fma_f32 v[0:1], v[26:27], v[108:109], v[0:1]
	v_mfma_f32_32x32x16_bf16 v[6:21], v[90:93], v[42:45], v[6:21]
	v_max_f32_e32 v210, 0, v218
	v_max_f32_e32 v211, 0, v219
	v_pk_fma_f32 v[0:1], v[28:29], v[210:211], v[0:1]
	v_max_f32_e32 v108, 0, v220
	v_max_f32_e32 v109, 0, v221
	v_pk_fma_f32 v[0:1], v[30:31], v[108:109], v[0:1]
	v_max_f32_e32 v210, 0, v222
	v_max_f32_e32 v211, 0, v223
	v_pk_fma_f32 v[0:1], v[32:33], v[210:211], v[0:1]
	v_mfma_f32_32x32x16_bf16 v[6:21], v[94:97], v[46:49], v[6:21]
	v_max_f32_e32 v108, 0, v224
	v_max_f32_e32 v109, 0, v225
	v_pk_fma_f32 v[0:1], v[34:35], v[108:109], v[0:1]
	v_max_f32_e32 v210, 0, v226
	v_max_f32_e32 v211, 0, v227
	v_pk_fma_f32 v[0:1], v[36:37], v[210:211], v[0:1]
	v_add_f32_e32 v0, v0, v1
	v_ashrrev_i32_e32 v1, 31, v0
	v_mfma_f32_32x32x16_bf16 v[6:21], v[98:101], v[196:199], v[6:21]
	s_waitcnt vmcnt(10)
	ds_read_b128 v[38:41], v5 offset:43264
	ds_read_b128 v[42:45], v52 offset:43264
	ds_read_b128 v[46:49], v55 offset:43264
	ds_read_b128 v[196:199], v56 offset:43264
	v_or_b32_e32 v1, 0x80000000, v1
	s_cmpk_gt_i32 s11, 224
	s_cselect_b64 vcc, -1, 0
	v_xor_b32_e32 v0, v1, v0
	v_cndmask_b32_e32 v162, v123, v0, vcc
	s_nop 1
	s_waitcnt lgkmcnt(3)
	v_mfma_f32_32x32x16_bf16 v[212:227], v[70:73], v[38:41], 0
	v_max_f32_e32 v108, 0, v6
	v_max_f32_e32 v109, 0, v7
	v_pk_mul_f32 v[50:51], v[244:245], v[108:109]
	v_max_f32_e32 v210, 0, v8
	v_max_f32_e32 v211, 0, v9
	v_pk_fma_f32 v[50:51], v[246:247], v[210:211], v[50:51]
	v_max_f32_e32 v108, 0, v10
	v_max_f32_e32 v109, 0, v11
	v_pk_fma_f32 v[50:51], v[248:249], v[108:109], v[50:51]
	s_waitcnt lgkmcnt(2)
	v_mfma_f32_32x32x16_bf16 v[212:227], v[74:77], v[42:45], v[212:227]
	v_max_f32_e32 v210, 0, v12
	v_max_f32_e32 v211, 0, v13
	v_pk_fma_f32 v[50:51], v[250:251], v[210:211], v[50:51]
	v_max_f32_e32 v108, 0, v14
	v_max_f32_e32 v109, 0, v15
	v_pk_fma_f32 v[50:51], v[252:253], v[108:109], v[50:51]
	v_max_f32_e32 v210, 0, v16
	v_max_f32_e32 v211, 0, v17
	v_pk_fma_f32 v[50:51], v[254:255], v[210:211], v[50:51]
	s_waitcnt lgkmcnt(1)
	v_mfma_f32_32x32x16_bf16 v[212:227], v[78:81], v[46:49], v[212:227]
	v_max_f32_e32 v108, 0, v18
	v_max_f32_e32 v109, 0, v19
	v_pk_fma_f32 v[50:51], v[200:201], v[108:109], v[50:51]
	v_max_f32_e32 v210, 0, v20
	v_max_f32_e32 v211, 0, v21
	v_pk_fma_f32 v[50:51], v[202:203], v[210:211], v[50:51]
	v_add_f32_e32 v50, v50, v51
	v_ashrrev_i32_e32 v51, 31, v50
	s_waitcnt lgkmcnt(0)
	v_mfma_f32_32x32x16_bf16 v[212:227], v[82:85], v[196:199], v[212:227]
	v_or_b32_e32 v51, 0x80000000, v51
	s_cmpk_gt_i32 s11, 224
	s_cselect_b64 vcc, -1, 0
	v_xor_b32_e32 v50, v51, v50
	v_cndmask_b32_e32 v50, v123, v50, vcc
	global_store_dword v243, v50, s[8:9]
	v_mfma_f32_32x32x16_bf16 v[6:21], v[86:89], v[38:41], 0
	s_add_i32 m0, s10, 0
	s_nop 0
	global_load_lds_dwordx4 v102, s[6:7]
	s_add_i32 m0, s10, 1024
	s_nop 0
	global_load_lds_dwordx4 v110, s[6:7]
	s_add_i32 m0, s10, 2048
	s_nop 0
	global_load_lds_dwordx4 v112, s[6:7]
	s_add_i32 m0, s10, 3072
	s_nop 0
	global_load_lds_dwordx4 v193, s[6:7]
	s_add_u32 s6, s6, 0x8000
	s_addc_u32 s7, s7, 0
	v_max_f32_e32 v108, 0, v212
	v_max_f32_e32 v109, 0, v213
	v_pk_mul_f32 v[0:1], v[22:23], v[108:109]
	v_max_f32_e32 v210, 0, v214
	v_max_f32_e32 v211, 0, v215
	v_pk_fma_f32 v[0:1], v[24:25], v[210:211], v[0:1]
	v_max_f32_e32 v108, 0, v216
	v_max_f32_e32 v109, 0, v217
	v_pk_fma_f32 v[0:1], v[26:27], v[108:109], v[0:1]
	v_mfma_f32_32x32x16_bf16 v[6:21], v[90:93], v[42:45], v[6:21]
	v_max_f32_e32 v210, 0, v218
	v_max_f32_e32 v211, 0, v219
	v_pk_fma_f32 v[0:1], v[28:29], v[210:211], v[0:1]
	v_max_f32_e32 v108, 0, v220
	v_max_f32_e32 v109, 0, v221
	v_pk_fma_f32 v[0:1], v[30:31], v[108:109], v[0:1]
	v_max_f32_e32 v210, 0, v222
	v_max_f32_e32 v211, 0, v223
	v_pk_fma_f32 v[0:1], v[32:33], v[210:211], v[0:1]
	v_mfma_f32_32x32x16_bf16 v[6:21], v[94:97], v[46:49], v[6:21]
	v_max_f32_e32 v108, 0, v224
	v_max_f32_e32 v109, 0, v225
	v_pk_fma_f32 v[0:1], v[34:35], v[108:109], v[0:1]
	v_max_f32_e32 v210, 0, v226
	v_max_f32_e32 v211, 0, v227
	v_pk_fma_f32 v[0:1], v[36:37], v[210:211], v[0:1]
	v_add_f32_e32 v0, v0, v1
	v_ashrrev_i32_e32 v1, 31, v0
	v_mfma_f32_32x32x16_bf16 v[6:21], v[98:101], v[196:199], v[6:21]
	s_waitcnt vmcnt(10)
	v_add_u32_e32 v228, 0x10000, v5
	ds_read_b128 v[38:41], v228 offset:10496
	v_add_u32_e32 v228, 0x10000, v52
	ds_read_b128 v[42:45], v228 offset:10496
	v_add_u32_e32 v228, 0x10000, v55
	ds_read_b128 v[46:49], v228 offset:10496
	v_add_u32_e32 v228, 0x10000, v56
	ds_read_b128 v[196:199], v228 offset:10496
	v_or_b32_e32 v1, 0x80000000, v1
	s_cmpk_gt_i32 s11, 232
	s_cselect_b64 vcc, -1, 0
	v_xor_b32_e32 v0, v1, v0
	v_cndmask_b32_e32 v161, v123, v0, vcc
	s_nop 1
	s_waitcnt lgkmcnt(3)
	v_mfma_f32_32x32x16_bf16 v[212:227], v[70:73], v[38:41], 0
	v_max_f32_e32 v108, 0, v6
	v_max_f32_e32 v109, 0, v7
	v_pk_mul_f32 v[50:51], v[244:245], v[108:109]
	v_max_f32_e32 v210, 0, v8
	v_max_f32_e32 v211, 0, v9
	v_pk_fma_f32 v[50:51], v[246:247], v[210:211], v[50:51]
	v_max_f32_e32 v108, 0, v10
	v_max_f32_e32 v109, 0, v11
	v_pk_fma_f32 v[50:51], v[248:249], v[108:109], v[50:51]
	s_waitcnt lgkmcnt(2)
	v_mfma_f32_32x32x16_bf16 v[212:227], v[74:77], v[42:45], v[212:227]
	v_max_f32_e32 v210, 0, v12
	v_max_f32_e32 v211, 0, v13
	v_pk_fma_f32 v[50:51], v[250:251], v[210:211], v[50:51]
	v_max_f32_e32 v108, 0, v14
	v_max_f32_e32 v109, 0, v15
	v_pk_fma_f32 v[50:51], v[252:253], v[108:109], v[50:51]
	v_max_f32_e32 v210, 0, v16
	v_max_f32_e32 v211, 0, v17
	v_pk_fma_f32 v[50:51], v[254:255], v[210:211], v[50:51]
	s_waitcnt lgkmcnt(1)
	v_mfma_f32_32x32x16_bf16 v[212:227], v[78:81], v[46:49], v[212:227]
	v_max_f32_e32 v108, 0, v18
	v_max_f32_e32 v109, 0, v19
	v_pk_fma_f32 v[50:51], v[200:201], v[108:109], v[50:51]
	v_max_f32_e32 v210, 0, v20
	v_max_f32_e32 v211, 0, v21
	v_pk_fma_f32 v[50:51], v[202:203], v[210:211], v[50:51]
	v_add_f32_e32 v50, v50, v51
	v_ashrrev_i32_e32 v51, 31, v50
	s_waitcnt lgkmcnt(0)
	v_mfma_f32_32x32x16_bf16 v[212:227], v[82:85], v[196:199], v[212:227]
	v_or_b32_e32 v51, 0x80000000, v51
	s_cmpk_gt_i32 s11, 232
	s_cselect_b64 vcc, -1, 0
	v_xor_b32_e32 v50, v51, v50
	v_cndmask_b32_e32 v50, v123, v50, vcc
	global_store_dword v243, v50, s[8:9] offset:2048
	s_add_u32 s8, s8, 0x1000
	s_addc_u32 s9, s9, 0
	v_mfma_f32_32x32x16_bf16 v[6:21], v[86:89], v[38:41], 0
	s_add_i32 m0, s10, 32768
	s_nop 0
	global_load_lds_dwordx4 v102, s[6:7]
	s_add_i32 m0, s10, 33792
	s_nop 0
	global_load_lds_dwordx4 v110, s[6:7]
	s_add_i32 m0, s10, 34816
	s_nop 0
	global_load_lds_dwordx4 v112, s[6:7]
	s_add_i32 m0, s10, 35840
	s_nop 0
	global_load_lds_dwordx4 v193, s[6:7]
	s_add_u32 s6, s6, 0x8000
	s_addc_u32 s7, s7, 0
	v_max_f32_e32 v108, 0, v212
	v_max_f32_e32 v109, 0, v213
	v_pk_mul_f32 v[0:1], v[22:23], v[108:109]
	v_max_f32_e32 v210, 0, v214
	v_max_f32_e32 v211, 0, v215
	v_pk_fma_f32 v[0:1], v[24:25], v[210:211], v[0:1]
	v_max_f32_e32 v108, 0, v216
	v_max_f32_e32 v109, 0, v217
	v_pk_fma_f32 v[0:1], v[26:27], v[108:109], v[0:1]
	v_mfma_f32_32x32x16_bf16 v[6:21], v[90:93], v[42:45], v[6:21]
	v_max_f32_e32 v210, 0, v218
	v_max_f32_e32 v211, 0, v219
	v_pk_fma_f32 v[0:1], v[28:29], v[210:211], v[0:1]
	v_max_f32_e32 v108, 0, v220
	v_max_f32_e32 v109, 0, v221
	v_pk_fma_f32 v[0:1], v[30:31], v[108:109], v[0:1]
	v_max_f32_e32 v210, 0, v222
	v_max_f32_e32 v211, 0, v223
	v_pk_fma_f32 v[0:1], v[32:33], v[210:211], v[0:1]
	v_mfma_f32_32x32x16_bf16 v[6:21], v[94:97], v[46:49], v[6:21]
	v_max_f32_e32 v108, 0, v224
	v_max_f32_e32 v109, 0, v225
	v_pk_fma_f32 v[0:1], v[34:35], v[108:109], v[0:1]
	v_max_f32_e32 v210, 0, v226
	v_max_f32_e32 v211, 0, v227
	v_pk_fma_f32 v[0:1], v[36:37], v[210:211], v[0:1]
	v_add_f32_e32 v0, v0, v1
	v_ashrrev_i32_e32 v1, 31, v0
	v_mfma_f32_32x32x16_bf16 v[6:21], v[98:101], v[196:199], v[6:21]
	s_waitcnt vmcnt(10)
	v_add_u32_e32 v228, 0x10000, v5
	ds_read_b128 v[38:41], v228 offset:43264
	v_add_u32_e32 v228, 0x10000, v52
	ds_read_b128 v[42:45], v228 offset:43264
	v_add_u32_e32 v228, 0x10000, v55
	ds_read_b128 v[46:49], v228 offset:43264
	v_add_u32_e32 v228, 0x10000, v56
	ds_read_b128 v[196:199], v228 offset:43264
	v_or_b32_e32 v1, 0x80000000, v1
	s_cmpk_gt_i32 s11, 240
	s_cselect_b64 vcc, -1, 0
	v_xor_b32_e32 v0, v1, v0
	v_cndmask_b32_e32 v163, v123, v0, vcc
	s_nop 1
	s_waitcnt lgkmcnt(3)
	v_mfma_f32_32x32x16_bf16 v[212:227], v[70:73], v[38:41], 0
	v_max_f32_e32 v108, 0, v6
	v_max_f32_e32 v109, 0, v7
	v_pk_mul_f32 v[50:51], v[244:245], v[108:109]
	v_max_f32_e32 v210, 0, v8
	v_max_f32_e32 v211, 0, v9
	v_pk_fma_f32 v[50:51], v[246:247], v[210:211], v[50:51]
	v_max_f32_e32 v108, 0, v10
	v_max_f32_e32 v109, 0, v11
	v_pk_fma_f32 v[50:51], v[248:249], v[108:109], v[50:51]
	s_waitcnt lgkmcnt(2)
	v_mfma_f32_32x32x16_bf16 v[212:227], v[74:77], v[42:45], v[212:227]
	v_max_f32_e32 v210, 0, v12
	v_max_f32_e32 v211, 0, v13
	v_pk_fma_f32 v[50:51], v[250:251], v[210:211], v[50:51]
	v_max_f32_e32 v108, 0, v14
	v_max_f32_e32 v109, 0, v15
	v_pk_fma_f32 v[50:51], v[252:253], v[108:109], v[50:51]
	v_max_f32_e32 v210, 0, v16
	v_max_f32_e32 v211, 0, v17
	v_pk_fma_f32 v[50:51], v[254:255], v[210:211], v[50:51]
	s_waitcnt lgkmcnt(1)
	v_mfma_f32_32x32x16_bf16 v[212:227], v[78:81], v[46:49], v[212:227]
	v_max_f32_e32 v108, 0, v18
	v_max_f32_e32 v109, 0, v19
	v_pk_fma_f32 v[50:51], v[200:201], v[108:109], v[50:51]
	v_max_f32_e32 v210, 0, v20
	v_max_f32_e32 v211, 0, v21
	v_pk_fma_f32 v[50:51], v[202:203], v[210:211], v[50:51]
	v_add_f32_e32 v50, v50, v51
	v_ashrrev_i32_e32 v51, 31, v50
	s_waitcnt lgkmcnt(0)
	v_mfma_f32_32x32x16_bf16 v[212:227], v[82:85], v[196:199], v[212:227]
	v_or_b32_e32 v51, 0x80000000, v51
	s_cmpk_gt_i32 s11, 240
	s_cselect_b64 vcc, -1, 0
	v_xor_b32_e32 v50, v51, v50
	v_cndmask_b32_e32 v50, v123, v50, vcc
	global_store_dword v243, v50, s[8:9]
	v_mfma_f32_32x32x16_bf16 v[6:21], v[86:89], v[38:41], 0
	s_add_i32 m0, s10, 65536
	s_nop 0
	global_load_lds_dwordx4 v102, s[6:7]
	s_add_i32 m0, s10, 66560
	s_nop 0
	global_load_lds_dwordx4 v110, s[6:7]
	s_add_i32 m0, s10, 67584
	s_nop 0
	global_load_lds_dwordx4 v112, s[6:7]
	s_add_i32 m0, s10, 68608
	s_nop 0
	global_load_lds_dwordx4 v193, s[6:7]
	s_add_u32 s6, s6, 0x8000
	s_addc_u32 s7, s7, 0
	v_max_f32_e32 v108, 0, v212
	v_max_f32_e32 v109, 0, v213
	v_pk_mul_f32 v[0:1], v[22:23], v[108:109]
	v_max_f32_e32 v210, 0, v214
	v_max_f32_e32 v211, 0, v215
	v_pk_fma_f32 v[0:1], v[24:25], v[210:211], v[0:1]
	v_max_f32_e32 v108, 0, v216
	v_max_f32_e32 v109, 0, v217
	v_pk_fma_f32 v[0:1], v[26:27], v[108:109], v[0:1]
	v_mfma_f32_32x32x16_bf16 v[6:21], v[90:93], v[42:45], v[6:21]
	v_max_f32_e32 v210, 0, v218
	v_max_f32_e32 v211, 0, v219
	v_pk_fma_f32 v[0:1], v[28:29], v[210:211], v[0:1]
	v_max_f32_e32 v108, 0, v220
	v_max_f32_e32 v109, 0, v221
	v_pk_fma_f32 v[0:1], v[30:31], v[108:109], v[0:1]
	v_max_f32_e32 v210, 0, v222
	v_max_f32_e32 v211, 0, v223
	v_pk_fma_f32 v[0:1], v[32:33], v[210:211], v[0:1]
	v_mfma_f32_32x32x16_bf16 v[6:21], v[94:97], v[46:49], v[6:21]
	v_max_f32_e32 v108, 0, v224
	v_max_f32_e32 v109, 0, v225
	v_pk_fma_f32 v[0:1], v[34:35], v[108:109], v[0:1]
	v_max_f32_e32 v210, 0, v226
	v_max_f32_e32 v211, 0, v227
	v_pk_fma_f32 v[0:1], v[36:37], v[210:211], v[0:1]
	v_add_f32_e32 v0, v0, v1
	v_ashrrev_i32_e32 v1, 31, v0
	v_mfma_f32_32x32x16_bf16 v[6:21], v[98:101], v[196:199], v[6:21]
	s_waitcnt vmcnt(10)
	ds_read_b128 v[38:41], v5 offset:10496
	ds_read_b128 v[42:45], v52 offset:10496
	ds_read_b128 v[46:49], v55 offset:10496
	ds_read_b128 v[196:199], v56 offset:10496
	v_or_b32_e32 v1, 0x80000000, v1
	s_cmpk_gt_i32 s11, 248
	s_cselect_b64 vcc, -1, 0
	v_xor_b32_e32 v0, v1, v0
	v_cndmask_b32_e32 v152, v123, v0, vcc
	s_nop 1
	v_max_f32_e32 v108, 0, v6
	v_max_f32_e32 v109, 0, v7
	v_pk_mul_f32 v[50:51], v[244:245], v[108:109]
	v_max_f32_e32 v210, 0, v8
	v_max_f32_e32 v211, 0, v9
	v_pk_fma_f32 v[50:51], v[246:247], v[210:211], v[50:51]
	v_max_f32_e32 v108, 0, v10
	v_max_f32_e32 v109, 0, v11
	v_pk_fma_f32 v[50:51], v[248:249], v[108:109], v[50:51]
	v_max_f32_e32 v210, 0, v12
	v_max_f32_e32 v211, 0, v13
	v_pk_fma_f32 v[50:51], v[250:251], v[210:211], v[50:51]
	v_max_f32_e32 v108, 0, v14
	v_max_f32_e32 v109, 0, v15
	v_pk_fma_f32 v[50:51], v[252:253], v[108:109], v[50:51]
	v_max_f32_e32 v210, 0, v16
	v_max_f32_e32 v211, 0, v17
	v_pk_fma_f32 v[50:51], v[254:255], v[210:211], v[50:51]
	v_max_f32_e32 v108, 0, v18
	v_max_f32_e32 v109, 0, v19
	v_pk_fma_f32 v[50:51], v[200:201], v[108:109], v[50:51]
	v_max_f32_e32 v210, 0, v20
	v_max_f32_e32 v211, 0, v21
	v_pk_fma_f32 v[50:51], v[202:203], v[210:211], v[50:51]
	v_add_f32_e32 v50, v50, v51
	v_ashrrev_i32_e32 v51, 31, v50
	v_or_b32_e32 v51, 0x80000000, v51
	s_cmpk_gt_i32 s11, 248
	s_cselect_b64 vcc, -1, 0
	v_xor_b32_e32 v50, v51, v50
	v_cndmask_b32_e32 v50, v123, v50, vcc
	global_store_dword v243, v50, s[8:9] offset:2048
	s_add_u32 s8, s8, 0x1000
	s_addc_u32 s9, s9, 0
	s_cmpk_gt_i32 s81, 32
	s_cbranch_scc0 .Lix_fill_4
	s_waitcnt lgkmcnt(3)
	v_mfma_f32_32x32x16_bf16 v[212:227], v[70:73], v[38:41], 0
	s_add_i32 m0, s10, 98304
	s_nop 0
	global_load_lds_dwordx4 v102, s[6:7]
	s_waitcnt lgkmcnt(2)
	v_mfma_f32_32x32x16_bf16 v[212:227], v[74:77], v[42:45], v[212:227]
	s_add_i32 m0, s10, 99328
	s_nop 0
	global_load_lds_dwordx4 v110, s[6:7]
	s_waitcnt lgkmcnt(1)
	v_mfma_f32_32x32x16_bf16 v[212:227], v[78:81], v[46:49], v[212:227]
	s_add_i32 m0, s10, 100352
	s_nop 0
	global_load_lds_dwordx4 v112, s[6:7]
	s_waitcnt lgkmcnt(0)
	v_mfma_f32_32x32x16_bf16 v[212:227], v[82:85], v[196:199], v[212:227]
	s_add_i32 m0, s10, 101376
	s_nop 0
	global_load_lds_dwordx4 v193, s[6:7]
	s_add_u32 s6, s6, 0x8000
	s_addc_u32 s7, s7, 0
	v_mfma_f32_32x32x16_bf16 v[6:21], v[86:89], v[38:41], 0
	s_nop 7
	s_nop 2
	v_max_f32_e32 v108, 0, v212
	v_max_f32_e32 v109, 0, v213
	v_pk_mul_f32 v[0:1], v[22:23], v[108:109]
	v_max_f32_e32 v210, 0, v214
	v_max_f32_e32 v211, 0, v215
	v_pk_fma_f32 v[0:1], v[24:25], v[210:211], v[0:1]
	v_max_f32_e32 v108, 0, v216
	v_max_f32_e32 v109, 0, v217
	v_pk_fma_f32 v[0:1], v[26:27], v[108:109], v[0:1]
	v_mfma_f32_32x32x16_bf16 v[6:21], v[90:93], v[42:45], v[6:21]
	v_max_f32_e32 v210, 0, v218
	v_max_f32_e32 v211, 0, v219
	v_pk_fma_f32 v[0:1], v[28:29], v[210:211], v[0:1]
	v_max_f32_e32 v108, 0, v220
	v_max_f32_e32 v109, 0, v221
	v_pk_fma_f32 v[0:1], v[30:31], v[108:109], v[0:1]
	v_max_f32_e32 v210, 0, v222
	v_max_f32_e32 v211, 0, v223
	v_pk_fma_f32 v[0:1], v[32:33], v[210:211], v[0:1]
	v_mfma_f32_32x32x16_bf16 v[6:21], v[94:97], v[46:49], v[6:21]
	v_max_f32_e32 v108, 0, v224
	v_max_f32_e32 v109, 0, v225
	v_pk_fma_f32 v[0:1], v[34:35], v[108:109], v[0:1]
	v_max_f32_e32 v210, 0, v226
	v_max_f32_e32 v211, 0, v227
	v_pk_fma_f32 v[0:1], v[36:37], v[210:211], v[0:1]
	v_add_f32_e32 v0, v0, v1
	v_ashrrev_i32_e32 v1, 31, v0
	v_mfma_f32_32x32x16_bf16 v[6:21], v[98:101], v[196:199], v[6:21]
	s_waitcnt vmcnt(10)
	ds_read_b128 v[38:41], v5 offset:43264
	ds_read_b128 v[42:45], v52 offset:43264
	ds_read_b128 v[46:49], v55 offset:43264
	ds_read_b128 v[196:199], v56 offset:43264
	v_or_b32_e32 v1, 0x80000000, v1
	s_cmpk_gt_i32 s11, 256
	s_cselect_b64 vcc, -1, 0
	v_xor_b32_e32 v0, v1, v0
	v_cndmask_b32_e32 v165, v123, v0, vcc
	s_nop 1
	s_waitcnt lgkmcnt(3)
	v_mfma_f32_32x32x16_bf16 v[212:227], v[70:73], v[38:41], 0
	v_max_f32_e32 v108, 0, v6
	v_max_f32_e32 v109, 0, v7
	v_pk_mul_f32 v[50:51], v[244:245], v[108:109]
	v_max_f32_e32 v210, 0, v8
	v_max_f32_e32 v211, 0, v9
	v_pk_fma_f32 v[50:51], v[246:247], v[210:211], v[50:51]
	v_max_f32_e32 v108, 0, v10
	v_max_f32_e32 v109, 0, v11
	v_pk_fma_f32 v[50:51], v[248:249], v[108:109], v[50:51]
	s_waitcnt lgkmcnt(2)
	v_mfma_f32_32x32x16_bf16 v[212:227], v[74:77], v[42:45], v[212:227]
	v_max_f32_e32 v210, 0, v12
	v_max_f32_e32 v211, 0, v13
	v_pk_fma_f32 v[50:51], v[250:251], v[210:211], v[50:51]
	v_max_f32_e32 v108, 0, v14
	v_max_f32_e32 v109, 0, v15
	v_pk_fma_f32 v[50:51], v[252:253], v[108:109], v[50:51]
	v_max_f32_e32 v210, 0, v16
	v_max_f32_e32 v211, 0, v17
	v_pk_fma_f32 v[50:51], v[254:255], v[210:211], v[50:51]
	s_waitcnt lgkmcnt(1)
	v_mfma_f32_32x32x16_bf16 v[212:227], v[78:81], v[46:49], v[212:227]
	v_max_f32_e32 v108, 0, v18
	v_max_f32_e32 v109, 0, v19
	v_pk_fma_f32 v[50:51], v[200:201], v[108:109], v[50:51]
	v_max_f32_e32 v210, 0, v20
	v_max_f32_e32 v211, 0, v21
	v_pk_fma_f32 v[50:51], v[202:203], v[210:211], v[50:51]
	v_add_f32_e32 v50, v50, v51
	v_ashrrev_i32_e32 v51, 31, v50
	s_waitcnt lgkmcnt(0)
	v_mfma_f32_32x32x16_bf16 v[212:227], v[82:85], v[196:199], v[212:227]
	v_or_b32_e32 v51, 0x80000000, v51
	s_cmpk_gt_i32 s11, 256
	s_cselect_b64 vcc, -1, 0
	v_xor_b32_e32 v50, v51, v50
	v_cndmask_b32_e32 v50, v123, v50, vcc
	global_store_dword v243, v50, s[8:9]
	v_mfma_f32_32x32x16_bf16 v[6:21], v[86:89], v[38:41], 0
	s_add_i32 m0, s10, 0
	s_nop 0
	global_load_lds_dwordx4 v102, s[6:7]
	s_add_i32 m0, s10, 1024
	s_nop 0
	global_load_lds_dwordx4 v110, s[6:7]
	s_add_i32 m0, s10, 2048
	s_nop 0
	global_load_lds_dwordx4 v112, s[6:7]
	s_add_i32 m0, s10, 3072
	s_nop 0
	global_load_lds_dwordx4 v193, s[6:7]
	s_add_u32 s6, s6, 0x8000
	s_addc_u32 s7, s7, 0
	v_max_f32_e32 v108, 0, v212
	v_max_f32_e32 v109, 0, v213
	v_pk_mul_f32 v[0:1], v[22:23], v[108:109]
	v_max_f32_e32 v210, 0, v214
	v_max_f32_e32 v211, 0, v215
	v_pk_fma_f32 v[0:1], v[24:25], v[210:211], v[0:1]
	v_max_f32_e32 v108, 0, v216
	v_max_f32_e32 v109, 0, v217
	v_pk_fma_f32 v[0:1], v[26:27], v[108:109], v[0:1]
	v_mfma_f32_32x32x16_bf16 v[6:21], v[90:93], v[42:45], v[6:21]
	v_max_f32_e32 v210, 0, v218
	v_max_f32_e32 v211, 0, v219
	v_pk_fma_f32 v[0:1], v[28:29], v[210:211], v[0:1]
	v_max_f32_e32 v108, 0, v220
	v_max_f32_e32 v109, 0, v221
	v_pk_fma_f32 v[0:1], v[30:31], v[108:109], v[0:1]
	v_max_f32_e32 v210, 0, v222
	v_max_f32_e32 v211, 0, v223
	v_pk_fma_f32 v[0:1], v[32:33], v[210:211], v[0:1]
	v_mfma_f32_32x32x16_bf16 v[6:21], v[94:97], v[46:49], v[6:21]
	v_max_f32_e32 v108, 0, v224
	v_max_f32_e32 v109, 0, v225
	v_pk_fma_f32 v[0:1], v[34:35], v[108:109], v[0:1]
	v_max_f32_e32 v210, 0, v226
	v_max_f32_e32 v211, 0, v227
	v_pk_fma_f32 v[0:1], v[36:37], v[210:211], v[0:1]
	v_add_f32_e32 v0, v0, v1
	v_ashrrev_i32_e32 v1, 31, v0
	v_mfma_f32_32x32x16_bf16 v[6:21], v[98:101], v[196:199], v[6:21]
	s_waitcnt vmcnt(10)
	v_add_u32_e32 v228, 0x10000, v5
	ds_read_b128 v[38:41], v228 offset:10496
	v_add_u32_e32 v228, 0x10000, v52
	ds_read_b128 v[42:45], v228 offset:10496
	v_add_u32_e32 v228, 0x10000, v55
	ds_read_b128 v[46:49], v228 offset:10496
	v_add_u32_e32 v228, 0x10000, v56
	ds_read_b128 v[196:199], v228 offset:10496
	v_or_b32_e32 v1, 0x80000000, v1
	s_cmpk_gt_i32 s11, 264
	s_cselect_b64 vcc, -1, 0
	v_xor_b32_e32 v0, v1, v0
	v_cndmask_b32_e32 v164, v123, v0, vcc
	s_nop 1
	s_waitcnt lgkmcnt(3)
	v_mfma_f32_32x32x16_bf16 v[212:227], v[70:73], v[38:41], 0
	v_max_f32_e32 v108, 0, v6
	v_max_f32_e32 v109, 0, v7
	v_pk_mul_f32 v[50:51], v[244:245], v[108:109]
	v_max_f32_e32 v210, 0, v8
	v_max_f32_e32 v211, 0, v9
	v_pk_fma_f32 v[50:51], v[246:247], v[210:211], v[50:51]
	v_max_f32_e32 v108, 0, v10
	v_max_f32_e32 v109, 0, v11
	v_pk_fma_f32 v[50:51], v[248:249], v[108:109], v[50:51]
	s_waitcnt lgkmcnt(2)
	v_mfma_f32_32x32x16_bf16 v[212:227], v[74:77], v[42:45], v[212:227]
	v_max_f32_e32 v210, 0, v12
	v_max_f32_e32 v211, 0, v13
	v_pk_fma_f32 v[50:51], v[250:251], v[210:211], v[50:51]
	v_max_f32_e32 v108, 0, v14
	v_max_f32_e32 v109, 0, v15
	v_pk_fma_f32 v[50:51], v[252:253], v[108:109], v[50:51]
	v_max_f32_e32 v210, 0, v16
	v_max_f32_e32 v211, 0, v17
	v_pk_fma_f32 v[50:51], v[254:255], v[210:211], v[50:51]
	s_waitcnt lgkmcnt(1)
	v_mfma_f32_32x32x16_bf16 v[212:227], v[78:81], v[46:49], v[212:227]
	v_max_f32_e32 v108, 0, v18
	v_max_f32_e32 v109, 0, v19
	v_pk_fma_f32 v[50:51], v[200:201], v[108:109], v[50:51]
	v_max_f32_e32 v210, 0, v20
	v_max_f32_e32 v211, 0, v21
	v_pk_fma_f32 v[50:51], v[202:203], v[210:211], v[50:51]
	v_add_f32_e32 v50, v50, v51
	v_ashrrev_i32_e32 v51, 31, v50
	s_waitcnt lgkmcnt(0)
	v_mfma_f32_32x32x16_bf16 v[212:227], v[82:85], v[196:199], v[212:227]
	v_or_b32_e32 v51, 0x80000000, v51
	s_cmpk_gt_i32 s11, 264
	s_cselect_b64 vcc, -1, 0
	v_xor_b32_e32 v50, v51, v50
	v_cndmask_b32_e32 v50, v123, v50, vcc
	global_store_dword v243, v50, s[8:9] offset:2048
	s_add_u32 s8, s8, 0x1000
	s_addc_u32 s9, s9, 0
	v_mfma_f32_32x32x16_bf16 v[6:21], v[86:89], v[38:41], 0
	s_add_i32 m0, s10, 32768
	s_nop 0
	global_load_lds_dwordx4 v102, s[6:7]
	s_add_i32 m0, s10, 33792
	s_nop 0
	global_load_lds_dwordx4 v110, s[6:7]
	s_add_i32 m0, s10, 34816
	s_nop 0
	global_load_lds_dwordx4 v112, s[6:7]
	s_add_i32 m0, s10, 35840
	s_nop 0
	global_load_lds_dwordx4 v193, s[6:7]
	s_add_u32 s6, s6, 0x8000
	s_addc_u32 s7, s7, 0
	v_max_f32_e32 v108, 0, v212
	v_max_f32_e32 v109, 0, v213
	v_pk_mul_f32 v[0:1], v[22:23], v[108:109]
	v_max_f32_e32 v210, 0, v214
	v_max_f32_e32 v211, 0, v215
	v_pk_fma_f32 v[0:1], v[24:25], v[210:211], v[0:1]
	v_max_f32_e32 v108, 0, v216
	v_max_f32_e32 v109, 0, v217
	v_pk_fma_f32 v[0:1], v[26:27], v[108:109], v[0:1]
	v_mfma_f32_32x32x16_bf16 v[6:21], v[90:93], v[42:45], v[6:21]
	v_max_f32_e32 v210, 0, v218
	v_max_f32_e32 v211, 0, v219
	v_pk_fma_f32 v[0:1], v[28:29], v[210:211], v[0:1]
	v_max_f32_e32 v108, 0, v220
	v_max_f32_e32 v109, 0, v221
	v_pk_fma_f32 v[0:1], v[30:31], v[108:109], v[0:1]
	v_max_f32_e32 v210, 0, v222
	v_max_f32_e32 v211, 0, v223
	v_pk_fma_f32 v[0:1], v[32:33], v[210:211], v[0:1]
	v_mfma_f32_32x32x16_bf16 v[6:21], v[94:97], v[46:49], v[6:21]
	v_max_f32_e32 v108, 0, v224
	v_max_f32_e32 v109, 0, v225
	v_pk_fma_f32 v[0:1], v[34:35], v[108:109], v[0:1]
	v_max_f32_e32 v210, 0, v226
	v_max_f32_e32 v211, 0, v227
	v_pk_fma_f32 v[0:1], v[36:37], v[210:211], v[0:1]
	v_add_f32_e32 v0, v0, v1
	v_ashrrev_i32_e32 v1, 31, v0
	v_mfma_f32_32x32x16_bf16 v[6:21], v[98:101], v[196:199], v[6:21]
	s_waitcnt vmcnt(10)
	v_add_u32_e32 v228, 0x10000, v5
	ds_read_b128 v[38:41], v228 offset:43264
	v_add_u32_e32 v228, 0x10000, v52
	ds_read_b128 v[42:45], v228 offset:43264
	v_add_u32_e32 v228, 0x10000, v55
	ds_read_b128 v[46:49], v228 offset:43264
	v_add_u32_e32 v228, 0x10000, v56
	ds_read_b128 v[196:199], v228 offset:43264
	v_or_b32_e32 v1, 0x80000000, v1
	s_cmpk_gt_i32 s11, 272
	s_cselect_b64 vcc, -1, 0
	v_xor_b32_e32 v0, v1, v0
	v_cndmask_b32_e32 v167, v123, v0, vcc
	s_nop 1
	s_waitcnt lgkmcnt(3)
	v_mfma_f32_32x32x16_bf16 v[212:227], v[70:73], v[38:41], 0
	v_max_f32_e32 v108, 0, v6
	v_max_f32_e32 v109, 0, v7
	v_pk_mul_f32 v[50:51], v[244:245], v[108:109]
	v_max_f32_e32 v210, 0, v8
	v_max_f32_e32 v211, 0, v9
	v_pk_fma_f32 v[50:51], v[246:247], v[210:211], v[50:51]
	v_max_f32_e32 v108, 0, v10
	v_max_f32_e32 v109, 0, v11
	v_pk_fma_f32 v[50:51], v[248:249], v[108:109], v[50:51]
	s_waitcnt lgkmcnt(2)
	v_mfma_f32_32x32x16_bf16 v[212:227], v[74:77], v[42:45], v[212:227]
	v_max_f32_e32 v210, 0, v12
	v_max_f32_e32 v211, 0, v13
	v_pk_fma_f32 v[50:51], v[250:251], v[210:211], v[50:51]
	v_max_f32_e32 v108, 0, v14
	v_max_f32_e32 v109, 0, v15
	v_pk_fma_f32 v[50:51], v[252:253], v[108:109], v[50:51]
	v_max_f32_e32 v210, 0, v16
	v_max_f32_e32 v211, 0, v17
	v_pk_fma_f32 v[50:51], v[254:255], v[210:211], v[50:51]
	s_waitcnt lgkmcnt(1)
	v_mfma_f32_32x32x16_bf16 v[212:227], v[78:81], v[46:49], v[212:227]
	v_max_f32_e32 v108, 0, v18
	v_max_f32_e32 v109, 0, v19
	v_pk_fma_f32 v[50:51], v[200:201], v[108:109], v[50:51]
	v_max_f32_e32 v210, 0, v20
	v_max_f32_e32 v211, 0, v21
	v_pk_fma_f32 v[50:51], v[202:203], v[210:211], v[50:51]
	v_add_f32_e32 v50, v50, v51
	v_ashrrev_i32_e32 v51, 31, v50
	s_waitcnt lgkmcnt(0)
	v_mfma_f32_32x32x16_bf16 v[212:227], v[82:85], v[196:199], v[212:227]
	v_or_b32_e32 v51, 0x80000000, v51
	s_cmpk_gt_i32 s11, 272
	s_cselect_b64 vcc, -1, 0
	v_xor_b32_e32 v50, v51, v50
	v_cndmask_b32_e32 v50, v123, v50, vcc
	global_store_dword v243, v50, s[8:9]
	v_mfma_f32_32x32x16_bf16 v[6:21], v[86:89], v[38:41], 0
	s_add_i32 m0, s10, 65536
	s_nop 0
	global_load_lds_dwordx4 v102, s[6:7]
	s_add_i32 m0, s10, 66560
	s_nop 0
	global_load_lds_dwordx4 v110, s[6:7]
	s_add_i32 m0, s10, 67584
	s_nop 0
	global_load_lds_dwordx4 v112, s[6:7]
	s_add_i32 m0, s10, 68608
	s_nop 0
	global_load_lds_dwordx4 v193, s[6:7]
	s_add_u32 s6, s6, 0x8000
	s_addc_u32 s7, s7, 0
	v_max_f32_e32 v108, 0, v212
	v_max_f32_e32 v109, 0, v213
	v_pk_mul_f32 v[0:1], v[22:23], v[108:109]
	v_max_f32_e32 v210, 0, v214
	v_max_f32_e32 v211, 0, v215
	v_pk_fma_f32 v[0:1], v[24:25], v[210:211], v[0:1]
	v_max_f32_e32 v108, 0, v216
	v_max_f32_e32 v109, 0, v217
	v_pk_fma_f32 v[0:1], v[26:27], v[108:109], v[0:1]
	v_mfma_f32_32x32x16_bf16 v[6:21], v[90:93], v[42:45], v[6:21]
	v_max_f32_e32 v210, 0, v218
	v_max_f32_e32 v211, 0, v219
	v_pk_fma_f32 v[0:1], v[28:29], v[210:211], v[0:1]
	v_max_f32_e32 v108, 0, v220
	v_max_f32_e32 v109, 0, v221
	v_pk_fma_f32 v[0:1], v[30:31], v[108:109], v[0:1]
	v_max_f32_e32 v210, 0, v222
	v_max_f32_e32 v211, 0, v223
	v_pk_fma_f32 v[0:1], v[32:33], v[210:211], v[0:1]
	v_mfma_f32_32x32x16_bf16 v[6:21], v[94:97], v[46:49], v[6:21]
	v_max_f32_e32 v108, 0, v224
	v_max_f32_e32 v109, 0, v225
	v_pk_fma_f32 v[0:1], v[34:35], v[108:109], v[0:1]
	v_max_f32_e32 v210, 0, v226
	v_max_f32_e32 v211, 0, v227
	v_pk_fma_f32 v[0:1], v[36:37], v[210:211], v[0:1]
	v_add_f32_e32 v0, v0, v1
	v_ashrrev_i32_e32 v1, 31, v0
	v_mfma_f32_32x32x16_bf16 v[6:21], v[98:101], v[196:199], v[6:21]
	s_waitcnt vmcnt(10)
	ds_read_b128 v[38:41], v5 offset:10496
	ds_read_b128 v[42:45], v52 offset:10496
	ds_read_b128 v[46:49], v55 offset:10496
	ds_read_b128 v[196:199], v56 offset:10496
	v_or_b32_e32 v1, 0x80000000, v1
	s_cmpk_gt_i32 s11, 280
	s_cselect_b64 vcc, -1, 0
	v_xor_b32_e32 v0, v1, v0
	v_cndmask_b32_e32 v166, v123, v0, vcc
	s_nop 1
	s_waitcnt lgkmcnt(3)
	v_mfma_f32_32x32x16_bf16 v[212:227], v[70:73], v[38:41], 0
	v_max_f32_e32 v108, 0, v6
	v_max_f32_e32 v109, 0, v7
	v_pk_mul_f32 v[50:51], v[244:245], v[108:109]
	v_max_f32_e32 v210, 0, v8
	v_max_f32_e32 v211, 0, v9
	v_pk_fma_f32 v[50:51], v[246:247], v[210:211], v[50:51]
	v_max_f32_e32 v108, 0, v10
	v_max_f32_e32 v109, 0, v11
	v_pk_fma_f32 v[50:51], v[248:249], v[108:109], v[50:51]
	s_waitcnt lgkmcnt(2)
	v_mfma_f32_32x32x16_bf16 v[212:227], v[74:77], v[42:45], v[212:227]
	v_max_f32_e32 v210, 0, v12
	v_max_f32_e32 v211, 0, v13
	v_pk_fma_f32 v[50:51], v[250:251], v[210:211], v[50:51]
	v_max_f32_e32 v108, 0, v14
	v_max_f32_e32 v109, 0, v15
	v_pk_fma_f32 v[50:51], v[252:253], v[108:109], v[50:51]
	v_max_f32_e32 v210, 0, v16
	v_max_f32_e32 v211, 0, v17
	v_pk_fma_f32 v[50:51], v[254:255], v[210:211], v[50:51]
	s_waitcnt lgkmcnt(1)
	v_mfma_f32_32x32x16_bf16 v[212:227], v[78:81], v[46:49], v[212:227]
	v_max_f32_e32 v108, 0, v18
	v_max_f32_e32 v109, 0, v19
	v_pk_fma_f32 v[50:51], v[200:201], v[108:109], v[50:51]
	v_max_f32_e32 v210, 0, v20
	v_max_f32_e32 v211, 0, v21
	v_pk_fma_f32 v[50:51], v[202:203], v[210:211], v[50:51]
	v_add_f32_e32 v50, v50, v51
	v_ashrrev_i32_e32 v51, 31, v50
	s_waitcnt lgkmcnt(0)
	v_mfma_f32_32x32x16_bf16 v[212:227], v[82:85], v[196:199], v[212:227]
	v_or_b32_e32 v51, 0x80000000, v51
	s_cmpk_gt_i32 s11, 280
	s_cselect_b64 vcc, -1, 0
	v_xor_b32_e32 v50, v51, v50
	v_cndmask_b32_e32 v50, v123, v50, vcc
	global_store_dword v243, v50, s[8:9] offset:2048
	s_add_u32 s8, s8, 0x1000
	s_addc_u32 s9, s9, 0
	v_mfma_f32_32x32x16_bf16 v[6:21], v[86:89], v[38:41], 0
	s_add_i32 m0, s10, 98304
	s_nop 0
	global_load_lds_dwordx4 v102, s[6:7]
	s_add_i32 m0, s10, 99328
	s_nop 0
	global_load_lds_dwordx4 v110, s[6:7]
	s_add_i32 m0, s10, 100352
	s_nop 0
	global_load_lds_dwordx4 v112, s[6:7]
	s_add_i32 m0, s10, 101376
	s_nop 0
	global_load_lds_dwordx4 v193, s[6:7]
	s_add_u32 s6, s6, 0x8000
	s_addc_u32 s7, s7, 0
	v_max_f32_e32 v108, 0, v212
	v_max_f32_e32 v109, 0, v213
	v_pk_mul_f32 v[0:1], v[22:23], v[108:109]
	v_max_f32_e32 v210, 0, v214
	v_max_f32_e32 v211, 0, v215
	v_pk_fma_f32 v[0:1], v[24:25], v[210:211], v[0:1]
	v_max_f32_e32 v108, 0, v216
	v_max_f32_e32 v109, 0, v217
	v_pk_fma_f32 v[0:1], v[26:27], v[108:109], v[0:1]
	v_mfma_f32_32x32x16_bf16 v[6:21], v[90:93], v[42:45], v[6:21]
	v_max_f32_e32 v210, 0, v218
	v_max_f32_e32 v211, 0, v219
	v_pk_fma_f32 v[0:1], v[28:29], v[210:211], v[0:1]
	v_max_f32_e32 v108, 0, v220
	v_max_f32_e32 v109, 0, v221
	v_pk_fma_f32 v[0:1], v[30:31], v[108:109], v[0:1]
	v_max_f32_e32 v210, 0, v222
	v_max_f32_e32 v211, 0, v223
	v_pk_fma_f32 v[0:1], v[32:33], v[210:211], v[0:1]
	v_mfma_f32_32x32x16_bf16 v[6:21], v[94:97], v[46:49], v[6:21]
	v_max_f32_e32 v108, 0, v224
	v_max_f32_e32 v109, 0, v225
	v_pk_fma_f32 v[0:1], v[34:35], v[108:109], v[0:1]
	v_max_f32_e32 v210, 0, v226
	v_max_f32_e32 v211, 0, v227
	v_pk_fma_f32 v[0:1], v[36:37], v[210:211], v[0:1]
	v_add_f32_e32 v0, v0, v1
	v_ashrrev_i32_e32 v1, 31, v0
	v_mfma_f32_32x32x16_bf16 v[6:21], v[98:101], v[196:199], v[6:21]
	s_waitcnt vmcnt(10)
	ds_read_b128 v[38:41], v5 offset:43264
	ds_read_b128 v[42:45], v52 offset:43264
	ds_read_b128 v[46:49], v55 offset:43264
	ds_read_b128 v[196:199], v56 offset:43264
	v_or_b32_e32 v1, 0x80000000, v1
	s_cmpk_gt_i32 s11, 288
	s_cselect_b64 vcc, -1, 0
	v_xor_b32_e32 v0, v1, v0
	v_cndmask_b32_e32 v170, v123, v0, vcc
	s_nop 1
	s_waitcnt lgkmcnt(3)
	v_mfma_f32_32x32x16_bf16 v[212:227], v[70:73], v[38:41], 0
	v_max_f32_e32 v108, 0, v6
	v_max_f32_e32 v109, 0, v7
	v_pk_mul_f32 v[50:51], v[244:245], v[108:109]
	v_max_f32_e32 v210, 0, v8
	v_max_f32_e32 v211, 0, v9
	v_pk_fma_f32 v[50:51], v[246:247], v[210:211], v[50:51]
	v_max_f32_e32 v108, 0, v10
	v_max_f32_e32 v109, 0, v11
	v_pk_fma_f32 v[50:51], v[248:249], v[108:109], v[50:51]
	s_waitcnt lgkmcnt(2)
	v_mfma_f32_32x32x16_bf16 v[212:227], v[74:77], v[42:45], v[212:227]
	v_max_f32_e32 v210, 0, v12
	v_max_f32_e32 v211, 0, v13
	v_pk_fma_f32 v[50:51], v[250:251], v[210:211], v[50:51]
	v_max_f32_e32 v108, 0, v14
	v_max_f32_e32 v109, 0, v15
	v_pk_fma_f32 v[50:51], v[252:253], v[108:109], v[50:51]
	v_max_f32_e32 v210, 0, v16
	v_max_f32_e32 v211, 0, v17
	v_pk_fma_f32 v[50:51], v[254:255], v[210:211], v[50:51]
	s_waitcnt lgkmcnt(1)
	v_mfma_f32_32x32x16_bf16 v[212:227], v[78:81], v[46:49], v[212:227]
	v_max_f32_e32 v108, 0, v18
	v_max_f32_e32 v109, 0, v19
	v_pk_fma_f32 v[50:51], v[200:201], v[108:109], v[50:51]
	v_max_f32_e32 v210, 0, v20
	v_max_f32_e32 v211, 0, v21
	v_pk_fma_f32 v[50:51], v[202:203], v[210:211], v[50:51]
	v_add_f32_e32 v50, v50, v51
	v_ashrrev_i32_e32 v51, 31, v50
	s_waitcnt lgkmcnt(0)
	v_mfma_f32_32x32x16_bf16 v[212:227], v[82:85], v[196:199], v[212:227]
	v_or_b32_e32 v51, 0x80000000, v51
	s_cmpk_gt_i32 s11, 288
	s_cselect_b64 vcc, -1, 0
	v_xor_b32_e32 v50, v51, v50
	v_cndmask_b32_e32 v50, v123, v50, vcc
	global_store_dword v243, v50, s[8:9]
	v_mfma_f32_32x32x16_bf16 v[6:21], v[86:89], v[38:41], 0
	s_add_i32 m0, s10, 0
	s_nop 0
	global_load_lds_dwordx4 v102, s[6:7]
	s_add_i32 m0, s10, 1024
	s_nop 0
	global_load_lds_dwordx4 v110, s[6:7]
	s_add_i32 m0, s10, 2048
	s_nop 0
	global_load_lds_dwordx4 v112, s[6:7]
	s_add_i32 m0, s10, 3072
	s_nop 0
	global_load_lds_dwordx4 v193, s[6:7]
	s_add_u32 s6, s6, 0x8000
	s_addc_u32 s7, s7, 0
	v_max_f32_e32 v108, 0, v212
	v_max_f32_e32 v109, 0, v213
	v_pk_mul_f32 v[0:1], v[22:23], v[108:109]
	v_max_f32_e32 v210, 0, v214
	v_max_f32_e32 v211, 0, v215
	v_pk_fma_f32 v[0:1], v[24:25], v[210:211], v[0:1]
	v_max_f32_e32 v108, 0, v216
	v_max_f32_e32 v109, 0, v217
	v_pk_fma_f32 v[0:1], v[26:27], v[108:109], v[0:1]
	v_mfma_f32_32x32x16_bf16 v[6:21], v[90:93], v[42:45], v[6:21]
	v_max_f32_e32 v210, 0, v218
	v_max_f32_e32 v211, 0, v219
	v_pk_fma_f32 v[0:1], v[28:29], v[210:211], v[0:1]
	v_max_f32_e32 v108, 0, v220
	v_max_f32_e32 v109, 0, v221
	v_pk_fma_f32 v[0:1], v[30:31], v[108:109], v[0:1]
	v_max_f32_e32 v210, 0, v222
	v_max_f32_e32 v211, 0, v223
	v_pk_fma_f32 v[0:1], v[32:33], v[210:211], v[0:1]
	v_mfma_f32_32x32x16_bf16 v[6:21], v[94:97], v[46:49], v[6:21]
	v_max_f32_e32 v108, 0, v224
	v_max_f32_e32 v109, 0, v225
	v_pk_fma_f32 v[0:1], v[34:35], v[108:109], v[0:1]
	v_max_f32_e32 v210, 0, v226
	v_max_f32_e32 v211, 0, v227
	v_pk_fma_f32 v[0:1], v[36:37], v[210:211], v[0:1]
	v_add_f32_e32 v0, v0, v1
	v_ashrrev_i32_e32 v1, 31, v0
	v_mfma_f32_32x32x16_bf16 v[6:21], v[98:101], v[196:199], v[6:21]
	s_waitcnt vmcnt(10)
	v_add_u32_e32 v228, 0x10000, v5
	ds_read_b128 v[38:41], v228 offset:10496
	v_add_u32_e32 v228, 0x10000, v52
	ds_read_b128 v[42:45], v228 offset:10496
	v_add_u32_e32 v228, 0x10000, v55
	ds_read_b128 v[46:49], v228 offset:10496
	v_add_u32_e32 v228, 0x10000, v56
	ds_read_b128 v[196:199], v228 offset:10496
	v_or_b32_e32 v1, 0x80000000, v1
	s_cmpk_gt_i32 s11, 296
	s_cselect_b64 vcc, -1, 0
	v_xor_b32_e32 v0, v1, v0
	v_cndmask_b32_e32 v169, v123, v0, vcc
	s_nop 1
	s_waitcnt lgkmcnt(3)
	v_mfma_f32_32x32x16_bf16 v[212:227], v[70:73], v[38:41], 0
	v_max_f32_e32 v108, 0, v6
	v_max_f32_e32 v109, 0, v7
	v_pk_mul_f32 v[50:51], v[244:245], v[108:109]
	v_max_f32_e32 v210, 0, v8
	v_max_f32_e32 v211, 0, v9
	v_pk_fma_f32 v[50:51], v[246:247], v[210:211], v[50:51]
	v_max_f32_e32 v108, 0, v10
	v_max_f32_e32 v109, 0, v11
	v_pk_fma_f32 v[50:51], v[248:249], v[108:109], v[50:51]
	s_waitcnt lgkmcnt(2)
	v_mfma_f32_32x32x16_bf16 v[212:227], v[74:77], v[42:45], v[212:227]
	v_max_f32_e32 v210, 0, v12
	v_max_f32_e32 v211, 0, v13
	v_pk_fma_f32 v[50:51], v[250:251], v[210:211], v[50:51]
	v_max_f32_e32 v108, 0, v14
	v_max_f32_e32 v109, 0, v15
	v_pk_fma_f32 v[50:51], v[252:253], v[108:109], v[50:51]
	v_max_f32_e32 v210, 0, v16
	v_max_f32_e32 v211, 0, v17
	v_pk_fma_f32 v[50:51], v[254:255], v[210:211], v[50:51]
	s_waitcnt lgkmcnt(1)
	v_mfma_f32_32x32x16_bf16 v[212:227], v[78:81], v[46:49], v[212:227]
	v_max_f32_e32 v108, 0, v18
	v_max_f32_e32 v109, 0, v19
	v_pk_fma_f32 v[50:51], v[200:201], v[108:109], v[50:51]
	v_max_f32_e32 v210, 0, v20
	v_max_f32_e32 v211, 0, v21
	v_pk_fma_f32 v[50:51], v[202:203], v[210:211], v[50:51]
	v_add_f32_e32 v50, v50, v51
	v_ashrrev_i32_e32 v51, 31, v50
	s_waitcnt lgkmcnt(0)
	v_mfma_f32_32x32x16_bf16 v[212:227], v[82:85], v[196:199], v[212:227]
	v_or_b32_e32 v51, 0x80000000, v51
	s_cmpk_gt_i32 s11, 296
	s_cselect_b64 vcc, -1, 0
	v_xor_b32_e32 v50, v51, v50
	v_cndmask_b32_e32 v50, v123, v50, vcc
	global_store_dword v243, v50, s[8:9] offset:2048
	s_add_u32 s8, s8, 0x1000
	s_addc_u32 s9, s9, 0
	v_mfma_f32_32x32x16_bf16 v[6:21], v[86:89], v[38:41], 0
	s_add_i32 m0, s10, 32768
	s_nop 0
	global_load_lds_dwordx4 v102, s[6:7]
	s_add_i32 m0, s10, 33792
	s_nop 0
	global_load_lds_dwordx4 v110, s[6:7]
	s_add_i32 m0, s10, 34816
	s_nop 0
	global_load_lds_dwordx4 v112, s[6:7]
	s_add_i32 m0, s10, 35840
	s_nop 0
	global_load_lds_dwordx4 v193, s[6:7]
	s_add_u32 s6, s6, 0x8000
	s_addc_u32 s7, s7, 0
	v_max_f32_e32 v108, 0, v212
	v_max_f32_e32 v109, 0, v213
	v_pk_mul_f32 v[0:1], v[22:23], v[108:109]
	v_max_f32_e32 v210, 0, v214
	v_max_f32_e32 v211, 0, v215
	v_pk_fma_f32 v[0:1], v[24:25], v[210:211], v[0:1]
	v_max_f32_e32 v108, 0, v216
	v_max_f32_e32 v109, 0, v217
	v_pk_fma_f32 v[0:1], v[26:27], v[108:109], v[0:1]
	v_mfma_f32_32x32x16_bf16 v[6:21], v[90:93], v[42:45], v[6:21]
	v_max_f32_e32 v210, 0, v218
	v_max_f32_e32 v211, 0, v219
	v_pk_fma_f32 v[0:1], v[28:29], v[210:211], v[0:1]
	v_max_f32_e32 v108, 0, v220
	v_max_f32_e32 v109, 0, v221
	v_pk_fma_f32 v[0:1], v[30:31], v[108:109], v[0:1]
	v_max_f32_e32 v210, 0, v222
	v_max_f32_e32 v211, 0, v223
	v_pk_fma_f32 v[0:1], v[32:33], v[210:211], v[0:1]
	v_mfma_f32_32x32x16_bf16 v[6:21], v[94:97], v[46:49], v[6:21]
	v_max_f32_e32 v108, 0, v224
	v_max_f32_e32 v109, 0, v225
	v_pk_fma_f32 v[0:1], v[34:35], v[108:109], v[0:1]
	v_max_f32_e32 v210, 0, v226
	v_max_f32_e32 v211, 0, v227
	v_pk_fma_f32 v[0:1], v[36:37], v[210:211], v[0:1]
	v_add_f32_e32 v0, v0, v1
	v_ashrrev_i32_e32 v1, 31, v0
	v_mfma_f32_32x32x16_bf16 v[6:21], v[98:101], v[196:199], v[6:21]
	s_waitcnt vmcnt(10)
	v_add_u32_e32 v228, 0x10000, v5
	ds_read_b128 v[38:41], v228 offset:43264
	v_add_u32_e32 v228, 0x10000, v52
	ds_read_b128 v[42:45], v228 offset:43264
	v_add_u32_e32 v228, 0x10000, v55
	ds_read_b128 v[46:49], v228 offset:43264
	v_add_u32_e32 v228, 0x10000, v56
	ds_read_b128 v[196:199], v228 offset:43264
	v_or_b32_e32 v1, 0x80000000, v1
	s_cmpk_gt_i32 s11, 304
	s_cselect_b64 vcc, -1, 0
	v_xor_b32_e32 v0, v1, v0
	v_cndmask_b32_e32 v172, v123, v0, vcc
	s_nop 1
	s_waitcnt lgkmcnt(3)
	v_mfma_f32_32x32x16_bf16 v[212:227], v[70:73], v[38:41], 0
	v_max_f32_e32 v108, 0, v6
	v_max_f32_e32 v109, 0, v7
	v_pk_mul_f32 v[50:51], v[244:245], v[108:109]
	v_max_f32_e32 v210, 0, v8
	v_max_f32_e32 v211, 0, v9
	v_pk_fma_f32 v[50:51], v[246:247], v[210:211], v[50:51]
	v_max_f32_e32 v108, 0, v10
	v_max_f32_e32 v109, 0, v11
	v_pk_fma_f32 v[50:51], v[248:249], v[108:109], v[50:51]
	s_waitcnt lgkmcnt(2)
	v_mfma_f32_32x32x16_bf16 v[212:227], v[74:77], v[42:45], v[212:227]
	v_max_f32_e32 v210, 0, v12
	v_max_f32_e32 v211, 0, v13
	v_pk_fma_f32 v[50:51], v[250:251], v[210:211], v[50:51]
	v_max_f32_e32 v108, 0, v14
	v_max_f32_e32 v109, 0, v15
	v_pk_fma_f32 v[50:51], v[252:253], v[108:109], v[50:51]
	v_max_f32_e32 v210, 0, v16
	v_max_f32_e32 v211, 0, v17
	v_pk_fma_f32 v[50:51], v[254:255], v[210:211], v[50:51]
	s_waitcnt lgkmcnt(1)
	v_mfma_f32_32x32x16_bf16 v[212:227], v[78:81], v[46:49], v[212:227]
	v_max_f32_e32 v108, 0, v18
	v_max_f32_e32 v109, 0, v19
	v_pk_fma_f32 v[50:51], v[200:201], v[108:109], v[50:51]
	v_max_f32_e32 v210, 0, v20
	v_max_f32_e32 v211, 0, v21
	v_pk_fma_f32 v[50:51], v[202:203], v[210:211], v[50:51]
	v_add_f32_e32 v50, v50, v51
	v_ashrrev_i32_e32 v51, 31, v50
	s_waitcnt lgkmcnt(0)
	v_mfma_f32_32x32x16_bf16 v[212:227], v[82:85], v[196:199], v[212:227]
	v_or_b32_e32 v51, 0x80000000, v51
	s_cmpk_gt_i32 s11, 304
	s_cselect_b64 vcc, -1, 0
	v_xor_b32_e32 v50, v51, v50
	v_cndmask_b32_e32 v50, v123, v50, vcc
	global_store_dword v243, v50, s[8:9]
	v_mfma_f32_32x32x16_bf16 v[6:21], v[86:89], v[38:41], 0
	s_add_i32 m0, s10, 65536
	s_nop 0
	global_load_lds_dwordx4 v102, s[6:7]
	s_add_i32 m0, s10, 66560
	s_nop 0
	global_load_lds_dwordx4 v110, s[6:7]
	s_add_i32 m0, s10, 67584
	s_nop 0
	global_load_lds_dwordx4 v112, s[6:7]
	s_add_i32 m0, s10, 68608
	s_nop 0
	global_load_lds_dwordx4 v193, s[6:7]
	s_add_u32 s6, s6, 0x8000
	s_addc_u32 s7, s7, 0
	v_max_f32_e32 v108, 0, v212
	v_max_f32_e32 v109, 0, v213
	v_pk_mul_f32 v[0:1], v[22:23], v[108:109]
	v_max_f32_e32 v210, 0, v214
	v_max_f32_e32 v211, 0, v215
	v_pk_fma_f32 v[0:1], v[24:25], v[210:211], v[0:1]
	v_max_f32_e32 v108, 0, v216
	v_max_f32_e32 v109, 0, v217
	v_pk_fma_f32 v[0:1], v[26:27], v[108:109], v[0:1]
	v_mfma_f32_32x32x16_bf16 v[6:21], v[90:93], v[42:45], v[6:21]
	v_max_f32_e32 v210, 0, v218
	v_max_f32_e32 v211, 0, v219
	v_pk_fma_f32 v[0:1], v[28:29], v[210:211], v[0:1]
	v_max_f32_e32 v108, 0, v220
	v_max_f32_e32 v109, 0, v221
	v_pk_fma_f32 v[0:1], v[30:31], v[108:109], v[0:1]
	v_max_f32_e32 v210, 0, v222
	v_max_f32_e32 v211, 0, v223
	v_pk_fma_f32 v[0:1], v[32:33], v[210:211], v[0:1]
	v_mfma_f32_32x32x16_bf16 v[6:21], v[94:97], v[46:49], v[6:21]
	v_max_f32_e32 v108, 0, v224
	v_max_f32_e32 v109, 0, v225
	v_pk_fma_f32 v[0:1], v[34:35], v[108:109], v[0:1]
	v_max_f32_e32 v210, 0, v226
	v_max_f32_e32 v211, 0, v227
	v_pk_fma_f32 v[0:1], v[36:37], v[210:211], v[0:1]
	v_add_f32_e32 v0, v0, v1
	v_ashrrev_i32_e32 v1, 31, v0
	v_mfma_f32_32x32x16_bf16 v[6:21], v[98:101], v[196:199], v[6:21]
	s_waitcnt vmcnt(10)
	ds_read_b128 v[38:41], v5 offset:10496
	ds_read_b128 v[42:45], v52 offset:10496
	ds_read_b128 v[46:49], v55 offset:10496
	ds_read_b128 v[196:199], v56 offset:10496
	v_or_b32_e32 v1, 0x80000000, v1
	s_cmpk_gt_i32 s11, 312
	s_cselect_b64 vcc, -1, 0
	v_xor_b32_e32 v0, v1, v0
	v_cndmask_b32_e32 v171, v123, v0, vcc
	s_nop 1
	v_max_f32_e32 v108, 0, v6
	v_max_f32_e32 v109, 0, v7
	v_pk_mul_f32 v[50:51], v[244:245], v[108:109]
	v_max_f32_e32 v210, 0, v8
	v_max_f32_e32 v211, 0, v9
	v_pk_fma_f32 v[50:51], v[246:247], v[210:211], v[50:51]
	v_max_f32_e32 v108, 0, v10
	v_max_f32_e32 v109, 0, v11
	v_pk_fma_f32 v[50:51], v[248:249], v[108:109], v[50:51]
	v_max_f32_e32 v210, 0, v12
	v_max_f32_e32 v211, 0, v13
	v_pk_fma_f32 v[50:51], v[250:251], v[210:211], v[50:51]
	v_max_f32_e32 v108, 0, v14
	v_max_f32_e32 v109, 0, v15
	v_pk_fma_f32 v[50:51], v[252:253], v[108:109], v[50:51]
	v_max_f32_e32 v210, 0, v16
	v_max_f32_e32 v211, 0, v17
	v_pk_fma_f32 v[50:51], v[254:255], v[210:211], v[50:51]
	v_max_f32_e32 v108, 0, v18
	v_max_f32_e32 v109, 0, v19
	v_pk_fma_f32 v[50:51], v[200:201], v[108:109], v[50:51]
	v_max_f32_e32 v210, 0, v20
	v_max_f32_e32 v211, 0, v21
	v_pk_fma_f32 v[50:51], v[202:203], v[210:211], v[50:51]
	v_add_f32_e32 v50, v50, v51
	v_ashrrev_i32_e32 v51, 31, v50
	v_or_b32_e32 v51, 0x80000000, v51
	s_cmpk_gt_i32 s11, 312
	s_cselect_b64 vcc, -1, 0
	v_xor_b32_e32 v50, v51, v50
	v_cndmask_b32_e32 v50, v123, v50, vcc
	global_store_dword v243, v50, s[8:9] offset:2048
	s_add_u32 s8, s8, 0x1000
	s_addc_u32 s9, s9, 0
	s_cmpk_gt_i32 s81, 40
	s_cbranch_scc0 .Lix_fill_5
	s_waitcnt lgkmcnt(3)
	v_mfma_f32_32x32x16_bf16 v[212:227], v[70:73], v[38:41], 0
	s_add_i32 m0, s10, 98304
	s_nop 0
	global_load_lds_dwordx4 v102, s[6:7]
	s_waitcnt lgkmcnt(2)
	v_mfma_f32_32x32x16_bf16 v[212:227], v[74:77], v[42:45], v[212:227]
	s_add_i32 m0, s10, 99328
	s_nop 0
	global_load_lds_dwordx4 v110, s[6:7]
	s_waitcnt lgkmcnt(1)
	v_mfma_f32_32x32x16_bf16 v[212:227], v[78:81], v[46:49], v[212:227]
	s_add_i32 m0, s10, 100352
	s_nop 0
	global_load_lds_dwordx4 v112, s[6:7]
	s_waitcnt lgkmcnt(0)
	v_mfma_f32_32x32x16_bf16 v[212:227], v[82:85], v[196:199], v[212:227]
	s_add_i32 m0, s10, 101376
	s_nop 0
	global_load_lds_dwordx4 v193, s[6:7]
	s_add_u32 s6, s6, 0x8000
	s_addc_u32 s7, s7, 0
	v_mfma_f32_32x32x16_bf16 v[6:21], v[86:89], v[38:41], 0
	s_nop 7
	s_nop 2
	v_max_f32_e32 v108, 0, v212
	v_max_f32_e32 v109, 0, v213
	v_pk_mul_f32 v[0:1], v[22:23], v[108:109]
	v_max_f32_e32 v210, 0, v214
	v_max_f32_e32 v211, 0, v215
	v_pk_fma_f32 v[0:1], v[24:25], v[210:211], v[0:1]
	v_max_f32_e32 v108, 0, v216
	v_max_f32_e32 v109, 0, v217
	v_pk_fma_f32 v[0:1], v[26:27], v[108:109], v[0:1]
	v_mfma_f32_32x32x16_bf16 v[6:21], v[90:93], v[42:45], v[6:21]
	v_max_f32_e32 v210, 0, v218
	v_max_f32_e32 v211, 0, v219
	v_pk_fma_f32 v[0:1], v[28:29], v[210:211], v[0:1]
	v_max_f32_e32 v108, 0, v220
	v_max_f32_e32 v109, 0, v221
	v_pk_fma_f32 v[0:1], v[30:31], v[108:109], v[0:1]
	v_max_f32_e32 v210, 0, v222
	v_max_f32_e32 v211, 0, v223
	v_pk_fma_f32 v[0:1], v[32:33], v[210:211], v[0:1]
	v_mfma_f32_32x32x16_bf16 v[6:21], v[94:97], v[46:49], v[6:21]
	v_max_f32_e32 v108, 0, v224
	v_max_f32_e32 v109, 0, v225
	v_pk_fma_f32 v[0:1], v[34:35], v[108:109], v[0:1]
	v_max_f32_e32 v210, 0, v226
	v_max_f32_e32 v211, 0, v227
	v_pk_fma_f32 v[0:1], v[36:37], v[210:211], v[0:1]
	v_add_f32_e32 v0, v0, v1
	v_ashrrev_i32_e32 v1, 31, v0
	v_mfma_f32_32x32x16_bf16 v[6:21], v[98:101], v[196:199], v[6:21]
	s_waitcnt vmcnt(10)
	ds_read_b128 v[38:41], v5 offset:43264
	ds_read_b128 v[42:45], v52 offset:43264
	ds_read_b128 v[46:49], v55 offset:43264
	ds_read_b128 v[196:199], v56 offset:43264
	v_or_b32_e32 v1, 0x80000000, v1
	s_cmpk_gt_i32 s11, 320
	s_cselect_b64 vcc, -1, 0
	v_xor_b32_e32 v0, v1, v0
	v_cndmask_b32_e32 v174, v123, v0, vcc
	s_nop 1
	s_waitcnt lgkmcnt(3)
	v_mfma_f32_32x32x16_bf16 v[212:227], v[70:73], v[38:41], 0
	v_max_f32_e32 v108, 0, v6
	v_max_f32_e32 v109, 0, v7
	v_pk_mul_f32 v[50:51], v[244:245], v[108:109]
	v_max_f32_e32 v210, 0, v8
	v_max_f32_e32 v211, 0, v9
	v_pk_fma_f32 v[50:51], v[246:247], v[210:211], v[50:51]
	v_max_f32_e32 v108, 0, v10
	v_max_f32_e32 v109, 0, v11
	v_pk_fma_f32 v[50:51], v[248:249], v[108:109], v[50:51]
	s_waitcnt lgkmcnt(2)
	v_mfma_f32_32x32x16_bf16 v[212:227], v[74:77], v[42:45], v[212:227]
	v_max_f32_e32 v210, 0, v12
	v_max_f32_e32 v211, 0, v13
	v_pk_fma_f32 v[50:51], v[250:251], v[210:211], v[50:51]
	v_max_f32_e32 v108, 0, v14
	v_max_f32_e32 v109, 0, v15
	v_pk_fma_f32 v[50:51], v[252:253], v[108:109], v[50:51]
	v_max_f32_e32 v210, 0, v16
	v_max_f32_e32 v211, 0, v17
	v_pk_fma_f32 v[50:51], v[254:255], v[210:211], v[50:51]
	s_waitcnt lgkmcnt(1)
	v_mfma_f32_32x32x16_bf16 v[212:227], v[78:81], v[46:49], v[212:227]
	v_max_f32_e32 v108, 0, v18
	v_max_f32_e32 v109, 0, v19
	v_pk_fma_f32 v[50:51], v[200:201], v[108:109], v[50:51]
	v_max_f32_e32 v210, 0, v20
	v_max_f32_e32 v211, 0, v21
	v_pk_fma_f32 v[50:51], v[202:203], v[210:211], v[50:51]
	v_add_f32_e32 v50, v50, v51
	v_ashrrev_i32_e32 v51, 31, v50
	s_waitcnt lgkmcnt(0)
	v_mfma_f32_32x32x16_bf16 v[212:227], v[82:85], v[196:199], v[212:227]
	v_or_b32_e32 v51, 0x80000000, v51
	s_cmpk_gt_i32 s11, 320
	s_cselect_b64 vcc, -1, 0
	v_xor_b32_e32 v50, v51, v50
	v_cndmask_b32_e32 v50, v123, v50, vcc
	global_store_dword v243, v50, s[8:9]
	v_mfma_f32_32x32x16_bf16 v[6:21], v[86:89], v[38:41], 0
	s_add_i32 m0, s10, 0
	s_nop 0
	global_load_lds_dwordx4 v102, s[6:7]
	s_add_i32 m0, s10, 1024
	s_nop 0
	global_load_lds_dwordx4 v110, s[6:7]
	s_add_i32 m0, s10, 2048
	s_nop 0
	global_load_lds_dwordx4 v112, s[6:7]
	s_add_i32 m0, s10, 3072
	s_nop 0
	global_load_lds_dwordx4 v193, s[6:7]
	s_add_u32 s6, s6, 0x8000
	s_addc_u32 s7, s7, 0
	v_max_f32_e32 v108, 0, v212
	v_max_f32_e32 v109, 0, v213
	v_pk_mul_f32 v[0:1], v[22:23], v[108:109]
	v_max_f32_e32 v210, 0, v214
	v_max_f32_e32 v211, 0, v215
	v_pk_fma_f32 v[0:1], v[24:25], v[210:211], v[0:1]
	v_max_f32_e32 v108, 0, v216
	v_max_f32_e32 v109, 0, v217
	v_pk_fma_f32 v[0:1], v[26:27], v[108:109], v[0:1]
	v_mfma_f32_32x32x16_bf16 v[6:21], v[90:93], v[42:45], v[6:21]
	v_max_f32_e32 v210, 0, v218
	v_max_f32_e32 v211, 0, v219
	v_pk_fma_f32 v[0:1], v[28:29], v[210:211], v[0:1]
	v_max_f32_e32 v108, 0, v220
	v_max_f32_e32 v109, 0, v221
	v_pk_fma_f32 v[0:1], v[30:31], v[108:109], v[0:1]
	v_max_f32_e32 v210, 0, v222
	v_max_f32_e32 v211, 0, v223
	v_pk_fma_f32 v[0:1], v[32:33], v[210:211], v[0:1]
	v_mfma_f32_32x32x16_bf16 v[6:21], v[94:97], v[46:49], v[6:21]
	v_max_f32_e32 v108, 0, v224
	v_max_f32_e32 v109, 0, v225
	v_pk_fma_f32 v[0:1], v[34:35], v[108:109], v[0:1]
	v_max_f32_e32 v210, 0, v226
	v_max_f32_e32 v211, 0, v227
	v_pk_fma_f32 v[0:1], v[36:37], v[210:211], v[0:1]
	v_add_f32_e32 v0, v0, v1
	v_ashrrev_i32_e32 v1, 31, v0
	v_mfma_f32_32x32x16_bf16 v[6:21], v[98:101], v[196:199], v[6:21]
	s_waitcnt vmcnt(10)
	v_add_u32_e32 v228, 0x10000, v5
	ds_read_b128 v[38:41], v228 offset:10496
	v_add_u32_e32 v228, 0x10000, v52
	ds_read_b128 v[42:45], v228 offset:10496
	v_add_u32_e32 v228, 0x10000, v55
	ds_read_b128 v[46:49], v228 offset:10496
	v_add_u32_e32 v228, 0x10000, v56
	ds_read_b128 v[196:199], v228 offset:10496
	v_or_b32_e32 v1, 0x80000000, v1
	s_cmpk_gt_i32 s11, 328
	s_cselect_b64 vcc, -1, 0
	v_xor_b32_e32 v0, v1, v0
	v_cndmask_b32_e32 v173, v123, v0, vcc
	s_nop 1
	s_waitcnt lgkmcnt(3)
	v_mfma_f32_32x32x16_bf16 v[212:227], v[70:73], v[38:41], 0
	v_max_f32_e32 v108, 0, v6
	v_max_f32_e32 v109, 0, v7
	v_pk_mul_f32 v[50:51], v[244:245], v[108:109]
	v_max_f32_e32 v210, 0, v8
	v_max_f32_e32 v211, 0, v9
	v_pk_fma_f32 v[50:51], v[246:247], v[210:211], v[50:51]
	v_max_f32_e32 v108, 0, v10
	v_max_f32_e32 v109, 0, v11
	v_pk_fma_f32 v[50:51], v[248:249], v[108:109], v[50:51]
	s_waitcnt lgkmcnt(2)
	v_mfma_f32_32x32x16_bf16 v[212:227], v[74:77], v[42:45], v[212:227]
	v_max_f32_e32 v210, 0, v12
	v_max_f32_e32 v211, 0, v13
	v_pk_fma_f32 v[50:51], v[250:251], v[210:211], v[50:51]
	v_max_f32_e32 v108, 0, v14
	v_max_f32_e32 v109, 0, v15
	v_pk_fma_f32 v[50:51], v[252:253], v[108:109], v[50:51]
	v_max_f32_e32 v210, 0, v16
	v_max_f32_e32 v211, 0, v17
	v_pk_fma_f32 v[50:51], v[254:255], v[210:211], v[50:51]
	s_waitcnt lgkmcnt(1)
	v_mfma_f32_32x32x16_bf16 v[212:227], v[78:81], v[46:49], v[212:227]
	v_max_f32_e32 v108, 0, v18
	v_max_f32_e32 v109, 0, v19
	v_pk_fma_f32 v[50:51], v[200:201], v[108:109], v[50:51]
	v_max_f32_e32 v210, 0, v20
	v_max_f32_e32 v211, 0, v21
	v_pk_fma_f32 v[50:51], v[202:203], v[210:211], v[50:51]
	v_add_f32_e32 v50, v50, v51
	v_ashrrev_i32_e32 v51, 31, v50
	s_waitcnt lgkmcnt(0)
	v_mfma_f32_32x32x16_bf16 v[212:227], v[82:85], v[196:199], v[212:227]
	v_or_b32_e32 v51, 0x80000000, v51
	s_cmpk_gt_i32 s11, 328
	s_cselect_b64 vcc, -1, 0
	v_xor_b32_e32 v50, v51, v50
	v_cndmask_b32_e32 v50, v123, v50, vcc
	global_store_dword v243, v50, s[8:9] offset:2048
	s_add_u32 s8, s8, 0x1000
	s_addc_u32 s9, s9, 0
	v_mfma_f32_32x32x16_bf16 v[6:21], v[86:89], v[38:41], 0
	s_add_i32 m0, s10, 32768
	s_nop 0
	global_load_lds_dwordx4 v102, s[6:7]
	s_add_i32 m0, s10, 33792
	s_nop 0
	global_load_lds_dwordx4 v110, s[6:7]
	s_add_i32 m0, s10, 34816
	s_nop 0
	global_load_lds_dwordx4 v112, s[6:7]
	s_add_i32 m0, s10, 35840
	s_nop 0
	global_load_lds_dwordx4 v193, s[6:7]
	s_add_u32 s6, s6, 0x8000
	s_addc_u32 s7, s7, 0
	v_max_f32_e32 v108, 0, v212
	v_max_f32_e32 v109, 0, v213
	v_pk_mul_f32 v[0:1], v[22:23], v[108:109]
	v_max_f32_e32 v210, 0, v214
	v_max_f32_e32 v211, 0, v215
	v_pk_fma_f32 v[0:1], v[24:25], v[210:211], v[0:1]
	v_max_f32_e32 v108, 0, v216
	v_max_f32_e32 v109, 0, v217
	v_pk_fma_f32 v[0:1], v[26:27], v[108:109], v[0:1]
	v_mfma_f32_32x32x16_bf16 v[6:21], v[90:93], v[42:45], v[6:21]
	v_max_f32_e32 v210, 0, v218
	v_max_f32_e32 v211, 0, v219
	v_pk_fma_f32 v[0:1], v[28:29], v[210:211], v[0:1]
	v_max_f32_e32 v108, 0, v220
	v_max_f32_e32 v109, 0, v221
	v_pk_fma_f32 v[0:1], v[30:31], v[108:109], v[0:1]
	v_max_f32_e32 v210, 0, v222
	v_max_f32_e32 v211, 0, v223
	v_pk_fma_f32 v[0:1], v[32:33], v[210:211], v[0:1]
	v_mfma_f32_32x32x16_bf16 v[6:21], v[94:97], v[46:49], v[6:21]
	v_max_f32_e32 v108, 0, v224
	v_max_f32_e32 v109, 0, v225
	v_pk_fma_f32 v[0:1], v[34:35], v[108:109], v[0:1]
	v_max_f32_e32 v210, 0, v226
	v_max_f32_e32 v211, 0, v227
	v_pk_fma_f32 v[0:1], v[36:37], v[210:211], v[0:1]
	v_add_f32_e32 v0, v0, v1
	v_ashrrev_i32_e32 v1, 31, v0
	v_mfma_f32_32x32x16_bf16 v[6:21], v[98:101], v[196:199], v[6:21]
	s_waitcnt vmcnt(10)
	v_add_u32_e32 v228, 0x10000, v5
	ds_read_b128 v[38:41], v228 offset:43264
	v_add_u32_e32 v228, 0x10000, v52
	ds_read_b128 v[42:45], v228 offset:43264
	v_add_u32_e32 v228, 0x10000, v55
	ds_read_b128 v[46:49], v228 offset:43264
	v_add_u32_e32 v228, 0x10000, v56
	ds_read_b128 v[196:199], v228 offset:43264
	v_or_b32_e32 v1, 0x80000000, v1
	s_cmpk_gt_i32 s11, 336
	s_cselect_b64 vcc, -1, 0
	v_xor_b32_e32 v0, v1, v0
	v_cndmask_b32_e32 v176, v123, v0, vcc
	s_nop 1
	s_waitcnt lgkmcnt(3)
	v_mfma_f32_32x32x16_bf16 v[212:227], v[70:73], v[38:41], 0
	v_max_f32_e32 v108, 0, v6
	v_max_f32_e32 v109, 0, v7
	v_pk_mul_f32 v[50:51], v[244:245], v[108:109]
	v_max_f32_e32 v210, 0, v8
	v_max_f32_e32 v211, 0, v9
	v_pk_fma_f32 v[50:51], v[246:247], v[210:211], v[50:51]
	v_max_f32_e32 v108, 0, v10
	v_max_f32_e32 v109, 0, v11
	v_pk_fma_f32 v[50:51], v[248:249], v[108:109], v[50:51]
	s_waitcnt lgkmcnt(2)
	v_mfma_f32_32x32x16_bf16 v[212:227], v[74:77], v[42:45], v[212:227]
	v_max_f32_e32 v210, 0, v12
	v_max_f32_e32 v211, 0, v13
	v_pk_fma_f32 v[50:51], v[250:251], v[210:211], v[50:51]
	v_max_f32_e32 v108, 0, v14
	v_max_f32_e32 v109, 0, v15
	v_pk_fma_f32 v[50:51], v[252:253], v[108:109], v[50:51]
	v_max_f32_e32 v210, 0, v16
	v_max_f32_e32 v211, 0, v17
	v_pk_fma_f32 v[50:51], v[254:255], v[210:211], v[50:51]
	s_waitcnt lgkmcnt(1)
	v_mfma_f32_32x32x16_bf16 v[212:227], v[78:81], v[46:49], v[212:227]
	v_max_f32_e32 v108, 0, v18
	v_max_f32_e32 v109, 0, v19
	v_pk_fma_f32 v[50:51], v[200:201], v[108:109], v[50:51]
	v_max_f32_e32 v210, 0, v20
	v_max_f32_e32 v211, 0, v21
	v_pk_fma_f32 v[50:51], v[202:203], v[210:211], v[50:51]
	v_add_f32_e32 v50, v50, v51
	v_ashrrev_i32_e32 v51, 31, v50
	s_waitcnt lgkmcnt(0)
	v_mfma_f32_32x32x16_bf16 v[212:227], v[82:85], v[196:199], v[212:227]
	v_or_b32_e32 v51, 0x80000000, v51
	s_cmpk_gt_i32 s11, 336
	s_cselect_b64 vcc, -1, 0
	v_xor_b32_e32 v50, v51, v50
	v_cndmask_b32_e32 v50, v123, v50, vcc
	global_store_dword v243, v50, s[8:9]
	v_mfma_f32_32x32x16_bf16 v[6:21], v[86:89], v[38:41], 0
	s_add_i32 m0, s10, 65536
	s_nop 0
	global_load_lds_dwordx4 v102, s[6:7]
	s_add_i32 m0, s10, 66560
	s_nop 0
	global_load_lds_dwordx4 v110, s[6:7]
	s_add_i32 m0, s10, 67584
	s_nop 0
	global_load_lds_dwordx4 v112, s[6:7]
	s_add_i32 m0, s10, 68608
	s_nop 0
	global_load_lds_dwordx4 v193, s[6:7]
	s_add_u32 s6, s6, 0x8000
	s_addc_u32 s7, s7, 0
	v_max_f32_e32 v108, 0, v212
	v_max_f32_e32 v109, 0, v213
	v_pk_mul_f32 v[0:1], v[22:23], v[108:109]
	v_max_f32_e32 v210, 0, v214
	v_max_f32_e32 v211, 0, v215
	v_pk_fma_f32 v[0:1], v[24:25], v[210:211], v[0:1]
	v_max_f32_e32 v108, 0, v216
	v_max_f32_e32 v109, 0, v217
	v_pk_fma_f32 v[0:1], v[26:27], v[108:109], v[0:1]
	v_mfma_f32_32x32x16_bf16 v[6:21], v[90:93], v[42:45], v[6:21]
	v_max_f32_e32 v210, 0, v218
	v_max_f32_e32 v211, 0, v219
	v_pk_fma_f32 v[0:1], v[28:29], v[210:211], v[0:1]
	v_max_f32_e32 v108, 0, v220
	v_max_f32_e32 v109, 0, v221
	v_pk_fma_f32 v[0:1], v[30:31], v[108:109], v[0:1]
	v_max_f32_e32 v210, 0, v222
	v_max_f32_e32 v211, 0, v223
	v_pk_fma_f32 v[0:1], v[32:33], v[210:211], v[0:1]
	v_mfma_f32_32x32x16_bf16 v[6:21], v[94:97], v[46:49], v[6:21]
	v_max_f32_e32 v108, 0, v224
	v_max_f32_e32 v109, 0, v225
	v_pk_fma_f32 v[0:1], v[34:35], v[108:109], v[0:1]
	v_max_f32_e32 v210, 0, v226
	v_max_f32_e32 v211, 0, v227
	v_pk_fma_f32 v[0:1], v[36:37], v[210:211], v[0:1]
	v_add_f32_e32 v0, v0, v1
	v_ashrrev_i32_e32 v1, 31, v0
	v_mfma_f32_32x32x16_bf16 v[6:21], v[98:101], v[196:199], v[6:21]
	s_waitcnt vmcnt(10)
	ds_read_b128 v[38:41], v5 offset:10496
	ds_read_b128 v[42:45], v52 offset:10496
	ds_read_b128 v[46:49], v55 offset:10496
	ds_read_b128 v[196:199], v56 offset:10496
	v_or_b32_e32 v1, 0x80000000, v1
	s_cmpk_gt_i32 s11, 344
	s_cselect_b64 vcc, -1, 0
	v_xor_b32_e32 v0, v1, v0
	v_cndmask_b32_e32 v175, v123, v0, vcc
	s_nop 1
	s_waitcnt lgkmcnt(3)
	v_mfma_f32_32x32x16_bf16 v[212:227], v[70:73], v[38:41], 0
	v_max_f32_e32 v108, 0, v6
	v_max_f32_e32 v109, 0, v7
	v_pk_mul_f32 v[50:51], v[244:245], v[108:109]
	v_max_f32_e32 v210, 0, v8
	v_max_f32_e32 v211, 0, v9
	v_pk_fma_f32 v[50:51], v[246:247], v[210:211], v[50:51]
	v_max_f32_e32 v108, 0, v10
	v_max_f32_e32 v109, 0, v11
	v_pk_fma_f32 v[50:51], v[248:249], v[108:109], v[50:51]
	s_waitcnt lgkmcnt(2)
	v_mfma_f32_32x32x16_bf16 v[212:227], v[74:77], v[42:45], v[212:227]
	v_max_f32_e32 v210, 0, v12
	v_max_f32_e32 v211, 0, v13
	v_pk_fma_f32 v[50:51], v[250:251], v[210:211], v[50:51]
	v_max_f32_e32 v108, 0, v14
	v_max_f32_e32 v109, 0, v15
	v_pk_fma_f32 v[50:51], v[252:253], v[108:109], v[50:51]
	v_max_f32_e32 v210, 0, v16
	v_max_f32_e32 v211, 0, v17
	v_pk_fma_f32 v[50:51], v[254:255], v[210:211], v[50:51]
	s_waitcnt lgkmcnt(1)
	v_mfma_f32_32x32x16_bf16 v[212:227], v[78:81], v[46:49], v[212:227]
	v_max_f32_e32 v108, 0, v18
	v_max_f32_e32 v109, 0, v19
	v_pk_fma_f32 v[50:51], v[200:201], v[108:109], v[50:51]
	v_max_f32_e32 v210, 0, v20
	v_max_f32_e32 v211, 0, v21
	v_pk_fma_f32 v[50:51], v[202:203], v[210:211], v[50:51]
	v_add_f32_e32 v50, v50, v51
	v_ashrrev_i32_e32 v51, 31, v50
	s_waitcnt lgkmcnt(0)
	v_mfma_f32_32x32x16_bf16 v[212:227], v[82:85], v[196:199], v[212:227]
	v_or_b32_e32 v51, 0x80000000, v51
	s_cmpk_gt_i32 s11, 344
	s_cselect_b64 vcc, -1, 0
	v_xor_b32_e32 v50, v51, v50
	v_cndmask_b32_e32 v50, v123, v50, vcc
	global_store_dword v243, v50, s[8:9] offset:2048
	s_add_u32 s8, s8, 0x1000
	s_addc_u32 s9, s9, 0
	v_mfma_f32_32x32x16_bf16 v[6:21], v[86:89], v[38:41], 0
	s_add_i32 m0, s10, 98304
	s_nop 0
	global_load_lds_dwordx4 v102, s[6:7]
	s_add_i32 m0, s10, 99328
	s_nop 0
	global_load_lds_dwordx4 v110, s[6:7]
	s_add_i32 m0, s10, 100352
	s_nop 0
	global_load_lds_dwordx4 v112, s[6:7]
	s_add_i32 m0, s10, 101376
	s_nop 0
	global_load_lds_dwordx4 v193, s[6:7]
	s_add_u32 s6, s6, 0x8000
	s_addc_u32 s7, s7, 0
	v_max_f32_e32 v108, 0, v212
	v_max_f32_e32 v109, 0, v213
	v_pk_mul_f32 v[0:1], v[22:23], v[108:109]
	v_max_f32_e32 v210, 0, v214
	v_max_f32_e32 v211, 0, v215
	v_pk_fma_f32 v[0:1], v[24:25], v[210:211], v[0:1]
	v_max_f32_e32 v108, 0, v216
	v_max_f32_e32 v109, 0, v217
	v_pk_fma_f32 v[0:1], v[26:27], v[108:109], v[0:1]
	v_mfma_f32_32x32x16_bf16 v[6:21], v[90:93], v[42:45], v[6:21]
	v_max_f32_e32 v210, 0, v218
	v_max_f32_e32 v211, 0, v219
	v_pk_fma_f32 v[0:1], v[28:29], v[210:211], v[0:1]
	v_max_f32_e32 v108, 0, v220
	v_max_f32_e32 v109, 0, v221
	v_pk_fma_f32 v[0:1], v[30:31], v[108:109], v[0:1]
	v_max_f32_e32 v210, 0, v222
	v_max_f32_e32 v211, 0, v223
	v_pk_fma_f32 v[0:1], v[32:33], v[210:211], v[0:1]
	v_mfma_f32_32x32x16_bf16 v[6:21], v[94:97], v[46:49], v[6:21]
	v_max_f32_e32 v108, 0, v224
	v_max_f32_e32 v109, 0, v225
	v_pk_fma_f32 v[0:1], v[34:35], v[108:109], v[0:1]
	v_max_f32_e32 v210, 0, v226
	v_max_f32_e32 v211, 0, v227
	v_pk_fma_f32 v[0:1], v[36:37], v[210:211], v[0:1]
	v_add_f32_e32 v0, v0, v1
	v_ashrrev_i32_e32 v1, 31, v0
	v_mfma_f32_32x32x16_bf16 v[6:21], v[98:101], v[196:199], v[6:21]
	s_waitcnt vmcnt(10)
	ds_read_b128 v[38:41], v5 offset:43264
	ds_read_b128 v[42:45], v52 offset:43264
	ds_read_b128 v[46:49], v55 offset:43264
	ds_read_b128 v[196:199], v56 offset:43264
	v_or_b32_e32 v1, 0x80000000, v1
	s_cmpk_gt_i32 s11, 352
	s_cselect_b64 vcc, -1, 0
	v_xor_b32_e32 v0, v1, v0
	v_cndmask_b32_e32 v178, v123, v0, vcc
	s_nop 1
	s_waitcnt lgkmcnt(3)
	v_mfma_f32_32x32x16_bf16 v[212:227], v[70:73], v[38:41], 0
	v_max_f32_e32 v108, 0, v6
	v_max_f32_e32 v109, 0, v7
	v_pk_mul_f32 v[50:51], v[244:245], v[108:109]
	v_max_f32_e32 v210, 0, v8
	v_max_f32_e32 v211, 0, v9
	v_pk_fma_f32 v[50:51], v[246:247], v[210:211], v[50:51]
	v_max_f32_e32 v108, 0, v10
	v_max_f32_e32 v109, 0, v11
	v_pk_fma_f32 v[50:51], v[248:249], v[108:109], v[50:51]
	s_waitcnt lgkmcnt(2)
	v_mfma_f32_32x32x16_bf16 v[212:227], v[74:77], v[42:45], v[212:227]
	v_max_f32_e32 v210, 0, v12
	v_max_f32_e32 v211, 0, v13
	v_pk_fma_f32 v[50:51], v[250:251], v[210:211], v[50:51]
	v_max_f32_e32 v108, 0, v14
	v_max_f32_e32 v109, 0, v15
	v_pk_fma_f32 v[50:51], v[252:253], v[108:109], v[50:51]
	v_max_f32_e32 v210, 0, v16
	v_max_f32_e32 v211, 0, v17
	v_pk_fma_f32 v[50:51], v[254:255], v[210:211], v[50:51]
	s_waitcnt lgkmcnt(1)
	v_mfma_f32_32x32x16_bf16 v[212:227], v[78:81], v[46:49], v[212:227]
	v_max_f32_e32 v108, 0, v18
	v_max_f32_e32 v109, 0, v19
	v_pk_fma_f32 v[50:51], v[200:201], v[108:109], v[50:51]
	v_max_f32_e32 v210, 0, v20
	v_max_f32_e32 v211, 0, v21
	v_pk_fma_f32 v[50:51], v[202:203], v[210:211], v[50:51]
	v_add_f32_e32 v50, v50, v51
	v_ashrrev_i32_e32 v51, 31, v50
	s_waitcnt lgkmcnt(0)
	v_mfma_f32_32x32x16_bf16 v[212:227], v[82:85], v[196:199], v[212:227]
	v_or_b32_e32 v51, 0x80000000, v51
	s_cmpk_gt_i32 s11, 352
	s_cselect_b64 vcc, -1, 0
	v_xor_b32_e32 v50, v51, v50
	v_cndmask_b32_e32 v50, v123, v50, vcc
	global_store_dword v243, v50, s[8:9]
	v_mfma_f32_32x32x16_bf16 v[6:21], v[86:89], v[38:41], 0
	s_add_i32 m0, s10, 0
	s_nop 0
	global_load_lds_dwordx4 v102, s[6:7]
	s_add_i32 m0, s10, 1024
	s_nop 0
	global_load_lds_dwordx4 v110, s[6:7]
	s_add_i32 m0, s10, 2048
	s_nop 0
	global_load_lds_dwordx4 v112, s[6:7]
	s_add_i32 m0, s10, 3072
	s_nop 0
	global_load_lds_dwordx4 v193, s[6:7]
	s_add_u32 s6, s6, 0x8000
	s_addc_u32 s7, s7, 0
	v_max_f32_e32 v108, 0, v212
	v_max_f32_e32 v109, 0, v213
	v_pk_mul_f32 v[0:1], v[22:23], v[108:109]
	v_max_f32_e32 v210, 0, v214
	v_max_f32_e32 v211, 0, v215
	v_pk_fma_f32 v[0:1], v[24:25], v[210:211], v[0:1]
	v_max_f32_e32 v108, 0, v216
	v_max_f32_e32 v109, 0, v217
	v_pk_fma_f32 v[0:1], v[26:27], v[108:109], v[0:1]
	v_mfma_f32_32x32x16_bf16 v[6:21], v[90:93], v[42:45], v[6:21]
	v_max_f32_e32 v210, 0, v218
	v_max_f32_e32 v211, 0, v219
	v_pk_fma_f32 v[0:1], v[28:29], v[210:211], v[0:1]
	v_max_f32_e32 v108, 0, v220
	v_max_f32_e32 v109, 0, v221
	v_pk_fma_f32 v[0:1], v[30:31], v[108:109], v[0:1]
	v_max_f32_e32 v210, 0, v222
	v_max_f32_e32 v211, 0, v223
	v_pk_fma_f32 v[0:1], v[32:33], v[210:211], v[0:1]
	v_mfma_f32_32x32x16_bf16 v[6:21], v[94:97], v[46:49], v[6:21]
	v_max_f32_e32 v108, 0, v224
	v_max_f32_e32 v109, 0, v225
	v_pk_fma_f32 v[0:1], v[34:35], v[108:109], v[0:1]
	v_max_f32_e32 v210, 0, v226
	v_max_f32_e32 v211, 0, v227
	v_pk_fma_f32 v[0:1], v[36:37], v[210:211], v[0:1]
	v_add_f32_e32 v0, v0, v1
	v_ashrrev_i32_e32 v1, 31, v0
	v_mfma_f32_32x32x16_bf16 v[6:21], v[98:101], v[196:199], v[6:21]
	s_waitcnt vmcnt(10)
	v_add_u32_e32 v228, 0x10000, v5
	ds_read_b128 v[38:41], v228 offset:10496
	v_add_u32_e32 v228, 0x10000, v52
	ds_read_b128 v[42:45], v228 offset:10496
	v_add_u32_e32 v228, 0x10000, v55
	ds_read_b128 v[46:49], v228 offset:10496
	v_add_u32_e32 v228, 0x10000, v56
	ds_read_b128 v[196:199], v228 offset:10496
	v_or_b32_e32 v1, 0x80000000, v1
	s_cmpk_gt_i32 s11, 360
	s_cselect_b64 vcc, -1, 0
	v_xor_b32_e32 v0, v1, v0
	v_cndmask_b32_e32 v177, v123, v0, vcc
	s_nop 1
	s_waitcnt lgkmcnt(3)
	v_mfma_f32_32x32x16_bf16 v[212:227], v[70:73], v[38:41], 0
	v_max_f32_e32 v108, 0, v6
	v_max_f32_e32 v109, 0, v7
	v_pk_mul_f32 v[50:51], v[244:245], v[108:109]
	v_max_f32_e32 v210, 0, v8
	v_max_f32_e32 v211, 0, v9
	v_pk_fma_f32 v[50:51], v[246:247], v[210:211], v[50:51]
	v_max_f32_e32 v108, 0, v10
	v_max_f32_e32 v109, 0, v11
	v_pk_fma_f32 v[50:51], v[248:249], v[108:109], v[50:51]
	s_waitcnt lgkmcnt(2)
	v_mfma_f32_32x32x16_bf16 v[212:227], v[74:77], v[42:45], v[212:227]
	v_max_f32_e32 v210, 0, v12
	v_max_f32_e32 v211, 0, v13
	v_pk_fma_f32 v[50:51], v[250:251], v[210:211], v[50:51]
	v_max_f32_e32 v108, 0, v14
	v_max_f32_e32 v109, 0, v15
	v_pk_fma_f32 v[50:51], v[252:253], v[108:109], v[50:51]
	v_max_f32_e32 v210, 0, v16
	v_max_f32_e32 v211, 0, v17
	v_pk_fma_f32 v[50:51], v[254:255], v[210:211], v[50:51]
	s_waitcnt lgkmcnt(1)
	v_mfma_f32_32x32x16_bf16 v[212:227], v[78:81], v[46:49], v[212:227]
	v_max_f32_e32 v108, 0, v18
	v_max_f32_e32 v109, 0, v19
	v_pk_fma_f32 v[50:51], v[200:201], v[108:109], v[50:51]
	v_max_f32_e32 v210, 0, v20
	v_max_f32_e32 v211, 0, v21
	v_pk_fma_f32 v[50:51], v[202:203], v[210:211], v[50:51]
	v_add_f32_e32 v50, v50, v51
	v_ashrrev_i32_e32 v51, 31, v50
	s_waitcnt lgkmcnt(0)
	v_mfma_f32_32x32x16_bf16 v[212:227], v[82:85], v[196:199], v[212:227]
	v_or_b32_e32 v51, 0x80000000, v51
	s_cmpk_gt_i32 s11, 360
	s_cselect_b64 vcc, -1, 0
	v_xor_b32_e32 v50, v51, v50
	v_cndmask_b32_e32 v50, v123, v50, vcc
	global_store_dword v243, v50, s[8:9] offset:2048
	s_add_u32 s8, s8, 0x1000
	s_addc_u32 s9, s9, 0
	v_mfma_f32_32x32x16_bf16 v[6:21], v[86:89], v[38:41], 0
	s_add_i32 m0, s10, 32768
	s_nop 0
	global_load_lds_dwordx4 v102, s[6:7]
	s_add_i32 m0, s10, 33792
	s_nop 0
	global_load_lds_dwordx4 v110, s[6:7]
	s_add_i32 m0, s10, 34816
	s_nop 0
	global_load_lds_dwordx4 v112, s[6:7]
	s_add_i32 m0, s10, 35840
	s_nop 0
	global_load_lds_dwordx4 v193, s[6:7]
	s_add_u32 s6, s6, 0x8000
	s_addc_u32 s7, s7, 0
	v_max_f32_e32 v108, 0, v212
	v_max_f32_e32 v109, 0, v213
	v_pk_mul_f32 v[0:1], v[22:23], v[108:109]
	v_max_f32_e32 v210, 0, v214
	v_max_f32_e32 v211, 0, v215
	v_pk_fma_f32 v[0:1], v[24:25], v[210:211], v[0:1]
	v_max_f32_e32 v108, 0, v216
	v_max_f32_e32 v109, 0, v217
	v_pk_fma_f32 v[0:1], v[26:27], v[108:109], v[0:1]
	v_mfma_f32_32x32x16_bf16 v[6:21], v[90:93], v[42:45], v[6:21]
	v_max_f32_e32 v210, 0, v218
	v_max_f32_e32 v211, 0, v219
	v_pk_fma_f32 v[0:1], v[28:29], v[210:211], v[0:1]
	v_max_f32_e32 v108, 0, v220
	v_max_f32_e32 v109, 0, v221
	v_pk_fma_f32 v[0:1], v[30:31], v[108:109], v[0:1]
	v_max_f32_e32 v210, 0, v222
	v_max_f32_e32 v211, 0, v223
	v_pk_fma_f32 v[0:1], v[32:33], v[210:211], v[0:1]
	v_mfma_f32_32x32x16_bf16 v[6:21], v[94:97], v[46:49], v[6:21]
	v_max_f32_e32 v108, 0, v224
	v_max_f32_e32 v109, 0, v225
	v_pk_fma_f32 v[0:1], v[34:35], v[108:109], v[0:1]
	v_max_f32_e32 v210, 0, v226
	v_max_f32_e32 v211, 0, v227
	v_pk_fma_f32 v[0:1], v[36:37], v[210:211], v[0:1]
	v_add_f32_e32 v0, v0, v1
	v_ashrrev_i32_e32 v1, 31, v0
	v_mfma_f32_32x32x16_bf16 v[6:21], v[98:101], v[196:199], v[6:21]
	s_waitcnt vmcnt(10)
	v_add_u32_e32 v228, 0x10000, v5
	ds_read_b128 v[38:41], v228 offset:43264
	v_add_u32_e32 v228, 0x10000, v52
	ds_read_b128 v[42:45], v228 offset:43264
	v_add_u32_e32 v228, 0x10000, v55
	ds_read_b128 v[46:49], v228 offset:43264
	v_add_u32_e32 v228, 0x10000, v56
	ds_read_b128 v[196:199], v228 offset:43264
	v_or_b32_e32 v1, 0x80000000, v1
	s_cmpk_gt_i32 s11, 368
	s_cselect_b64 vcc, -1, 0
	v_xor_b32_e32 v0, v1, v0
	v_cndmask_b32_e32 v179, v123, v0, vcc
	s_nop 1
	s_waitcnt lgkmcnt(3)
	v_mfma_f32_32x32x16_bf16 v[212:227], v[70:73], v[38:41], 0
	v_max_f32_e32 v108, 0, v6
	v_max_f32_e32 v109, 0, v7
	v_pk_mul_f32 v[50:51], v[244:245], v[108:109]
	v_max_f32_e32 v210, 0, v8
	v_max_f32_e32 v211, 0, v9
	v_pk_fma_f32 v[50:51], v[246:247], v[210:211], v[50:51]
	v_max_f32_e32 v108, 0, v10
	v_max_f32_e32 v109, 0, v11
	v_pk_fma_f32 v[50:51], v[248:249], v[108:109], v[50:51]
	s_waitcnt lgkmcnt(2)
	v_mfma_f32_32x32x16_bf16 v[212:227], v[74:77], v[42:45], v[212:227]
	v_max_f32_e32 v210, 0, v12
	v_max_f32_e32 v211, 0, v13
	v_pk_fma_f32 v[50:51], v[250:251], v[210:211], v[50:51]
	v_max_f32_e32 v108, 0, v14
	v_max_f32_e32 v109, 0, v15
	v_pk_fma_f32 v[50:51], v[252:253], v[108:109], v[50:51]
	v_max_f32_e32 v210, 0, v16
	v_max_f32_e32 v211, 0, v17
	v_pk_fma_f32 v[50:51], v[254:255], v[210:211], v[50:51]
	s_waitcnt lgkmcnt(1)
	v_mfma_f32_32x32x16_bf16 v[212:227], v[78:81], v[46:49], v[212:227]
	v_max_f32_e32 v108, 0, v18
	v_max_f32_e32 v109, 0, v19
	v_pk_fma_f32 v[50:51], v[200:201], v[108:109], v[50:51]
	v_max_f32_e32 v210, 0, v20
	v_max_f32_e32 v211, 0, v21
	v_pk_fma_f32 v[50:51], v[202:203], v[210:211], v[50:51]
	v_add_f32_e32 v50, v50, v51
	v_ashrrev_i32_e32 v51, 31, v50
	s_waitcnt lgkmcnt(0)
	v_mfma_f32_32x32x16_bf16 v[212:227], v[82:85], v[196:199], v[212:227]
	v_or_b32_e32 v51, 0x80000000, v51
	s_cmpk_gt_i32 s11, 368
	s_cselect_b64 vcc, -1, 0
	v_xor_b32_e32 v50, v51, v50
	v_cndmask_b32_e32 v50, v123, v50, vcc
	global_store_dword v243, v50, s[8:9]
	v_mfma_f32_32x32x16_bf16 v[6:21], v[86:89], v[38:41], 0
	s_add_i32 m0, s10, 65536
	s_nop 0
	global_load_lds_dwordx4 v102, s[6:7]
	s_add_i32 m0, s10, 66560
	s_nop 0
	global_load_lds_dwordx4 v110, s[6:7]
	s_add_i32 m0, s10, 67584
	s_nop 0
	global_load_lds_dwordx4 v112, s[6:7]
	s_add_i32 m0, s10, 68608
	s_nop 0
	global_load_lds_dwordx4 v193, s[6:7]
	s_add_u32 s6, s6, 0x8000
	s_addc_u32 s7, s7, 0
	v_max_f32_e32 v108, 0, v212
	v_max_f32_e32 v109, 0, v213
	v_pk_mul_f32 v[0:1], v[22:23], v[108:109]
	v_max_f32_e32 v210, 0, v214
	v_max_f32_e32 v211, 0, v215
	v_pk_fma_f32 v[0:1], v[24:25], v[210:211], v[0:1]
	v_max_f32_e32 v108, 0, v216
	v_max_f32_e32 v109, 0, v217
	v_pk_fma_f32 v[0:1], v[26:27], v[108:109], v[0:1]
	v_mfma_f32_32x32x16_bf16 v[6:21], v[90:93], v[42:45], v[6:21]
	v_max_f32_e32 v210, 0, v218
	v_max_f32_e32 v211, 0, v219
	v_pk_fma_f32 v[0:1], v[28:29], v[210:211], v[0:1]
	v_max_f32_e32 v108, 0, v220
	v_max_f32_e32 v109, 0, v221
	v_pk_fma_f32 v[0:1], v[30:31], v[108:109], v[0:1]
	v_max_f32_e32 v210, 0, v222
	v_max_f32_e32 v211, 0, v223
	v_pk_fma_f32 v[0:1], v[32:33], v[210:211], v[0:1]
	v_mfma_f32_32x32x16_bf16 v[6:21], v[94:97], v[46:49], v[6:21]
	v_max_f32_e32 v108, 0, v224
	v_max_f32_e32 v109, 0, v225
	v_pk_fma_f32 v[0:1], v[34:35], v[108:109], v[0:1]
	v_max_f32_e32 v210, 0, v226
	v_max_f32_e32 v211, 0, v227
	v_pk_fma_f32 v[0:1], v[36:37], v[210:211], v[0:1]
	v_add_f32_e32 v0, v0, v1
	v_ashrrev_i32_e32 v1, 31, v0
	v_mfma_f32_32x32x16_bf16 v[6:21], v[98:101], v[196:199], v[6:21]
	s_waitcnt vmcnt(10)
	ds_read_b128 v[38:41], v5 offset:10496
	ds_read_b128 v[42:45], v52 offset:10496
	ds_read_b128 v[46:49], v55 offset:10496
	ds_read_b128 v[196:199], v56 offset:10496
	v_or_b32_e32 v1, 0x80000000, v1
	s_cmpk_gt_i32 s11, 376
	s_cselect_b64 vcc, -1, 0
	v_xor_b32_e32 v0, v1, v0
	v_cndmask_b32_e32 v168, v123, v0, vcc
	s_nop 1
	v_max_f32_e32 v108, 0, v6
	v_max_f32_e32 v109, 0, v7
	v_pk_mul_f32 v[50:51], v[244:245], v[108:109]
	v_max_f32_e32 v210, 0, v8
	v_max_f32_e32 v211, 0, v9
	v_pk_fma_f32 v[50:51], v[246:247], v[210:211], v[50:51]
	v_max_f32_e32 v108, 0, v10
	v_max_f32_e32 v109, 0, v11
	v_pk_fma_f32 v[50:51], v[248:249], v[108:109], v[50:51]
	v_max_f32_e32 v210, 0, v12
	v_max_f32_e32 v211, 0, v13
	v_pk_fma_f32 v[50:51], v[250:251], v[210:211], v[50:51]
	v_max_f32_e32 v108, 0, v14
	v_max_f32_e32 v109, 0, v15
	v_pk_fma_f32 v[50:51], v[252:253], v[108:109], v[50:51]
	v_max_f32_e32 v210, 0, v16
	v_max_f32_e32 v211, 0, v17
	v_pk_fma_f32 v[50:51], v[254:255], v[210:211], v[50:51]
	v_max_f32_e32 v108, 0, v18
	v_max_f32_e32 v109, 0, v19
	v_pk_fma_f32 v[50:51], v[200:201], v[108:109], v[50:51]
	v_max_f32_e32 v210, 0, v20
	v_max_f32_e32 v211, 0, v21
	v_pk_fma_f32 v[50:51], v[202:203], v[210:211], v[50:51]
	v_add_f32_e32 v50, v50, v51
	v_ashrrev_i32_e32 v51, 31, v50
	v_or_b32_e32 v51, 0x80000000, v51
	s_cmpk_gt_i32 s11, 376
	s_cselect_b64 vcc, -1, 0
	v_xor_b32_e32 v50, v51, v50
	v_cndmask_b32_e32 v50, v123, v50, vcc
	global_store_dword v243, v50, s[8:9] offset:2048
	s_add_u32 s8, s8, 0x1000
	s_addc_u32 s9, s9, 0
	s_cmpk_gt_i32 s81, 48
	s_cbranch_scc0 .Lix_fill_6
	s_waitcnt lgkmcnt(3)
	v_mfma_f32_32x32x16_bf16 v[212:227], v[70:73], v[38:41], 0
	s_add_i32 m0, s10, 98304
	s_nop 0
	global_load_lds_dwordx4 v102, s[6:7]
	s_waitcnt lgkmcnt(2)
	v_mfma_f32_32x32x16_bf16 v[212:227], v[74:77], v[42:45], v[212:227]
	s_add_i32 m0, s10, 99328
	s_nop 0
	global_load_lds_dwordx4 v110, s[6:7]
	s_waitcnt lgkmcnt(1)
	v_mfma_f32_32x32x16_bf16 v[212:227], v[78:81], v[46:49], v[212:227]
	s_add_i32 m0, s10, 100352
	s_nop 0
	global_load_lds_dwordx4 v112, s[6:7]
	s_waitcnt lgkmcnt(0)
	v_mfma_f32_32x32x16_bf16 v[212:227], v[82:85], v[196:199], v[212:227]
	s_add_i32 m0, s10, 101376
	s_nop 0
	global_load_lds_dwordx4 v193, s[6:7]
	s_add_u32 s6, s6, 0x8000
	s_addc_u32 s7, s7, 0
	v_mfma_f32_32x32x16_bf16 v[6:21], v[86:89], v[38:41], 0
	s_nop 7
	s_nop 2
	v_max_f32_e32 v108, 0, v212
	v_max_f32_e32 v109, 0, v213
	v_pk_mul_f32 v[0:1], v[22:23], v[108:109]
	v_max_f32_e32 v210, 0, v214
	v_max_f32_e32 v211, 0, v215
	v_pk_fma_f32 v[0:1], v[24:25], v[210:211], v[0:1]
	v_max_f32_e32 v108, 0, v216
	v_max_f32_e32 v109, 0, v217
	v_pk_fma_f32 v[0:1], v[26:27], v[108:109], v[0:1]
	v_mfma_f32_32x32x16_bf16 v[6:21], v[90:93], v[42:45], v[6:21]
	v_max_f32_e32 v210, 0, v218
	v_max_f32_e32 v211, 0, v219
	v_pk_fma_f32 v[0:1], v[28:29], v[210:211], v[0:1]
	v_max_f32_e32 v108, 0, v220
	v_max_f32_e32 v109, 0, v221
	v_pk_fma_f32 v[0:1], v[30:31], v[108:109], v[0:1]
	v_max_f32_e32 v210, 0, v222
	v_max_f32_e32 v211, 0, v223
	v_pk_fma_f32 v[0:1], v[32:33], v[210:211], v[0:1]
	v_mfma_f32_32x32x16_bf16 v[6:21], v[94:97], v[46:49], v[6:21]
	v_max_f32_e32 v108, 0, v224
	v_max_f32_e32 v109, 0, v225
	v_pk_fma_f32 v[0:1], v[34:35], v[108:109], v[0:1]
	v_max_f32_e32 v210, 0, v226
	v_max_f32_e32 v211, 0, v227
	v_pk_fma_f32 v[0:1], v[36:37], v[210:211], v[0:1]
	v_add_f32_e32 v0, v0, v1
	v_ashrrev_i32_e32 v1, 31, v0
	v_mfma_f32_32x32x16_bf16 v[6:21], v[98:101], v[196:199], v[6:21]
	s_waitcnt vmcnt(10)
	ds_read_b128 v[38:41], v5 offset:43264
	ds_read_b128 v[42:45], v52 offset:43264
	ds_read_b128 v[46:49], v55 offset:43264
	ds_read_b128 v[196:199], v56 offset:43264
	v_or_b32_e32 v1, 0x80000000, v1
	s_cmpk_gt_i32 s11, 384
	s_cselect_b64 vcc, -1, 0
	v_xor_b32_e32 v0, v1, v0
	v_cndmask_b32_e32 v182, v123, v0, vcc
	s_nop 1
	s_waitcnt lgkmcnt(3)
	v_mfma_f32_32x32x16_bf16 v[212:227], v[70:73], v[38:41], 0
	v_max_f32_e32 v108, 0, v6
	v_max_f32_e32 v109, 0, v7
	v_pk_mul_f32 v[50:51], v[244:245], v[108:109]
	v_max_f32_e32 v210, 0, v8
	v_max_f32_e32 v211, 0, v9
	v_pk_fma_f32 v[50:51], v[246:247], v[210:211], v[50:51]
	v_max_f32_e32 v108, 0, v10
	v_max_f32_e32 v109, 0, v11
	v_pk_fma_f32 v[50:51], v[248:249], v[108:109], v[50:51]
	s_waitcnt lgkmcnt(2)
	v_mfma_f32_32x32x16_bf16 v[212:227], v[74:77], v[42:45], v[212:227]
	v_max_f32_e32 v210, 0, v12
	v_max_f32_e32 v211, 0, v13
	v_pk_fma_f32 v[50:51], v[250:251], v[210:211], v[50:51]
	v_max_f32_e32 v108, 0, v14
	v_max_f32_e32 v109, 0, v15
	v_pk_fma_f32 v[50:51], v[252:253], v[108:109], v[50:51]
	v_max_f32_e32 v210, 0, v16
	v_max_f32_e32 v211, 0, v17
	v_pk_fma_f32 v[50:51], v[254:255], v[210:211], v[50:51]
	s_waitcnt lgkmcnt(1)
	v_mfma_f32_32x32x16_bf16 v[212:227], v[78:81], v[46:49], v[212:227]
	v_max_f32_e32 v108, 0, v18
	v_max_f32_e32 v109, 0, v19
	v_pk_fma_f32 v[50:51], v[200:201], v[108:109], v[50:51]
	v_max_f32_e32 v210, 0, v20
	v_max_f32_e32 v211, 0, v21
	v_pk_fma_f32 v[50:51], v[202:203], v[210:211], v[50:51]
	v_add_f32_e32 v50, v50, v51
	v_ashrrev_i32_e32 v51, 31, v50
	s_waitcnt lgkmcnt(0)
	v_mfma_f32_32x32x16_bf16 v[212:227], v[82:85], v[196:199], v[212:227]
	v_or_b32_e32 v51, 0x80000000, v51
	s_cmpk_gt_i32 s11, 384
	s_cselect_b64 vcc, -1, 0
	v_xor_b32_e32 v50, v51, v50
	v_cndmask_b32_e32 v50, v123, v50, vcc
	global_store_dword v243, v50, s[8:9]
	v_mfma_f32_32x32x16_bf16 v[6:21], v[86:89], v[38:41], 0
	s_add_i32 m0, s10, 0
	s_nop 0
	global_load_lds_dwordx4 v102, s[6:7]
	s_add_i32 m0, s10, 1024
	s_nop 0
	global_load_lds_dwordx4 v110, s[6:7]
	s_add_i32 m0, s10, 2048
	s_nop 0
	global_load_lds_dwordx4 v112, s[6:7]
	s_add_i32 m0, s10, 3072
	s_nop 0
	global_load_lds_dwordx4 v193, s[6:7]
	s_add_u32 s6, s6, 0x8000
	s_addc_u32 s7, s7, 0
	v_max_f32_e32 v108, 0, v212
	v_max_f32_e32 v109, 0, v213
	v_pk_mul_f32 v[0:1], v[22:23], v[108:109]
	v_max_f32_e32 v210, 0, v214
	v_max_f32_e32 v211, 0, v215
	v_pk_fma_f32 v[0:1], v[24:25], v[210:211], v[0:1]
	v_max_f32_e32 v108, 0, v216
	v_max_f32_e32 v109, 0, v217
	v_pk_fma_f32 v[0:1], v[26:27], v[108:109], v[0:1]
	v_mfma_f32_32x32x16_bf16 v[6:21], v[90:93], v[42:45], v[6:21]
	v_max_f32_e32 v210, 0, v218
	v_max_f32_e32 v211, 0, v219
	v_pk_fma_f32 v[0:1], v[28:29], v[210:211], v[0:1]
	v_max_f32_e32 v108, 0, v220
	v_max_f32_e32 v109, 0, v221
	v_pk_fma_f32 v[0:1], v[30:31], v[108:109], v[0:1]
	v_max_f32_e32 v210, 0, v222
	v_max_f32_e32 v211, 0, v223
	v_pk_fma_f32 v[0:1], v[32:33], v[210:211], v[0:1]
	v_mfma_f32_32x32x16_bf16 v[6:21], v[94:97], v[46:49], v[6:21]
	v_max_f32_e32 v108, 0, v224
	v_max_f32_e32 v109, 0, v225
	v_pk_fma_f32 v[0:1], v[34:35], v[108:109], v[0:1]
	v_max_f32_e32 v210, 0, v226
	v_max_f32_e32 v211, 0, v227
	v_pk_fma_f32 v[0:1], v[36:37], v[210:211], v[0:1]
	v_add_f32_e32 v0, v0, v1
	v_ashrrev_i32_e32 v1, 31, v0
	v_mfma_f32_32x32x16_bf16 v[6:21], v[98:101], v[196:199], v[6:21]
	s_waitcnt vmcnt(10)
	v_add_u32_e32 v228, 0x10000, v5
	ds_read_b128 v[38:41], v228 offset:10496
	v_add_u32_e32 v228, 0x10000, v52
	ds_read_b128 v[42:45], v228 offset:10496
	v_add_u32_e32 v228, 0x10000, v55
	ds_read_b128 v[46:49], v228 offset:10496
	v_add_u32_e32 v228, 0x10000, v56
	ds_read_b128 v[196:199], v228 offset:10496
	v_or_b32_e32 v1, 0x80000000, v1
	s_cmpk_gt_i32 s11, 392
	s_cselect_b64 vcc, -1, 0
	v_xor_b32_e32 v0, v1, v0
	v_cndmask_b32_e32 v181, v123, v0, vcc
	s_nop 1
	s_waitcnt lgkmcnt(3)
	v_mfma_f32_32x32x16_bf16 v[212:227], v[70:73], v[38:41], 0
	v_max_f32_e32 v108, 0, v6
	v_max_f32_e32 v109, 0, v7
	v_pk_mul_f32 v[50:51], v[244:245], v[108:109]
	v_max_f32_e32 v210, 0, v8
	v_max_f32_e32 v211, 0, v9
	v_pk_fma_f32 v[50:51], v[246:247], v[210:211], v[50:51]
	v_max_f32_e32 v108, 0, v10
	v_max_f32_e32 v109, 0, v11
	v_pk_fma_f32 v[50:51], v[248:249], v[108:109], v[50:51]
	s_waitcnt lgkmcnt(2)
	v_mfma_f32_32x32x16_bf16 v[212:227], v[74:77], v[42:45], v[212:227]
	v_max_f32_e32 v210, 0, v12
	v_max_f32_e32 v211, 0, v13
	v_pk_fma_f32 v[50:51], v[250:251], v[210:211], v[50:51]
	v_max_f32_e32 v108, 0, v14
	v_max_f32_e32 v109, 0, v15
	v_pk_fma_f32 v[50:51], v[252:253], v[108:109], v[50:51]
	v_max_f32_e32 v210, 0, v16
	v_max_f32_e32 v211, 0, v17
	v_pk_fma_f32 v[50:51], v[254:255], v[210:211], v[50:51]
	s_waitcnt lgkmcnt(1)
	v_mfma_f32_32x32x16_bf16 v[212:227], v[78:81], v[46:49], v[212:227]
	v_max_f32_e32 v108, 0, v18
	v_max_f32_e32 v109, 0, v19
	v_pk_fma_f32 v[50:51], v[200:201], v[108:109], v[50:51]
	v_max_f32_e32 v210, 0, v20
	v_max_f32_e32 v211, 0, v21
	v_pk_fma_f32 v[50:51], v[202:203], v[210:211], v[50:51]
	v_add_f32_e32 v50, v50, v51
	v_ashrrev_i32_e32 v51, 31, v50
	s_waitcnt lgkmcnt(0)
	v_mfma_f32_32x32x16_bf16 v[212:227], v[82:85], v[196:199], v[212:227]
	v_or_b32_e32 v51, 0x80000000, v51
	s_cmpk_gt_i32 s11, 392
	s_cselect_b64 vcc, -1, 0
	v_xor_b32_e32 v50, v51, v50
	v_cndmask_b32_e32 v50, v123, v50, vcc
	global_store_dword v243, v50, s[8:9] offset:2048
	s_add_u32 s8, s8, 0x1000
	s_addc_u32 s9, s9, 0
	v_mfma_f32_32x32x16_bf16 v[6:21], v[86:89], v[38:41], 0
	s_add_i32 m0, s10, 32768
	s_nop 0
	global_load_lds_dwordx4 v102, s[6:7]
	s_add_i32 m0, s10, 33792
	s_nop 0
	global_load_lds_dwordx4 v110, s[6:7]
	s_add_i32 m0, s10, 34816
	s_nop 0
	global_load_lds_dwordx4 v112, s[6:7]
	s_add_i32 m0, s10, 35840
	s_nop 0
	global_load_lds_dwordx4 v193, s[6:7]
	s_add_u32 s6, s6, 0x8000
	s_addc_u32 s7, s7, 0
	v_max_f32_e32 v108, 0, v212
	v_max_f32_e32 v109, 0, v213
	v_pk_mul_f32 v[0:1], v[22:23], v[108:109]
	v_max_f32_e32 v210, 0, v214
	v_max_f32_e32 v211, 0, v215
	v_pk_fma_f32 v[0:1], v[24:25], v[210:211], v[0:1]
	v_max_f32_e32 v108, 0, v216
	v_max_f32_e32 v109, 0, v217
	v_pk_fma_f32 v[0:1], v[26:27], v[108:109], v[0:1]
	v_mfma_f32_32x32x16_bf16 v[6:21], v[90:93], v[42:45], v[6:21]
	v_max_f32_e32 v210, 0, v218
	v_max_f32_e32 v211, 0, v219
	v_pk_fma_f32 v[0:1], v[28:29], v[210:211], v[0:1]
	v_max_f32_e32 v108, 0, v220
	v_max_f32_e32 v109, 0, v221
	v_pk_fma_f32 v[0:1], v[30:31], v[108:109], v[0:1]
	v_max_f32_e32 v210, 0, v222
	v_max_f32_e32 v211, 0, v223
	v_pk_fma_f32 v[0:1], v[32:33], v[210:211], v[0:1]
	v_mfma_f32_32x32x16_bf16 v[6:21], v[94:97], v[46:49], v[6:21]
	v_max_f32_e32 v108, 0, v224
	v_max_f32_e32 v109, 0, v225
	v_pk_fma_f32 v[0:1], v[34:35], v[108:109], v[0:1]
	v_max_f32_e32 v210, 0, v226
	v_max_f32_e32 v211, 0, v227
	v_pk_fma_f32 v[0:1], v[36:37], v[210:211], v[0:1]
	v_add_f32_e32 v0, v0, v1
	v_ashrrev_i32_e32 v1, 31, v0
	v_mfma_f32_32x32x16_bf16 v[6:21], v[98:101], v[196:199], v[6:21]
	s_waitcnt vmcnt(10)
	v_add_u32_e32 v228, 0x10000, v5
	ds_read_b128 v[38:41], v228 offset:43264
	v_add_u32_e32 v228, 0x10000, v52
	ds_read_b128 v[42:45], v228 offset:43264
	v_add_u32_e32 v228, 0x10000, v55
	ds_read_b128 v[46:49], v228 offset:43264
	v_add_u32_e32 v228, 0x10000, v56
	ds_read_b128 v[196:199], v228 offset:43264
	v_or_b32_e32 v1, 0x80000000, v1
	s_cmpk_gt_i32 s11, 400
	s_cselect_b64 vcc, -1, 0
	v_xor_b32_e32 v0, v1, v0
	v_cndmask_b32_e32 v184, v123, v0, vcc
	s_nop 1
	s_waitcnt lgkmcnt(3)
	v_mfma_f32_32x32x16_bf16 v[212:227], v[70:73], v[38:41], 0
	v_max_f32_e32 v108, 0, v6
	v_max_f32_e32 v109, 0, v7
	v_pk_mul_f32 v[50:51], v[244:245], v[108:109]
	v_max_f32_e32 v210, 0, v8
	v_max_f32_e32 v211, 0, v9
	v_pk_fma_f32 v[50:51], v[246:247], v[210:211], v[50:51]
	v_max_f32_e32 v108, 0, v10
	v_max_f32_e32 v109, 0, v11
	v_pk_fma_f32 v[50:51], v[248:249], v[108:109], v[50:51]
	s_waitcnt lgkmcnt(2)
	v_mfma_f32_32x32x16_bf16 v[212:227], v[74:77], v[42:45], v[212:227]
	v_max_f32_e32 v210, 0, v12
	v_max_f32_e32 v211, 0, v13
	v_pk_fma_f32 v[50:51], v[250:251], v[210:211], v[50:51]
	v_max_f32_e32 v108, 0, v14
	v_max_f32_e32 v109, 0, v15
	v_pk_fma_f32 v[50:51], v[252:253], v[108:109], v[50:51]
	v_max_f32_e32 v210, 0, v16
	v_max_f32_e32 v211, 0, v17
	v_pk_fma_f32 v[50:51], v[254:255], v[210:211], v[50:51]
	s_waitcnt lgkmcnt(1)
	v_mfma_f32_32x32x16_bf16 v[212:227], v[78:81], v[46:49], v[212:227]
	v_max_f32_e32 v108, 0, v18
	v_max_f32_e32 v109, 0, v19
	v_pk_fma_f32 v[50:51], v[200:201], v[108:109], v[50:51]
	v_max_f32_e32 v210, 0, v20
	v_max_f32_e32 v211, 0, v21
	v_pk_fma_f32 v[50:51], v[202:203], v[210:211], v[50:51]
	v_add_f32_e32 v50, v50, v51
	v_ashrrev_i32_e32 v51, 31, v50
	s_waitcnt lgkmcnt(0)
	v_mfma_f32_32x32x16_bf16 v[212:227], v[82:85], v[196:199], v[212:227]
	v_or_b32_e32 v51, 0x80000000, v51
	s_cmpk_gt_i32 s11, 400
	s_cselect_b64 vcc, -1, 0
	v_xor_b32_e32 v50, v51, v50
	v_cndmask_b32_e32 v50, v123, v50, vcc
	global_store_dword v243, v50, s[8:9]
	v_mfma_f32_32x32x16_bf16 v[6:21], v[86:89], v[38:41], 0
	s_add_i32 m0, s10, 65536
	s_nop 0
	global_load_lds_dwordx4 v102, s[6:7]
	s_add_i32 m0, s10, 66560
	s_nop 0
	global_load_lds_dwordx4 v110, s[6:7]
	s_add_i32 m0, s10, 67584
	s_nop 0
	global_load_lds_dwordx4 v112, s[6:7]
	s_add_i32 m0, s10, 68608
	s_nop 0
	global_load_lds_dwordx4 v193, s[6:7]
	s_add_u32 s6, s6, 0x8000
	s_addc_u32 s7, s7, 0
	v_max_f32_e32 v108, 0, v212
	v_max_f32_e32 v109, 0, v213
	v_pk_mul_f32 v[0:1], v[22:23], v[108:109]
	v_max_f32_e32 v210, 0, v214
	v_max_f32_e32 v211, 0, v215
	v_pk_fma_f32 v[0:1], v[24:25], v[210:211], v[0:1]
	v_max_f32_e32 v108, 0, v216
	v_max_f32_e32 v109, 0, v217
	v_pk_fma_f32 v[0:1], v[26:27], v[108:109], v[0:1]
	v_mfma_f32_32x32x16_bf16 v[6:21], v[90:93], v[42:45], v[6:21]
	v_max_f32_e32 v210, 0, v218
	v_max_f32_e32 v211, 0, v219
	v_pk_fma_f32 v[0:1], v[28:29], v[210:211], v[0:1]
	v_max_f32_e32 v108, 0, v220
	v_max_f32_e32 v109, 0, v221
	v_pk_fma_f32 v[0:1], v[30:31], v[108:109], v[0:1]
	v_max_f32_e32 v210, 0, v222
	v_max_f32_e32 v211, 0, v223
	v_pk_fma_f32 v[0:1], v[32:33], v[210:211], v[0:1]
	v_mfma_f32_32x32x16_bf16 v[6:21], v[94:97], v[46:49], v[6:21]
	v_max_f32_e32 v108, 0, v224
	v_max_f32_e32 v109, 0, v225
	v_pk_fma_f32 v[0:1], v[34:35], v[108:109], v[0:1]
	v_max_f32_e32 v210, 0, v226
	v_max_f32_e32 v211, 0, v227
	v_pk_fma_f32 v[0:1], v[36:37], v[210:211], v[0:1]
	v_add_f32_e32 v0, v0, v1
	v_ashrrev_i32_e32 v1, 31, v0
	v_mfma_f32_32x32x16_bf16 v[6:21], v[98:101], v[196:199], v[6:21]
	s_waitcnt vmcnt(10)
	ds_read_b128 v[38:41], v5 offset:10496
	ds_read_b128 v[42:45], v52 offset:10496
	ds_read_b128 v[46:49], v55 offset:10496
	ds_read_b128 v[196:199], v56 offset:10496
	v_or_b32_e32 v1, 0x80000000, v1
	s_cmpk_gt_i32 s11, 408
	s_cselect_b64 vcc, -1, 0
	v_xor_b32_e32 v0, v1, v0
	v_cndmask_b32_e32 v183, v123, v0, vcc
	s_nop 1
	s_waitcnt lgkmcnt(3)
	v_mfma_f32_32x32x16_bf16 v[212:227], v[70:73], v[38:41], 0
	v_max_f32_e32 v108, 0, v6
	v_max_f32_e32 v109, 0, v7
	v_pk_mul_f32 v[50:51], v[244:245], v[108:109]
	v_max_f32_e32 v210, 0, v8
	v_max_f32_e32 v211, 0, v9
	v_pk_fma_f32 v[50:51], v[246:247], v[210:211], v[50:51]
	v_max_f32_e32 v108, 0, v10
	v_max_f32_e32 v109, 0, v11
	v_pk_fma_f32 v[50:51], v[248:249], v[108:109], v[50:51]
	s_waitcnt lgkmcnt(2)
	v_mfma_f32_32x32x16_bf16 v[212:227], v[74:77], v[42:45], v[212:227]
	v_max_f32_e32 v210, 0, v12
	v_max_f32_e32 v211, 0, v13
	v_pk_fma_f32 v[50:51], v[250:251], v[210:211], v[50:51]
	v_max_f32_e32 v108, 0, v14
	v_max_f32_e32 v109, 0, v15
	v_pk_fma_f32 v[50:51], v[252:253], v[108:109], v[50:51]
	v_max_f32_e32 v210, 0, v16
	v_max_f32_e32 v211, 0, v17
	v_pk_fma_f32 v[50:51], v[254:255], v[210:211], v[50:51]
	s_waitcnt lgkmcnt(1)
	v_mfma_f32_32x32x16_bf16 v[212:227], v[78:81], v[46:49], v[212:227]
	v_max_f32_e32 v108, 0, v18
	v_max_f32_e32 v109, 0, v19
	v_pk_fma_f32 v[50:51], v[200:201], v[108:109], v[50:51]
	v_max_f32_e32 v210, 0, v20
	v_max_f32_e32 v211, 0, v21
	v_pk_fma_f32 v[50:51], v[202:203], v[210:211], v[50:51]
	v_add_f32_e32 v50, v50, v51
	v_ashrrev_i32_e32 v51, 31, v50
	s_waitcnt lgkmcnt(0)
	v_mfma_f32_32x32x16_bf16 v[212:227], v[82:85], v[196:199], v[212:227]
	v_or_b32_e32 v51, 0x80000000, v51
	s_cmpk_gt_i32 s11, 408
	s_cselect_b64 vcc, -1, 0
	v_xor_b32_e32 v50, v51, v50
	v_cndmask_b32_e32 v50, v123, v50, vcc
	global_store_dword v243, v50, s[8:9] offset:2048
	s_add_u32 s8, s8, 0x1000
	s_addc_u32 s9, s9, 0
	v_mfma_f32_32x32x16_bf16 v[6:21], v[86:89], v[38:41], 0
	s_add_i32 m0, s10, 98304
	s_nop 0
	global_load_lds_dwordx4 v102, s[6:7]
	s_add_i32 m0, s10, 99328
	s_nop 0
	global_load_lds_dwordx4 v110, s[6:7]
	s_add_i32 m0, s10, 100352
	s_nop 0
	global_load_lds_dwordx4 v112, s[6:7]
	s_add_i32 m0, s10, 101376
	s_nop 0
	global_load_lds_dwordx4 v193, s[6:7]
	s_add_u32 s6, s6, 0x8000
	s_addc_u32 s7, s7, 0
	v_max_f32_e32 v108, 0, v212
	v_max_f32_e32 v109, 0, v213
	v_pk_mul_f32 v[0:1], v[22:23], v[108:109]
	v_max_f32_e32 v210, 0, v214
	v_max_f32_e32 v211, 0, v215
	v_pk_fma_f32 v[0:1], v[24:25], v[210:211], v[0:1]
	v_max_f32_e32 v108, 0, v216
	v_max_f32_e32 v109, 0, v217
	v_pk_fma_f32 v[0:1], v[26:27], v[108:109], v[0:1]
	v_mfma_f32_32x32x16_bf16 v[6:21], v[90:93], v[42:45], v[6:21]
	v_max_f32_e32 v210, 0, v218
	v_max_f32_e32 v211, 0, v219
	v_pk_fma_f32 v[0:1], v[28:29], v[210:211], v[0:1]
	v_max_f32_e32 v108, 0, v220
	v_max_f32_e32 v109, 0, v221
	v_pk_fma_f32 v[0:1], v[30:31], v[108:109], v[0:1]
	v_max_f32_e32 v210, 0, v222
	v_max_f32_e32 v211, 0, v223
	v_pk_fma_f32 v[0:1], v[32:33], v[210:211], v[0:1]
	v_mfma_f32_32x32x16_bf16 v[6:21], v[94:97], v[46:49], v[6:21]
	v_max_f32_e32 v108, 0, v224
	v_max_f32_e32 v109, 0, v225
	v_pk_fma_f32 v[0:1], v[34:35], v[108:109], v[0:1]
	v_max_f32_e32 v210, 0, v226
	v_max_f32_e32 v211, 0, v227
	v_pk_fma_f32 v[0:1], v[36:37], v[210:211], v[0:1]
	v_add_f32_e32 v0, v0, v1
	v_ashrrev_i32_e32 v1, 31, v0
	v_mfma_f32_32x32x16_bf16 v[6:21], v[98:101], v[196:199], v[6:21]
	s_waitcnt vmcnt(10)
	ds_read_b128 v[38:41], v5 offset:43264
	ds_read_b128 v[42:45], v52 offset:43264
	ds_read_b128 v[46:49], v55 offset:43264
	ds_read_b128 v[196:199], v56 offset:43264
	v_or_b32_e32 v1, 0x80000000, v1
	s_cmpk_gt_i32 s11, 416
	s_cselect_b64 vcc, -1, 0
	v_xor_b32_e32 v0, v1, v0
	v_cndmask_b32_e32 v187, v123, v0, vcc
	s_nop 1
	s_waitcnt lgkmcnt(3)
	v_mfma_f32_32x32x16_bf16 v[212:227], v[70:73], v[38:41], 0
	v_max_f32_e32 v108, 0, v6
	v_max_f32_e32 v109, 0, v7
	v_pk_mul_f32 v[50:51], v[244:245], v[108:109]
	v_max_f32_e32 v210, 0, v8
	v_max_f32_e32 v211, 0, v9
	v_pk_fma_f32 v[50:51], v[246:247], v[210:211], v[50:51]
	v_max_f32_e32 v108, 0, v10
	v_max_f32_e32 v109, 0, v11
	v_pk_fma_f32 v[50:51], v[248:249], v[108:109], v[50:51]
	s_waitcnt lgkmcnt(2)
	v_mfma_f32_32x32x16_bf16 v[212:227], v[74:77], v[42:45], v[212:227]
	v_max_f32_e32 v210, 0, v12
	v_max_f32_e32 v211, 0, v13
	v_pk_fma_f32 v[50:51], v[250:251], v[210:211], v[50:51]
	v_max_f32_e32 v108, 0, v14
	v_max_f32_e32 v109, 0, v15
	v_pk_fma_f32 v[50:51], v[252:253], v[108:109], v[50:51]
	v_max_f32_e32 v210, 0, v16
	v_max_f32_e32 v211, 0, v17
	v_pk_fma_f32 v[50:51], v[254:255], v[210:211], v[50:51]
	s_waitcnt lgkmcnt(1)
	v_mfma_f32_32x32x16_bf16 v[212:227], v[78:81], v[46:49], v[212:227]
	v_max_f32_e32 v108, 0, v18
	v_max_f32_e32 v109, 0, v19
	v_pk_fma_f32 v[50:51], v[200:201], v[108:109], v[50:51]
	v_max_f32_e32 v210, 0, v20
	v_max_f32_e32 v211, 0, v21
	v_pk_fma_f32 v[50:51], v[202:203], v[210:211], v[50:51]
	v_add_f32_e32 v50, v50, v51
	v_ashrrev_i32_e32 v51, 31, v50
	s_waitcnt lgkmcnt(0)
	v_mfma_f32_32x32x16_bf16 v[212:227], v[82:85], v[196:199], v[212:227]
	v_or_b32_e32 v51, 0x80000000, v51
	s_cmpk_gt_i32 s11, 416
	s_cselect_b64 vcc, -1, 0
	v_xor_b32_e32 v50, v51, v50
	v_cndmask_b32_e32 v50, v123, v50, vcc
	global_store_dword v243, v50, s[8:9]
	v_mfma_f32_32x32x16_bf16 v[6:21], v[86:89], v[38:41], 0
	s_add_i32 m0, s10, 0
	s_nop 0
	global_load_lds_dwordx4 v102, s[6:7]
	s_add_i32 m0, s10, 1024
	s_nop 0
	global_load_lds_dwordx4 v110, s[6:7]
	s_add_i32 m0, s10, 2048
	s_nop 0
	global_load_lds_dwordx4 v112, s[6:7]
	s_add_i32 m0, s10, 3072
	s_nop 0
	global_load_lds_dwordx4 v193, s[6:7]
	s_add_u32 s6, s6, 0x8000
	s_addc_u32 s7, s7, 0
	v_max_f32_e32 v108, 0, v212
	v_max_f32_e32 v109, 0, v213
	v_pk_mul_f32 v[0:1], v[22:23], v[108:109]
	v_max_f32_e32 v210, 0, v214
	v_max_f32_e32 v211, 0, v215
	v_pk_fma_f32 v[0:1], v[24:25], v[210:211], v[0:1]
	v_max_f32_e32 v108, 0, v216
	v_max_f32_e32 v109, 0, v217
	v_pk_fma_f32 v[0:1], v[26:27], v[108:109], v[0:1]
	v_mfma_f32_32x32x16_bf16 v[6:21], v[90:93], v[42:45], v[6:21]
	v_max_f32_e32 v210, 0, v218
	v_max_f32_e32 v211, 0, v219
	v_pk_fma_f32 v[0:1], v[28:29], v[210:211], v[0:1]
	v_max_f32_e32 v108, 0, v220
	v_max_f32_e32 v109, 0, v221
	v_pk_fma_f32 v[0:1], v[30:31], v[108:109], v[0:1]
	v_max_f32_e32 v210, 0, v222
	v_max_f32_e32 v211, 0, v223
	v_pk_fma_f32 v[0:1], v[32:33], v[210:211], v[0:1]
	v_mfma_f32_32x32x16_bf16 v[6:21], v[94:97], v[46:49], v[6:21]
	v_max_f32_e32 v108, 0, v224
	v_max_f32_e32 v109, 0, v225
	v_pk_fma_f32 v[0:1], v[34:35], v[108:109], v[0:1]
	v_max_f32_e32 v210, 0, v226
	v_max_f32_e32 v211, 0, v227
	v_pk_fma_f32 v[0:1], v[36:37], v[210:211], v[0:1]
	v_add_f32_e32 v0, v0, v1
	v_ashrrev_i32_e32 v1, 31, v0
	v_mfma_f32_32x32x16_bf16 v[6:21], v[98:101], v[196:199], v[6:21]
	s_waitcnt vmcnt(10)
	v_add_u32_e32 v228, 0x10000, v5
	ds_read_b128 v[38:41], v228 offset:10496
	v_add_u32_e32 v228, 0x10000, v52
	ds_read_b128 v[42:45], v228 offset:10496
	v_add_u32_e32 v228, 0x10000, v55
	ds_read_b128 v[46:49], v228 offset:10496
	v_add_u32_e32 v228, 0x10000, v56
	ds_read_b128 v[196:199], v228 offset:10496
	v_or_b32_e32 v1, 0x80000000, v1
	s_cmpk_gt_i32 s11, 424
	s_cselect_b64 vcc, -1, 0
	v_xor_b32_e32 v0, v1, v0
	v_cndmask_b32_e32 v186, v123, v0, vcc
	s_nop 1
	s_waitcnt lgkmcnt(3)
	v_mfma_f32_32x32x16_bf16 v[212:227], v[70:73], v[38:41], 0
	v_max_f32_e32 v108, 0, v6
	v_max_f32_e32 v109, 0, v7
	v_pk_mul_f32 v[50:51], v[244:245], v[108:109]
	v_max_f32_e32 v210, 0, v8
	v_max_f32_e32 v211, 0, v9
	v_pk_fma_f32 v[50:51], v[246:247], v[210:211], v[50:51]
	v_max_f32_e32 v108, 0, v10
	v_max_f32_e32 v109, 0, v11
	v_pk_fma_f32 v[50:51], v[248:249], v[108:109], v[50:51]
	s_waitcnt lgkmcnt(2)
	v_mfma_f32_32x32x16_bf16 v[212:227], v[74:77], v[42:45], v[212:227]
	v_max_f32_e32 v210, 0, v12
	v_max_f32_e32 v211, 0, v13
	v_pk_fma_f32 v[50:51], v[250:251], v[210:211], v[50:51]
	v_max_f32_e32 v108, 0, v14
	v_max_f32_e32 v109, 0, v15
	v_pk_fma_f32 v[50:51], v[252:253], v[108:109], v[50:51]
	v_max_f32_e32 v210, 0, v16
	v_max_f32_e32 v211, 0, v17
	v_pk_fma_f32 v[50:51], v[254:255], v[210:211], v[50:51]
	s_waitcnt lgkmcnt(1)
	v_mfma_f32_32x32x16_bf16 v[212:227], v[78:81], v[46:49], v[212:227]
	v_max_f32_e32 v108, 0, v18
	v_max_f32_e32 v109, 0, v19
	v_pk_fma_f32 v[50:51], v[200:201], v[108:109], v[50:51]
	v_max_f32_e32 v210, 0, v20
	v_max_f32_e32 v211, 0, v21
	v_pk_fma_f32 v[50:51], v[202:203], v[210:211], v[50:51]
	v_add_f32_e32 v50, v50, v51
	v_ashrrev_i32_e32 v51, 31, v50
	s_waitcnt lgkmcnt(0)
	v_mfma_f32_32x32x16_bf16 v[212:227], v[82:85], v[196:199], v[212:227]
	v_or_b32_e32 v51, 0x80000000, v51
	s_cmpk_gt_i32 s11, 424
	s_cselect_b64 vcc, -1, 0
	v_xor_b32_e32 v50, v51, v50
	v_cndmask_b32_e32 v50, v123, v50, vcc
	global_store_dword v243, v50, s[8:9] offset:2048
	s_add_u32 s8, s8, 0x1000
	s_addc_u32 s9, s9, 0
	v_mfma_f32_32x32x16_bf16 v[6:21], v[86:89], v[38:41], 0
	s_add_i32 m0, s10, 32768
	s_nop 0
	global_load_lds_dwordx4 v102, s[6:7]
	s_add_i32 m0, s10, 33792
	s_nop 0
	global_load_lds_dwordx4 v110, s[6:7]
	s_add_i32 m0, s10, 34816
	s_nop 0
	global_load_lds_dwordx4 v112, s[6:7]
	s_add_i32 m0, s10, 35840
	s_nop 0
	global_load_lds_dwordx4 v193, s[6:7]
	s_add_u32 s6, s6, 0x8000
	s_addc_u32 s7, s7, 0
	v_max_f32_e32 v108, 0, v212
	v_max_f32_e32 v109, 0, v213
	v_pk_mul_f32 v[0:1], v[22:23], v[108:109]
	v_max_f32_e32 v210, 0, v214
	v_max_f32_e32 v211, 0, v215
	v_pk_fma_f32 v[0:1], v[24:25], v[210:211], v[0:1]
	v_max_f32_e32 v108, 0, v216
	v_max_f32_e32 v109, 0, v217
	v_pk_fma_f32 v[0:1], v[26:27], v[108:109], v[0:1]
	v_mfma_f32_32x32x16_bf16 v[6:21], v[90:93], v[42:45], v[6:21]
	v_max_f32_e32 v210, 0, v218
	v_max_f32_e32 v211, 0, v219
	v_pk_fma_f32 v[0:1], v[28:29], v[210:211], v[0:1]
	v_max_f32_e32 v108, 0, v220
	v_max_f32_e32 v109, 0, v221
	v_pk_fma_f32 v[0:1], v[30:31], v[108:109], v[0:1]
	v_max_f32_e32 v210, 0, v222
	v_max_f32_e32 v211, 0, v223
	v_pk_fma_f32 v[0:1], v[32:33], v[210:211], v[0:1]
	v_mfma_f32_32x32x16_bf16 v[6:21], v[94:97], v[46:49], v[6:21]
	v_max_f32_e32 v108, 0, v224
	v_max_f32_e32 v109, 0, v225
	v_pk_fma_f32 v[0:1], v[34:35], v[108:109], v[0:1]
	v_max_f32_e32 v210, 0, v226
	v_max_f32_e32 v211, 0, v227
	v_pk_fma_f32 v[0:1], v[36:37], v[210:211], v[0:1]
	v_add_f32_e32 v0, v0, v1
	v_ashrrev_i32_e32 v1, 31, v0
	v_mfma_f32_32x32x16_bf16 v[6:21], v[98:101], v[196:199], v[6:21]
	s_waitcnt vmcnt(10)
	v_add_u32_e32 v228, 0x10000, v5
	ds_read_b128 v[38:41], v228 offset:43264
	v_add_u32_e32 v228, 0x10000, v52
	ds_read_b128 v[42:45], v228 offset:43264
	v_add_u32_e32 v228, 0x10000, v55
	ds_read_b128 v[46:49], v228 offset:43264
	v_add_u32_e32 v228, 0x10000, v56
	ds_read_b128 v[196:199], v228 offset:43264
	v_or_b32_e32 v1, 0x80000000, v1
	s_cmpk_gt_i32 s11, 432
	s_cselect_b64 vcc, -1, 0
	v_xor_b32_e32 v0, v1, v0
	v_cndmask_b32_e32 v189, v123, v0, vcc
	s_nop 1
	s_waitcnt lgkmcnt(3)
	v_mfma_f32_32x32x16_bf16 v[212:227], v[70:73], v[38:41], 0
	v_max_f32_e32 v108, 0, v6
	v_max_f32_e32 v109, 0, v7
	v_pk_mul_f32 v[50:51], v[244:245], v[108:109]
	v_max_f32_e32 v210, 0, v8
	v_max_f32_e32 v211, 0, v9
	v_pk_fma_f32 v[50:51], v[246:247], v[210:211], v[50:51]
	v_max_f32_e32 v108, 0, v10
	v_max_f32_e32 v109, 0, v11
	v_pk_fma_f32 v[50:51], v[248:249], v[108:109], v[50:51]
	s_waitcnt lgkmcnt(2)
	v_mfma_f32_32x32x16_bf16 v[212:227], v[74:77], v[42:45], v[212:227]
	v_max_f32_e32 v210, 0, v12
	v_max_f32_e32 v211, 0, v13
	v_pk_fma_f32 v[50:51], v[250:251], v[210:211], v[50:51]
	v_max_f32_e32 v108, 0, v14
	v_max_f32_e32 v109, 0, v15
	v_pk_fma_f32 v[50:51], v[252:253], v[108:109], v[50:51]
	v_max_f32_e32 v210, 0, v16
	v_max_f32_e32 v211, 0, v17
	v_pk_fma_f32 v[50:51], v[254:255], v[210:211], v[50:51]
	s_waitcnt lgkmcnt(1)
	v_mfma_f32_32x32x16_bf16 v[212:227], v[78:81], v[46:49], v[212:227]
	v_max_f32_e32 v108, 0, v18
	v_max_f32_e32 v109, 0, v19
	v_pk_fma_f32 v[50:51], v[200:201], v[108:109], v[50:51]
	v_max_f32_e32 v210, 0, v20
	v_max_f32_e32 v211, 0, v21
	v_pk_fma_f32 v[50:51], v[202:203], v[210:211], v[50:51]
	v_add_f32_e32 v50, v50, v51
	v_ashrrev_i32_e32 v51, 31, v50
	s_waitcnt lgkmcnt(0)
	v_mfma_f32_32x32x16_bf16 v[212:227], v[82:85], v[196:199], v[212:227]
	v_or_b32_e32 v51, 0x80000000, v51
	s_cmpk_gt_i32 s11, 432
	s_cselect_b64 vcc, -1, 0
	v_xor_b32_e32 v50, v51, v50
	v_cndmask_b32_e32 v50, v123, v50, vcc
	global_store_dword v243, v50, s[8:9]
	v_mfma_f32_32x32x16_bf16 v[6:21], v[86:89], v[38:41], 0
	s_add_i32 m0, s10, 65536
	s_nop 0
	global_load_lds_dwordx4 v102, s[6:7]
	s_add_i32 m0, s10, 66560
	s_nop 0
	global_load_lds_dwordx4 v110, s[6:7]
	s_add_i32 m0, s10, 67584
	s_nop 0
	global_load_lds_dwordx4 v112, s[6:7]
	s_add_i32 m0, s10, 68608
	s_nop 0
	global_load_lds_dwordx4 v193, s[6:7]
	s_add_u32 s6, s6, 0x8000
	s_addc_u32 s7, s7, 0
	v_max_f32_e32 v108, 0, v212
	v_max_f32_e32 v109, 0, v213
	v_pk_mul_f32 v[0:1], v[22:23], v[108:109]
	v_max_f32_e32 v210, 0, v214
	v_max_f32_e32 v211, 0, v215
	v_pk_fma_f32 v[0:1], v[24:25], v[210:211], v[0:1]
	v_max_f32_e32 v108, 0, v216
	v_max_f32_e32 v109, 0, v217
	v_pk_fma_f32 v[0:1], v[26:27], v[108:109], v[0:1]
	v_mfma_f32_32x32x16_bf16 v[6:21], v[90:93], v[42:45], v[6:21]
	v_max_f32_e32 v210, 0, v218
	v_max_f32_e32 v211, 0, v219
	v_pk_fma_f32 v[0:1], v[28:29], v[210:211], v[0:1]
	v_max_f32_e32 v108, 0, v220
	v_max_f32_e32 v109, 0, v221
	v_pk_fma_f32 v[0:1], v[30:31], v[108:109], v[0:1]
	v_max_f32_e32 v210, 0, v222
	v_max_f32_e32 v211, 0, v223
	v_pk_fma_f32 v[0:1], v[32:33], v[210:211], v[0:1]
	v_mfma_f32_32x32x16_bf16 v[6:21], v[94:97], v[46:49], v[6:21]
	v_max_f32_e32 v108, 0, v224
	v_max_f32_e32 v109, 0, v225
	v_pk_fma_f32 v[0:1], v[34:35], v[108:109], v[0:1]
	v_max_f32_e32 v210, 0, v226
	v_max_f32_e32 v211, 0, v227
	v_pk_fma_f32 v[0:1], v[36:37], v[210:211], v[0:1]
	v_add_f32_e32 v0, v0, v1
	v_ashrrev_i32_e32 v1, 31, v0
	v_mfma_f32_32x32x16_bf16 v[6:21], v[98:101], v[196:199], v[6:21]
	s_waitcnt vmcnt(10)
	ds_read_b128 v[38:41], v5 offset:10496
	ds_read_b128 v[42:45], v52 offset:10496
	ds_read_b128 v[46:49], v55 offset:10496
	ds_read_b128 v[196:199], v56 offset:10496
	v_or_b32_e32 v1, 0x80000000, v1
	s_cmpk_gt_i32 s11, 440
	s_cselect_b64 vcc, -1, 0
	v_xor_b32_e32 v0, v1, v0
	v_cndmask_b32_e32 v188, v123, v0, vcc
	s_nop 1
	v_max_f32_e32 v108, 0, v6
	v_max_f32_e32 v109, 0, v7
	v_pk_mul_f32 v[50:51], v[244:245], v[108:109]
	v_max_f32_e32 v210, 0, v8
	v_max_f32_e32 v211, 0, v9
	v_pk_fma_f32 v[50:51], v[246:247], v[210:211], v[50:51]
	v_max_f32_e32 v108, 0, v10
	v_max_f32_e32 v109, 0, v11
	v_pk_fma_f32 v[50:51], v[248:249], v[108:109], v[50:51]
	v_max_f32_e32 v210, 0, v12
	v_max_f32_e32 v211, 0, v13
	v_pk_fma_f32 v[50:51], v[250:251], v[210:211], v[50:51]
	v_max_f32_e32 v108, 0, v14
	v_max_f32_e32 v109, 0, v15
	v_pk_fma_f32 v[50:51], v[252:253], v[108:109], v[50:51]
	v_max_f32_e32 v210, 0, v16
	v_max_f32_e32 v211, 0, v17
	v_pk_fma_f32 v[50:51], v[254:255], v[210:211], v[50:51]
	v_max_f32_e32 v108, 0, v18
	v_max_f32_e32 v109, 0, v19
	v_pk_fma_f32 v[50:51], v[200:201], v[108:109], v[50:51]
	v_max_f32_e32 v210, 0, v20
	v_max_f32_e32 v211, 0, v21
	v_pk_fma_f32 v[50:51], v[202:203], v[210:211], v[50:51]
	v_add_f32_e32 v50, v50, v51
	v_ashrrev_i32_e32 v51, 31, v50
	v_or_b32_e32 v51, 0x80000000, v51
	s_cmpk_gt_i32 s11, 440
	s_cselect_b64 vcc, -1, 0
	v_xor_b32_e32 v50, v51, v50
	v_cndmask_b32_e32 v50, v123, v50, vcc
	global_store_dword v243, v50, s[8:9] offset:2048
	s_add_u32 s8, s8, 0x1000
	s_addc_u32 s9, s9, 0
	s_cmpk_gt_i32 s81, 56
	s_cbranch_scc0 .Lix_fill_7
	s_waitcnt lgkmcnt(3)
	v_mfma_f32_32x32x16_bf16 v[212:227], v[70:73], v[38:41], 0
	s_add_i32 m0, s10, 98304
	s_nop 0
	global_load_lds_dwordx4 v102, s[6:7]
	s_waitcnt lgkmcnt(2)
	v_mfma_f32_32x32x16_bf16 v[212:227], v[74:77], v[42:45], v[212:227]
	s_add_i32 m0, s10, 99328
	s_nop 0
	global_load_lds_dwordx4 v110, s[6:7]
	s_waitcnt lgkmcnt(1)
	v_mfma_f32_32x32x16_bf16 v[212:227], v[78:81], v[46:49], v[212:227]
	s_add_i32 m0, s10, 100352
	s_nop 0
	global_load_lds_dwordx4 v112, s[6:7]
	s_waitcnt lgkmcnt(0)
	v_mfma_f32_32x32x16_bf16 v[212:227], v[82:85], v[196:199], v[212:227]
	s_add_i32 m0, s10, 101376
	s_nop 0
	global_load_lds_dwordx4 v193, s[6:7]
	s_add_u32 s6, s6, 0x8000
	s_addc_u32 s7, s7, 0
	v_mfma_f32_32x32x16_bf16 v[6:21], v[86:89], v[38:41], 0
	s_nop 7
	s_nop 2
	v_max_f32_e32 v108, 0, v212
	v_max_f32_e32 v109, 0, v213
	v_pk_mul_f32 v[0:1], v[22:23], v[108:109]
	v_max_f32_e32 v210, 0, v214
	v_max_f32_e32 v211, 0, v215
	v_pk_fma_f32 v[0:1], v[24:25], v[210:211], v[0:1]
	v_max_f32_e32 v108, 0, v216
	v_max_f32_e32 v109, 0, v217
	v_pk_fma_f32 v[0:1], v[26:27], v[108:109], v[0:1]
	v_mfma_f32_32x32x16_bf16 v[6:21], v[90:93], v[42:45], v[6:21]
	v_max_f32_e32 v210, 0, v218
	v_max_f32_e32 v211, 0, v219
	v_pk_fma_f32 v[0:1], v[28:29], v[210:211], v[0:1]
	v_max_f32_e32 v108, 0, v220
	v_max_f32_e32 v109, 0, v221
	v_pk_fma_f32 v[0:1], v[30:31], v[108:109], v[0:1]
	v_max_f32_e32 v210, 0, v222
	v_max_f32_e32 v211, 0, v223
	v_pk_fma_f32 v[0:1], v[32:33], v[210:211], v[0:1]
	v_mfma_f32_32x32x16_bf16 v[6:21], v[94:97], v[46:49], v[6:21]
	v_max_f32_e32 v108, 0, v224
	v_max_f32_e32 v109, 0, v225
	v_pk_fma_f32 v[0:1], v[34:35], v[108:109], v[0:1]
	v_max_f32_e32 v210, 0, v226
	v_max_f32_e32 v211, 0, v227
	v_pk_fma_f32 v[0:1], v[36:37], v[210:211], v[0:1]
	v_add_f32_e32 v0, v0, v1
	v_ashrrev_i32_e32 v1, 31, v0
	v_mfma_f32_32x32x16_bf16 v[6:21], v[98:101], v[196:199], v[6:21]
	s_waitcnt vmcnt(10)
	ds_read_b128 v[38:41], v5 offset:43264
	ds_read_b128 v[42:45], v52 offset:43264
	ds_read_b128 v[46:49], v55 offset:43264
	ds_read_b128 v[196:199], v56 offset:43264
	v_or_b32_e32 v1, 0x80000000, v1
	s_cmpk_gt_i32 s11, 448
	s_cselect_b64 vcc, -1, 0
	v_xor_b32_e32 v0, v1, v0
	v_cndmask_b32_e32 v190, v123, v0, vcc
	s_nop 1
	s_waitcnt lgkmcnt(3)
	v_mfma_f32_32x32x16_bf16 v[212:227], v[70:73], v[38:41], 0
	v_max_f32_e32 v108, 0, v6
	v_max_f32_e32 v109, 0, v7
	v_pk_mul_f32 v[50:51], v[244:245], v[108:109]
	v_max_f32_e32 v210, 0, v8
	v_max_f32_e32 v211, 0, v9
	v_pk_fma_f32 v[50:51], v[246:247], v[210:211], v[50:51]
	v_max_f32_e32 v108, 0, v10
	v_max_f32_e32 v109, 0, v11
	v_pk_fma_f32 v[50:51], v[248:249], v[108:109], v[50:51]
	s_waitcnt lgkmcnt(2)
	v_mfma_f32_32x32x16_bf16 v[212:227], v[74:77], v[42:45], v[212:227]
	v_max_f32_e32 v210, 0, v12
	v_max_f32_e32 v211, 0, v13
	v_pk_fma_f32 v[50:51], v[250:251], v[210:211], v[50:51]
	v_max_f32_e32 v108, 0, v14
	v_max_f32_e32 v109, 0, v15
	v_pk_fma_f32 v[50:51], v[252:253], v[108:109], v[50:51]
	v_max_f32_e32 v210, 0, v16
	v_max_f32_e32 v211, 0, v17
	v_pk_fma_f32 v[50:51], v[254:255], v[210:211], v[50:51]
	s_waitcnt lgkmcnt(1)
	v_mfma_f32_32x32x16_bf16 v[212:227], v[78:81], v[46:49], v[212:227]
	v_max_f32_e32 v108, 0, v18
	v_max_f32_e32 v109, 0, v19
	v_pk_fma_f32 v[50:51], v[200:201], v[108:109], v[50:51]
	v_max_f32_e32 v210, 0, v20
	v_max_f32_e32 v211, 0, v21
	v_pk_fma_f32 v[50:51], v[202:203], v[210:211], v[50:51]
	v_add_f32_e32 v50, v50, v51
	v_ashrrev_i32_e32 v51, 31, v50
	s_waitcnt lgkmcnt(0)
	v_mfma_f32_32x32x16_bf16 v[212:227], v[82:85], v[196:199], v[212:227]
	v_or_b32_e32 v51, 0x80000000, v51
	s_cmpk_gt_i32 s11, 448
	s_cselect_b64 vcc, -1, 0
	v_xor_b32_e32 v50, v51, v50
	v_cndmask_b32_e32 v50, v123, v50, vcc
	global_store_dword v243, v50, s[8:9]
	v_mfma_f32_32x32x16_bf16 v[6:21], v[86:89], v[38:41], 0
	s_add_i32 m0, s10, 0
	s_nop 0
	global_load_lds_dwordx4 v102, s[6:7]
	s_add_i32 m0, s10, 1024
	s_nop 0
	global_load_lds_dwordx4 v110, s[6:7]
	s_add_i32 m0, s10, 2048
	s_nop 0
	global_load_lds_dwordx4 v112, s[6:7]
	s_add_i32 m0, s10, 3072
	s_nop 0
	global_load_lds_dwordx4 v193, s[6:7]
	s_add_u32 s6, s6, 0x8000
	s_addc_u32 s7, s7, 0
	v_max_f32_e32 v108, 0, v212
	v_max_f32_e32 v109, 0, v213
	v_pk_mul_f32 v[0:1], v[22:23], v[108:109]
	v_max_f32_e32 v210, 0, v214
	v_max_f32_e32 v211, 0, v215
	v_pk_fma_f32 v[0:1], v[24:25], v[210:211], v[0:1]
	v_max_f32_e32 v108, 0, v216
	v_max_f32_e32 v109, 0, v217
	v_pk_fma_f32 v[0:1], v[26:27], v[108:109], v[0:1]
	v_mfma_f32_32x32x16_bf16 v[6:21], v[90:93], v[42:45], v[6:21]
	v_max_f32_e32 v210, 0, v218
	v_max_f32_e32 v211, 0, v219
	v_pk_fma_f32 v[0:1], v[28:29], v[210:211], v[0:1]
	v_max_f32_e32 v108, 0, v220
	v_max_f32_e32 v109, 0, v221
	v_pk_fma_f32 v[0:1], v[30:31], v[108:109], v[0:1]
	v_max_f32_e32 v210, 0, v222
	v_max_f32_e32 v211, 0, v223
	v_pk_fma_f32 v[0:1], v[32:33], v[210:211], v[0:1]
	v_mfma_f32_32x32x16_bf16 v[6:21], v[94:97], v[46:49], v[6:21]
	v_max_f32_e32 v108, 0, v224
	v_max_f32_e32 v109, 0, v225
	v_pk_fma_f32 v[0:1], v[34:35], v[108:109], v[0:1]
	v_max_f32_e32 v210, 0, v226
	v_max_f32_e32 v211, 0, v227
	v_pk_fma_f32 v[0:1], v[36:37], v[210:211], v[0:1]
	v_add_f32_e32 v0, v0, v1
	v_ashrrev_i32_e32 v1, 31, v0
	v_mfma_f32_32x32x16_bf16 v[6:21], v[98:101], v[196:199], v[6:21]
	s_waitcnt vmcnt(10)
	v_add_u32_e32 v228, 0x10000, v5
	ds_read_b128 v[38:41], v228 offset:10496
	v_add_u32_e32 v228, 0x10000, v52
	ds_read_b128 v[42:45], v228 offset:10496
	v_add_u32_e32 v228, 0x10000, v55
	ds_read_b128 v[46:49], v228 offset:10496
	v_add_u32_e32 v228, 0x10000, v56
	ds_read_b128 v[196:199], v228 offset:10496
	v_or_b32_e32 v1, 0x80000000, v1
	s_cmpk_gt_i32 s11, 456
	s_cselect_b64 vcc, -1, 0
	v_xor_b32_e32 v0, v1, v0
	v_cndmask_b32_e32 v53, v123, v0, vcc
	s_nop 1
	s_waitcnt lgkmcnt(3)
	v_mfma_f32_32x32x16_bf16 v[212:227], v[70:73], v[38:41], 0
	v_max_f32_e32 v108, 0, v6
	v_max_f32_e32 v109, 0, v7
	v_pk_mul_f32 v[50:51], v[244:245], v[108:109]
	v_max_f32_e32 v210, 0, v8
	v_max_f32_e32 v211, 0, v9
	v_pk_fma_f32 v[50:51], v[246:247], v[210:211], v[50:51]
	v_max_f32_e32 v108, 0, v10
	v_max_f32_e32 v109, 0, v11
	v_pk_fma_f32 v[50:51], v[248:249], v[108:109], v[50:51]
	s_waitcnt lgkmcnt(2)
	v_mfma_f32_32x32x16_bf16 v[212:227], v[74:77], v[42:45], v[212:227]
	v_max_f32_e32 v210, 0, v12
	v_max_f32_e32 v211, 0, v13
	v_pk_fma_f32 v[50:51], v[250:251], v[210:211], v[50:51]
	v_max_f32_e32 v108, 0, v14
	v_max_f32_e32 v109, 0, v15
	v_pk_fma_f32 v[50:51], v[252:253], v[108:109], v[50:51]
	v_max_f32_e32 v210, 0, v16
	v_max_f32_e32 v211, 0, v17
	v_pk_fma_f32 v[50:51], v[254:255], v[210:211], v[50:51]
	s_waitcnt lgkmcnt(1)
	v_mfma_f32_32x32x16_bf16 v[212:227], v[78:81], v[46:49], v[212:227]
	v_max_f32_e32 v108, 0, v18
	v_max_f32_e32 v109, 0, v19
	v_pk_fma_f32 v[50:51], v[200:201], v[108:109], v[50:51]
	v_max_f32_e32 v210, 0, v20
	v_max_f32_e32 v211, 0, v21
	v_pk_fma_f32 v[50:51], v[202:203], v[210:211], v[50:51]
	v_add_f32_e32 v50, v50, v51
	v_ashrrev_i32_e32 v51, 31, v50
	s_waitcnt lgkmcnt(0)
	v_mfma_f32_32x32x16_bf16 v[212:227], v[82:85], v[196:199], v[212:227]
	v_or_b32_e32 v51, 0x80000000, v51
	s_cmpk_gt_i32 s11, 456
	s_cselect_b64 vcc, -1, 0
	v_xor_b32_e32 v50, v51, v50
	v_cndmask_b32_e32 v50, v123, v50, vcc
	global_store_dword v243, v50, s[8:9] offset:2048
	s_add_u32 s8, s8, 0x1000
	s_addc_u32 s9, s9, 0
	v_mfma_f32_32x32x16_bf16 v[6:21], v[86:89], v[38:41], 0
	s_add_i32 m0, s10, 32768
	s_nop 0
	global_load_lds_dwordx4 v102, s[6:7]
	s_add_i32 m0, s10, 33792
	s_nop 0
	global_load_lds_dwordx4 v110, s[6:7]
	s_add_i32 m0, s10, 34816
	s_nop 0
	global_load_lds_dwordx4 v112, s[6:7]
	s_add_i32 m0, s10, 35840
	s_nop 0
	global_load_lds_dwordx4 v193, s[6:7]
	s_add_u32 s6, s6, 0x8000
	s_addc_u32 s7, s7, 0
	v_max_f32_e32 v108, 0, v212
	v_max_f32_e32 v109, 0, v213
	v_pk_mul_f32 v[0:1], v[22:23], v[108:109]
	v_max_f32_e32 v210, 0, v214
	v_max_f32_e32 v211, 0, v215
	v_pk_fma_f32 v[0:1], v[24:25], v[210:211], v[0:1]
	v_max_f32_e32 v108, 0, v216
	v_max_f32_e32 v109, 0, v217
	v_pk_fma_f32 v[0:1], v[26:27], v[108:109], v[0:1]
	v_mfma_f32_32x32x16_bf16 v[6:21], v[90:93], v[42:45], v[6:21]
	v_max_f32_e32 v210, 0, v218
	v_max_f32_e32 v211, 0, v219
	v_pk_fma_f32 v[0:1], v[28:29], v[210:211], v[0:1]
	v_max_f32_e32 v108, 0, v220
	v_max_f32_e32 v109, 0, v221
	v_pk_fma_f32 v[0:1], v[30:31], v[108:109], v[0:1]
	v_max_f32_e32 v210, 0, v222
	v_max_f32_e32 v211, 0, v223
	v_pk_fma_f32 v[0:1], v[32:33], v[210:211], v[0:1]
	v_mfma_f32_32x32x16_bf16 v[6:21], v[94:97], v[46:49], v[6:21]
	v_max_f32_e32 v108, 0, v224
	v_max_f32_e32 v109, 0, v225
	v_pk_fma_f32 v[0:1], v[34:35], v[108:109], v[0:1]
	v_max_f32_e32 v210, 0, v226
	v_max_f32_e32 v211, 0, v227
	v_pk_fma_f32 v[0:1], v[36:37], v[210:211], v[0:1]
	v_add_f32_e32 v0, v0, v1
	v_ashrrev_i32_e32 v1, 31, v0
	v_mfma_f32_32x32x16_bf16 v[6:21], v[98:101], v[196:199], v[6:21]
	s_waitcnt vmcnt(10)
	v_add_u32_e32 v228, 0x10000, v5
	ds_read_b128 v[38:41], v228 offset:43264
	v_add_u32_e32 v228, 0x10000, v52
	ds_read_b128 v[42:45], v228 offset:43264
	v_add_u32_e32 v228, 0x10000, v55
	ds_read_b128 v[46:49], v228 offset:43264
	v_add_u32_e32 v228, 0x10000, v56
	ds_read_b128 v[196:199], v228 offset:43264
	v_or_b32_e32 v1, 0x80000000, v1
	s_cmpk_gt_i32 s11, 464
	s_cselect_b64 vcc, -1, 0
	v_xor_b32_e32 v0, v1, v0
	v_cndmask_b32_e32 v192, v123, v0, vcc
	s_nop 1
	s_waitcnt lgkmcnt(3)
	v_mfma_f32_32x32x16_bf16 v[212:227], v[70:73], v[38:41], 0
	v_max_f32_e32 v108, 0, v6
	v_max_f32_e32 v109, 0, v7
	v_pk_mul_f32 v[50:51], v[244:245], v[108:109]
	v_max_f32_e32 v210, 0, v8
	v_max_f32_e32 v211, 0, v9
	v_pk_fma_f32 v[50:51], v[246:247], v[210:211], v[50:51]
	v_max_f32_e32 v108, 0, v10
	v_max_f32_e32 v109, 0, v11
	v_pk_fma_f32 v[50:51], v[248:249], v[108:109], v[50:51]
	s_waitcnt lgkmcnt(2)
	v_mfma_f32_32x32x16_bf16 v[212:227], v[74:77], v[42:45], v[212:227]
	v_max_f32_e32 v210, 0, v12
	v_max_f32_e32 v211, 0, v13
	v_pk_fma_f32 v[50:51], v[250:251], v[210:211], v[50:51]
	v_max_f32_e32 v108, 0, v14
	v_max_f32_e32 v109, 0, v15
	v_pk_fma_f32 v[50:51], v[252:253], v[108:109], v[50:51]
	v_max_f32_e32 v210, 0, v16
	v_max_f32_e32 v211, 0, v17
	v_pk_fma_f32 v[50:51], v[254:255], v[210:211], v[50:51]
	s_waitcnt lgkmcnt(1)
	v_mfma_f32_32x32x16_bf16 v[212:227], v[78:81], v[46:49], v[212:227]
	v_max_f32_e32 v108, 0, v18
	v_max_f32_e32 v109, 0, v19
	v_pk_fma_f32 v[50:51], v[200:201], v[108:109], v[50:51]
	v_max_f32_e32 v210, 0, v20
	v_max_f32_e32 v211, 0, v21
	v_pk_fma_f32 v[50:51], v[202:203], v[210:211], v[50:51]
	v_add_f32_e32 v50, v50, v51
	v_ashrrev_i32_e32 v51, 31, v50
	s_waitcnt lgkmcnt(0)
	v_mfma_f32_32x32x16_bf16 v[212:227], v[82:85], v[196:199], v[212:227]
	v_or_b32_e32 v51, 0x80000000, v51
	s_cmpk_gt_i32 s11, 464
	s_cselect_b64 vcc, -1, 0
	v_xor_b32_e32 v50, v51, v50
	v_cndmask_b32_e32 v50, v123, v50, vcc
	global_store_dword v243, v50, s[8:9]
	v_mfma_f32_32x32x16_bf16 v[6:21], v[86:89], v[38:41], 0
	s_add_i32 m0, s10, 65536
	s_nop 0
	global_load_lds_dwordx4 v102, s[6:7]
	s_add_i32 m0, s10, 66560
	s_nop 0
	global_load_lds_dwordx4 v110, s[6:7]
	s_add_i32 m0, s10, 67584
	s_nop 0
	global_load_lds_dwordx4 v112, s[6:7]
	s_add_i32 m0, s10, 68608
	s_nop 0
	global_load_lds_dwordx4 v193, s[6:7]
	s_add_u32 s6, s6, 0x8000
	s_addc_u32 s7, s7, 0
	v_max_f32_e32 v108, 0, v212
	v_max_f32_e32 v109, 0, v213
	v_pk_mul_f32 v[0:1], v[22:23], v[108:109]
	v_max_f32_e32 v210, 0, v214
	v_max_f32_e32 v211, 0, v215
	v_pk_fma_f32 v[0:1], v[24:25], v[210:211], v[0:1]
	v_max_f32_e32 v108, 0, v216
	v_max_f32_e32 v109, 0, v217
	v_pk_fma_f32 v[0:1], v[26:27], v[108:109], v[0:1]
	v_mfma_f32_32x32x16_bf16 v[6:21], v[90:93], v[42:45], v[6:21]
	v_max_f32_e32 v210, 0, v218
	v_max_f32_e32 v211, 0, v219
	v_pk_fma_f32 v[0:1], v[28:29], v[210:211], v[0:1]
	v_max_f32_e32 v108, 0, v220
	v_max_f32_e32 v109, 0, v221
	v_pk_fma_f32 v[0:1], v[30:31], v[108:109], v[0:1]
	v_max_f32_e32 v210, 0, v222
	v_max_f32_e32 v211, 0, v223
	v_pk_fma_f32 v[0:1], v[32:33], v[210:211], v[0:1]
	v_mfma_f32_32x32x16_bf16 v[6:21], v[94:97], v[46:49], v[6:21]
	v_max_f32_e32 v108, 0, v224
	v_max_f32_e32 v109, 0, v225
	v_pk_fma_f32 v[0:1], v[34:35], v[108:109], v[0:1]
	v_max_f32_e32 v210, 0, v226
	v_max_f32_e32 v211, 0, v227
	v_pk_fma_f32 v[0:1], v[36:37], v[210:211], v[0:1]
	v_add_f32_e32 v0, v0, v1
	v_ashrrev_i32_e32 v1, 31, v0
	v_mfma_f32_32x32x16_bf16 v[6:21], v[98:101], v[196:199], v[6:21]
	s_waitcnt vmcnt(10)
	ds_read_b128 v[38:41], v5 offset:10496
	ds_read_b128 v[42:45], v52 offset:10496
	ds_read_b128 v[46:49], v55 offset:10496
	ds_read_b128 v[196:199], v56 offset:10496
	v_or_b32_e32 v1, 0x80000000, v1
	s_cmpk_gt_i32 s11, 472
	s_cselect_b64 vcc, -1, 0
	v_xor_b32_e32 v0, v1, v0
	v_cndmask_b32_e32 v191, v123, v0, vcc
	s_nop 1
	s_waitcnt lgkmcnt(3)
	v_mfma_f32_32x32x16_bf16 v[212:227], v[70:73], v[38:41], 0
	v_max_f32_e32 v108, 0, v6
	v_max_f32_e32 v109, 0, v7
	v_pk_mul_f32 v[50:51], v[244:245], v[108:109]
	v_max_f32_e32 v210, 0, v8
	v_max_f32_e32 v211, 0, v9
	v_pk_fma_f32 v[50:51], v[246:247], v[210:211], v[50:51]
	v_max_f32_e32 v108, 0, v10
	v_max_f32_e32 v109, 0, v11
	v_pk_fma_f32 v[50:51], v[248:249], v[108:109], v[50:51]
	s_waitcnt lgkmcnt(2)
	v_mfma_f32_32x32x16_bf16 v[212:227], v[74:77], v[42:45], v[212:227]
	v_max_f32_e32 v210, 0, v12
	v_max_f32_e32 v211, 0, v13
	v_pk_fma_f32 v[50:51], v[250:251], v[210:211], v[50:51]
	v_max_f32_e32 v108, 0, v14
	v_max_f32_e32 v109, 0, v15
	v_pk_fma_f32 v[50:51], v[252:253], v[108:109], v[50:51]
	v_max_f32_e32 v210, 0, v16
	v_max_f32_e32 v211, 0, v17
	v_pk_fma_f32 v[50:51], v[254:255], v[210:211], v[50:51]
	s_waitcnt lgkmcnt(1)
	v_mfma_f32_32x32x16_bf16 v[212:227], v[78:81], v[46:49], v[212:227]
	v_max_f32_e32 v108, 0, v18
	v_max_f32_e32 v109, 0, v19
	v_pk_fma_f32 v[50:51], v[200:201], v[108:109], v[50:51]
	v_max_f32_e32 v210, 0, v20
	v_max_f32_e32 v211, 0, v21
	v_pk_fma_f32 v[50:51], v[202:203], v[210:211], v[50:51]
	v_add_f32_e32 v50, v50, v51
	v_ashrrev_i32_e32 v51, 31, v50
	s_waitcnt lgkmcnt(0)
	v_mfma_f32_32x32x16_bf16 v[212:227], v[82:85], v[196:199], v[212:227]
	v_or_b32_e32 v51, 0x80000000, v51
	s_cmpk_gt_i32 s11, 472
	s_cselect_b64 vcc, -1, 0
	v_xor_b32_e32 v50, v51, v50
	v_cndmask_b32_e32 v50, v123, v50, vcc
	global_store_dword v243, v50, s[8:9] offset:2048
	s_add_u32 s8, s8, 0x1000
	s_addc_u32 s9, s9, 0
	v_mfma_f32_32x32x16_bf16 v[6:21], v[86:89], v[38:41], 0
	s_add_i32 m0, s10, 98304
	s_nop 0
	global_load_lds_dwordx4 v102, s[6:7]
	s_add_i32 m0, s10, 99328
	s_nop 0
	global_load_lds_dwordx4 v110, s[6:7]
	s_add_i32 m0, s10, 100352
	s_nop 0
	global_load_lds_dwordx4 v112, s[6:7]
	s_add_i32 m0, s10, 101376
	s_nop 0
	global_load_lds_dwordx4 v193, s[6:7]
	s_add_u32 s6, s6, 0x8000
	s_addc_u32 s7, s7, 0
	v_max_f32_e32 v108, 0, v212
	v_max_f32_e32 v109, 0, v213
	v_pk_mul_f32 v[0:1], v[22:23], v[108:109]
	v_max_f32_e32 v210, 0, v214
	v_max_f32_e32 v211, 0, v215
	v_pk_fma_f32 v[0:1], v[24:25], v[210:211], v[0:1]
	v_max_f32_e32 v108, 0, v216
	v_max_f32_e32 v109, 0, v217
	v_pk_fma_f32 v[0:1], v[26:27], v[108:109], v[0:1]
	v_mfma_f32_32x32x16_bf16 v[6:21], v[90:93], v[42:45], v[6:21]
	v_max_f32_e32 v210, 0, v218
	v_max_f32_e32 v211, 0, v219
	v_pk_fma_f32 v[0:1], v[28:29], v[210:211], v[0:1]
	v_max_f32_e32 v108, 0, v220
	v_max_f32_e32 v109, 0, v221
	v_pk_fma_f32 v[0:1], v[30:31], v[108:109], v[0:1]
	v_max_f32_e32 v210, 0, v222
	v_max_f32_e32 v211, 0, v223
	v_pk_fma_f32 v[0:1], v[32:33], v[210:211], v[0:1]
	v_mfma_f32_32x32x16_bf16 v[6:21], v[94:97], v[46:49], v[6:21]
	v_max_f32_e32 v108, 0, v224
	v_max_f32_e32 v109, 0, v225
	v_pk_fma_f32 v[0:1], v[34:35], v[108:109], v[0:1]
	v_max_f32_e32 v210, 0, v226
	v_max_f32_e32 v211, 0, v227
	v_pk_fma_f32 v[0:1], v[36:37], v[210:211], v[0:1]
	v_add_f32_e32 v0, v0, v1
	v_ashrrev_i32_e32 v1, 31, v0
	v_mfma_f32_32x32x16_bf16 v[6:21], v[98:101], v[196:199], v[6:21]
	s_waitcnt vmcnt(10)
	ds_read_b128 v[38:41], v5 offset:43264
	ds_read_b128 v[42:45], v52 offset:43264
	ds_read_b128 v[46:49], v55 offset:43264
	ds_read_b128 v[196:199], v56 offset:43264
	v_or_b32_e32 v1, 0x80000000, v1
	s_cmpk_gt_i32 s11, 480
	s_cselect_b64 vcc, -1, 0
	v_xor_b32_e32 v0, v1, v0
	v_cndmask_b32_e32 v3, v123, v0, vcc
	s_nop 1
	s_waitcnt lgkmcnt(3)
	v_mfma_f32_32x32x16_bf16 v[212:227], v[70:73], v[38:41], 0
	v_max_f32_e32 v108, 0, v6
	v_max_f32_e32 v109, 0, v7
	v_pk_mul_f32 v[50:51], v[244:245], v[108:109]
	v_max_f32_e32 v210, 0, v8
	v_max_f32_e32 v211, 0, v9
	v_pk_fma_f32 v[50:51], v[246:247], v[210:211], v[50:51]
	v_max_f32_e32 v108, 0, v10
	v_max_f32_e32 v109, 0, v11
	v_pk_fma_f32 v[50:51], v[248:249], v[108:109], v[50:51]
	s_waitcnt lgkmcnt(2)
	v_mfma_f32_32x32x16_bf16 v[212:227], v[74:77], v[42:45], v[212:227]
	v_max_f32_e32 v210, 0, v12
	v_max_f32_e32 v211, 0, v13
	v_pk_fma_f32 v[50:51], v[250:251], v[210:211], v[50:51]
	v_max_f32_e32 v108, 0, v14
	v_max_f32_e32 v109, 0, v15
	v_pk_fma_f32 v[50:51], v[252:253], v[108:109], v[50:51]
	v_max_f32_e32 v210, 0, v16
	v_max_f32_e32 v211, 0, v17
	v_pk_fma_f32 v[50:51], v[254:255], v[210:211], v[50:51]
	s_waitcnt lgkmcnt(1)
	v_mfma_f32_32x32x16_bf16 v[212:227], v[78:81], v[46:49], v[212:227]
	v_max_f32_e32 v108, 0, v18
	v_max_f32_e32 v109, 0, v19
	v_pk_fma_f32 v[50:51], v[200:201], v[108:109], v[50:51]
	v_max_f32_e32 v210, 0, v20
	v_max_f32_e32 v211, 0, v21
	v_pk_fma_f32 v[50:51], v[202:203], v[210:211], v[50:51]
	v_add_f32_e32 v50, v50, v51
	v_ashrrev_i32_e32 v51, 31, v50
	s_waitcnt lgkmcnt(0)
	v_mfma_f32_32x32x16_bf16 v[212:227], v[82:85], v[196:199], v[212:227]
	v_or_b32_e32 v51, 0x80000000, v51
	s_cmpk_gt_i32 s11, 480
	s_cselect_b64 vcc, -1, 0
	v_xor_b32_e32 v50, v51, v50
	v_cndmask_b32_e32 v50, v123, v50, vcc
	global_store_dword v243, v50, s[8:9]
	v_mfma_f32_32x32x16_bf16 v[6:21], v[86:89], v[38:41], 0
	s_add_i32 m0, s10, 0
	s_nop 0
	global_load_lds_dwordx4 v102, s[6:7]
	s_add_i32 m0, s10, 1024
	s_nop 0
	global_load_lds_dwordx4 v110, s[6:7]
	s_add_i32 m0, s10, 2048
	s_nop 0
	global_load_lds_dwordx4 v112, s[6:7]
	s_add_i32 m0, s10, 3072
	s_nop 0
	global_load_lds_dwordx4 v193, s[6:7]
	s_add_u32 s6, s6, 0x8000
	s_addc_u32 s7, s7, 0
	v_max_f32_e32 v108, 0, v212
	v_max_f32_e32 v109, 0, v213
	v_pk_mul_f32 v[0:1], v[22:23], v[108:109]
	v_max_f32_e32 v210, 0, v214
	v_max_f32_e32 v211, 0, v215
	v_pk_fma_f32 v[0:1], v[24:25], v[210:211], v[0:1]
	v_max_f32_e32 v108, 0, v216
	v_max_f32_e32 v109, 0, v217
	v_pk_fma_f32 v[0:1], v[26:27], v[108:109], v[0:1]
	v_mfma_f32_32x32x16_bf16 v[6:21], v[90:93], v[42:45], v[6:21]
	v_max_f32_e32 v210, 0, v218
	v_max_f32_e32 v211, 0, v219
	v_pk_fma_f32 v[0:1], v[28:29], v[210:211], v[0:1]
	v_max_f32_e32 v108, 0, v220
	v_max_f32_e32 v109, 0, v221
	v_pk_fma_f32 v[0:1], v[30:31], v[108:109], v[0:1]
	v_max_f32_e32 v210, 0, v222
	v_max_f32_e32 v211, 0, v223
	v_pk_fma_f32 v[0:1], v[32:33], v[210:211], v[0:1]
	v_mfma_f32_32x32x16_bf16 v[6:21], v[94:97], v[46:49], v[6:21]
	v_max_f32_e32 v108, 0, v224
	v_max_f32_e32 v109, 0, v225
	v_pk_fma_f32 v[0:1], v[34:35], v[108:109], v[0:1]
	v_max_f32_e32 v210, 0, v226
	v_max_f32_e32 v211, 0, v227
	v_pk_fma_f32 v[0:1], v[36:37], v[210:211], v[0:1]
	v_add_f32_e32 v0, v0, v1
	v_ashrrev_i32_e32 v1, 31, v0
	v_mfma_f32_32x32x16_bf16 v[6:21], v[98:101], v[196:199], v[6:21]
	s_waitcnt vmcnt(10)
	v_add_u32_e32 v228, 0x10000, v5
	ds_read_b128 v[38:41], v228 offset:10496
	v_add_u32_e32 v228, 0x10000, v52
	ds_read_b128 v[42:45], v228 offset:10496
	v_add_u32_e32 v228, 0x10000, v55
	ds_read_b128 v[46:49], v228 offset:10496
	v_add_u32_e32 v228, 0x10000, v56
	ds_read_b128 v[196:199], v228 offset:10496
	v_or_b32_e32 v1, 0x80000000, v1
	s_cmpk_gt_i32 s11, 488
	s_cselect_b64 vcc, -1, 0
	v_xor_b32_e32 v0, v1, v0
	v_cndmask_b32_e32 v2, v123, v0, vcc
	s_nop 1
	s_waitcnt lgkmcnt(3)
	v_mfma_f32_32x32x16_bf16 v[212:227], v[70:73], v[38:41], 0
	v_max_f32_e32 v108, 0, v6
	v_max_f32_e32 v109, 0, v7
	v_pk_mul_f32 v[50:51], v[244:245], v[108:109]
	v_max_f32_e32 v210, 0, v8
	v_max_f32_e32 v211, 0, v9
	v_pk_fma_f32 v[50:51], v[246:247], v[210:211], v[50:51]
	v_max_f32_e32 v108, 0, v10
	v_max_f32_e32 v109, 0, v11
	v_pk_fma_f32 v[50:51], v[248:249], v[108:109], v[50:51]
	s_waitcnt lgkmcnt(2)
	v_mfma_f32_32x32x16_bf16 v[212:227], v[74:77], v[42:45], v[212:227]
	v_max_f32_e32 v210, 0, v12
	v_max_f32_e32 v211, 0, v13
	v_pk_fma_f32 v[50:51], v[250:251], v[210:211], v[50:51]
	v_max_f32_e32 v108, 0, v14
	v_max_f32_e32 v109, 0, v15
	v_pk_fma_f32 v[50:51], v[252:253], v[108:109], v[50:51]
	v_max_f32_e32 v210, 0, v16
	v_max_f32_e32 v211, 0, v17
	v_pk_fma_f32 v[50:51], v[254:255], v[210:211], v[50:51]
	s_waitcnt lgkmcnt(1)
	v_mfma_f32_32x32x16_bf16 v[212:227], v[78:81], v[46:49], v[212:227]
	v_max_f32_e32 v108, 0, v18
	v_max_f32_e32 v109, 0, v19
	v_pk_fma_f32 v[50:51], v[200:201], v[108:109], v[50:51]
	v_max_f32_e32 v210, 0, v20
	v_max_f32_e32 v211, 0, v21
	v_pk_fma_f32 v[50:51], v[202:203], v[210:211], v[50:51]
	v_add_f32_e32 v50, v50, v51
	v_ashrrev_i32_e32 v51, 31, v50
	s_waitcnt lgkmcnt(0)
	v_mfma_f32_32x32x16_bf16 v[212:227], v[82:85], v[196:199], v[212:227]
	v_or_b32_e32 v51, 0x80000000, v51
	s_cmpk_gt_i32 s11, 488
	s_cselect_b64 vcc, -1, 0
	v_xor_b32_e32 v50, v51, v50
	v_cndmask_b32_e32 v50, v123, v50, vcc
	global_store_dword v243, v50, s[8:9] offset:2048
	s_add_u32 s8, s8, 0x1000
	s_addc_u32 s9, s9, 0
	v_mfma_f32_32x32x16_bf16 v[6:21], v[86:89], v[38:41], 0
	s_add_i32 m0, s10, 32768
	s_nop 0
	global_load_lds_dwordx4 v102, s[6:7]
	s_add_i32 m0, s10, 33792
	s_nop 0
	global_load_lds_dwordx4 v110, s[6:7]
	s_add_i32 m0, s10, 34816
	s_nop 0
	global_load_lds_dwordx4 v112, s[6:7]
	s_add_i32 m0, s10, 35840
	s_nop 0
	global_load_lds_dwordx4 v193, s[6:7]
	s_add_u32 s6, s6, 0x8000
	s_addc_u32 s7, s7, 0
	v_max_f32_e32 v108, 0, v212
	v_max_f32_e32 v109, 0, v213
	v_pk_mul_f32 v[0:1], v[22:23], v[108:109]
	v_max_f32_e32 v210, 0, v214
	v_max_f32_e32 v211, 0, v215
	v_pk_fma_f32 v[0:1], v[24:25], v[210:211], v[0:1]
	v_max_f32_e32 v108, 0, v216
	v_max_f32_e32 v109, 0, v217
	v_pk_fma_f32 v[0:1], v[26:27], v[108:109], v[0:1]
	v_mfma_f32_32x32x16_bf16 v[6:21], v[90:93], v[42:45], v[6:21]
	v_max_f32_e32 v210, 0, v218
	v_max_f32_e32 v211, 0, v219
	v_pk_fma_f32 v[0:1], v[28:29], v[210:211], v[0:1]
	v_max_f32_e32 v108, 0, v220
	v_max_f32_e32 v109, 0, v221
	v_pk_fma_f32 v[0:1], v[30:31], v[108:109], v[0:1]
	v_max_f32_e32 v210, 0, v222
	v_max_f32_e32 v211, 0, v223
	v_pk_fma_f32 v[0:1], v[32:33], v[210:211], v[0:1]
	v_mfma_f32_32x32x16_bf16 v[6:21], v[94:97], v[46:49], v[6:21]
	v_max_f32_e32 v108, 0, v224
	v_max_f32_e32 v109, 0, v225
	v_pk_fma_f32 v[0:1], v[34:35], v[108:109], v[0:1]
	v_max_f32_e32 v210, 0, v226
	v_max_f32_e32 v211, 0, v227
	v_pk_fma_f32 v[0:1], v[36:37], v[210:211], v[0:1]
	v_add_f32_e32 v0, v0, v1
	v_ashrrev_i32_e32 v1, 31, v0
	v_mfma_f32_32x32x16_bf16 v[6:21], v[98:101], v[196:199], v[6:21]
	s_waitcnt vmcnt(10)
	v_add_u32_e32 v228, 0x10000, v5
	ds_read_b128 v[38:41], v228 offset:43264
	v_add_u32_e32 v228, 0x10000, v52
	ds_read_b128 v[42:45], v228 offset:43264
	v_add_u32_e32 v228, 0x10000, v55
	ds_read_b128 v[46:49], v228 offset:43264
	v_add_u32_e32 v228, 0x10000, v56
	ds_read_b128 v[196:199], v228 offset:43264
	v_or_b32_e32 v1, 0x80000000, v1
	s_cmpk_gt_i32 s11, 496
	s_cselect_b64 vcc, -1, 0
	v_xor_b32_e32 v0, v1, v0
	v_cndmask_b32_e32 v4, v123, v0, vcc
	s_nop 1
	s_waitcnt lgkmcnt(3)
	v_mfma_f32_32x32x16_bf16 v[212:227], v[70:73], v[38:41], 0
	v_max_f32_e32 v108, 0, v6
	v_max_f32_e32 v109, 0, v7
	v_pk_mul_f32 v[50:51], v[244:245], v[108:109]
	v_max_f32_e32 v210, 0, v8
	v_max_f32_e32 v211, 0, v9
	v_pk_fma_f32 v[50:51], v[246:247], v[210:211], v[50:51]
	v_max_f32_e32 v108, 0, v10
	v_max_f32_e32 v109, 0, v11
	v_pk_fma_f32 v[50:51], v[248:249], v[108:109], v[50:51]
	s_waitcnt lgkmcnt(2)
	v_mfma_f32_32x32x16_bf16 v[212:227], v[74:77], v[42:45], v[212:227]
	v_max_f32_e32 v210, 0, v12
	v_max_f32_e32 v211, 0, v13
	v_pk_fma_f32 v[50:51], v[250:251], v[210:211], v[50:51]
	v_max_f32_e32 v108, 0, v14
	v_max_f32_e32 v109, 0, v15
	v_pk_fma_f32 v[50:51], v[252:253], v[108:109], v[50:51]
	v_max_f32_e32 v210, 0, v16
	v_max_f32_e32 v211, 0, v17
	v_pk_fma_f32 v[50:51], v[254:255], v[210:211], v[50:51]
	s_waitcnt lgkmcnt(1)
	v_mfma_f32_32x32x16_bf16 v[212:227], v[78:81], v[46:49], v[212:227]
	v_max_f32_e32 v108, 0, v18
	v_max_f32_e32 v109, 0, v19
	v_pk_fma_f32 v[50:51], v[200:201], v[108:109], v[50:51]
	v_max_f32_e32 v210, 0, v20
	v_max_f32_e32 v211, 0, v21
	v_pk_fma_f32 v[50:51], v[202:203], v[210:211], v[50:51]
	v_add_f32_e32 v50, v50, v51
	v_ashrrev_i32_e32 v51, 31, v50
	s_waitcnt lgkmcnt(0)
	v_mfma_f32_32x32x16_bf16 v[212:227], v[82:85], v[196:199], v[212:227]
	v_or_b32_e32 v51, 0x80000000, v51
	s_cmpk_gt_i32 s11, 496
	s_cselect_b64 vcc, -1, 0
	v_xor_b32_e32 v50, v51, v50
	v_cndmask_b32_e32 v50, v123, v50, vcc
	global_store_dword v243, v50, s[8:9]
	v_mfma_f32_32x32x16_bf16 v[6:21], v[86:89], v[38:41], 0
	s_add_i32 m0, s10, 65536
	s_nop 0
	global_load_lds_dwordx4 v102, s[6:7]
	s_add_i32 m0, s10, 66560
	s_nop 0
	global_load_lds_dwordx4 v110, s[6:7]
	s_add_i32 m0, s10, 67584
	s_nop 0
	global_load_lds_dwordx4 v112, s[6:7]
	s_add_i32 m0, s10, 68608
	s_nop 0
	global_load_lds_dwordx4 v193, s[6:7]
	s_add_u32 s6, s6, 0x8000
	s_addc_u32 s7, s7, 0
	v_max_f32_e32 v108, 0, v212
	v_max_f32_e32 v109, 0, v213
	v_pk_mul_f32 v[0:1], v[22:23], v[108:109]
	v_max_f32_e32 v210, 0, v214
	v_max_f32_e32 v211, 0, v215
	v_pk_fma_f32 v[0:1], v[24:25], v[210:211], v[0:1]
	v_max_f32_e32 v108, 0, v216
	v_max_f32_e32 v109, 0, v217
	v_pk_fma_f32 v[0:1], v[26:27], v[108:109], v[0:1]
	v_mfma_f32_32x32x16_bf16 v[6:21], v[90:93], v[42:45], v[6:21]
	v_max_f32_e32 v210, 0, v218
	v_max_f32_e32 v211, 0, v219
	v_pk_fma_f32 v[0:1], v[28:29], v[210:211], v[0:1]
	v_max_f32_e32 v108, 0, v220
	v_max_f32_e32 v109, 0, v221
	v_pk_fma_f32 v[0:1], v[30:31], v[108:109], v[0:1]
	v_max_f32_e32 v210, 0, v222
	v_max_f32_e32 v211, 0, v223
	v_pk_fma_f32 v[0:1], v[32:33], v[210:211], v[0:1]
	v_mfma_f32_32x32x16_bf16 v[6:21], v[94:97], v[46:49], v[6:21]
	v_max_f32_e32 v108, 0, v224
	v_max_f32_e32 v109, 0, v225
	v_pk_fma_f32 v[0:1], v[34:35], v[108:109], v[0:1]
	v_max_f32_e32 v210, 0, v226
	v_max_f32_e32 v211, 0, v227
	v_pk_fma_f32 v[0:1], v[36:37], v[210:211], v[0:1]
	v_add_f32_e32 v0, v0, v1
	v_ashrrev_i32_e32 v1, 31, v0
	v_mfma_f32_32x32x16_bf16 v[6:21], v[98:101], v[196:199], v[6:21]
	s_waitcnt vmcnt(10)
	ds_read_b128 v[38:41], v5 offset:10496
	ds_read_b128 v[42:45], v52 offset:10496
	ds_read_b128 v[46:49], v55 offset:10496
	ds_read_b128 v[196:199], v56 offset:10496
	v_or_b32_e32 v1, 0x80000000, v1
	s_cmpk_gt_i32 s11, 504
	s_cselect_b64 vcc, -1, 0
	v_xor_b32_e32 v0, v1, v0
	v_cndmask_b32_e32 v185, v123, v0, vcc
	s_nop 1
	v_max_f32_e32 v108, 0, v6
	v_max_f32_e32 v109, 0, v7
	v_pk_mul_f32 v[50:51], v[244:245], v[108:109]
	v_max_f32_e32 v210, 0, v8
	v_max_f32_e32 v211, 0, v9
	v_pk_fma_f32 v[50:51], v[246:247], v[210:211], v[50:51]
	v_max_f32_e32 v108, 0, v10
	v_max_f32_e32 v109, 0, v11
	v_pk_fma_f32 v[50:51], v[248:249], v[108:109], v[50:51]
	v_max_f32_e32 v210, 0, v12
	v_max_f32_e32 v211, 0, v13
	v_pk_fma_f32 v[50:51], v[250:251], v[210:211], v[50:51]
	v_max_f32_e32 v108, 0, v14
	v_max_f32_e32 v109, 0, v15
	v_pk_fma_f32 v[50:51], v[252:253], v[108:109], v[50:51]
	v_max_f32_e32 v210, 0, v16
	v_max_f32_e32 v211, 0, v17
	v_pk_fma_f32 v[50:51], v[254:255], v[210:211], v[50:51]
	v_max_f32_e32 v108, 0, v18
	v_max_f32_e32 v109, 0, v19
	v_pk_fma_f32 v[50:51], v[200:201], v[108:109], v[50:51]
	v_max_f32_e32 v210, 0, v20
	v_max_f32_e32 v211, 0, v21
	v_pk_fma_f32 v[50:51], v[202:203], v[210:211], v[50:51]
	v_add_f32_e32 v50, v50, v51
	v_ashrrev_i32_e32 v51, 31, v50
	v_or_b32_e32 v51, 0x80000000, v51
	s_cmpk_gt_i32 s11, 504
	s_cselect_b64 vcc, -1, 0
	v_xor_b32_e32 v50, v51, v50
	v_cndmask_b32_e32 v50, v123, v50, vcc
	global_store_dword v243, v50, s[8:9] offset:2048
	s_add_u32 s8, s8, 0x1000
	s_addc_u32 s9, s9, 0
	s_branch .Lix_done

.Lix_rdone:
.Lix_done:
	s_waitcnt vmcnt(0) lgkmcnt(0)

.LBB0_1337:
	s_or_b64 exec, exec, s[0:1]
	s_ashr_i32 s85, s83, 8
	s_cmpk_lt_u32 s83, 0x100
	s_cselect_b64 vcc, -1, 0
	s_lshl_b32 s0, s85, 13
	v_and_b32_e32 v9, 0xff, v129
	v_cndmask_b32_e32 v1, v105, v104, vcc
	s_add_i32 s0, s0, 0
	v_cmp_lt_i32_e32 vcc, v9, v1
	v_mov_b32_e32 v16, 0
	v_lshl_add_u32 v0, v9, 2, s0
	v_mov_b32_e32 v17, 0
	s_waitcnt vmcnt(0) lgkmcnt(0)
	s_barrier
	s_and_saveexec_b64 s[0:1], vcc
	ds_read_b32 v17, v0 offset:10496
	s_or_b64 exec, exec, s[0:1]
	v_or_b32_e32 v2, 0x100, v9
	v_cmp_lt_i32_e32 vcc, v2, v1
	s_and_saveexec_b64 s[0:1], vcc
	ds_read_b32 v16, v0 offset:11520
	s_or_b64 exec, exec, s[0:1]
	v_or_b32_e32 v2, 0x200, v9
	v_cmp_lt_i32_e32 vcc, v2, v1
	v_mov_b32_e32 v14, 0
	v_mov_b32_e32 v15, 0
	s_and_saveexec_b64 s[0:1], vcc
	ds_read_b32 v15, v0 offset:12544
	s_or_b64 exec, exec, s[0:1]
	v_or_b32_e32 v2, 0x300, v9
	v_cmp_lt_i32_e32 vcc, v2, v1
	s_and_saveexec_b64 s[0:1], vcc
	ds_read_b32 v14, v0 offset:13568
	s_or_b64 exec, exec, s[0:1]
	v_or_b32_e32 v2, 0x400, v9
	v_cmp_lt_i32_e32 vcc, v2, v1
	v_mov_b32_e32 v12, 0
	v_mov_b32_e32 v13, 0
	s_and_saveexec_b64 s[0:1], vcc
	ds_read_b32 v13, v0 offset:14592
	s_or_b64 exec, exec, s[0:1]
	v_or_b32_e32 v2, 0x500, v9
	v_cmp_lt_i32_e32 vcc, v2, v1
	s_and_saveexec_b64 s[0:1], vcc
	ds_read_b32 v12, v0 offset:15616
	s_or_b64 exec, exec, s[0:1]
	v_or_b32_e32 v2, 0x600, v9
	v_cmp_lt_i32_e32 vcc, v2, v1
	v_mov_b32_e32 v10, 0
	v_mov_b32_e32 v11, 0
	s_and_saveexec_b64 s[0:1], vcc
	ds_read_b32 v11, v0 offset:16640
	s_or_b64 exec, exec, s[0:1]
	v_or_b32_e32 v2, 0x700, v9
	v_cmp_lt_i32_e32 vcc, v2, v1
	s_and_saveexec_b64 s[0:1], vcc
	ds_read_b32 v10, v0 offset:17664
	s_or_b64 exec, exec, s[0:1]
	s_cmp_gt_i32 s84, 1
	s_cbranch_scc1 .LBB0_1436
	s_lshl_b32 s86, s84, 2
	v_mov_b32_e32 v0, s86
	v_add_u32_e32 v20, 0x1800, v0
	ds_read2_b32 v[0:1], v20 offset1:2
	ds_read2_b32 v[2:3], v20 offset0:4 offset1:6
	ds_read2_b32 v[4:5], v20 offset0:8 offset1:10
	ds_read2_b32 v[6:7], v20 offset0:12 offset1:14
	ds_read2_b32 v[18:19], v20 offset0:16 offset1:18
	ds_read2_b32 v[20:21], v20 offset0:20 offset1:22
	ds_read2_b32 v[22:23], v20 offset0:24 offset1:26
	ds_read2_b32 v[24:25], v20 offset0:28 offset1:30
	s_cmp_lt_u32 s83, 64
	s_cselect_b64 vcc, -1, 0
	v_cndmask_b32_e32 v32, v105, v104, vcc
	s_lshl_b32 s0, s84, 13
	v_lshl_add_u32 v50, v8, 2, s0
	v_readfirstlane_b32 s1, v32
	s_waitcnt lgkmcnt(0)
	v_min_u32_e32 v0, v0, v1
	v_min3_u32 v0, v0, v2, v3
	v_min3_u32 v0, v0, v4, v5
	v_min3_u32 v0, v0, v6, v7
	v_max_u32_e32 v1, v18, v19
	v_max3_u32 v1, v1, v20, v21
	v_max3_u32 v1, v1, v22, v23
	v_max3_u32 v1, v1, v24, v25
	s_add_i32 s20, s1, 63
	s_lshr_b32 s20, s20, 6
	v_readfirstlane_b32 s87, v0
	v_readfirstlane_b32 s0, v1
	s_nop 0
	s_sub_u32 s90, s0, s87
	ds_read_b32 v18, v50 offset:10496
	ds_read_b32 v19, v50 offset:10752
	ds_read_b32 v20, v50 offset:11008
	ds_read_b32 v21, v50 offset:11264
	ds_read_b32 v22, v50 offset:11520
	ds_read_b32 v23, v50 offset:11776
	ds_read_b32 v24, v50 offset:12032
	ds_read_b32 v25, v50 offset:12288
	s_cmp_gt_u32 s20, 8
	s_cbranch_scc0 .Lbs_ld_done
	ds_read_b32 v26, v50 offset:12544
	ds_read_b32 v27, v50 offset:12800
	ds_read_b32 v28, v50 offset:13056
	ds_read_b32 v29, v50 offset:13312
	ds_read_b32 v30, v50 offset:13568
	ds_read_b32 v31, v50 offset:13824
	ds_read_b32 v32, v50 offset:14080
	ds_read_b32 v33, v50 offset:14336
	s_cmp_gt_u32 s20, 16
	s_cbranch_scc0 .Lbs_ld_done
	ds_read_b32 v34, v50 offset:14592
	ds_read_b32 v35, v50 offset:14848
	ds_read_b32 v36, v50 offset:15104
	ds_read_b32 v37, v50 offset:15360
	ds_read_b32 v38, v50 offset:15616
	ds_read_b32 v39, v50 offset:15872
	ds_read_b32 v40, v50 offset:16128
	ds_read_b32 v41, v50 offset:16384
	s_cmp_gt_u32 s20, 24
	s_cbranch_scc0 .Lbs_ld_done
	ds_read_b32 v42, v50 offset:16640
	ds_read_b32 v43, v50 offset:16896
	ds_read_b32 v44, v50 offset:17152
	ds_read_b32 v45, v50 offset:17408
	ds_read_b32 v46, v50 offset:17664
	ds_read_b32 v47, v50 offset:17920
	ds_read_b32 v48, v50 offset:18176
	ds_read_b32 v49, v50 offset:18432
.Lbs_ld_done:
	s_waitcnt lgkmcnt(0)
	s_sub_i32 s91, s1, 0
	v_cmp_gt_i32_e64 s[6:7], s91, v8
	s_sub_i32 s91, s1, 64
	v_cmp_gt_i32_e64 s[8:9], s91, v8
	s_sub_i32 s91, s1, 128
	v_cmp_gt_i32_e64 s[10:11], s91, v8
	s_sub_i32 s91, s1, 192
	v_cmp_gt_i32_e64 s[12:13], s91, v8
	v_subrev_u32_e32 v18, s87, v18
	v_subrev_u32_e32 v19, s87, v19
	v_subrev_u32_e32 v20, s87, v20
	v_subrev_u32_e32 v21, s87, v21
	v_cndmask_b32_e64 v18, 0, v18, s[6:7]
	v_cndmask_b32_e64 v19, 0, v19, s[8:9]
	v_cndmask_b32_e64 v20, 0, v20, s[10:11]
	v_cndmask_b32_e64 v21, 0, v21, s[12:13]
	s_sub_i32 s91, s1, 256
	v_cmp_gt_i32_e64 s[6:7], s91, v8
	s_sub_i32 s91, s1, 320
	v_cmp_gt_i32_e64 s[8:9], s91, v8
	s_sub_i32 s91, s1, 384
	v_cmp_gt_i32_e64 s[10:11], s91, v8
	s_sub_i32 s91, s1, 448
	v_cmp_gt_i32_e64 s[12:13], s91, v8
	v_subrev_u32_e32 v22, s87, v22
	v_subrev_u32_e32 v23, s87, v23
	v_subrev_u32_e32 v24, s87, v24
	v_subrev_u32_e32 v25, s87, v25
	v_cndmask_b32_e64 v22, 0, v22, s[6:7]
	v_cndmask_b32_e64 v23, 0, v23, s[8:9]
	v_cndmask_b32_e64 v24, 0, v24, s[10:11]
	v_cndmask_b32_e64 v25, 0, v25, s[12:13]
	s_cmp_gt_u32 s20, 8
	s_cbranch_scc0 .Lbs_prep_done
	s_sub_i32 s91, s1, 512
	v_cmp_gt_i32_e64 s[6:7], s91, v8
	s_sub_i32 s91, s1, 576
	v_cmp_gt_i32_e64 s[8:9], s91, v8
	s_sub_i32 s91, s1, 640
	v_cmp_gt_i32_e64 s[10:11], s91, v8
	s_sub_i32 s91, s1, 704
	v_cmp_gt_i32_e64 s[12:13], s91, v8
	v_subrev_u32_e32 v26, s87, v26
	v_subrev_u32_e32 v27, s87, v27
	v_subrev_u32_e32 v28, s87, v28
	v_subrev_u32_e32 v29, s87, v29
	v_cndmask_b32_e64 v26, 0, v26, s[6:7]
	v_cndmask_b32_e64 v27, 0, v27, s[8:9]
	v_cndmask_b32_e64 v28, 0, v28, s[10:11]
	v_cndmask_b32_e64 v29, 0, v29, s[12:13]
	s_sub_i32 s91, s1, 768
	v_cmp_gt_i32_e64 s[6:7], s91, v8
	s_sub_i32 s91, s1, 832
	v_cmp_gt_i32_e64 s[8:9], s91, v8
	s_sub_i32 s91, s1, 896
	v_cmp_gt_i32_e64 s[10:11], s91, v8
	s_sub_i32 s91, s1, 960
	v_cmp_gt_i32_e64 s[12:13], s91, v8
	v_subrev_u32_e32 v30, s87, v30
	v_subrev_u32_e32 v31, s87, v31
	v_subrev_u32_e32 v32, s87, v32
	v_subrev_u32_e32 v33, s87, v33
	v_cndmask_b32_e64 v30, 0, v30, s[6:7]
	v_cndmask_b32_e64 v31, 0, v31, s[8:9]
	v_cndmask_b32_e64 v32, 0, v32, s[10:11]
	v_cndmask_b32_e64 v33, 0, v33, s[12:13]
	s_cmp_gt_u32 s20, 16
	s_cbranch_scc0 .Lbs_prep_done
	s_sub_i32 s91, s1, 1024
	v_cmp_gt_i32_e64 s[6:7], s91, v8
	s_sub_i32 s91, s1, 1088
	v_cmp_gt_i32_e64 s[8:9], s91, v8
	s_sub_i32 s91, s1, 1152
	v_cmp_gt_i32_e64 s[10:11], s91, v8
	s_sub_i32 s91, s1, 1216
	v_cmp_gt_i32_e64 s[12:13], s91, v8
	v_subrev_u32_e32 v34, s87, v34
	v_subrev_u32_e32 v35, s87, v35
	v_subrev_u32_e32 v36, s87, v36
	v_subrev_u32_e32 v37, s87, v37
	v_cndmask_b32_e64 v34, 0, v34, s[6:7]
	v_cndmask_b32_e64 v35, 0, v35, s[8:9]
	v_cndmask_b32_e64 v36, 0, v36, s[10:11]
	v_cndmask_b32_e64 v37, 0, v37, s[12:13]
	s_sub_i32 s91, s1, 1280
	v_cmp_gt_i32_e64 s[6:7], s91, v8
	s_sub_i32 s91, s1, 1344
	v_cmp_gt_i32_e64 s[8:9], s91, v8
	s_sub_i32 s91, s1, 1408
	v_cmp_gt_i32_e64 s[10:11], s91, v8
	s_sub_i32 s91, s1, 1472
	v_cmp_gt_i32_e64 s[12:13], s91, v8
	v_subrev_u32_e32 v38, s87, v38
	v_subrev_u32_e32 v39, s87, v39
	v_subrev_u32_e32 v40, s87, v40
	v_subrev_u32_e32 v41, s87, v41
	v_cndmask_b32_e64 v38, 0, v38, s[6:7]
	v_cndmask_b32_e64 v39, 0, v39, s[8:9]
	v_cndmask_b32_e64 v40, 0, v40, s[10:11]
	v_cndmask_b32_e64 v41, 0, v41, s[12:13]
	s_cmp_gt_u32 s20, 24
	s_cbranch_scc0 .Lbs_prep_done
	s_sub_i32 s91, s1, 1536
	v_cmp_gt_i32_e64 s[6:7], s91, v8
	s_sub_i32 s91, s1, 1600
	v_cmp_gt_i32_e64 s[8:9], s91, v8
	s_sub_i32 s91, s1, 1664
	v_cmp_gt_i32_e64 s[10:11], s91, v8
	s_sub_i32 s91, s1, 1728
	v_cmp_gt_i32_e64 s[12:13], s91, v8
	v_subrev_u32_e32 v42, s87, v42
	v_subrev_u32_e32 v43, s87, v43
	v_subrev_u32_e32 v44, s87, v44
	v_subrev_u32_e32 v45, s87, v45
	v_cndmask_b32_e64 v42, 0, v42, s[6:7]
	v_cndmask_b32_e64 v43, 0, v43, s[8:9]
	v_cndmask_b32_e64 v44, 0, v44, s[10:11]
	v_cndmask_b32_e64 v45, 0, v45, s[12:13]
	s_sub_i32 s91, s1, 1792
	v_cmp_gt_i32_e64 s[6:7], s91, v8
	s_sub_i32 s91, s1, 1856
	v_cmp_gt_i32_e64 s[8:9], s91, v8
	s_sub_i32 s91, s1, 1920
	v_cmp_gt_i32_e64 s[10:11], s91, v8
	s_sub_i32 s91, s1, 1984
	v_cmp_gt_i32_e64 s[12:13], s91, v8
	v_subrev_u32_e32 v46, s87, v46
	v_subrev_u32_e32 v47, s87, v47
	v_subrev_u32_e32 v48, s87, v48
	v_subrev_u32_e32 v49, s87, v49
	v_cndmask_b32_e64 v46, 0, v46, s[6:7]
	v_cndmask_b32_e64 v47, 0, v47, s[8:9]
	v_cndmask_b32_e64 v48, 0, v48, s[10:11]
	v_cndmask_b32_e64 v49, 0, v49, s[12:13]
.Lbs_prep_done:
	s_mov_b32 s0, s90
	s_mov_b32 s88, 0
	s_cmp_eq_u32 s0, 0
	s_cbranch_scc1 .Lbs_done
	s_flbit_i32_b32 s0, s0
	s_xor_b32 s89, s0, 31
.Lbs_loop:
	s_lshl_b32 s0, 1, s89
	s_or_b32 s90, s0, s88
	s_mov_b32 s91, 0
	v_cmp_le_u32_e64 s[6:7], s90, v18
	v_cmp_le_u32_e64 s[8:9], s90, v19
	v_cmp_le_u32_e64 s[10:11], s90, v20
	v_cmp_le_u32_e64 s[12:13], s90, v21
	s_bcnt1_i32_b64 s0, s[6:7]
	s_add_i32 s91, s91, s0
	s_bcnt1_i32_b64 s0, s[8:9]
	s_add_i32 s91, s91, s0
	s_bcnt1_i32_b64 s0, s[10:11]
	s_add_i32 s91, s91, s0
	s_bcnt1_i32_b64 s0, s[12:13]
	s_add_i32 s91, s91, s0
	v_cmp_le_u32_e64 s[6:7], s90, v22
	v_cmp_le_u32_e64 s[8:9], s90, v23
	v_cmp_le_u32_e64 s[10:11], s90, v24
	v_cmp_le_u32_e64 s[12:13], s90, v25
	s_bcnt1_i32_b64 s0, s[6:7]
	s_add_i32 s91, s91, s0
	s_bcnt1_i32_b64 s0, s[8:9]
	s_add_i32 s91, s91, s0
	s_bcnt1_i32_b64 s0, s[10:11]
	s_add_i32 s91, s91, s0
	s_bcnt1_i32_b64 s0, s[12:13]
	s_add_i32 s91, s91, s0
	s_cmp_gt_u32 s20, 8
	s_cbranch_scc0 .Lbs_cnt_done
	v_cmp_le_u32_e64 s[6:7], s90, v26
	v_cmp_le_u32_e64 s[8:9], s90, v27
	v_cmp_le_u32_e64 s[10:11], s90, v28
	v_cmp_le_u32_e64 s[12:13], s90, v29
	s_bcnt1_i32_b64 s0, s[6:7]
	s_add_i32 s91, s91, s0
	s_bcnt1_i32_b64 s0, s[8:9]
	s_add_i32 s91, s91, s0
	s_bcnt1_i32_b64 s0, s[10:11]
	s_add_i32 s91, s91, s0
	s_bcnt1_i32_b64 s0, s[12:13]
	s_add_i32 s91, s91, s0
	v_cmp_le_u32_e64 s[6:7], s90, v30
	v_cmp_le_u32_e64 s[8:9], s90, v31
	v_cmp_le_u32_e64 s[10:11], s90, v32
	v_cmp_le_u32_e64 s[12:13], s90, v33
	s_bcnt1_i32_b64 s0, s[6:7]
	s_add_i32 s91, s91, s0
	s_bcnt1_i32_b64 s0, s[8:9]
	s_add_i32 s91, s91, s0
	s_bcnt1_i32_b64 s0, s[10:11]
	s_add_i32 s91, s91, s0
	s_bcnt1_i32_b64 s0, s[12:13]
	s_add_i32 s91, s91, s0
	s_cmp_gt_u32 s20, 16
	s_cbranch_scc0 .Lbs_cnt_done
	v_cmp_le_u32_e64 s[6:7], s90, v34
	v_cmp_le_u32_e64 s[8:9], s90, v35
	v_cmp_le_u32_e64 s[10:11], s90, v36
	v_cmp_le_u32_e64 s[12:13], s90, v37
	s_bcnt1_i32_b64 s0, s[6:7]
	s_add_i32 s91, s91, s0
	s_bcnt1_i32_b64 s0, s[8:9]
	s_add_i32 s91, s91, s0
	s_bcnt1_i32_b64 s0, s[10:11]
	s_add_i32 s91, s91, s0
	s_bcnt1_i32_b64 s0, s[12:13]
	s_add_i32 s91, s91, s0
	v_cmp_le_u32_e64 s[6:7], s90, v38
	v_cmp_le_u32_e64 s[8:9], s90, v39
	v_cmp_le_u32_e64 s[10:11], s90, v40
	v_cmp_le_u32_e64 s[12:13], s90, v41
	s_bcnt1_i32_b64 s0, s[6:7]
	s_add_i32 s91, s91, s0
	s_bcnt1_i32_b64 s0, s[8:9]
	s_add_i32 s91, s91, s0
	s_bcnt1_i32_b64 s0, s[10:11]
	s_add_i32 s91, s91, s0
	s_bcnt1_i32_b64 s0, s[12:13]
	s_add_i32 s91, s91, s0
	s_cmp_gt_u32 s20, 24
	s_cbranch_scc0 .Lbs_cnt_done
	v_cmp_le_u32_e64 s[6:7], s90, v42
	v_cmp_le_u32_e64 s[8:9], s90, v43
	v_cmp_le_u32_e64 s[10:11], s90, v44
	v_cmp_le_u32_e64 s[12:13], s90, v45
	s_bcnt1_i32_b64 s0, s[6:7]
	s_add_i32 s91, s91, s0
	s_bcnt1_i32_b64 s0, s[8:9]
	s_add_i32 s91, s91, s0
	s_bcnt1_i32_b64 s0, s[10:11]
	s_add_i32 s91, s91, s0
	s_bcnt1_i32_b64 s0, s[12:13]
	s_add_i32 s91, s91, s0
	v_cmp_le_u32_e64 s[6:7], s90, v46
	v_cmp_le_u32_e64 s[8:9], s90, v47
	v_cmp_le_u32_e64 s[10:11], s90, v48
	v_cmp_le_u32_e64 s[12:13], s90, v49
	s_bcnt1_i32_b64 s0, s[6:7]
	s_add_i32 s91, s91, s0
	s_bcnt1_i32_b64 s0, s[8:9]
	s_add_i32 s91, s91, s0
	s_bcnt1_i32_b64 s0, s[10:11]
	s_add_i32 s91, s91, s0
	s_bcnt1_i32_b64 s0, s[12:13]
	s_add_i32 s91, s91, s0
.Lbs_cnt_done:
	s_cmpk_eq_i32 s91, 0x100
	s_cbranch_scc1 .Lbs_exact
	s_cmpk_gt_u32 s91, 0x100
	s_cselect_b32 s88, s90, s88
	s_add_i32 s89, s89, -1
	s_cmp_lt_i32 s89, 0
	s_cbranch_scc0 .Lbs_loop
	s_branch .Lbs_done
.Lbs_exact:
	s_add_i32 s88, s90, -1
.Lbs_done:
	s_add_i32 s6, s88, s87
	v_mov_b32_e32 v0, s86
	v_mov_b32_e32 v1, s6
	ds_write_b32 v0, v1 offset:6336
